# speedup vs baseline: 1.0471x; 1.0112x over previous
;   const int lane = tid & 63, wid = tid >> 6, fr = lane & 15, fq = lane >> 4;
;   float* stg = (float*)(smem + PATCH) + wid * (16 * 68);
;   asm volatile("" ::: "memory");
; #pragma unroll
;   for (int n = 0; n < 4; ++n)
; #pragma unroll
;     for (int j = 0; j < 4; ++j) stg[(fq * 4 + j) * 68 + n * 16 + fr] = am[n][j];
;   asm volatile("s_waitcnt lgkmcnt(0)" ::: "memory");
;   const float* rp = stg + (lane >> 2) * 68 + (lane & 3) * 16;
; #pragma unroll
;   for (int i = 0; i < 4; ++i) { f32x4 t = *(const f32x4*)(rp + i * 4); v[4 * i] = t[0]; v[4 * i + 1] = t[1]; v[4 * i + 2] = t[2]; v[4 * i + 3] = t[3]; }
; DI void phase_inproj0(const Params& p) {
;     ...
;       float rs = r0[row];
; #pragma unroll
;       for (int i = 0; i < 16; ++i) v[i] *= rs;
;       if (col < 1024) store16_bf(u + (size_t)row * 1024 + col, v);
;       else if (col < 1728) store16_bf(lat + (size_t)row * 704 + col - 1024, v);
;       else if (col < 3776) {
.LBB0_169:
	v_lshrrev_b32_e32 v2, 6, v150
	v_mul_lo_u32 v2, v2, s40
	s_add_i32 s6, 16, 0x10000
	v_add_u32_e32 v5, s6, v2
	v_lshrrev_b32_e32 v2, 2, v150
	v_and_b32_e32 v4, 15, v150
	v_and_b32_e32 v2, 12, v2
	v_lshlrev_b32_e32 v4, 2, v4
	v_mul_u32_u24_e32 v2, 0x110, v2
	v_add3_u32 v2, v5, v4, v2
	v_bfe_u32 v4, v150, 2, 4
	v_and_b32_e32 v137, 48, v151
	v_mul_u32_u24_e32 v134, 0x110, v4
	v_lshlrev_b32_e32 v135, 2, v137
	v_add3_u32 v144, v5, v134, v135
	v_ashrrev_i32_e32 v5, 1, v150
	v_and_b32_e32 v5, 0xffffff80, v5
	v_add_u32_e32 v5, s11, v5
	s_waitcnt vmcnt(0)
	s_barrier
	v_or_b32_e32 v134, v5, v4
	ds_write2_b32 v2, v130, v126 offset1:16
	ds_write2_b32 v2, v131, v127 offset0:68 offset1:84
	ds_write2_b32 v2, v132, v128 offset0:136 offset1:152
	ds_write2_b32 v2, v133, v129 offset0:204 offset1:220
	ds_write2_b32 v2, v122, v118 offset0:32 offset1:48
	ds_write2_b32 v2, v123, v119 offset0:100 offset1:116
	ds_write2_b32 v2, v124, v120 offset0:168 offset1:184
	ds_write2_b32 v2, v125, v121 offset0:236 offset1:252
	s_waitcnt lgkmcnt(0)
	v_ashrrev_i32_e32 v135, 31, v134
	ds_read_b128 v[120:123], v144
	ds_read_b128 v[124:127], v144 offset:16
	ds_read_b128 v[128:131], v144 offset:32
	ds_read_b128 v[146:149], v144 offset:48
	v_lshl_add_u64 v[4:5], v[134:135], 2, s[16:17]
	global_load_dword v136, v[4:5], off
	v_and_b32_e32 v4, 0xc0, v150
	v_or_b32_e32 v4, s10, v4
	v_mov_b32_e32 v119, v3
	v_or_b32_e32 v118, v4, v137
	s_waitcnt lgkmcnt(3)
	v_mov_b32_e32 v132, v120
	v_mov_b32_e32 v133, v122
	v_mov_b32_e32 v122, v121
	s_waitcnt lgkmcnt(2)
	v_mov_b32_e32 v120, v124
	v_mov_b32_e32 v121, v126
	v_mov_b32_e32 v126, v125
	s_waitcnt lgkmcnt(1)
	v_mov_b32_e32 v124, v128
	v_mov_b32_e32 v125, v130
	v_mov_b32_e32 v130, v129
	s_waitcnt lgkmcnt(0)
	v_mov_b32_e32 v128, v146
	v_mov_b32_e32 v129, v148
	v_mov_b32_e32 v148, v147
	v_cmp_lt_u32_e64 s[8:9], s42, v4
	v_cmp_gt_u32_e64 s[6:7], s43, v4
	v_cmp_lt_i32_e64 s[10:11], s41, v118
	v_lshl_add_u64 v[4:5], v[118:119], 1, s[12:13]
	s_waitcnt vmcnt(0)
	v_pk_mul_f32 v[142:143], v[132:133], v[136:137] op_sel_hi:[1,0]
	v_pk_mul_f32 v[140:141], v[122:123], v[136:137] op_sel_hi:[1,0]
	v_pk_mul_f32 v[138:139], v[120:121], v[136:137] op_sel_hi:[1,0]
	v_pk_mul_f32 v[132:133], v[126:127], v[136:137] op_sel_hi:[1,0]
	v_pk_mul_f32 v[126:127], v[124:125], v[136:137] op_sel_hi:[1,0]
	v_pk_mul_f32 v[124:125], v[130:131], v[136:137] op_sel_hi:[1,0]
	v_pk_mul_f32 v[122:123], v[128:129], v[136:137] op_sel_hi:[1,0]
	v_pk_mul_f32 v[120:121], v[148:149], v[136:137] op_sel_hi:[1,0]
	s_and_saveexec_b64 s[26:27], s[10:11]
	s_xor_b64 s[26:27], exec, s[26:27]
	s_cbranch_execz .LBB0_177
	s_and_saveexec_b64 s[36:37], s[8:9]
	s_xor_b64 s[36:37], exec, s[36:37]
	s_cbranch_execz .LBB0_174
	s_and_saveexec_b64 s[38:39], s[6:7]
	s_cbranch_execz .LBB0_173
; DI float sigm(float x) { return 1.f / (1.f + __expf(-x)); }
; DI float siluf(float x) { return x * sigm(x); }
; DI void phase_inproj0(const Params& p) {
;     ...
;       else if (col < 3776) {
; #pragma unroll
;         for (int i = 0; i < 16; ++i) v[i] = siluf(v[i]);
;         store16_bf(G0 + (size_t)row * 2048 + col - 1728, v); }
	v_mul_f32_e32 v119, 0xbfb8aa3b, v142
	v_exp_f32_e32 v128, v119
	v_mul_f32_e32 v119, 0xbfb8aa3b, v140
	v_exp_f32_e32 v146, v119
	v_mul_f32_e32 v119, 0xbfb8aa3b, v143
	v_exp_f32_e32 v129, v119
	v_mul_f32_e32 v119, 0xbfb8aa3b, v141
	v_exp_f32_e32 v147, v119
	v_mul_f32_e32 v119, 0xbfb8aa3b, v138
	v_exp_f32_e32 v148, v119
	v_mul_f32_e32 v119, 0xbfb8aa3b, v132
	v_exp_f32_e32 v150, v119
	v_mul_f32_e32 v119, 0xbfb8aa3b, v139
	v_exp_f32_e32 v149, v119
	v_mul_f32_e32 v119, 0xbfb8aa3b, v133
	v_exp_f32_e32 v151, v119
	v_mul_f32_e32 v119, 0xbfb8aa3b, v126
	v_exp_f32_e32 v152, v119
	v_mul_f32_e32 v119, 0xbfb8aa3b, v124
	v_exp_f32_e32 v154, v119
	v_mul_f32_e32 v119, 0xbfb8aa3b, v127
	v_pk_add_f32 v[158:159], v[128:129], 1.0 op_sel_hi:[1,0]
	v_exp_f32_e32 v153, v119
	v_mul_f32_e32 v119, 0xbfb8aa3b, v125
	v_exp_f32_e32 v155, v119
	v_mul_f32_e32 v119, 0xbfb8aa3b, v122
	v_exp_f32_e32 v136, v119
	v_mul_f32_e32 v119, 0xbfb8aa3b, v120
	v_exp_f32_e32 v130, v119
	v_mul_f32_e32 v119, 0xbfb8aa3b, v123
	v_exp_f32_e32 v137, v119
	v_mul_f32_e32 v119, 0xbfb8aa3b, v121
	v_exp_f32_e32 v131, v119
	v_rcp_f32_e32 v159, v159
	v_pk_add_f32 v[146:147], v[146:147], 1.0 op_sel_hi:[1,0]
	v_rcp_f32_e32 v158, v158
	s_nop 0
	v_pk_mul_f32 v[142:143], v[142:143], v[158:159]
	v_rcp_f32_e32 v147, v147
	v_pk_add_f32 v[148:149], v[148:149], 1.0 op_sel_hi:[1,0]
	v_rcp_f32_e32 v146, v146
	s_nop 0
	v_pk_mul_f32 v[140:141], v[140:141], v[146:147]
	v_rcp_f32_e32 v147, v149
	v_pk_add_f32 v[150:151], v[150:151], 1.0 op_sel_hi:[1,0]
	v_rcp_f32_e32 v146, v148
	s_nop 0
	v_pk_mul_f32 v[138:139], v[138:139], v[146:147]
	v_rcp_f32_e32 v147, v151
	v_pk_add_f32 v[136:137], v[136:137], 1.0 op_sel_hi:[1,0]
	v_rcp_f32_e32 v146, v150
	s_nop 0
	v_pk_mul_f32 v[132:133], v[132:133], v[146:147]
	v_bfe_u32 v147, v140, 16, 1
	v_bfe_u32 v145, v132, 16, 1
	v_bfe_u32 v119, v133, 16, 1
	v_add3_u32 v147, v140, v147, s44
	v_add3_u32 v140, v132, v145, s44
	v_bfe_u32 v132, v142, 16, 1
	v_bfe_u32 v145, v139, 16, 1
	v_bfe_u32 v146, v141, 16, 1
	v_add3_u32 v119, v133, v119, s44
	v_bfe_u32 v133, v143, 16, 1
	v_add3_u32 v139, v139, v145, s44
	v_add3_u32 v132, v142, v132, s44
	v_add3_u32 v146, v141, v146, s44
	v_bfe_u32 v141, v138, 16, 1
	v_add3_u32 v133, v143, v133, s44
	v_lshrrev_b32_e32 v142, 16, v132
	v_lshrrev_b32_e32 v132, 16, v139
	v_add3_u32 v138, v138, v141, s44
	v_lshrrev_b32_e32 v143, 16, v133
	v_and_or_b32 v141, v119, s33, v132
	v_pk_add_f32 v[132:133], v[152:153], 1.0 op_sel_hi:[1,0]
	v_lshrrev_b32_e32 v138, 16, v138
	v_and_or_b32 v140, v140, s33, v138
	v_and_or_b32 v138, v147, s33, v142
	v_and_or_b32 v139, v146, s33, v143
	v_rcp_f32_e32 v133, v133
	v_pk_add_f32 v[130:131], v[130:131], 1.0 op_sel_hi:[1,0]
	v_pk_add_f32 v[142:143], v[154:155], 1.0 op_sel_hi:[1,0]
	v_rcp_f32_e32 v132, v132
	s_nop 0
	v_pk_mul_f32 v[126:127], v[126:127], v[132:133]
	v_rcp_f32_e32 v133, v143
	v_rcp_f32_e32 v132, v142
	s_nop 0
	v_pk_mul_f32 v[124:125], v[124:125], v[132:133]
	v_rcp_f32_e32 v133, v137
	v_lshlrev_b64 v[128:129], 12, v[134:135]
	v_rcp_f32_e32 v132, v136
	s_nop 0
	v_pk_mul_f32 v[122:123], v[122:123], v[132:133]
	v_div_scale_f32 v133, s[46:47], v130, v130, 1.0
	v_rcp_f32_e32 v136, v133
	v_rcp_f32_e32 v131, v131
	v_fma_f32 v119, -v133, v136, 1.0
	v_fmac_f32_e32 v136, v119, v136
	v_div_scale_f32 v119, vcc, 1.0, v130, 1.0
	v_mul_f32_e32 v132, v119, v136
	v_fma_f32 v137, -v133, v132, v119
	v_fmac_f32_e32 v132, v137, v136
	v_fma_f32 v119, -v133, v132, v119
	v_div_fmas_f32 v119, v119, v136, v132
	v_div_fixup_f32 v130, v119, v130, 1.0
	v_pk_mul_f32 v[120:121], v[120:121], v[130:131]
	v_bfe_u32 v131, v125, 16, 1
	v_bfe_u32 v119, v121, 16, 1
	v_bfe_u32 v130, v120, 16, 1
	v_add3_u32 v125, v125, v131, s44
	v_add3_u32 v119, v121, v119, s44
	v_bfe_u32 v121, v126, 16, 1
	v_bfe_u32 v131, v122, 16, 1
	v_bfe_u32 v132, v124, 16, 1
	v_add3_u32 v120, v120, v130, s44
	v_bfe_u32 v130, v127, 16, 1
	v_add3_u32 v122, v122, v131, s44
	v_add3_u32 v121, v126, v121, s44
	v_lshl_add_u64 v[128:129], v[4:5], 0, v[128:129]
	v_add3_u32 v124, v124, v132, s44
	v_bfe_u32 v132, v123, 16, 1
	v_add3_u32 v127, v127, v130, s44
	v_lshrrev_b32_e32 v126, 16, v121
	v_lshrrev_b32_e32 v122, 16, v122
	v_add3_u32 v123, v123, v132, s44
	v_lshrrev_b32_e32 v121, 16, v127
	v_and_or_b32 v122, v120, s33, v122
	v_and_or_b32 v120, v124, s33, v126
	v_add_co_u32_e32 v124, vcc, 0x13bfb000, v128
	v_lshrrev_b32_e32 v123, 16, v123
	v_and_or_b32 v121, v125, s33, v121
	v_addc_co_u32_e32 v125, vcc, 0, v129, vcc
	v_and_or_b32 v123, v119, s33, v123
	global_store_dwordx4 v[124:125], v[138:141], off offset:640
	global_store_dwordx4 v[124:125], v[120:123], off offset:656

; DI float siluf(float x) { return x * sigm(x); }
;   const int lane = tid & 63, wid = tid >> 6, fr = lane & 15, fq = lane >> 4;
;   float* stg = (float*)(smem + PATCH) + wid * (16 * 68);
;   asm volatile("" ::: "memory");
; #pragma unroll
;   for (int n = 0; n < 4; ++n)
; #pragma unroll
;     for (int j = 0; j < 4; ++j) stg[(fq * 4 + j) * 68 + n * 16 + fr] = am[n][j];
;   asm volatile("s_waitcnt lgkmcnt(0)" ::: "memory");
;   const float* rp = stg + (lane >> 2) * 68 + (lane & 3) * 16;
; #pragma unroll
;   for (int i = 0; i < 4; ++i) { f32x4 t = *(const f32x4*)(rp + i * 4); v[4 * i] = t[0]; v[4 * i + 1] = t[1]; v[4 * i + 2] = t[2]; v[4 * i + 3] = t[3]; }
; DI void phase_inproj0(const Params& p) {
;     ...
;       float rs = r0[row];
; #pragma unroll
;       for (int i = 0; i < 16; ++i) v[i] *= rs;
;       if (col < 1024) store16_bf(u + (size_t)row * 1024 + col, v);
;       else if (col < 1728) store16_bf(lat + (size_t)row * 704 + col - 1024, v);
;       else if (col < 3776) {
; #pragma unroll
;         for (int i = 0; i < 16; ++i) v[i] = siluf(v[i]);
;         store16_bf(G0 + (size_t)row * 2048 + col - 1728, v); }
.LBB0_179:
	s_or_b64 exec, exec, s[26:27]
	ds_write2_b32 v2, v114, v110 offset1:16
	ds_write2_b32 v2, v115, v111 offset0:68 offset1:84
	ds_write2_b32 v2, v116, v112 offset0:136 offset1:152
	ds_write2_b32 v2, v117, v113 offset0:204 offset1:220
	ds_write2_b32 v2, v106, v102 offset0:32 offset1:48
	ds_write2_b32 v2, v107, v103 offset0:100 offset1:116
	ds_write2_b32 v2, v108, v104 offset0:168 offset1:184
	ds_write2_b32 v2, v109, v105 offset0:236 offset1:252
	v_or_b32_e32 v110, 16, v134
	s_waitcnt lgkmcnt(0)
	v_ashrrev_i32_e32 v111, 31, v110
	ds_read_b128 v[102:105], v144
	ds_read_b128 v[106:109], v144 offset:16
	ds_read_b128 v[124:127], v144 offset:32
	ds_read_b128 v[128:131], v144 offset:48
	v_lshl_add_u64 v[112:113], v[110:111], 2, s[16:17]
	global_load_dword v112, v[112:113], off
	s_waitcnt lgkmcnt(3)
	v_mov_b32_e32 v114, v102
	v_mov_b32_e32 v115, v104
	v_mov_b32_e32 v104, v103
	s_waitcnt lgkmcnt(2)
	v_mov_b32_e32 v102, v106
	v_mov_b32_e32 v103, v108
	v_mov_b32_e32 v108, v107
	s_waitcnt lgkmcnt(1)
	v_mov_b32_e32 v106, v124
	v_mov_b32_e32 v107, v126
	v_mov_b32_e32 v126, v125
	s_waitcnt lgkmcnt(0)
	v_mov_b32_e32 v120, v128
	v_mov_b32_e32 v121, v130
	v_mov_b32_e32 v130, v129
	s_waitcnt vmcnt(0)
	v_pk_mul_f32 v[124:125], v[114:115], v[112:113] op_sel_hi:[1,0]
	v_pk_mul_f32 v[122:123], v[104:105], v[112:113] op_sel_hi:[1,0]
	v_pk_mul_f32 v[116:117], v[102:103], v[112:113] op_sel_hi:[1,0]
	v_pk_mul_f32 v[114:115], v[108:109], v[112:113] op_sel_hi:[1,0]
	v_pk_mul_f32 v[108:109], v[106:107], v[112:113] op_sel_hi:[1,0]
	v_pk_mul_f32 v[106:107], v[126:127], v[112:113] op_sel_hi:[1,0]
	v_pk_mul_f32 v[104:105], v[120:121], v[112:113] op_sel_hi:[1,0]
	v_pk_mul_f32 v[102:103], v[130:131], v[112:113] op_sel_hi:[1,0]
	s_and_saveexec_b64 s[26:27], s[10:11]
	s_xor_b64 s[26:27], exec, s[26:27]
	s_cbranch_execz .LBB0_187
	s_and_saveexec_b64 s[36:37], s[8:9]
	s_xor_b64 s[36:37], exec, s[36:37]
	s_cbranch_execz .LBB0_184
	s_and_saveexec_b64 s[38:39], s[6:7]
	s_cbranch_execz .LBB0_183
	v_mul_f32_e32 v112, 0xbfb8aa3b, v124
	v_exp_f32_e32 v126, v112
	v_mul_f32_e32 v112, 0xbfb8aa3b, v122
	v_exp_f32_e32 v128, v112
	v_mul_f32_e32 v112, 0xbfb8aa3b, v125
	v_exp_f32_e32 v127, v112
	v_mul_f32_e32 v112, 0xbfb8aa3b, v123
	v_exp_f32_e32 v129, v112
	v_mul_f32_e32 v112, 0xbfb8aa3b, v116
	v_pk_add_f32 v[126:127], v[126:127], 1.0 op_sel_hi:[1,0]
	v_exp_f32_e32 v130, v112
	v_pk_add_f32 v[128:129], v[128:129], 1.0 op_sel_hi:[1,0]
	v_mul_f32_e32 v112, 0xbfb8aa3b, v114
	v_exp_f32_e32 v132, v112
	v_rcp_f32_e32 v127, v127
	v_mul_f32_e32 v112, 0xbfb8aa3b, v117
	v_rcp_f32_e32 v126, v126
	s_nop 0
	v_pk_mul_f32 v[124:125], v[124:125], v[126:127]
	v_exp_f32_e32 v131, v112
	v_rcp_f32_e32 v127, v129
	v_pk_add_f32 v[130:131], v[130:131], 1.0 op_sel_hi:[1,0]
	v_rcp_f32_e32 v126, v128
	s_nop 0
	v_pk_mul_f32 v[122:123], v[122:123], v[126:127]
	v_mul_f32_e32 v112, 0xbfb8aa3b, v115
	v_rcp_f32_e32 v127, v131
	v_exp_f32_e32 v133, v112
	s_nop 0
	v_pk_add_f32 v[128:129], v[132:133], 1.0 op_sel_hi:[1,0]
	v_rcp_f32_e32 v126, v130
	s_nop 0
	v_pk_mul_f32 v[116:117], v[116:117], v[126:127]
	v_mul_f32_e32 v112, 0xbfb8aa3b, v108
	v_rcp_f32_e32 v127, v129
	v_exp_f32_e32 v136, v112
	v_mul_f32_e32 v112, 0xbfb8aa3b, v106
	v_exp_f32_e32 v138, v112
	v_mul_f32_e32 v112, 0xbfb8aa3b, v109
	v_exp_f32_e32 v137, v112
	v_rcp_f32_e32 v126, v128
	v_bfe_u32 v128, v123, 16, 1
	v_bfe_u32 v129, v122, 16, 1
	v_pk_mul_f32 v[114:115], v[114:115], v[126:127]
	v_add3_u32 v129, v122, v129, s44
	v_add3_u32 v128, v123, v128, s44
	v_bfe_u32 v122, v124, 16, 1
	v_bfe_u32 v123, v125, 16, 1
	v_bfe_u32 v126, v115, 16, 1
	v_add3_u32 v123, v125, v123, s44
	v_add3_u32 v122, v124, v122, s44
	v_bfe_u32 v127, v114, 16, 1
	v_add3_u32 v115, v115, v126, s44
	v_bfe_u32 v126, v116, 16, 1
	v_lshrrev_b32_e32 v124, 16, v122
	v_lshrrev_b32_e32 v125, 16, v123
	v_pk_add_f32 v[122:123], v[136:137], 1.0 op_sel_hi:[1,0]
	v_add3_u32 v114, v114, v127, s44
	v_bfe_u32 v127, v117, 16, 1
	v_add3_u32 v116, v116, v126, s44
	v_add3_u32 v117, v117, v127, s44
	v_lshrrev_b32_e32 v116, 16, v116
	v_and_or_b32 v116, v114, s33, v116
	v_and_or_b32 v114, v129, s33, v124
	v_lshrrev_b32_e32 v117, 16, v117
	v_and_or_b32 v117, v115, s33, v117
	v_and_or_b32 v115, v128, s33, v125
	v_mul_f32_e32 v112, 0xbfb8aa3b, v107
	v_rcp_f32_e32 v123, v123
	v_exp_f32_e32 v139, v112
	s_nop 0
	v_pk_add_f32 v[124:125], v[138:139], 1.0 op_sel_hi:[1,0]
	v_rcp_f32_e32 v122, v122
	s_nop 0
	v_pk_mul_f32 v[108:109], v[108:109], v[122:123]
	v_mul_f32_e32 v112, 0xbfb8aa3b, v104
	v_mul_f32_e32 v113, 0xbfb8aa3b, v105
	v_exp_f32_e32 v120, v112
	v_exp_f32_e32 v121, v113
	v_rcp_f32_e32 v123, v125
	v_pk_add_f32 v[120:121], v[120:121], 1.0 op_sel_hi:[1,0]
	v_rcp_f32_e32 v122, v124
	s_nop 0
	v_pk_mul_f32 v[106:107], v[106:107], v[122:123]
	v_mul_f32_e32 v112, 0xbfb8aa3b, v102
	v_mul_f32_e32 v113, 0xbfb8aa3b, v103
	v_exp_f32_e32 v112, v112
	v_exp_f32_e32 v113, v113
	v_rcp_f32_e32 v121, v121
	v_pk_add_f32 v[112:113], v[112:113], 1.0 op_sel_hi:[1,0]
	v_rcp_f32_e32 v120, v120
	s_nop 0
	v_pk_mul_f32 v[104:105], v[104:105], v[120:121]
	v_div_scale_f32 v122, s[46:47], v112, v112, 1.0
	v_rcp_f32_e32 v123, v122
	v_rcp_f32_e32 v113, v113
	v_fma_f32 v120, -v122, v123, 1.0
	v_fmac_f32_e32 v123, v120, v123
	v_div_scale_f32 v120, vcc, 1.0, v112, 1.0
	v_mul_f32_e32 v121, v120, v123
	v_fma_f32 v124, -v122, v121, v120
	v_fmac_f32_e32 v121, v124, v123
	v_fma_f32 v120, -v122, v121, v120
	v_div_fmas_f32 v120, v120, v123, v121
	v_div_fixup_f32 v112, v120, v112, 1.0
	v_pk_mul_f32 v[102:103], v[102:103], v[112:113]
	v_bfe_u32 v120, v107, 16, 1
	v_bfe_u32 v112, v103, 16, 1
	v_bfe_u32 v113, v102, 16, 1
	v_bfe_u32 v121, v106, 16, 1
	v_add3_u32 v107, v107, v120, s44
	v_add3_u32 v103, v103, v112, s44
	v_bfe_u32 v112, v108, 16, 1
	v_bfe_u32 v120, v104, 16, 1
	v_lshlrev_b64 v[110:111], 12, v[110:111]
	v_add3_u32 v106, v106, v121, s44
	v_add3_u32 v102, v102, v113, s44
	v_bfe_u32 v113, v109, 16, 1
	v_bfe_u32 v121, v105, 16, 1
	v_add3_u32 v104, v104, v120, s44
	v_add3_u32 v108, v108, v112, s44
	v_lshl_add_u64 v[110:111], v[4:5], 0, v[110:111]
	v_add3_u32 v105, v105, v121, s44
	v_add3_u32 v109, v109, v113, s44
	v_lshrrev_b32_e32 v108, 16, v108
	v_lshrrev_b32_e32 v104, 16, v104
	v_lshrrev_b32_e32 v109, 16, v109
	v_lshrrev_b32_e32 v105, 16, v105
	v_and_or_b32 v104, v102, s33, v104
	v_and_or_b32 v102, v106, s33, v108
	v_add_co_u32_e32 v106, vcc, 0x13bfb000, v110
	v_and_or_b32 v105, v103, s33, v105
	v_and_or_b32 v103, v107, s33, v109
	v_addc_co_u32_e32 v107, vcc, 0, v111, vcc
	global_store_dwordx4 v[106:107], v[114:117], off offset:640
	global_store_dwordx4 v[106:107], v[102:105], off offset:656

; DI float siluf(float x) { return x * sigm(x); }
;   const int lane = tid & 63, wid = tid >> 6, fr = lane & 15, fq = lane >> 4;
;   float* stg = (float*)(smem + PATCH) + wid * (16 * 68);
;   asm volatile("" ::: "memory");
; #pragma unroll
;   for (int n = 0; n < 4; ++n)
; #pragma unroll
;     for (int j = 0; j < 4; ++j) stg[(fq * 4 + j) * 68 + n * 16 + fr] = am[n][j];
;   asm volatile("s_waitcnt lgkmcnt(0)" ::: "memory");
;   const float* rp = stg + (lane >> 2) * 68 + (lane & 3) * 16;
; #pragma unroll
;   for (int i = 0; i < 4; ++i) { f32x4 t = *(const f32x4*)(rp + i * 4); v[4 * i] = t[0]; v[4 * i + 1] = t[1]; v[4 * i + 2] = t[2]; v[4 * i + 3] = t[3]; }
; DI void phase_inproj0(const Params& p) {
;     ...
;       float rs = r0[row];
; #pragma unroll
;       for (int i = 0; i < 16; ++i) v[i] *= rs;
;       if (col < 1024) store16_bf(u + (size_t)row * 1024 + col, v);
;       else if (col < 1728) store16_bf(lat + (size_t)row * 704 + col - 1024, v);
;       else if (col < 3776) {
; #pragma unroll
;         for (int i = 0; i < 16; ++i) v[i] = siluf(v[i]);
;         store16_bf(G0 + (size_t)row * 2048 + col - 1728, v); }
.LBB0_189:
	s_or_b64 exec, exec, s[26:27]
	ds_write2_b32 v2, v98, v94 offset1:16
	ds_write2_b32 v2, v99, v95 offset0:68 offset1:84
	ds_write2_b32 v2, v100, v96 offset0:136 offset1:152
	ds_write2_b32 v2, v101, v97 offset0:204 offset1:220
	ds_write2_b32 v2, v90, v86 offset0:32 offset1:48
	ds_write2_b32 v2, v91, v87 offset0:100 offset1:116
	ds_write2_b32 v2, v92, v88 offset0:168 offset1:184
	ds_write2_b32 v2, v93, v89 offset0:236 offset1:252
	v_or_b32_e32 v94, 32, v134
	s_waitcnt lgkmcnt(0)
	v_ashrrev_i32_e32 v95, 31, v94
	ds_read_b128 v[86:89], v144
	ds_read_b128 v[90:93], v144 offset:16
	ds_read_b128 v[100:103], v144 offset:32
	ds_read_b128 v[106:109], v144 offset:48
	v_lshl_add_u64 v[96:97], v[94:95], 2, s[16:17]
	global_load_dword v96, v[96:97], off
	s_waitcnt lgkmcnt(3)
	v_mov_b32_e32 v98, v86
	v_mov_b32_e32 v99, v88
	v_mov_b32_e32 v88, v87
	s_waitcnt lgkmcnt(2)
	v_mov_b32_e32 v86, v90
	v_mov_b32_e32 v87, v92
	v_mov_b32_e32 v92, v91
	s_waitcnt lgkmcnt(1)
	v_mov_b32_e32 v90, v100
	v_mov_b32_e32 v91, v102
	v_mov_b32_e32 v102, v101
	s_waitcnt lgkmcnt(0)
	v_mov_b32_e32 v110, v106
	v_mov_b32_e32 v111, v108
	v_mov_b32_e32 v108, v107
	s_waitcnt vmcnt(0)
	v_pk_mul_f32 v[106:107], v[98:99], v[96:97] op_sel_hi:[1,0]
	v_pk_mul_f32 v[104:105], v[88:89], v[96:97] op_sel_hi:[1,0]
	v_pk_mul_f32 v[100:101], v[86:87], v[96:97] op_sel_hi:[1,0]
	v_pk_mul_f32 v[98:99], v[92:93], v[96:97] op_sel_hi:[1,0]
	v_pk_mul_f32 v[92:93], v[90:91], v[96:97] op_sel_hi:[1,0]
	v_pk_mul_f32 v[90:91], v[102:103], v[96:97] op_sel_hi:[1,0]
	v_pk_mul_f32 v[88:89], v[110:111], v[96:97] op_sel_hi:[1,0]
	v_pk_mul_f32 v[86:87], v[108:109], v[96:97] op_sel_hi:[1,0]
	s_and_saveexec_b64 s[26:27], s[10:11]
	s_xor_b64 s[26:27], exec, s[26:27]
	s_cbranch_execz .LBB0_197
	s_and_saveexec_b64 s[36:37], s[8:9]
	s_xor_b64 s[36:37], exec, s[36:37]
	s_cbranch_execz .LBB0_194
	s_and_saveexec_b64 s[38:39], s[6:7]
	s_cbranch_execz .LBB0_193
	v_mul_f32_e32 v96, 0xbfb8aa3b, v106
	v_exp_f32_e32 v108, v96
	v_mul_f32_e32 v96, 0xbfb8aa3b, v104
	v_exp_f32_e32 v110, v96
	v_mul_f32_e32 v96, 0xbfb8aa3b, v107
	v_exp_f32_e32 v109, v96
	v_mul_f32_e32 v96, 0xbfb8aa3b, v105
	v_exp_f32_e32 v111, v96
	v_mul_f32_e32 v96, 0xbfb8aa3b, v100
	v_pk_add_f32 v[108:109], v[108:109], 1.0 op_sel_hi:[1,0]
	v_exp_f32_e32 v112, v96
	v_pk_add_f32 v[110:111], v[110:111], 1.0 op_sel_hi:[1,0]
	v_mul_f32_e32 v96, 0xbfb8aa3b, v98
	v_exp_f32_e32 v114, v96
	v_rcp_f32_e32 v109, v109
	v_mul_f32_e32 v96, 0xbfb8aa3b, v101
	v_rcp_f32_e32 v108, v108
	s_nop 0
	v_pk_mul_f32 v[106:107], v[106:107], v[108:109]
	v_exp_f32_e32 v113, v96
	v_rcp_f32_e32 v109, v111
	v_pk_add_f32 v[112:113], v[112:113], 1.0 op_sel_hi:[1,0]
	v_rcp_f32_e32 v108, v110
	s_nop 0
	v_pk_mul_f32 v[104:105], v[104:105], v[108:109]
	v_mul_f32_e32 v96, 0xbfb8aa3b, v99
	v_rcp_f32_e32 v109, v113
	v_exp_f32_e32 v115, v96
	s_nop 0
	v_pk_add_f32 v[110:111], v[114:115], 1.0 op_sel_hi:[1,0]
	v_rcp_f32_e32 v108, v112
	s_nop 0
	v_pk_mul_f32 v[100:101], v[100:101], v[108:109]
	v_mul_f32_e32 v96, 0xbfb8aa3b, v92
	v_rcp_f32_e32 v109, v111
	v_exp_f32_e32 v116, v96
	v_mul_f32_e32 v96, 0xbfb8aa3b, v90
	v_exp_f32_e32 v120, v96
	v_mul_f32_e32 v96, 0xbfb8aa3b, v93
	v_exp_f32_e32 v117, v96
	v_rcp_f32_e32 v108, v110
	v_bfe_u32 v110, v105, 16, 1
	v_bfe_u32 v111, v104, 16, 1
	v_pk_mul_f32 v[98:99], v[98:99], v[108:109]
	v_add3_u32 v111, v104, v111, s44
	v_add3_u32 v110, v105, v110, s44
	v_bfe_u32 v104, v106, 16, 1
	v_bfe_u32 v105, v107, 16, 1
	v_bfe_u32 v108, v99, 16, 1
	v_add3_u32 v105, v107, v105, s44
	v_add3_u32 v104, v106, v104, s44
	v_bfe_u32 v109, v98, 16, 1
	v_add3_u32 v99, v99, v108, s44
	v_bfe_u32 v108, v100, 16, 1
	v_lshrrev_b32_e32 v106, 16, v104
	v_lshrrev_b32_e32 v107, 16, v105
	v_pk_add_f32 v[104:105], v[116:117], 1.0 op_sel_hi:[1,0]
	v_add3_u32 v98, v98, v109, s44
	v_bfe_u32 v109, v101, 16, 1
	v_add3_u32 v100, v100, v108, s44
	v_add3_u32 v101, v101, v109, s44
	v_lshrrev_b32_e32 v100, 16, v100
	v_and_or_b32 v100, v98, s33, v100
	v_and_or_b32 v98, v111, s33, v106
	v_lshrrev_b32_e32 v101, 16, v101
	v_and_or_b32 v101, v99, s33, v101
	v_and_or_b32 v99, v110, s33, v107
	v_mul_f32_e32 v96, 0xbfb8aa3b, v91
	v_rcp_f32_e32 v105, v105
	v_exp_f32_e32 v121, v96
	s_nop 0
	v_pk_add_f32 v[106:107], v[120:121], 1.0 op_sel_hi:[1,0]
	v_rcp_f32_e32 v104, v104
	s_nop 0
	v_pk_mul_f32 v[92:93], v[92:93], v[104:105]
	v_mul_f32_e32 v96, 0xbfb8aa3b, v88
	v_mul_f32_e32 v97, 0xbfb8aa3b, v89
	v_exp_f32_e32 v102, v96
	v_exp_f32_e32 v103, v97
	v_rcp_f32_e32 v105, v107
	v_pk_add_f32 v[102:103], v[102:103], 1.0 op_sel_hi:[1,0]
	v_rcp_f32_e32 v104, v106
	s_nop 0
	v_pk_mul_f32 v[90:91], v[90:91], v[104:105]
	v_mul_f32_e32 v96, 0xbfb8aa3b, v86
	v_mul_f32_e32 v97, 0xbfb8aa3b, v87
	v_exp_f32_e32 v96, v96
	v_exp_f32_e32 v97, v97
	v_rcp_f32_e32 v103, v103
	v_pk_add_f32 v[96:97], v[96:97], 1.0 op_sel_hi:[1,0]
	v_rcp_f32_e32 v102, v102
	s_nop 0
	v_pk_mul_f32 v[88:89], v[88:89], v[102:103]
	v_div_scale_f32 v104, s[46:47], v96, v96, 1.0
	v_rcp_f32_e32 v105, v104
	v_rcp_f32_e32 v97, v97
	v_fma_f32 v102, -v104, v105, 1.0
	v_fmac_f32_e32 v105, v102, v105
	v_div_scale_f32 v102, vcc, 1.0, v96, 1.0
	v_mul_f32_e32 v103, v102, v105
	v_fma_f32 v106, -v104, v103, v102
	v_fmac_f32_e32 v103, v106, v105
	v_fma_f32 v102, -v104, v103, v102
	v_div_fmas_f32 v102, v102, v105, v103
	v_div_fixup_f32 v96, v102, v96, 1.0
	v_pk_mul_f32 v[86:87], v[86:87], v[96:97]
	v_bfe_u32 v102, v91, 16, 1
	v_bfe_u32 v96, v87, 16, 1
	v_bfe_u32 v97, v86, 16, 1
	v_bfe_u32 v103, v90, 16, 1
	v_add3_u32 v91, v91, v102, s44
	v_add3_u32 v87, v87, v96, s44
	v_bfe_u32 v96, v92, 16, 1
	v_bfe_u32 v102, v88, 16, 1
	v_lshlrev_b64 v[94:95], 12, v[94:95]
	v_add3_u32 v90, v90, v103, s44
	v_add3_u32 v86, v86, v97, s44
	v_bfe_u32 v97, v93, 16, 1
	v_bfe_u32 v103, v89, 16, 1
	v_add3_u32 v88, v88, v102, s44
	v_add3_u32 v92, v92, v96, s44
	v_lshl_add_u64 v[94:95], v[4:5], 0, v[94:95]
	v_add3_u32 v89, v89, v103, s44
	v_add3_u32 v93, v93, v97, s44
	v_lshrrev_b32_e32 v92, 16, v92
	v_lshrrev_b32_e32 v88, 16, v88
	v_lshrrev_b32_e32 v93, 16, v93
	v_lshrrev_b32_e32 v89, 16, v89
	v_and_or_b32 v88, v86, s33, v88
	v_and_or_b32 v86, v90, s33, v92
	v_add_co_u32_e32 v90, vcc, 0x13bfb000, v94
	v_and_or_b32 v89, v87, s33, v89
	v_and_or_b32 v87, v91, s33, v93
	v_addc_co_u32_e32 v91, vcc, 0, v95, vcc
	global_store_dwordx4 v[90:91], v[98:101], off offset:640
	global_store_dwordx4 v[90:91], v[86:89], off offset:656

; DI float siluf(float x) { return x * sigm(x); }
;   const int lane = tid & 63, wid = tid >> 6, fr = lane & 15, fq = lane >> 4;
;   float* stg = (float*)(smem + PATCH) + wid * (16 * 68);
;   asm volatile("" ::: "memory");
; #pragma unroll
;   for (int n = 0; n < 4; ++n)
; #pragma unroll
;     for (int j = 0; j < 4; ++j) stg[(fq * 4 + j) * 68 + n * 16 + fr] = am[n][j];
;   asm volatile("s_waitcnt lgkmcnt(0)" ::: "memory");
;   const float* rp = stg + (lane >> 2) * 68 + (lane & 3) * 16;
; #pragma unroll
;   for (int i = 0; i < 4; ++i) { f32x4 t = *(const f32x4*)(rp + i * 4); v[4 * i] = t[0]; v[4 * i + 1] = t[1]; v[4 * i + 2] = t[2]; v[4 * i + 3] = t[3]; }
; DI void phase_inproj0(const Params& p) {
;     ...
;       float rs = r0[row];
; #pragma unroll
;       for (int i = 0; i < 16; ++i) v[i] *= rs;
;       if (col < 1024) store16_bf(u + (size_t)row * 1024 + col, v);
;       else if (col < 1728) store16_bf(lat + (size_t)row * 704 + col - 1024, v);
;       else if (col < 3776) {
; #pragma unroll
;         for (int i = 0; i < 16; ++i) v[i] = siluf(v[i]);
;         store16_bf(G0 + (size_t)row * 2048 + col - 1728, v); }
.LBB0_199:
	s_or_b64 exec, exec, s[26:27]
	ds_write2_b32 v2, v82, v78 offset1:16
	ds_write2_b32 v2, v83, v79 offset0:68 offset1:84
	ds_write2_b32 v2, v84, v80 offset0:136 offset1:152
	ds_write2_b32 v2, v85, v81 offset0:204 offset1:220
	ds_write2_b32 v2, v74, v70 offset0:32 offset1:48
	ds_write2_b32 v2, v75, v71 offset0:100 offset1:116
	ds_write2_b32 v2, v76, v72 offset0:168 offset1:184
	ds_write2_b32 v2, v77, v73 offset0:236 offset1:252
	v_or_b32_e32 v78, 48, v134
	s_waitcnt lgkmcnt(0)
	v_ashrrev_i32_e32 v79, 31, v78
	ds_read_b128 v[70:73], v144
	ds_read_b128 v[74:77], v144 offset:16
	ds_read_b128 v[84:87], v144 offset:32
	ds_read_b128 v[90:93], v144 offset:48
	v_lshl_add_u64 v[80:81], v[78:79], 2, s[16:17]
	global_load_dword v80, v[80:81], off
	s_waitcnt lgkmcnt(3)
	v_mov_b32_e32 v82, v70
	v_mov_b32_e32 v83, v72
	v_mov_b32_e32 v72, v71
	s_waitcnt lgkmcnt(2)
	v_mov_b32_e32 v70, v74
	v_mov_b32_e32 v71, v76
	v_mov_b32_e32 v76, v75
	s_waitcnt lgkmcnt(1)
	v_mov_b32_e32 v74, v84
	v_mov_b32_e32 v75, v86
	v_mov_b32_e32 v86, v85
	s_waitcnt lgkmcnt(0)
	v_mov_b32_e32 v94, v90
	v_mov_b32_e32 v95, v92
	v_mov_b32_e32 v92, v91
	s_waitcnt vmcnt(0)
	v_pk_mul_f32 v[90:91], v[82:83], v[80:81] op_sel_hi:[1,0]
	v_pk_mul_f32 v[88:89], v[72:73], v[80:81] op_sel_hi:[1,0]
	v_pk_mul_f32 v[84:85], v[70:71], v[80:81] op_sel_hi:[1,0]
	v_pk_mul_f32 v[82:83], v[76:77], v[80:81] op_sel_hi:[1,0]
	v_pk_mul_f32 v[76:77], v[74:75], v[80:81] op_sel_hi:[1,0]
	v_pk_mul_f32 v[74:75], v[86:87], v[80:81] op_sel_hi:[1,0]
	v_pk_mul_f32 v[72:73], v[94:95], v[80:81] op_sel_hi:[1,0]
	v_pk_mul_f32 v[70:71], v[92:93], v[80:81] op_sel_hi:[1,0]
	s_and_saveexec_b64 s[26:27], s[10:11]
	s_xor_b64 s[26:27], exec, s[26:27]
	s_cbranch_execz .LBB0_207
	s_and_saveexec_b64 s[36:37], s[8:9]
	s_xor_b64 s[36:37], exec, s[36:37]
	s_cbranch_execz .LBB0_204
	s_and_saveexec_b64 s[38:39], s[6:7]
	s_cbranch_execz .LBB0_203
	v_mul_f32_e32 v80, 0xbfb8aa3b, v90
	v_exp_f32_e32 v92, v80
	v_mul_f32_e32 v80, 0xbfb8aa3b, v88
	v_exp_f32_e32 v94, v80
	v_mul_f32_e32 v80, 0xbfb8aa3b, v91
	v_exp_f32_e32 v93, v80
	v_mul_f32_e32 v80, 0xbfb8aa3b, v89
	v_exp_f32_e32 v95, v80
	v_mul_f32_e32 v80, 0xbfb8aa3b, v84
	v_pk_add_f32 v[92:93], v[92:93], 1.0 op_sel_hi:[1,0]
	v_exp_f32_e32 v96, v80
	v_pk_add_f32 v[94:95], v[94:95], 1.0 op_sel_hi:[1,0]
	v_mul_f32_e32 v80, 0xbfb8aa3b, v82
	v_exp_f32_e32 v98, v80
	v_rcp_f32_e32 v93, v93
	v_mul_f32_e32 v80, 0xbfb8aa3b, v85
	v_rcp_f32_e32 v92, v92
	s_nop 0
	v_pk_mul_f32 v[90:91], v[90:91], v[92:93]
	v_exp_f32_e32 v97, v80
	v_rcp_f32_e32 v93, v95
	v_pk_add_f32 v[96:97], v[96:97], 1.0 op_sel_hi:[1,0]
	v_rcp_f32_e32 v92, v94
	s_nop 0
	v_pk_mul_f32 v[88:89], v[88:89], v[92:93]
	v_mul_f32_e32 v80, 0xbfb8aa3b, v83
	v_rcp_f32_e32 v93, v97
	v_exp_f32_e32 v99, v80
	s_nop 0
	v_pk_add_f32 v[94:95], v[98:99], 1.0 op_sel_hi:[1,0]
	v_rcp_f32_e32 v92, v96
	s_nop 0
	v_pk_mul_f32 v[84:85], v[84:85], v[92:93]
	v_mul_f32_e32 v80, 0xbfb8aa3b, v76
	v_rcp_f32_e32 v93, v95
	v_exp_f32_e32 v100, v80
	v_mul_f32_e32 v80, 0xbfb8aa3b, v74
	v_exp_f32_e32 v102, v80
	v_mul_f32_e32 v80, 0xbfb8aa3b, v77
	v_exp_f32_e32 v101, v80
	v_rcp_f32_e32 v92, v94
	v_bfe_u32 v94, v89, 16, 1
	v_bfe_u32 v95, v88, 16, 1
	v_pk_mul_f32 v[82:83], v[82:83], v[92:93]
	v_add3_u32 v95, v88, v95, s44
	v_add3_u32 v94, v89, v94, s44
	v_bfe_u32 v88, v90, 16, 1
	v_bfe_u32 v89, v91, 16, 1
	v_bfe_u32 v92, v83, 16, 1
	v_add3_u32 v89, v91, v89, s44
	v_add3_u32 v88, v90, v88, s44
	v_bfe_u32 v93, v82, 16, 1
	v_add3_u32 v83, v83, v92, s44
	v_bfe_u32 v92, v84, 16, 1
	v_lshrrev_b32_e32 v90, 16, v88
	v_lshrrev_b32_e32 v91, 16, v89
	v_pk_add_f32 v[88:89], v[100:101], 1.0 op_sel_hi:[1,0]
	v_add3_u32 v82, v82, v93, s44
	v_bfe_u32 v93, v85, 16, 1
	v_add3_u32 v84, v84, v92, s44
	v_add3_u32 v85, v85, v93, s44
	v_lshrrev_b32_e32 v84, 16, v84
	v_and_or_b32 v84, v82, s33, v84
	v_and_or_b32 v82, v95, s33, v90
	v_lshrrev_b32_e32 v85, 16, v85
	v_and_or_b32 v85, v83, s33, v85
	v_and_or_b32 v83, v94, s33, v91
	v_mul_f32_e32 v80, 0xbfb8aa3b, v75
	v_rcp_f32_e32 v89, v89
	v_exp_f32_e32 v103, v80
	s_nop 0
	v_pk_add_f32 v[90:91], v[102:103], 1.0 op_sel_hi:[1,0]
	v_rcp_f32_e32 v88, v88
	s_nop 0
	v_pk_mul_f32 v[76:77], v[76:77], v[88:89]
	v_mul_f32_e32 v80, 0xbfb8aa3b, v72
	v_mul_f32_e32 v81, 0xbfb8aa3b, v73
	v_exp_f32_e32 v86, v80
	v_exp_f32_e32 v87, v81
	v_rcp_f32_e32 v89, v91
	v_pk_add_f32 v[86:87], v[86:87], 1.0 op_sel_hi:[1,0]
	v_rcp_f32_e32 v88, v90
	s_nop 0
	v_pk_mul_f32 v[74:75], v[74:75], v[88:89]
	v_mul_f32_e32 v80, 0xbfb8aa3b, v70
	v_mul_f32_e32 v81, 0xbfb8aa3b, v71
	v_exp_f32_e32 v80, v80
	v_exp_f32_e32 v81, v81
	v_rcp_f32_e32 v87, v87
	v_pk_add_f32 v[80:81], v[80:81], 1.0 op_sel_hi:[1,0]
	v_rcp_f32_e32 v86, v86
	s_nop 0
	v_pk_mul_f32 v[72:73], v[72:73], v[86:87]
	v_div_scale_f32 v88, s[46:47], v80, v80, 1.0
	v_rcp_f32_e32 v89, v88
	v_rcp_f32_e32 v81, v81
	v_fma_f32 v86, -v88, v89, 1.0
	v_fmac_f32_e32 v89, v86, v89
	v_div_scale_f32 v86, vcc, 1.0, v80, 1.0
	v_mul_f32_e32 v87, v86, v89
	v_fma_f32 v90, -v88, v87, v86
	v_fmac_f32_e32 v87, v90, v89
	v_fma_f32 v86, -v88, v87, v86
	v_div_fmas_f32 v86, v86, v89, v87
	v_div_fixup_f32 v80, v86, v80, 1.0
	v_pk_mul_f32 v[70:71], v[70:71], v[80:81]
	v_bfe_u32 v86, v75, 16, 1
	v_bfe_u32 v80, v71, 16, 1
	v_bfe_u32 v81, v70, 16, 1
	v_bfe_u32 v87, v74, 16, 1
	v_add3_u32 v75, v75, v86, s44
	v_add3_u32 v71, v71, v80, s44
	v_bfe_u32 v80, v76, 16, 1
	v_bfe_u32 v86, v72, 16, 1
	v_lshlrev_b64 v[78:79], 12, v[78:79]
	v_add3_u32 v74, v74, v87, s44
	v_add3_u32 v70, v70, v81, s44
	v_bfe_u32 v81, v77, 16, 1
	v_bfe_u32 v87, v73, 16, 1
	v_add3_u32 v72, v72, v86, s44
	v_add3_u32 v76, v76, v80, s44
	v_lshl_add_u64 v[78:79], v[4:5], 0, v[78:79]
	v_add3_u32 v73, v73, v87, s44
	v_add3_u32 v77, v77, v81, s44
	v_lshrrev_b32_e32 v76, 16, v76
	v_lshrrev_b32_e32 v72, 16, v72
	v_lshrrev_b32_e32 v77, 16, v77
	v_lshrrev_b32_e32 v73, 16, v73
	v_and_or_b32 v72, v70, s33, v72
	v_and_or_b32 v70, v74, s33, v76
	v_add_co_u32_e32 v74, vcc, 0x13bfb000, v78
	v_and_or_b32 v73, v71, s33, v73
	v_and_or_b32 v71, v75, s33, v77
	v_addc_co_u32_e32 v75, vcc, 0, v79, vcc
	global_store_dwordx4 v[74:75], v[82:85], off offset:640
	global_store_dwordx4 v[74:75], v[70:73], off offset:656

; DI float siluf(float x) { return x * sigm(x); }
;   const int lane = tid & 63, wid = tid >> 6, fr = lane & 15, fq = lane >> 4;
;   float* stg = (float*)(smem + PATCH) + wid * (16 * 68);
;   asm volatile("" ::: "memory");
; #pragma unroll
;   for (int n = 0; n < 4; ++n)
; #pragma unroll
;     for (int j = 0; j < 4; ++j) stg[(fq * 4 + j) * 68 + n * 16 + fr] = am[n][j];
;   asm volatile("s_waitcnt lgkmcnt(0)" ::: "memory");
;   const float* rp = stg + (lane >> 2) * 68 + (lane & 3) * 16;
; #pragma unroll
;   for (int i = 0; i < 4; ++i) { f32x4 t = *(const f32x4*)(rp + i * 4); v[4 * i] = t[0]; v[4 * i + 1] = t[1]; v[4 * i + 2] = t[2]; v[4 * i + 3] = t[3]; }
; DI void phase_inproj0(const Params& p) {
;     ...
;       float rs = r0[row];
; #pragma unroll
;       for (int i = 0; i < 16; ++i) v[i] *= rs;
;       if (col < 1024) store16_bf(u + (size_t)row * 1024 + col, v);
;       else if (col < 1728) store16_bf(lat + (size_t)row * 704 + col - 1024, v);
;       else if (col < 3776) {
; #pragma unroll
;         for (int i = 0; i < 16; ++i) v[i] = siluf(v[i]);
;         store16_bf(G0 + (size_t)row * 2048 + col - 1728, v); }
.LBB0_209:
	s_or_b64 exec, exec, s[26:27]
	ds_write2_b32 v2, v66, v62 offset1:16
	ds_write2_b32 v2, v67, v63 offset0:68 offset1:84
	ds_write2_b32 v2, v68, v64 offset0:136 offset1:152
	ds_write2_b32 v2, v69, v65 offset0:204 offset1:220
	ds_write2_b32 v2, v58, v54 offset0:32 offset1:48
	ds_write2_b32 v2, v59, v55 offset0:100 offset1:116
	ds_write2_b32 v2, v60, v56 offset0:168 offset1:184
	ds_write2_b32 v2, v61, v57 offset0:236 offset1:252
	v_or_b32_e32 v62, 64, v134
	s_waitcnt lgkmcnt(0)
	v_ashrrev_i32_e32 v63, 31, v62
	ds_read_b128 v[54:57], v144
	ds_read_b128 v[58:61], v144 offset:16
	ds_read_b128 v[68:71], v144 offset:32
	ds_read_b128 v[74:77], v144 offset:48
	v_lshl_add_u64 v[64:65], v[62:63], 2, s[16:17]
	global_load_dword v64, v[64:65], off
	s_waitcnt lgkmcnt(3)
	v_mov_b32_e32 v66, v54
	v_mov_b32_e32 v67, v56
	v_mov_b32_e32 v56, v55
	s_waitcnt lgkmcnt(2)
	v_mov_b32_e32 v54, v58
	v_mov_b32_e32 v55, v60
	v_mov_b32_e32 v60, v59
	s_waitcnt lgkmcnt(1)
	v_mov_b32_e32 v58, v68
	v_mov_b32_e32 v59, v70
	v_mov_b32_e32 v70, v69
	s_waitcnt lgkmcnt(0)
	v_mov_b32_e32 v78, v74
	v_mov_b32_e32 v79, v76
	v_mov_b32_e32 v76, v75
	s_waitcnt vmcnt(0)
	v_pk_mul_f32 v[74:75], v[66:67], v[64:65] op_sel_hi:[1,0]
	v_pk_mul_f32 v[72:73], v[56:57], v[64:65] op_sel_hi:[1,0]
	v_pk_mul_f32 v[68:69], v[54:55], v[64:65] op_sel_hi:[1,0]
	v_pk_mul_f32 v[66:67], v[60:61], v[64:65] op_sel_hi:[1,0]
	v_pk_mul_f32 v[60:61], v[58:59], v[64:65] op_sel_hi:[1,0]
	v_pk_mul_f32 v[58:59], v[70:71], v[64:65] op_sel_hi:[1,0]
	v_pk_mul_f32 v[56:57], v[78:79], v[64:65] op_sel_hi:[1,0]
	v_pk_mul_f32 v[54:55], v[76:77], v[64:65] op_sel_hi:[1,0]
	s_and_saveexec_b64 s[26:27], s[10:11]
	s_xor_b64 s[26:27], exec, s[26:27]
	s_cbranch_execz .LBB0_217
	s_and_saveexec_b64 s[36:37], s[8:9]
	s_xor_b64 s[36:37], exec, s[36:37]
	s_cbranch_execz .LBB0_214
	s_and_saveexec_b64 s[38:39], s[6:7]
	s_cbranch_execz .LBB0_213
	v_mul_f32_e32 v64, 0xbfb8aa3b, v74
	v_exp_f32_e32 v76, v64
	v_mul_f32_e32 v64, 0xbfb8aa3b, v72
	v_exp_f32_e32 v78, v64
	v_mul_f32_e32 v64, 0xbfb8aa3b, v75
	v_exp_f32_e32 v77, v64
	v_mul_f32_e32 v64, 0xbfb8aa3b, v73
	v_exp_f32_e32 v79, v64
	v_mul_f32_e32 v64, 0xbfb8aa3b, v68
	v_pk_add_f32 v[76:77], v[76:77], 1.0 op_sel_hi:[1,0]
	v_exp_f32_e32 v80, v64
	v_pk_add_f32 v[78:79], v[78:79], 1.0 op_sel_hi:[1,0]
	v_mul_f32_e32 v64, 0xbfb8aa3b, v66
	v_exp_f32_e32 v82, v64
	v_rcp_f32_e32 v77, v77
	v_mul_f32_e32 v64, 0xbfb8aa3b, v69
	v_rcp_f32_e32 v76, v76
	s_nop 0
	v_pk_mul_f32 v[74:75], v[74:75], v[76:77]
	v_exp_f32_e32 v81, v64
	v_rcp_f32_e32 v77, v79
	v_pk_add_f32 v[80:81], v[80:81], 1.0 op_sel_hi:[1,0]
	v_rcp_f32_e32 v76, v78
	s_nop 0
	v_pk_mul_f32 v[72:73], v[72:73], v[76:77]
	v_mul_f32_e32 v64, 0xbfb8aa3b, v67
	v_rcp_f32_e32 v77, v81
	v_exp_f32_e32 v83, v64
	s_nop 0
	v_pk_add_f32 v[78:79], v[82:83], 1.0 op_sel_hi:[1,0]
	v_rcp_f32_e32 v76, v80
	s_nop 0
	v_pk_mul_f32 v[68:69], v[68:69], v[76:77]
	v_mul_f32_e32 v64, 0xbfb8aa3b, v60
	v_rcp_f32_e32 v77, v79
	v_exp_f32_e32 v84, v64
	v_mul_f32_e32 v64, 0xbfb8aa3b, v58
	v_exp_f32_e32 v86, v64
	v_mul_f32_e32 v64, 0xbfb8aa3b, v61
	v_exp_f32_e32 v85, v64
	v_rcp_f32_e32 v76, v78
	v_bfe_u32 v78, v73, 16, 1
	v_bfe_u32 v79, v72, 16, 1
	v_pk_mul_f32 v[66:67], v[66:67], v[76:77]
	v_add3_u32 v79, v72, v79, s44
	v_add3_u32 v78, v73, v78, s44
	v_bfe_u32 v72, v74, 16, 1
	v_bfe_u32 v73, v75, 16, 1
	v_bfe_u32 v76, v67, 16, 1
	v_add3_u32 v73, v75, v73, s44
	v_add3_u32 v72, v74, v72, s44
	v_bfe_u32 v77, v66, 16, 1
	v_add3_u32 v67, v67, v76, s44
	v_bfe_u32 v76, v68, 16, 1
	v_lshrrev_b32_e32 v74, 16, v72
	v_lshrrev_b32_e32 v75, 16, v73
	v_pk_add_f32 v[72:73], v[84:85], 1.0 op_sel_hi:[1,0]
	v_add3_u32 v66, v66, v77, s44
	v_bfe_u32 v77, v69, 16, 1
	v_add3_u32 v68, v68, v76, s44
	v_add3_u32 v69, v69, v77, s44
	v_lshrrev_b32_e32 v68, 16, v68
	v_and_or_b32 v68, v66, s33, v68
	v_and_or_b32 v66, v79, s33, v74
	v_lshrrev_b32_e32 v69, 16, v69
	v_and_or_b32 v69, v67, s33, v69
	v_and_or_b32 v67, v78, s33, v75
	v_mul_f32_e32 v64, 0xbfb8aa3b, v59
	v_rcp_f32_e32 v73, v73
	v_exp_f32_e32 v87, v64
	s_nop 0
	v_pk_add_f32 v[74:75], v[86:87], 1.0 op_sel_hi:[1,0]
	v_rcp_f32_e32 v72, v72
	s_nop 0
	v_pk_mul_f32 v[60:61], v[60:61], v[72:73]
	v_mul_f32_e32 v64, 0xbfb8aa3b, v56
	v_mul_f32_e32 v65, 0xbfb8aa3b, v57
	v_exp_f32_e32 v70, v64
	v_exp_f32_e32 v71, v65
	v_rcp_f32_e32 v73, v75
	v_pk_add_f32 v[70:71], v[70:71], 1.0 op_sel_hi:[1,0]
	v_rcp_f32_e32 v72, v74
	s_nop 0
	v_pk_mul_f32 v[58:59], v[58:59], v[72:73]
	v_mul_f32_e32 v64, 0xbfb8aa3b, v54
	v_mul_f32_e32 v65, 0xbfb8aa3b, v55
	v_exp_f32_e32 v64, v64
	v_exp_f32_e32 v65, v65
	v_rcp_f32_e32 v71, v71
	v_pk_add_f32 v[64:65], v[64:65], 1.0 op_sel_hi:[1,0]
	v_rcp_f32_e32 v70, v70
	s_nop 0
	v_pk_mul_f32 v[56:57], v[56:57], v[70:71]
	v_div_scale_f32 v72, s[46:47], v64, v64, 1.0
	v_rcp_f32_e32 v73, v72
	v_rcp_f32_e32 v65, v65
	v_fma_f32 v70, -v72, v73, 1.0
	v_fmac_f32_e32 v73, v70, v73
	v_div_scale_f32 v70, vcc, 1.0, v64, 1.0
	v_mul_f32_e32 v71, v70, v73
	v_fma_f32 v74, -v72, v71, v70
	v_fmac_f32_e32 v71, v74, v73
	v_fma_f32 v70, -v72, v71, v70
	v_div_fmas_f32 v70, v70, v73, v71
	v_div_fixup_f32 v64, v70, v64, 1.0
	v_pk_mul_f32 v[54:55], v[54:55], v[64:65]
	v_bfe_u32 v70, v59, 16, 1
	v_bfe_u32 v64, v55, 16, 1
	v_bfe_u32 v65, v54, 16, 1
	v_bfe_u32 v71, v58, 16, 1
	v_add3_u32 v59, v59, v70, s44
	v_add3_u32 v55, v55, v64, s44
	v_bfe_u32 v64, v60, 16, 1
	v_bfe_u32 v70, v56, 16, 1
	v_lshlrev_b64 v[62:63], 12, v[62:63]
	v_add3_u32 v58, v58, v71, s44
	v_add3_u32 v54, v54, v65, s44
	v_bfe_u32 v65, v61, 16, 1
	v_bfe_u32 v71, v57, 16, 1
	v_add3_u32 v56, v56, v70, s44
	v_add3_u32 v60, v60, v64, s44
	v_lshl_add_u64 v[62:63], v[4:5], 0, v[62:63]
	v_add3_u32 v57, v57, v71, s44
	v_add3_u32 v61, v61, v65, s44
	v_lshrrev_b32_e32 v60, 16, v60
	v_lshrrev_b32_e32 v56, 16, v56
	v_lshrrev_b32_e32 v61, 16, v61
	v_lshrrev_b32_e32 v57, 16, v57
	v_and_or_b32 v56, v54, s33, v56
	v_and_or_b32 v54, v58, s33, v60
	v_add_co_u32_e32 v58, vcc, 0x13bfb000, v62
	v_and_or_b32 v57, v55, s33, v57
	v_and_or_b32 v55, v59, s33, v61
	v_addc_co_u32_e32 v59, vcc, 0, v63, vcc
	global_store_dwordx4 v[58:59], v[66:69], off offset:640
	global_store_dwordx4 v[58:59], v[54:57], off offset:656

; DI float siluf(float x) { return x * sigm(x); }
;   const int lane = tid & 63, wid = tid >> 6, fr = lane & 15, fq = lane >> 4;
;   float* stg = (float*)(smem + PATCH) + wid * (16 * 68);
;   asm volatile("" ::: "memory");
; #pragma unroll
;   for (int n = 0; n < 4; ++n)
; #pragma unroll
;     for (int j = 0; j < 4; ++j) stg[(fq * 4 + j) * 68 + n * 16 + fr] = am[n][j];
;   asm volatile("s_waitcnt lgkmcnt(0)" ::: "memory");
;   const float* rp = stg + (lane >> 2) * 68 + (lane & 3) * 16;
; #pragma unroll
;   for (int i = 0; i < 4; ++i) { f32x4 t = *(const f32x4*)(rp + i * 4); v[4 * i] = t[0]; v[4 * i + 1] = t[1]; v[4 * i + 2] = t[2]; v[4 * i + 3] = t[3]; }
; DI void phase_inproj0(const Params& p) {
;     ...
;       float rs = r0[row];
; #pragma unroll
;       for (int i = 0; i < 16; ++i) v[i] *= rs;
;       if (col < 1024) store16_bf(u + (size_t)row * 1024 + col, v);
;       else if (col < 1728) store16_bf(lat + (size_t)row * 704 + col - 1024, v);
;       else if (col < 3776) {
; #pragma unroll
;         for (int i = 0; i < 16; ++i) v[i] = siluf(v[i]);
;         store16_bf(G0 + (size_t)row * 2048 + col - 1728, v); }
.LBB0_219:
	s_or_b64 exec, exec, s[26:27]
	ds_write2_b32 v2, v50, v46 offset1:16
	ds_write2_b32 v2, v51, v47 offset0:68 offset1:84
	ds_write2_b32 v2, v52, v48 offset0:136 offset1:152
	ds_write2_b32 v2, v53, v49 offset0:204 offset1:220
	ds_write2_b32 v2, v42, v38 offset0:32 offset1:48
	ds_write2_b32 v2, v43, v39 offset0:100 offset1:116
	ds_write2_b32 v2, v44, v40 offset0:168 offset1:184
	ds_write2_b32 v2, v45, v41 offset0:236 offset1:252
	v_or_b32_e32 v46, 0x50, v134
	s_waitcnt lgkmcnt(0)
	v_ashrrev_i32_e32 v47, 31, v46
	ds_read_b128 v[38:41], v144
	ds_read_b128 v[42:45], v144 offset:16
	ds_read_b128 v[52:55], v144 offset:32
	ds_read_b128 v[58:61], v144 offset:48
	v_lshl_add_u64 v[48:49], v[46:47], 2, s[16:17]
	global_load_dword v48, v[48:49], off
	s_waitcnt lgkmcnt(3)
	v_mov_b32_e32 v50, v38
	v_mov_b32_e32 v51, v40
	v_mov_b32_e32 v40, v39
	s_waitcnt lgkmcnt(2)
	v_mov_b32_e32 v38, v42
	v_mov_b32_e32 v39, v44
	v_mov_b32_e32 v44, v43
	s_waitcnt lgkmcnt(1)
	v_mov_b32_e32 v42, v52
	v_mov_b32_e32 v43, v54
	v_mov_b32_e32 v54, v53
	s_waitcnt lgkmcnt(0)
	v_mov_b32_e32 v62, v58
	v_mov_b32_e32 v63, v60
	v_mov_b32_e32 v60, v59
	s_waitcnt vmcnt(0)
	v_pk_mul_f32 v[58:59], v[50:51], v[48:49] op_sel_hi:[1,0]
	v_pk_mul_f32 v[56:57], v[40:41], v[48:49] op_sel_hi:[1,0]
	v_pk_mul_f32 v[52:53], v[38:39], v[48:49] op_sel_hi:[1,0]
	v_pk_mul_f32 v[50:51], v[44:45], v[48:49] op_sel_hi:[1,0]
	v_pk_mul_f32 v[44:45], v[42:43], v[48:49] op_sel_hi:[1,0]
	v_pk_mul_f32 v[42:43], v[54:55], v[48:49] op_sel_hi:[1,0]
	v_pk_mul_f32 v[40:41], v[62:63], v[48:49] op_sel_hi:[1,0]
	v_pk_mul_f32 v[38:39], v[60:61], v[48:49] op_sel_hi:[1,0]
	s_and_saveexec_b64 s[26:27], s[10:11]
	s_xor_b64 s[26:27], exec, s[26:27]
	s_cbranch_execz .LBB0_227
	s_and_saveexec_b64 s[36:37], s[8:9]
	s_xor_b64 s[36:37], exec, s[36:37]
	s_cbranch_execz .LBB0_224
	s_and_saveexec_b64 s[38:39], s[6:7]
	s_cbranch_execz .LBB0_223
	v_mul_f32_e32 v48, 0xbfb8aa3b, v58
	v_exp_f32_e32 v60, v48
	v_mul_f32_e32 v48, 0xbfb8aa3b, v56
	v_exp_f32_e32 v62, v48
	v_mul_f32_e32 v48, 0xbfb8aa3b, v59
	v_exp_f32_e32 v61, v48
	v_mul_f32_e32 v48, 0xbfb8aa3b, v57
	v_exp_f32_e32 v63, v48
	v_mul_f32_e32 v48, 0xbfb8aa3b, v52
	v_pk_add_f32 v[60:61], v[60:61], 1.0 op_sel_hi:[1,0]
	v_exp_f32_e32 v64, v48
	v_pk_add_f32 v[62:63], v[62:63], 1.0 op_sel_hi:[1,0]
	v_mul_f32_e32 v48, 0xbfb8aa3b, v50
	v_exp_f32_e32 v66, v48
	v_rcp_f32_e32 v61, v61
	v_mul_f32_e32 v48, 0xbfb8aa3b, v53
	v_rcp_f32_e32 v60, v60
	s_nop 0
	v_pk_mul_f32 v[58:59], v[58:59], v[60:61]
	v_exp_f32_e32 v65, v48
	v_rcp_f32_e32 v61, v63
	v_pk_add_f32 v[64:65], v[64:65], 1.0 op_sel_hi:[1,0]
	v_rcp_f32_e32 v60, v62
	s_nop 0
	v_pk_mul_f32 v[56:57], v[56:57], v[60:61]
	v_mul_f32_e32 v48, 0xbfb8aa3b, v51
	v_rcp_f32_e32 v61, v65
	v_exp_f32_e32 v67, v48
	s_nop 0
	v_pk_add_f32 v[62:63], v[66:67], 1.0 op_sel_hi:[1,0]
	v_rcp_f32_e32 v60, v64
	s_nop 0
	v_pk_mul_f32 v[52:53], v[52:53], v[60:61]
	v_mul_f32_e32 v48, 0xbfb8aa3b, v44
	v_rcp_f32_e32 v61, v63
	v_exp_f32_e32 v68, v48
	v_mul_f32_e32 v48, 0xbfb8aa3b, v42
	v_exp_f32_e32 v70, v48
	v_mul_f32_e32 v48, 0xbfb8aa3b, v45
	v_exp_f32_e32 v69, v48
	v_rcp_f32_e32 v60, v62
	v_bfe_u32 v62, v57, 16, 1
	v_bfe_u32 v63, v56, 16, 1
	v_pk_mul_f32 v[50:51], v[50:51], v[60:61]
	v_add3_u32 v63, v56, v63, s44
	v_add3_u32 v62, v57, v62, s44
	v_bfe_u32 v56, v58, 16, 1
	v_bfe_u32 v57, v59, 16, 1
	v_bfe_u32 v60, v51, 16, 1
	v_add3_u32 v57, v59, v57, s44
	v_add3_u32 v56, v58, v56, s44
	v_bfe_u32 v61, v50, 16, 1
	v_add3_u32 v51, v51, v60, s44
	v_bfe_u32 v60, v52, 16, 1
	v_lshrrev_b32_e32 v58, 16, v56
	v_lshrrev_b32_e32 v59, 16, v57
	v_pk_add_f32 v[56:57], v[68:69], 1.0 op_sel_hi:[1,0]
	v_add3_u32 v50, v50, v61, s44
	v_bfe_u32 v61, v53, 16, 1
	v_add3_u32 v52, v52, v60, s44
	v_add3_u32 v53, v53, v61, s44
	v_lshrrev_b32_e32 v52, 16, v52
	v_and_or_b32 v52, v50, s33, v52
	v_and_or_b32 v50, v63, s33, v58
	v_lshrrev_b32_e32 v53, 16, v53
	v_and_or_b32 v53, v51, s33, v53
	v_and_or_b32 v51, v62, s33, v59
	v_mul_f32_e32 v48, 0xbfb8aa3b, v43
	v_rcp_f32_e32 v57, v57
	v_exp_f32_e32 v71, v48
	s_nop 0
	v_pk_add_f32 v[58:59], v[70:71], 1.0 op_sel_hi:[1,0]
	v_rcp_f32_e32 v56, v56
	s_nop 0
	v_pk_mul_f32 v[44:45], v[44:45], v[56:57]
	v_mul_f32_e32 v48, 0xbfb8aa3b, v40
	v_mul_f32_e32 v49, 0xbfb8aa3b, v41
	v_exp_f32_e32 v54, v48
	v_exp_f32_e32 v55, v49
	v_rcp_f32_e32 v57, v59
	v_pk_add_f32 v[54:55], v[54:55], 1.0 op_sel_hi:[1,0]
	v_rcp_f32_e32 v56, v58
	s_nop 0
	v_pk_mul_f32 v[42:43], v[42:43], v[56:57]
	v_mul_f32_e32 v48, 0xbfb8aa3b, v38
	v_mul_f32_e32 v49, 0xbfb8aa3b, v39
	v_exp_f32_e32 v48, v48
	v_exp_f32_e32 v49, v49
	v_rcp_f32_e32 v55, v55
	v_pk_add_f32 v[48:49], v[48:49], 1.0 op_sel_hi:[1,0]
	v_rcp_f32_e32 v54, v54
	s_nop 0
	v_pk_mul_f32 v[40:41], v[40:41], v[54:55]
	v_div_scale_f32 v56, s[46:47], v48, v48, 1.0
	v_rcp_f32_e32 v57, v56
	v_rcp_f32_e32 v49, v49
	v_fma_f32 v54, -v56, v57, 1.0
	v_fmac_f32_e32 v57, v54, v57
	v_div_scale_f32 v54, vcc, 1.0, v48, 1.0
	v_mul_f32_e32 v55, v54, v57
	v_fma_f32 v58, -v56, v55, v54
	v_fmac_f32_e32 v55, v58, v57
	v_fma_f32 v54, -v56, v55, v54
	v_div_fmas_f32 v54, v54, v57, v55
	v_div_fixup_f32 v48, v54, v48, 1.0
	v_pk_mul_f32 v[38:39], v[38:39], v[48:49]
	v_bfe_u32 v54, v43, 16, 1
	v_bfe_u32 v48, v39, 16, 1
	v_bfe_u32 v49, v38, 16, 1
	v_bfe_u32 v55, v42, 16, 1
	v_add3_u32 v43, v43, v54, s44
	v_add3_u32 v39, v39, v48, s44
	v_bfe_u32 v48, v44, 16, 1
	v_bfe_u32 v54, v40, 16, 1
	v_lshlrev_b64 v[46:47], 12, v[46:47]
	v_add3_u32 v42, v42, v55, s44
	v_add3_u32 v38, v38, v49, s44
	v_bfe_u32 v49, v45, 16, 1
	v_bfe_u32 v55, v41, 16, 1
	v_add3_u32 v40, v40, v54, s44
	v_add3_u32 v44, v44, v48, s44
	v_lshl_add_u64 v[46:47], v[4:5], 0, v[46:47]
	v_add3_u32 v41, v41, v55, s44
	v_add3_u32 v45, v45, v49, s44
	v_lshrrev_b32_e32 v44, 16, v44
	v_lshrrev_b32_e32 v40, 16, v40
	v_lshrrev_b32_e32 v45, 16, v45
	v_lshrrev_b32_e32 v41, 16, v41
	v_and_or_b32 v40, v38, s33, v40
	v_and_or_b32 v38, v42, s33, v44
	v_add_co_u32_e32 v42, vcc, 0x13bfb000, v46
	v_and_or_b32 v41, v39, s33, v41
	v_and_or_b32 v39, v43, s33, v45
	v_addc_co_u32_e32 v43, vcc, 0, v47, vcc
	global_store_dwordx4 v[42:43], v[50:53], off offset:640
	global_store_dwordx4 v[42:43], v[38:41], off offset:656

; DI float sigm(float x) { return 1.f / (1.f + __expf(-x)); }
; DI float siluf(float x) { return x * sigm(x); }
; DI void phase_inproj0(const Params& p) {
;     ...
;     EPI256_BEGIN
;       float rs = r0[row];
; #pragma unroll
;       for (int i = 0; i < 16; ++i) v[i] *= rs;
;       if (col < 1024) store16_bf(u + (size_t)row * 1024 + col, v);
;       else if (col < 1728) store16_bf(lat + (size_t)row * 704 + col - 1024, v);
;       else if (col < 3776) {
; #pragma unroll
;         for (int i = 0; i < 16; ++i) v[i] = siluf(v[i]);
;         store16_bf(G0 + (size_t)row * 2048 + col - 1728, v); }
.LBB0_229:
	s_or_b64 exec, exec, s[26:27]
	ds_write2_b32 v2, v34, v30 offset1:16
	ds_write2_b32 v2, v35, v31 offset0:68 offset1:84
	ds_write2_b32 v2, v36, v32 offset0:136 offset1:152
	ds_write2_b32 v2, v37, v33 offset0:204 offset1:220
	ds_write2_b32 v2, v26, v22 offset0:32 offset1:48
	ds_write2_b32 v2, v27, v23 offset0:100 offset1:116
	ds_write2_b32 v2, v28, v24 offset0:168 offset1:184
	ds_write2_b32 v2, v29, v25 offset0:236 offset1:252
	v_or_b32_e32 v30, 0x60, v134
	s_waitcnt lgkmcnt(0)
	v_ashrrev_i32_e32 v31, 31, v30
	ds_read_b128 v[22:25], v144
	ds_read_b128 v[26:29], v144 offset:16
	ds_read_b128 v[36:39], v144 offset:32
	ds_read_b128 v[42:45], v144 offset:48
	v_lshl_add_u64 v[32:33], v[30:31], 2, s[16:17]
	global_load_dword v32, v[32:33], off
	s_waitcnt lgkmcnt(3)
	v_mov_b32_e32 v34, v22
	v_mov_b32_e32 v35, v24
	v_mov_b32_e32 v24, v23
	s_waitcnt lgkmcnt(2)
	v_mov_b32_e32 v22, v26
	v_mov_b32_e32 v23, v28
	v_mov_b32_e32 v28, v27
	s_waitcnt lgkmcnt(1)
	v_mov_b32_e32 v26, v36
	v_mov_b32_e32 v27, v38
	v_mov_b32_e32 v38, v37
	s_waitcnt lgkmcnt(0)
	v_mov_b32_e32 v46, v42
	v_mov_b32_e32 v47, v44
	v_mov_b32_e32 v44, v43
	s_waitcnt vmcnt(0)
	v_pk_mul_f32 v[42:43], v[34:35], v[32:33] op_sel_hi:[1,0]
	v_pk_mul_f32 v[40:41], v[24:25], v[32:33] op_sel_hi:[1,0]
	v_pk_mul_f32 v[36:37], v[22:23], v[32:33] op_sel_hi:[1,0]
	v_pk_mul_f32 v[34:35], v[28:29], v[32:33] op_sel_hi:[1,0]
	v_pk_mul_f32 v[28:29], v[26:27], v[32:33] op_sel_hi:[1,0]
	v_pk_mul_f32 v[26:27], v[38:39], v[32:33] op_sel_hi:[1,0]
	v_pk_mul_f32 v[24:25], v[46:47], v[32:33] op_sel_hi:[1,0]
	v_pk_mul_f32 v[22:23], v[44:45], v[32:33] op_sel_hi:[1,0]
	s_and_saveexec_b64 s[26:27], s[10:11]
	s_xor_b64 s[26:27], exec, s[26:27]
	s_cbranch_execz .LBB0_237
	s_and_saveexec_b64 s[36:37], s[8:9]
	s_xor_b64 s[36:37], exec, s[36:37]
	s_cbranch_execz .LBB0_234
	s_and_saveexec_b64 s[38:39], s[6:7]
	s_cbranch_execz .LBB0_233
	v_mul_f32_e32 v32, 0xbfb8aa3b, v42
	v_exp_f32_e32 v44, v32
	v_mul_f32_e32 v32, 0xbfb8aa3b, v40
	v_exp_f32_e32 v46, v32
	v_mul_f32_e32 v32, 0xbfb8aa3b, v43
	v_exp_f32_e32 v45, v32
	v_mul_f32_e32 v32, 0xbfb8aa3b, v41
	v_exp_f32_e32 v47, v32
	v_mul_f32_e32 v32, 0xbfb8aa3b, v36
	v_pk_add_f32 v[44:45], v[44:45], 1.0 op_sel_hi:[1,0]
	v_exp_f32_e32 v48, v32
	v_pk_add_f32 v[46:47], v[46:47], 1.0 op_sel_hi:[1,0]
	v_mul_f32_e32 v32, 0xbfb8aa3b, v34
	v_exp_f32_e32 v50, v32
	v_rcp_f32_e32 v45, v45
	v_mul_f32_e32 v32, 0xbfb8aa3b, v37
	v_rcp_f32_e32 v44, v44
	s_nop 0
	v_pk_mul_f32 v[42:43], v[42:43], v[44:45]
	v_exp_f32_e32 v49, v32
	v_rcp_f32_e32 v45, v47
	v_pk_add_f32 v[48:49], v[48:49], 1.0 op_sel_hi:[1,0]
	v_rcp_f32_e32 v44, v46
	s_nop 0
	v_pk_mul_f32 v[40:41], v[40:41], v[44:45]
	v_mul_f32_e32 v32, 0xbfb8aa3b, v35
	v_rcp_f32_e32 v45, v49
	v_exp_f32_e32 v51, v32
	s_nop 0
	v_pk_add_f32 v[46:47], v[50:51], 1.0 op_sel_hi:[1,0]
	v_rcp_f32_e32 v44, v48
	s_nop 0
	v_pk_mul_f32 v[36:37], v[36:37], v[44:45]
	v_mul_f32_e32 v32, 0xbfb8aa3b, v28
	v_rcp_f32_e32 v45, v47
	v_exp_f32_e32 v52, v32
	v_mul_f32_e32 v32, 0xbfb8aa3b, v26
	v_exp_f32_e32 v54, v32
	v_mul_f32_e32 v32, 0xbfb8aa3b, v29
	v_exp_f32_e32 v53, v32
	v_rcp_f32_e32 v44, v46
	v_bfe_u32 v46, v41, 16, 1
	v_bfe_u32 v47, v40, 16, 1
	v_pk_mul_f32 v[34:35], v[34:35], v[44:45]
	v_add3_u32 v47, v40, v47, s44
	v_add3_u32 v46, v41, v46, s44
	v_bfe_u32 v40, v42, 16, 1
	v_bfe_u32 v41, v43, 16, 1
	v_bfe_u32 v44, v35, 16, 1
	v_add3_u32 v41, v43, v41, s44
	v_add3_u32 v40, v42, v40, s44
	v_bfe_u32 v45, v34, 16, 1
	v_add3_u32 v35, v35, v44, s44
	v_bfe_u32 v44, v36, 16, 1
	v_lshrrev_b32_e32 v42, 16, v40
	v_lshrrev_b32_e32 v43, 16, v41
	v_pk_add_f32 v[40:41], v[52:53], 1.0 op_sel_hi:[1,0]
	v_add3_u32 v34, v34, v45, s44
	v_bfe_u32 v45, v37, 16, 1
	v_add3_u32 v36, v36, v44, s44
	v_add3_u32 v37, v37, v45, s44
	v_lshrrev_b32_e32 v36, 16, v36
	v_and_or_b32 v36, v34, s33, v36
	v_and_or_b32 v34, v47, s33, v42
	v_lshrrev_b32_e32 v37, 16, v37
	v_and_or_b32 v37, v35, s33, v37
	v_and_or_b32 v35, v46, s33, v43
	v_mul_f32_e32 v32, 0xbfb8aa3b, v27
	v_rcp_f32_e32 v41, v41
	v_exp_f32_e32 v55, v32
	s_nop 0
	v_pk_add_f32 v[42:43], v[54:55], 1.0 op_sel_hi:[1,0]
	v_rcp_f32_e32 v40, v40
	s_nop 0
	v_pk_mul_f32 v[28:29], v[28:29], v[40:41]
	v_mul_f32_e32 v32, 0xbfb8aa3b, v24
	v_mul_f32_e32 v33, 0xbfb8aa3b, v25
	v_exp_f32_e32 v38, v32
	v_exp_f32_e32 v39, v33
	v_rcp_f32_e32 v41, v43
	v_pk_add_f32 v[38:39], v[38:39], 1.0 op_sel_hi:[1,0]
	v_rcp_f32_e32 v40, v42
	s_nop 0
	v_pk_mul_f32 v[26:27], v[26:27], v[40:41]
	v_mul_f32_e32 v32, 0xbfb8aa3b, v22
	v_mul_f32_e32 v33, 0xbfb8aa3b, v23
	v_exp_f32_e32 v32, v32
	v_exp_f32_e32 v33, v33
	v_rcp_f32_e32 v39, v39
	v_pk_add_f32 v[32:33], v[32:33], 1.0 op_sel_hi:[1,0]
	v_rcp_f32_e32 v38, v38
	s_nop 0
	v_pk_mul_f32 v[24:25], v[24:25], v[38:39]
	v_div_scale_f32 v40, s[46:47], v32, v32, 1.0
	v_rcp_f32_e32 v41, v40
	v_rcp_f32_e32 v33, v33
	v_fma_f32 v38, -v40, v41, 1.0
	v_fmac_f32_e32 v41, v38, v41
	v_div_scale_f32 v38, vcc, 1.0, v32, 1.0
	v_mul_f32_e32 v39, v38, v41
	v_fma_f32 v42, -v40, v39, v38
	v_fmac_f32_e32 v39, v42, v41
	v_fma_f32 v38, -v40, v39, v38
	v_div_fmas_f32 v38, v38, v41, v39
	v_div_fixup_f32 v32, v38, v32, 1.0
	v_pk_mul_f32 v[22:23], v[22:23], v[32:33]
	v_bfe_u32 v38, v27, 16, 1
	v_bfe_u32 v32, v23, 16, 1
	v_bfe_u32 v33, v22, 16, 1
	v_bfe_u32 v39, v26, 16, 1
	v_add3_u32 v27, v27, v38, s44
	v_add3_u32 v23, v23, v32, s44
	v_bfe_u32 v32, v28, 16, 1
	v_bfe_u32 v38, v24, 16, 1
	v_lshlrev_b64 v[30:31], 12, v[30:31]
	v_add3_u32 v26, v26, v39, s44
	v_add3_u32 v22, v22, v33, s44
	v_bfe_u32 v33, v29, 16, 1
	v_bfe_u32 v39, v25, 16, 1
	v_add3_u32 v24, v24, v38, s44
	v_add3_u32 v28, v28, v32, s44
	v_lshl_add_u64 v[30:31], v[4:5], 0, v[30:31]
	v_add3_u32 v25, v25, v39, s44
	v_add3_u32 v29, v29, v33, s44
	v_lshrrev_b32_e32 v28, 16, v28
	v_lshrrev_b32_e32 v24, 16, v24
	v_lshrrev_b32_e32 v29, 16, v29
	v_lshrrev_b32_e32 v25, 16, v25
	v_and_or_b32 v24, v22, s33, v24
	v_and_or_b32 v22, v26, s33, v28
	v_add_co_u32_e32 v26, vcc, 0x13bfb000, v30
	v_and_or_b32 v25, v23, s33, v25
	v_and_or_b32 v23, v27, s33, v29
	v_addc_co_u32_e32 v27, vcc, 0, v31, vcc
	global_store_dwordx4 v[26:27], v[34:37], off offset:640
	global_store_dwordx4 v[26:27], v[22:25], off offset:656

; DI float sigm(float x) { return 1.f / (1.f + __expf(-x)); }
; DI float siluf(float x) { return x * sigm(x); }
; DI void phase_inproj0(const Params& p) {
;     ...
;     EPI256_BEGIN
;       float rs = r0[row];
; #pragma unroll
;       for (int i = 0; i < 16; ++i) v[i] *= rs;
;       if (col < 1024) store16_bf(u + (size_t)row * 1024 + col, v);
;       else if (col < 1728) store16_bf(lat + (size_t)row * 704 + col - 1024, v);
;       else if (col < 3776) {
; #pragma unroll
;         for (int i = 0; i < 16; ++i) v[i] = siluf(v[i]);
;         store16_bf(G0 + (size_t)row * 2048 + col - 1728, v); }
.LBB0_239:
	s_or_b64 exec, exec, s[26:27]
	ds_write2_b32 v2, v18, v14 offset1:16
	ds_write2_b32 v2, v19, v15 offset0:68 offset1:84
	ds_write2_b32 v2, v20, v16 offset0:136 offset1:152
	ds_write2_b32 v2, v21, v17 offset0:204 offset1:220
	ds_write2_b32 v2, v10, v6 offset0:32 offset1:48
	ds_write2_b32 v2, v11, v7 offset0:100 offset1:116
	ds_write2_b32 v2, v12, v8 offset0:168 offset1:184
	ds_write2_b32 v2, v13, v9 offset0:236 offset1:252
	v_or_b32_e32 v26, 0x70, v134
	s_waitcnt lgkmcnt(0)
	v_ashrrev_i32_e32 v27, 31, v26
	ds_read_b128 v[6:9], v144
	ds_read_b128 v[10:13], v144 offset:16
	ds_read_b128 v[18:21], v144 offset:32
	ds_read_b128 v[28:31], v144 offset:48
	v_lshl_add_u64 v[14:15], v[26:27], 2, s[16:17]
	global_load_dword v2, v[14:15], off
	s_waitcnt lgkmcnt(3)
	v_mov_b32_e32 v14, v6
	v_mov_b32_e32 v15, v8
	v_mov_b32_e32 v8, v7
	s_waitcnt lgkmcnt(2)
	v_mov_b32_e32 v6, v10
	v_mov_b32_e32 v7, v12
	v_mov_b32_e32 v12, v11
	s_waitcnt lgkmcnt(1)
	v_mov_b32_e32 v10, v18
	v_mov_b32_e32 v11, v20
	v_mov_b32_e32 v20, v19
	s_waitcnt lgkmcnt(0)
	v_mov_b32_e32 v32, v28
	v_mov_b32_e32 v33, v30
	v_mov_b32_e32 v30, v29
	s_waitcnt vmcnt(0)
	v_pk_mul_f32 v[24:25], v[14:15], v[2:3] op_sel_hi:[1,0]
	v_pk_mul_f32 v[22:23], v[8:9], v[2:3] op_sel_hi:[1,0]
	v_pk_mul_f32 v[18:19], v[6:7], v[2:3] op_sel_hi:[1,0]
	v_pk_mul_f32 v[16:17], v[12:13], v[2:3] op_sel_hi:[1,0]
	v_pk_mul_f32 v[12:13], v[10:11], v[2:3] op_sel_hi:[1,0]
	v_pk_mul_f32 v[10:11], v[20:21], v[2:3] op_sel_hi:[1,0]
	v_pk_mul_f32 v[8:9], v[32:33], v[2:3] op_sel_hi:[1,0]
	v_pk_mul_f32 v[6:7], v[30:31], v[2:3] op_sel_hi:[1,0]
	s_and_saveexec_b64 s[26:27], s[10:11]
	s_xor_b64 s[10:11], exec, s[26:27]
	s_cbranch_execz .LBB0_247
	s_and_saveexec_b64 s[26:27], s[8:9]
	s_xor_b64 s[8:9], exec, s[26:27]
	s_cbranch_execz .LBB0_244
	s_and_saveexec_b64 s[26:27], s[6:7]
	s_cbranch_execz .LBB0_243
	v_mul_f32_e32 v2, 0xbfb8aa3b, v24
	v_exp_f32_e32 v28, v2
	v_mul_f32_e32 v2, 0xbfb8aa3b, v22
	v_exp_f32_e32 v30, v2
	v_mul_f32_e32 v2, 0xbfb8aa3b, v25
	v_exp_f32_e32 v29, v2
	v_mul_f32_e32 v2, 0xbfb8aa3b, v23
	v_exp_f32_e32 v31, v2
	v_mul_f32_e32 v2, 0xbfb8aa3b, v18
	v_exp_f32_e32 v32, v2
	v_mul_f32_e32 v2, 0xbfb8aa3b, v16
	v_exp_f32_e32 v34, v2
	v_mul_f32_e32 v2, 0xbfb8aa3b, v19
	v_exp_f32_e32 v33, v2
	v_mul_f32_e32 v2, 0xbfb8aa3b, v17
	v_exp_f32_e32 v35, v2
	v_mul_f32_e32 v2, 0xbfb8aa3b, v12
	v_exp_f32_e32 v36, v2
	v_mul_f32_e32 v2, 0xbfb8aa3b, v10
	v_exp_f32_e32 v38, v2
	v_mul_f32_e32 v2, 0xbfb8aa3b, v13
	v_pk_add_f32 v[28:29], v[28:29], 1.0 op_sel_hi:[1,0]
	v_exp_f32_e32 v37, v2
	v_mul_f32_e32 v2, 0xbfb8aa3b, v11
	v_exp_f32_e32 v39, v2
	v_mul_f32_e32 v2, 0xbfb8aa3b, v8
	v_exp_f32_e32 v20, v2
	v_mul_f32_e32 v2, 0xbfb8aa3b, v6
	v_exp_f32_e32 v14, v2
	v_mul_f32_e32 v2, 0xbfb8aa3b, v9
	v_exp_f32_e32 v21, v2
	v_mul_f32_e32 v2, 0xbfb8aa3b, v7
	v_exp_f32_e32 v15, v2
	v_lshlrev_b64 v[26:27], 12, v[26:27]
	v_lshl_add_u64 v[4:5], v[4:5], 0, v[26:27]
	v_rcp_f32_e32 v27, v29
	v_pk_add_f32 v[30:31], v[30:31], 1.0 op_sel_hi:[1,0]
	v_rcp_f32_e32 v26, v28
	s_nop 0
	v_pk_mul_f32 v[24:25], v[24:25], v[26:27]
	v_rcp_f32_e32 v27, v31
	v_pk_add_f32 v[28:29], v[32:33], 1.0 op_sel_hi:[1,0]
	v_rcp_f32_e32 v26, v30
	s_nop 0
	v_pk_mul_f32 v[22:23], v[22:23], v[26:27]
	v_rcp_f32_e32 v27, v29
	v_pk_add_f32 v[30:31], v[34:35], 1.0 op_sel_hi:[1,0]
	v_rcp_f32_e32 v26, v28
	s_nop 0
	v_pk_mul_f32 v[18:19], v[18:19], v[26:27]
	v_rcp_f32_e32 v27, v31
	v_pk_add_f32 v[20:21], v[20:21], 1.0 op_sel_hi:[1,0]
	v_rcp_f32_e32 v26, v30
	s_nop 0
	v_pk_mul_f32 v[16:17], v[16:17], v[26:27]
	v_bfe_u32 v28, v22, 16, 1
	v_bfe_u32 v2, v17, 16, 1
	v_bfe_u32 v26, v16, 16, 1
	v_bfe_u32 v27, v23, 16, 1
	v_add3_u32 v28, v22, v28, s44
	v_add3_u32 v16, v16, v26, s44
	v_add3_u32 v2, v17, v2, s44
	v_bfe_u32 v17, v24, 16, 1
	v_bfe_u32 v22, v25, 16, 1
	v_bfe_u32 v26, v19, 16, 1
	v_add3_u32 v27, v23, v27, s44
	v_bfe_u32 v23, v18, 16, 1
	v_add3_u32 v19, v19, v26, s44
	v_add3_u32 v22, v25, v22, s44
	v_add3_u32 v17, v24, v17, s44
	v_add3_u32 v18, v18, v23, s44
	v_lshrrev_b32_e32 v24, 16, v17
	v_lshrrev_b32_e32 v17, 16, v22
	v_lshrrev_b32_e32 v19, 16, v19
	v_pk_add_f32 v[22:23], v[36:37], 1.0 op_sel_hi:[1,0]
	v_and_or_b32 v19, v2, s33, v19
	v_lshrrev_b32_e32 v18, 16, v18
	v_and_or_b32 v18, v16, s33, v18
	v_and_or_b32 v16, v28, s33, v24
	v_and_or_b32 v17, v27, s33, v17
	v_rcp_f32_e32 v23, v23
	v_pk_add_f32 v[14:15], v[14:15], 1.0 op_sel_hi:[1,0]
	v_pk_add_f32 v[24:25], v[38:39], 1.0 op_sel_hi:[1,0]
	v_rcp_f32_e32 v22, v22
	s_nop 0
	v_pk_mul_f32 v[12:13], v[12:13], v[22:23]
	v_rcp_f32_e32 v23, v25
	v_rcp_f32_e32 v22, v24
	s_nop 0
	v_pk_mul_f32 v[10:11], v[10:11], v[22:23]
	v_rcp_f32_e32 v21, v21
	v_rcp_f32_e32 v20, v20
	s_nop 0
	v_pk_mul_f32 v[8:9], v[8:9], v[20:21]
	v_div_scale_f32 v21, s[6:7], v14, v14, 1.0
	v_rcp_f32_e32 v22, v21
	v_rcp_f32_e32 v15, v15
	v_fma_f32 v2, -v21, v22, 1.0
	v_fmac_f32_e32 v22, v2, v22
	v_div_scale_f32 v2, vcc, 1.0, v14, 1.0
	v_mul_f32_e32 v20, v2, v22
	v_fma_f32 v23, -v21, v20, v2
	v_fmac_f32_e32 v20, v23, v22
	v_fma_f32 v2, -v21, v20, v2
	v_div_fmas_f32 v2, v2, v22, v20
	v_div_fixup_f32 v14, v2, v14, 1.0
	v_pk_mul_f32 v[6:7], v[6:7], v[14:15]
	v_bfe_u32 v15, v11, 16, 1
	v_bfe_u32 v2, v7, 16, 1
	v_bfe_u32 v14, v6, 16, 1
	v_bfe_u32 v20, v10, 16, 1
	v_add3_u32 v10, v10, v20, s44
	v_add3_u32 v11, v11, v15, s44
	v_add3_u32 v6, v6, v14, s44
	v_add3_u32 v2, v7, v2, s44
	v_bfe_u32 v7, v12, 16, 1
	v_bfe_u32 v14, v13, 16, 1
	v_bfe_u32 v15, v8, 16, 1
	v_bfe_u32 v20, v9, 16, 1
	v_add3_u32 v9, v9, v20, s44
	v_add3_u32 v8, v8, v15, s44
	v_add3_u32 v13, v13, v14, s44
	v_add3_u32 v7, v12, v7, s44
	v_add_co_u32_e32 v4, vcc, 0x13bfb000, v4
	v_lshrrev_b32_e32 v12, 16, v7
	v_lshrrev_b32_e32 v7, 16, v13
	v_lshrrev_b32_e32 v8, 16, v8
	v_lshrrev_b32_e32 v9, 16, v9
	v_addc_co_u32_e32 v5, vcc, 0, v5, vcc
	v_and_or_b32 v9, v2, s33, v9
	v_and_or_b32 v8, v6, s33, v8
	v_and_or_b32 v7, v11, s33, v7
	v_and_or_b32 v6, v10, s33, v12
	global_store_dwordx4 v[4:5], v[16:19], off offset:640
	global_store_dwordx4 v[4:5], v[6:9], off offset:656

; DI float geluf(float x) { float z = 0.7978845608028654f * (x + 0.044715f * x * x * x); float t = 1.f - 2.f / (1.f + __expf(2.f * z)); return 0.5f * x * (1.f + t); }
; DI void phase_s5step3(const Params& p) {
;     ...
;     EPI256_BEGIN
; #pragma unroll
;       for (int i = 0; i < 16; ++i) v[i] = geluf(v[i]);
;       store16_bf(ys + ((size_t)row * 32 + (col >> 4)) * LDP + g * 16, v);
;     EPI_END
.LBB0_592:
	v_lshrrev_b32_e32 v2, 6, v159
	v_lshrrev_b32_e32 v132, 2, v159
	v_and_b32_e32 v3, 15, v159
	v_mul_lo_u32 v2, v2, s31
	v_and_b32_e32 v132, 12, v132
	v_add_u32_e32 v2, s33, v2
	v_lshlrev_b32_e32 v3, 2, v3
	v_mul_u32_u24_e32 v132, 0x110, v132
	v_add3_u32 v140, v2, v3, v132
	v_bfe_u32 v3, v159, 2, 4
	v_and_b32_e32 v133, 48, v160
	s_waitcnt vmcnt(0)
	s_barrier
	v_mul_u32_u24_e32 v132, 0x110, v3
	v_lshlrev_b32_e32 v134, 2, v133
	ds_write2_b32 v140, v128, v124 offset1:16
	ds_write2_b32 v140, v129, v125 offset0:68 offset1:84
	ds_write2_b32 v140, v130, v126 offset0:136 offset1:152
	ds_write2_b32 v140, v131, v127 offset0:204 offset1:220
	ds_write2_b32 v140, v120, v116 offset0:32 offset1:48
	ds_write2_b32 v140, v121, v117 offset0:100 offset1:116
	ds_write2_b32 v140, v122, v118 offset0:168 offset1:184
	ds_write2_b32 v140, v123, v119 offset0:236 offset1:252
	v_add3_u32 v141, v2, v132, v134
	s_waitcnt lgkmcnt(0)
	ds_read_b128 v[142:145], v141
	ds_read_b128 v[124:127], v141 offset:16
	ds_read_b128 v[120:123], v141 offset:32
	ds_read_b128 v[116:119], v141 offset:48
	v_ashrrev_i32_e32 v2, 1, v159
	s_waitcnt lgkmcnt(3)
	v_mul_f32_e32 v128, 0x3d372713, v145
	v_mul_f32_e32 v128, v145, v128
	v_fma_f32 v128, v145, v128, v145
	v_mul_f32_e32 v128, 0x3f4c422a, v128
	v_add_f32_e32 v128, v128, v128
	v_mul_f32_e32 v128, 0x3fb8aa3b, v128
	v_exp_f32_e32 v147, v128
	s_waitcnt lgkmcnt(2)
	v_mul_f32_e32 v128, 0x3d372713, v124
	v_mul_f32_e32 v128, v124, v128
	v_fma_f32 v128, v124, v128, v124
	v_mul_f32_e32 v128, 0x3f4c422a, v128
	v_add_f32_e32 v128, v128, v128
	v_mul_f32_e32 v128, 0x3fb8aa3b, v128
	v_exp_f32_e32 v148, v128
	v_mul_f32_e32 v128, 0x3d372713, v125
	v_mul_f32_e32 v128, v125, v128
	v_fma_f32 v128, v125, v128, v125
	v_mul_f32_e32 v128, 0x3f4c422a, v128
	v_add_f32_e32 v128, v128, v128
	v_mul_f32_e32 v128, 0x3fb8aa3b, v128
	v_exp_f32_e32 v150, v128
	v_mul_f32_e32 v128, 0x3d372713, v126
	v_mul_f32_e32 v128, v126, v128
	v_fma_f32 v128, v126, v128, v126
	v_mul_f32_e32 v128, 0x3f4c422a, v128
	v_add_f32_e32 v128, v128, v128
	v_mul_f32_e32 v128, 0x3fb8aa3b, v128
	v_exp_f32_e32 v149, v128
	v_mul_f32_e32 v128, 0x3d372713, v127
	v_mul_f32_e32 v128, v127, v128
	v_fma_f32 v128, v127, v128, v127
	v_mul_f32_e32 v128, 0x3f4c422a, v128
	v_add_f32_e32 v128, v128, v128
	v_mul_f32_e32 v128, 0x3fb8aa3b, v128
	v_exp_f32_e32 v151, v128
	s_waitcnt lgkmcnt(1)
	v_mul_f32_e32 v128, 0x3d372713, v120
	v_mul_f32_e32 v128, v120, v128
	v_fma_f32 v128, v120, v128, v120
	v_mul_f32_e32 v128, 0x3f4c422a, v128
	v_add_f32_e32 v128, v128, v128
	v_mul_f32_e32 v128, 0x3fb8aa3b, v128
	v_exp_f32_e32 v138, v128
	v_mul_f32_e32 v128, 0x3d372713, v121
	v_mul_f32_e32 v128, v121, v128
	v_fma_f32 v128, v121, v128, v121
	v_mul_f32_e32 v128, 0x3f4c422a, v128
	v_add_f32_e32 v128, v128, v128
	v_mul_f32_e32 v128, 0x3fb8aa3b, v128
	v_exp_f32_e32 v136, v128
	v_mul_f32_e32 v128, 0x3d372713, v122
	v_mul_f32_e32 v128, v122, v128
	v_fma_f32 v128, v122, v128, v122
	v_mul_f32_e32 v128, 0x3f4c422a, v128
	v_add_f32_e32 v128, v128, v128
	v_mul_f32_e32 v128, 0x3fb8aa3b, v128
	v_exp_f32_e32 v139, v128
	v_mul_f32_e32 v128, 0x3d372713, v123
	v_mul_f32_e32 v128, v123, v128
	v_fma_f32 v128, v123, v128, v123
	v_mul_f32_e32 v128, 0x3f4c422a, v128
	v_add_f32_e32 v128, v128, v128
	v_mul_f32_e32 v128, 0x3fb8aa3b, v128
	v_exp_f32_e32 v137, v128
	s_waitcnt lgkmcnt(0)
	v_mul_f32_e32 v128, 0x3d372713, v116
	v_mul_f32_e32 v128, v116, v128
	v_fma_f32 v128, v116, v128, v116
	v_mul_f32_e32 v128, 0x3f4c422a, v128
	v_add_f32_e32 v128, v128, v128
	v_and_b32_e32 v2, 0xffffff80, v2
	v_mul_f32_e32 v128, 0x3fb8aa3b, v128
	v_add_u32_e32 v2, s39, v2
	v_exp_f32_e32 v134, v128
	v_mul_f32_e32 v128, 0x3d372713, v117
	v_or_b32_e32 v132, v2, v3
	v_mul_f32_e32 v3, 0x3d372713, v143
	v_mul_f32_e32 v128, v117, v128
	v_mul_f32_e32 v3, v143, v3
	v_fma_f32 v128, v117, v128, v117
	v_fma_f32 v3, v143, v3, v143
	v_mul_f32_e32 v128, 0x3f4c422a, v128
	v_mul_f32_e32 v3, 0x3f4c422a, v3
	v_add_f32_e32 v128, v128, v128
	v_add_f32_e32 v3, v3, v3
	v_mul_f32_e32 v128, 0x3fb8aa3b, v128
	v_mul_f32_e32 v3, 0x3fb8aa3b, v3
	v_exp_f32_e32 v130, v128
	v_mul_f32_e32 v128, 0x3d372713, v118
	v_mul_f32_e32 v2, 0x3d372713, v142
	v_exp_f32_e32 v146, v3
	v_mul_f32_e32 v3, 0x3d372713, v144
	v_mul_f32_e32 v128, v118, v128
	v_mul_f32_e32 v2, v142, v2
	v_mul_f32_e32 v3, v144, v3
	v_fma_f32 v128, v118, v128, v118
	v_fma_f32 v2, v142, v2, v142
	v_fma_f32 v3, v144, v3, v144
	v_mul_f32_e32 v128, 0x3f4c422a, v128
	v_mul_f32_e32 v2, 0x3f4c422a, v2
	v_mul_f32_e32 v3, 0x3f4c422a, v3
	v_add_f32_e32 v128, v128, v128
	v_add_f32_e32 v2, v2, v2
	v_add_f32_e32 v3, v3, v3
	v_mul_f32_e32 v128, 0x3fb8aa3b, v128
	v_mul_f32_e32 v2, 0x3fb8aa3b, v2
	v_mul_f32_e32 v3, 0x3fb8aa3b, v3
	v_exp_f32_e32 v135, v128
	v_mul_f32_e32 v128, 0x3d372713, v119
	v_exp_f32_e32 v2, v2
	v_exp_f32_e32 v3, v3
	v_mul_f32_e32 v128, v119, v128
	v_fma_f32 v128, v119, v128, v119
	v_and_b32_e32 v0, 0xc0, v159
	v_mul_f32_e32 v128, 0x3f4c422a, v128
	s_add_u32 s8, s5, s14
	v_or3_b32 v0, v0, s38, v133
	v_add_f32_e32 v128, v128, v128
	v_ashrrev_i32_e32 v133, 31, v132
	s_addc_u32 s9, s22, s15
	v_lshrrev_b32_e32 v0, 4, v0
	v_mul_f32_e32 v128, 0x3fb8aa3b, v128
	v_lshlrev_b64 v[152:153], 5, v[132:133]
	v_pk_add_f32 v[154:155], v[2:3], 1.0 op_sel_hi:[1,0]
	v_exp_f32_e32 v131, v128
	v_or_b32_e32 v133, v152, v0
	v_mov_b64_e32 v[128:129], s[8:9]
	v_mad_u64_u32 v[2:3], s[8:9], v133, s36, v[128:129]
	v_mad_i32_i24 v3, v153, s36, v3
	v_rcp_f32_e32 v153, v155
	s_nop 0
	v_add_f32_e32 v153, v153, v153
	v_pk_add_f32 v[146:147], v[146:147], 1.0 op_sel_hi:[1,0]
	v_rcp_f32_e32 v152, v154
	s_nop 0
	v_add_f32_e32 v152, v152, v152
	v_mov_b32_e32 v154, v142
; DI float geluf(float x) { float z = 0.7978845608028654f * (x + 0.044715f * x * x * x); float t = 1.f - 2.f / (1.f + __expf(2.f * z)); return 0.5f * x * (1.f + t); }
; DI void phase_s5step3(const Params& p) {
;     ...
;     EPI256_BEGIN
; #pragma unroll
;       for (int i = 0; i < 16; ++i) v[i] = geluf(v[i]);
;       store16_bf(ys + ((size_t)row * 32 + (col >> 4)) * LDP + g * 16, v);
;     EPI_END
	v_pk_add_f32 v[152:153], v[152:153], 1.0 op_sel_hi:[1,0] neg_lo:[1,0] neg_hi:[1,0]
	v_mov_b32_e32 v155, v144
	v_pk_mul_f32 v[154:155], v[154:155], 0.5 op_sel_hi:[1,0]
	v_pk_add_f32 v[152:153], v[152:153], 1.0 op_sel_hi:[1,0]
	v_pk_mul_f32 v[152:153], v[154:155], v[152:153]
	v_rcp_f32_e32 v147, v147
	s_nop 0
	v_add_f32_e32 v147, v147, v147
	v_pk_add_f32 v[138:139], v[138:139], 1.0 op_sel_hi:[1,0]
	v_mov_b32_e32 v144, v143
	v_pk_add_f32 v[142:143], v[148:149], 1.0 op_sel_hi:[1,0]
	v_rcp_f32_e32 v146, v146
	s_nop 0
	v_add_f32_e32 v146, v146, v146
	v_pk_add_f32 v[146:147], v[146:147], 1.0 op_sel_hi:[1,0] neg_lo:[1,0] neg_hi:[1,0]
	v_pk_mul_f32 v[144:145], v[144:145], 0.5 op_sel_hi:[1,0]
	v_pk_add_f32 v[146:147], v[146:147], 1.0 op_sel_hi:[1,0]
	v_pk_add_f32 v[136:137], v[136:137], 1.0 op_sel_hi:[1,0]
	v_pk_mul_f32 v[144:145], v[144:145], v[146:147]
	v_rcp_f32_e32 v143, v143
	s_nop 0
	v_add_f32_e32 v143, v143, v143
	v_pk_add_f32 v[130:131], v[130:131], 1.0 op_sel_hi:[1,0]
	v_pk_add_f32 v[148:149], v[150:151], 1.0 op_sel_hi:[1,0]
	v_mov_b32_e32 v146, v124
	v_mov_b32_e32 v147, v126
	v_rcp_f32_e32 v142, v142
	s_nop 0
	v_add_f32_e32 v142, v142, v142
	v_pk_add_f32 v[142:143], v[142:143], 1.0 op_sel_hi:[1,0] neg_lo:[1,0] neg_hi:[1,0]
	v_pk_mul_f32 v[146:147], v[146:147], 0.5 op_sel_hi:[1,0]
	v_pk_add_f32 v[142:143], v[142:143], 1.0 op_sel_hi:[1,0]
	v_pk_mul_f32 v[142:143], v[146:147], v[142:143]
	v_rcp_f32_e32 v147, v149
	s_nop 0
	v_add_f32_e32 v147, v147, v147
	v_rcp_f32_e32 v146, v148
	s_nop 0
	v_add_f32_e32 v146, v146, v146
	v_pk_add_f32 v[146:147], v[146:147], 1.0 op_sel_hi:[1,0] neg_lo:[1,0] neg_hi:[1,0]
	v_mov_b32_e32 v126, v125
	v_pk_mul_f32 v[124:125], v[126:127], 0.5 op_sel_hi:[1,0]
	v_pk_add_f32 v[126:127], v[146:147], 1.0 op_sel_hi:[1,0]
	v_bfe_u32 v133, v145, 16, 1
	v_pk_mul_f32 v[124:125], v[124:125], v[126:127]
	v_bfe_u32 v146, v144, 16, 1
	v_bfe_u32 v126, v125, 16, 1
	v_bfe_u32 v127, v124, 16, 1
	v_add3_u32 v133, v145, v133, s37
	v_add3_u32 v125, v125, v126, s37
	v_bfe_u32 v126, v152, 16, 1
	v_bfe_u32 v145, v142, 16, 1
	v_add3_u32 v144, v144, v146, s37
	v_add3_u32 v124, v124, v127, s37
	v_bfe_u32 v127, v153, 16, 1
	v_bfe_u32 v146, v143, 16, 1
	v_add3_u32 v142, v142, v145, s37
	v_add3_u32 v126, v152, v126, s37
	v_add3_u32 v143, v143, v146, s37
	v_add3_u32 v127, v153, v127, s37
	v_lshrrev_b32_e32 v145, 16, v126
	v_lshrrev_b32_e32 v126, 16, v142
	v_lshrrev_b32_e32 v146, 16, v127
	v_lshrrev_b32_e32 v127, 16, v143
	v_and_or_b32 v127, v125, s30, v127
	v_and_or_b32 v125, v133, s30, v146
	v_and_or_b32 v126, v124, s30, v126
	v_and_or_b32 v124, v144, s30, v145
	v_rcp_f32_e32 v139, v139
	s_nop 0
	v_add_f32_e32 v139, v139, v139
	s_add_i32 s23, s23, 1
	v_mov_b32_e32 v142, v120
	v_mov_b32_e32 v143, v122
	v_rcp_f32_e32 v138, v138
	s_nop 0
	v_add_f32_e32 v138, v138, v138
	v_pk_add_f32 v[138:139], v[138:139], 1.0 op_sel_hi:[1,0] neg_lo:[1,0] neg_hi:[1,0]
	v_pk_mul_f32 v[142:143], v[142:143], 0.5 op_sel_hi:[1,0]
	v_pk_add_f32 v[138:139], v[138:139], 1.0 op_sel_hi:[1,0]
	v_pk_mul_f32 v[138:139], v[142:143], v[138:139]
	v_rcp_f32_e32 v137, v137
	s_nop 0
	v_add_f32_e32 v137, v137, v137
	v_rcp_f32_e32 v136, v136
	s_nop 0
	v_add_f32_e32 v136, v136, v136
	v_mov_b32_e32 v122, v121
	v_pk_add_f32 v[120:121], v[134:135], 1.0 op_sel_hi:[1,0]
	v_pk_add_f32 v[136:137], v[136:137], 1.0 op_sel_hi:[1,0] neg_lo:[1,0] neg_hi:[1,0]
	v_pk_mul_f32 v[122:123], v[122:123], 0.5 op_sel_hi:[1,0]
	v_pk_add_f32 v[134:135], v[136:137], 1.0 op_sel_hi:[1,0]
	s_nop 0
	v_pk_mul_f32 v[122:123], v[122:123], v[134:135]
	v_rcp_f32_e32 v121, v121
	s_nop 0
	v_add_f32_e32 v121, v121, v121
	v_mov_b32_e32 v134, v116
	v_div_scale_f32 v116, s[8:9], v131, v131, 2.0
	v_mov_b32_e32 v135, v118
	v_rcp_f32_e32 v118, v116
	v_rcp_f32_e32 v120, v120
	s_nop 0
	v_add_f32_e32 v120, v120, v120
	v_pk_add_f32 v[120:121], v[120:121], 1.0 op_sel_hi:[1,0] neg_lo:[1,0] neg_hi:[1,0]
	v_pk_mul_f32 v[134:135], v[134:135], 0.5 op_sel_hi:[1,0]
	v_fma_f32 v133, -v116, v118, 1.0
	v_pk_add_f32 v[120:121], v[120:121], 1.0 op_sel_hi:[1,0]
	v_fmac_f32_e32 v118, v133, v118
	v_div_scale_f32 v133, vcc, 2.0, v131, 2.0
	v_pk_mul_f32 v[120:121], v[134:135], v[120:121]
	v_mul_f32_e32 v134, v133, v118
	v_fma_f32 v135, -v116, v134, v133
	v_fmac_f32_e32 v134, v135, v118
	v_fma_f32 v116, -v116, v134, v133
	v_div_scale_f32 v133, s[8:9], v130, v130, 2.0
	v_rcp_f32_e32 v135, v133
	v_div_fmas_f32 v116, v116, v118, v134
	v_div_fixup_f32 v131, v116, v131, 2.0
	v_fma_f32 v116, -v133, v135, 1.0
	v_fmac_f32_e32 v135, v116, v135
	v_div_scale_f32 v116, vcc, 2.0, v130, 2.0
	v_mul_f32_e32 v118, v116, v135
	v_fma_f32 v134, -v133, v118, v116
	v_fmac_f32_e32 v118, v134, v135
	v_fma_f32 v116, -v133, v118, v116
	v_div_fmas_f32 v116, v116, v135, v118
	v_div_fixup_f32 v130, v116, v130, 2.0
	v_pk_add_f32 v[130:131], v[130:131], 1.0 op_sel_hi:[1,0] neg_lo:[1,0] neg_hi:[1,0]
	v_mov_b32_e32 v118, v117
	v_pk_mul_f32 v[116:117], v[118:119], 0.5 op_sel_hi:[1,0]
	v_pk_add_f32 v[118:119], v[130:131], 1.0 op_sel_hi:[1,0]
	v_bfe_u32 v130, v123, 16, 1
	v_pk_mul_f32 v[116:117], v[116:117], v[118:119]
	v_bfe_u32 v131, v122, 16, 1
	v_bfe_u32 v118, v117, 16, 1
	v_bfe_u32 v119, v116, 16, 1
	v_add3_u32 v122, v122, v131, s37
	v_add3_u32 v123, v123, v130, s37
	v_add3_u32 v116, v116, v119, s37
	v_add3_u32 v117, v117, v118, s37
	v_bfe_u32 v118, v138, 16, 1
	v_bfe_u32 v119, v139, 16, 1
	v_bfe_u32 v130, v120, 16, 1
	v_bfe_u32 v131, v121, 16, 1
	v_add3_u32 v121, v121, v131, s37
	v_add3_u32 v120, v120, v130, s37
	v_add3_u32 v119, v139, v119, s37
	v_add3_u32 v118, v138, v118, s37
	v_lshrrev_b32_e32 v130, 16, v118
	v_lshrrev_b32_e32 v131, 16, v119
	v_lshrrev_b32_e32 v118, 16, v120
	v_lshrrev_b32_e32 v119, 16, v121
	v_and_or_b32 v119, v117, s30, v119
	v_and_or_b32 v118, v116, s30, v118
	v_and_or_b32 v117, v123, s30, v131
	v_and_or_b32 v116, v122, s30, v130
	global_store_dwordx4 v[2:3], v[124:127], off
	global_store_dwordx4 v[2:3], v[116:119], off offset:16
	ds_write2_b32 v140, v112, v108 offset1:16
	ds_write2_b32 v140, v113, v109 offset0:68 offset1:84
	ds_write2_b32 v140, v114, v110 offset0:136 offset1:152
	ds_write2_b32 v140, v115, v111 offset0:204 offset1:220
	ds_write2_b32 v140, v104, v100 offset0:32 offset1:48
	ds_write2_b32 v140, v105, v101 offset0:100 offset1:116
	ds_write2_b32 v140, v106, v102 offset0:168 offset1:184
	ds_write2_b32 v140, v107, v103 offset0:236 offset1:252
	s_waitcnt lgkmcnt(0)
; DI float geluf(float x) { float z = 0.7978845608028654f * (x + 0.044715f * x * x * x); float t = 1.f - 2.f / (1.f + __expf(2.f * z)); return 0.5f * x * (1.f + t); }
; DI void phase_s5step3(const Params& p) {
;     ...
;     EPI256_BEGIN
; #pragma unroll
;       for (int i = 0; i < 16; ++i) v[i] = geluf(v[i]);
;       store16_bf(ys + ((size_t)row * 32 + (col >> 4)) * LDP + g * 16, v);
;     EPI_END
	ds_read_b128 v[120:123], v141
	ds_read_b128 v[108:111], v141 offset:16
	ds_read_b128 v[104:107], v141 offset:32
	ds_read_b128 v[100:103], v141 offset:48
	v_or_b32_e32 v134, 16, v132
	s_waitcnt lgkmcnt(3)
	v_mul_f32_e32 v3, 0x3d372713, v121
	v_mul_f32_e32 v3, v121, v3
	v_fma_f32 v3, v121, v3, v121
	v_mul_f32_e32 v3, 0x3f4c422a, v3
	v_add_f32_e32 v3, v3, v3
	v_mul_f32_e32 v3, 0x3fb8aa3b, v3
	v_mul_f32_e32 v2, 0x3d372713, v120
	v_exp_f32_e32 v124, v3
	v_mul_f32_e32 v3, 0x3d372713, v122
	v_mul_f32_e32 v2, v120, v2
	v_mul_f32_e32 v3, v122, v3
	v_fma_f32 v2, v120, v2, v120
	v_fma_f32 v3, v122, v3, v122
	v_mul_f32_e32 v2, 0x3f4c422a, v2
	v_mul_f32_e32 v3, 0x3f4c422a, v3
	v_add_f32_e32 v2, v2, v2
	v_add_f32_e32 v3, v3, v3
	v_mul_f32_e32 v2, 0x3fb8aa3b, v2
	v_mul_f32_e32 v3, 0x3fb8aa3b, v3
	v_exp_f32_e32 v2, v2
	v_exp_f32_e32 v3, v3
	v_ashrrev_i32_e32 v135, 31, v134
	v_lshlrev_b64 v[134:135], 5, v[134:135]
	v_or_b32_e32 v133, v134, v0
	v_pk_add_f32 v[136:137], v[2:3], 1.0 op_sel_hi:[1,0]
	v_mad_u64_u32 v[2:3], s[8:9], v133, s36, v[128:129]
	v_mad_i32_i24 v3, v135, s36, v3
	v_mul_f32_e32 v112, 0x3d372713, v123
	v_mul_f32_e32 v112, v123, v112
	v_fma_f32 v112, v123, v112, v123
	v_mul_f32_e32 v112, 0x3f4c422a, v112
	v_add_f32_e32 v112, v112, v112
	v_rcp_f32_e32 v135, v137
	s_nop 0
	v_add_f32_e32 v135, v135, v135
	v_mul_f32_e32 v112, 0x3fb8aa3b, v112
	v_exp_f32_e32 v125, v112
	s_nop 0
	v_pk_add_f32 v[124:125], v[124:125], 1.0 op_sel_hi:[1,0]
	s_waitcnt lgkmcnt(2)
	v_mul_f32_e32 v112, 0x3d372713, v108
	v_rcp_f32_e32 v134, v136
	s_nop 0
	v_add_f32_e32 v134, v134, v134
	v_mov_b32_e32 v136, v120
	v_mul_f32_e32 v112, v108, v112
	v_mov_b32_e32 v137, v122
	v_fma_f32 v112, v108, v112, v108
	v_mul_f32_e32 v112, 0x3f4c422a, v112
	v_add_f32_e32 v112, v112, v112
	v_mul_f32_e32 v112, 0x3fb8aa3b, v112
	v_pk_add_f32 v[134:135], v[134:135], 1.0 op_sel_hi:[1,0] neg_lo:[1,0] neg_hi:[1,0]
	v_exp_f32_e32 v126, v112
	v_mul_f32_e32 v112, 0x3d372713, v109
	v_pk_mul_f32 v[136:137], v[136:137], 0.5 op_sel_hi:[1,0]
	v_pk_add_f32 v[134:135], v[134:135], 1.0 op_sel_hi:[1,0]
	v_mul_f32_e32 v112, v109, v112
	v_pk_mul_f32 v[134:135], v[136:137], v[134:135]
	v_fma_f32 v112, v109, v112, v109
	v_mul_f32_e32 v112, 0x3f4c422a, v112
	v_add_f32_e32 v112, v112, v112
	v_mul_f32_e32 v112, 0x3fb8aa3b, v112
	v_exp_f32_e32 v130, v112
	v_mul_f32_e32 v112, 0x3d372713, v110
	v_mul_f32_e32 v112, v110, v112
	v_fma_f32 v112, v110, v112, v110
	v_mul_f32_e32 v112, 0x3f4c422a, v112
	v_rcp_f32_e32 v125, v125
	s_nop 0
	v_add_f32_e32 v125, v125, v125
	v_add_f32_e32 v112, v112, v112
	v_mul_f32_e32 v112, 0x3fb8aa3b, v112
	v_exp_f32_e32 v127, v112
	v_rcp_f32_e32 v124, v124
	s_nop 0
	v_add_f32_e32 v124, v124, v124
	v_mov_b32_e32 v122, v121
	v_pk_add_f32 v[120:121], v[126:127], 1.0 op_sel_hi:[1,0]
	v_pk_add_f32 v[124:125], v[124:125], 1.0 op_sel_hi:[1,0] neg_lo:[1,0] neg_hi:[1,0]
	v_pk_mul_f32 v[122:123], v[122:123], 0.5 op_sel_hi:[1,0]
	v_pk_add_f32 v[124:125], v[124:125], 1.0 op_sel_hi:[1,0]
	v_mul_f32_e32 v112, 0x3d372713, v111
	v_pk_mul_f32 v[122:123], v[122:123], v[124:125]
	v_mul_f32_e32 v112, v111, v112
	v_fma_f32 v112, v111, v112, v111
	v_mul_f32_e32 v112, 0x3f4c422a, v112
	v_add_f32_e32 v112, v112, v112
	v_rcp_f32_e32 v121, v121
	s_nop 0
	v_add_f32_e32 v121, v121, v121
	v_mul_f32_e32 v112, 0x3fb8aa3b, v112
	v_exp_f32_e32 v131, v112
	s_nop 0
	v_pk_add_f32 v[126:127], v[130:131], 1.0 op_sel_hi:[1,0]
	v_rcp_f32_e32 v120, v120
	s_nop 0
	v_add_f32_e32 v120, v120, v120
	v_mov_b32_e32 v124, v108
	v_mov_b32_e32 v125, v110
	v_pk_add_f32 v[120:121], v[120:121], 1.0 op_sel_hi:[1,0] neg_lo:[1,0] neg_hi:[1,0]
	v_pk_mul_f32 v[124:125], v[124:125], 0.5 op_sel_hi:[1,0]
	v_pk_add_f32 v[120:121], v[120:121], 1.0 op_sel_hi:[1,0]
	s_waitcnt lgkmcnt(1)
	v_mul_f32_e32 v112, 0x3d372713, v104
	v_pk_mul_f32 v[120:121], v[124:125], v[120:121]
	v_mul_f32_e32 v112, v104, v112
	v_fma_f32 v112, v104, v112, v104
	v_mul_f32_e32 v112, 0x3f4c422a, v112
	v_add_f32_e32 v112, v112, v112
	v_mul_f32_e32 v112, 0x3fb8aa3b, v112
	v_exp_f32_e32 v118, v112
	v_mul_f32_e32 v112, 0x3d372713, v105
	v_mul_f32_e32 v112, v105, v112
	v_fma_f32 v112, v105, v112, v105
	v_mul_f32_e32 v112, 0x3f4c422a, v112
	v_rcp_f32_e32 v125, v127
	s_nop 0
	v_add_f32_e32 v125, v125, v125
	v_add_f32_e32 v112, v112, v112
	v_mul_f32_e32 v112, 0x3fb8aa3b, v112
	v_exp_f32_e32 v116, v112
	v_mul_f32_e32 v112, 0x3d372713, v106
	v_mul_f32_e32 v112, v106, v112
	v_fma_f32 v112, v106, v112, v106
	v_mul_f32_e32 v112, 0x3f4c422a, v112
	v_add_f32_e32 v112, v112, v112
	v_rcp_f32_e32 v124, v126
	s_nop 0
	v_add_f32_e32 v124, v124, v124
	v_mul_f32_e32 v112, 0x3fb8aa3b, v112
	v_pk_add_f32 v[124:125], v[124:125], 1.0 op_sel_hi:[1,0] neg_lo:[1,0] neg_hi:[1,0]
	v_mov_b32_e32 v110, v109
	v_exp_f32_e32 v119, v112
	v_pk_mul_f32 v[108:109], v[110:111], 0.5 op_sel_hi:[1,0]
	v_pk_add_f32 v[110:111], v[124:125], 1.0 op_sel_hi:[1,0]
	v_bfe_u32 v124, v123, 16, 1
	v_pk_mul_f32 v[108:109], v[108:109], v[110:111]
	v_bfe_u32 v125, v122, 16, 1
	v_bfe_u32 v110, v109, 16, 1
	v_bfe_u32 v111, v108, 16, 1
	v_add3_u32 v123, v123, v124, s37
	v_add3_u32 v109, v109, v110, s37
	v_bfe_u32 v110, v134, 16, 1
	v_bfe_u32 v124, v120, 16, 1
	v_add3_u32 v122, v122, v125, s37
	v_add3_u32 v108, v108, v111, s37
	v_bfe_u32 v111, v135, 16, 1
	v_bfe_u32 v125, v121, 16, 1
	v_add3_u32 v120, v120, v124, s37
	v_add3_u32 v110, v134, v110, s37
	v_pk_add_f32 v[118:119], v[118:119], 1.0 op_sel_hi:[1,0]
	v_add3_u32 v121, v121, v125, s37
	v_add3_u32 v111, v135, v111, s37
	v_lshrrev_b32_e32 v124, 16, v110
	v_lshrrev_b32_e32 v110, 16, v120
	v_lshrrev_b32_e32 v125, 16, v111
	v_lshrrev_b32_e32 v111, 16, v121
	v_and_or_b32 v110, v108, s30, v110
	v_and_or_b32 v108, v122, s30, v124
	v_and_or_b32 v111, v109, s30, v111
	v_and_or_b32 v109, v123, s30, v125
	v_mul_f32_e32 v112, 0x3d372713, v107
	v_mul_f32_e32 v112, v107, v112
	v_fma_f32 v112, v107, v112, v107
	v_mul_f32_e32 v112, 0x3f4c422a, v112
	v_add_f32_e32 v112, v112, v112
	v_rcp_f32_e32 v119, v119
	s_nop 0
	v_add_f32_e32 v119, v119, v119
	v_mul_f32_e32 v112, 0x3fb8aa3b, v112
	v_exp_f32_e32 v117, v112
	s_nop 0
	v_pk_add_f32 v[116:117], v[116:117], 1.0 op_sel_hi:[1,0]
	v_rcp_f32_e32 v118, v118
	s_nop 0
	v_add_f32_e32 v118, v118, v118
	v_mov_b32_e32 v120, v104
	v_mov_b32_e32 v121, v106
	v_pk_add_f32 v[118:119], v[118:119], 1.0 op_sel_hi:[1,0] neg_lo:[1,0] neg_hi:[1,0]
	v_pk_mul_f32 v[120:121], v[120:121], 0.5 op_sel_hi:[1,0]
	v_pk_add_f32 v[118:119], v[118:119], 1.0 op_sel_hi:[1,0]
	s_waitcnt lgkmcnt(0)
; DI float geluf(float x) { float z = 0.7978845608028654f * (x + 0.044715f * x * x * x); float t = 1.f - 2.f / (1.f + __expf(2.f * z)); return 0.5f * x * (1.f + t); }
; DI void phase_s5step3(const Params& p) {
;     ...
;     EPI256_BEGIN
; #pragma unroll
;       for (int i = 0; i < 16; ++i) v[i] = geluf(v[i]);
;       store16_bf(ys + ((size_t)row * 32 + (col >> 4)) * LDP + g * 16, v);
;     EPI_END
	v_mul_f32_e32 v112, 0x3d372713, v100
	v_pk_mul_f32 v[118:119], v[120:121], v[118:119]
	v_mul_f32_e32 v113, 0x3d372713, v102
	v_mul_f32_e32 v112, v100, v112
	v_mul_f32_e32 v113, v102, v113
	v_fma_f32 v112, v100, v112, v100
	v_fma_f32 v113, v102, v113, v102
	v_mul_f32_e32 v112, 0x3f4c422a, v112
	v_mul_f32_e32 v113, 0x3f4c422a, v113
	v_rcp_f32_e32 v117, v117
	s_nop 0
	v_add_f32_e32 v117, v117, v117
	v_add_f32_e32 v112, v112, v112
	v_add_f32_e32 v113, v113, v113
	v_mul_f32_e32 v112, 0x3fb8aa3b, v112
	v_mul_f32_e32 v113, 0x3fb8aa3b, v113
	v_exp_f32_e32 v114, v112
	v_exp_f32_e32 v115, v113
	v_rcp_f32_e32 v116, v116
	s_nop 0
	v_add_f32_e32 v116, v116, v116
	v_mov_b32_e32 v106, v105
	v_pk_add_f32 v[104:105], v[114:115], 1.0 op_sel_hi:[1,0]
	v_pk_add_f32 v[116:117], v[116:117], 1.0 op_sel_hi:[1,0] neg_lo:[1,0] neg_hi:[1,0]
	v_pk_mul_f32 v[106:107], v[106:107], 0.5 op_sel_hi:[1,0]
	v_pk_add_f32 v[114:115], v[116:117], 1.0 op_sel_hi:[1,0]
	v_mul_f32_e32 v112, 0x3d372713, v101
	v_pk_mul_f32 v[106:107], v[106:107], v[114:115]
	v_mul_f32_e32 v113, 0x3d372713, v103
	v_mul_f32_e32 v112, v101, v112
	v_mul_f32_e32 v113, v103, v113
	v_fma_f32 v112, v101, v112, v101
	v_fma_f32 v113, v103, v113, v103
	v_mul_f32_e32 v112, 0x3f4c422a, v112
	v_mul_f32_e32 v113, 0x3f4c422a, v113
	v_add_f32_e32 v112, v112, v112
	v_add_f32_e32 v113, v113, v113
	v_rcp_f32_e32 v105, v105
	s_nop 0
	v_add_f32_e32 v105, v105, v105
	v_mul_f32_e32 v112, 0x3fb8aa3b, v112
	v_mul_f32_e32 v113, 0x3fb8aa3b, v113
	v_exp_f32_e32 v112, v112
	v_exp_f32_e32 v113, v113
	s_nop 0
	v_pk_add_f32 v[112:113], v[112:113], 1.0 op_sel_hi:[1,0]
	v_rcp_f32_e32 v104, v104
	s_nop 0
	v_add_f32_e32 v104, v104, v104
	v_mov_b32_e32 v114, v100
	v_div_scale_f32 v100, s[8:9], v113, v113, 2.0
	v_mov_b32_e32 v115, v102
	v_rcp_f32_e32 v102, v100
	v_pk_add_f32 v[104:105], v[104:105], 1.0 op_sel_hi:[1,0] neg_lo:[1,0] neg_hi:[1,0]
	v_pk_mul_f32 v[114:115], v[114:115], 0.5 op_sel_hi:[1,0]
	v_pk_add_f32 v[104:105], v[104:105], 1.0 op_sel_hi:[1,0]
	s_nop 0
	v_pk_mul_f32 v[104:105], v[114:115], v[104:105]
	v_fma_f32 v114, -v100, v102, 1.0
	v_fmac_f32_e32 v102, v114, v102
	v_div_scale_f32 v114, vcc, 2.0, v113, 2.0
	v_mul_f32_e32 v115, v114, v102
	v_fma_f32 v116, -v100, v115, v114
	v_fmac_f32_e32 v115, v116, v102
	v_fma_f32 v100, -v100, v115, v114
	v_div_scale_f32 v114, s[8:9], v112, v112, 2.0
	v_rcp_f32_e32 v116, v114
	v_div_fmas_f32 v100, v100, v102, v115
	v_div_fixup_f32 v113, v100, v113, 2.0
	v_fma_f32 v100, -v114, v116, 1.0
	v_fmac_f32_e32 v116, v100, v116
	v_div_scale_f32 v100, vcc, 2.0, v112, 2.0
	v_mul_f32_e32 v102, v100, v116
	v_fma_f32 v115, -v114, v102, v100
	v_fmac_f32_e32 v102, v115, v116
	v_fma_f32 v100, -v114, v102, v100
	v_div_fmas_f32 v100, v100, v116, v102
	v_div_fixup_f32 v112, v100, v112, 2.0
	v_pk_add_f32 v[112:113], v[112:113], 1.0 op_sel_hi:[1,0] neg_lo:[1,0] neg_hi:[1,0]
	v_mov_b32_e32 v102, v101
	v_pk_mul_f32 v[100:101], v[102:103], 0.5 op_sel_hi:[1,0]
	v_pk_add_f32 v[102:103], v[112:113], 1.0 op_sel_hi:[1,0]
	v_bfe_u32 v112, v107, 16, 1
	v_pk_mul_f32 v[100:101], v[100:101], v[102:103]
	v_bfe_u32 v113, v106, 16, 1
	v_bfe_u32 v102, v101, 16, 1
	v_bfe_u32 v103, v100, 16, 1
	v_add3_u32 v106, v106, v113, s37
	v_add3_u32 v107, v107, v112, s37
	v_add3_u32 v100, v100, v103, s37
	v_add3_u32 v101, v101, v102, s37
	v_bfe_u32 v102, v118, 16, 1
	v_bfe_u32 v103, v119, 16, 1
	v_bfe_u32 v112, v104, 16, 1
	v_bfe_u32 v113, v105, 16, 1
	v_add3_u32 v105, v105, v113, s37
	v_add3_u32 v104, v104, v112, s37
	v_add3_u32 v103, v119, v103, s37
	v_add3_u32 v102, v118, v102, s37
	v_lshrrev_b32_e32 v112, 16, v102
	v_lshrrev_b32_e32 v113, 16, v103
	v_lshrrev_b32_e32 v102, 16, v104
	v_lshrrev_b32_e32 v103, 16, v105
	v_and_or_b32 v103, v101, s30, v103
	v_and_or_b32 v102, v100, s30, v102
	v_and_or_b32 v101, v107, s30, v113
	v_and_or_b32 v100, v106, s30, v112
	global_store_dwordx4 v[2:3], v[108:111], off
	global_store_dwordx4 v[2:3], v[100:103], off offset:16
	ds_write2_b32 v140, v96, v92 offset1:16
	ds_write2_b32 v140, v97, v93 offset0:68 offset1:84
	ds_write2_b32 v140, v98, v94 offset0:136 offset1:152
	ds_write2_b32 v140, v99, v95 offset0:204 offset1:220
	ds_write2_b32 v140, v88, v84 offset0:32 offset1:48
	ds_write2_b32 v140, v89, v85 offset0:100 offset1:116
	ds_write2_b32 v140, v90, v86 offset0:168 offset1:184
	ds_write2_b32 v140, v91, v87 offset0:236 offset1:252
	s_waitcnt lgkmcnt(0)
	ds_read_b128 v[104:107], v141
	ds_read_b128 v[92:95], v141 offset:16
	ds_read_b128 v[88:91], v141 offset:32
	ds_read_b128 v[84:87], v141 offset:48
	v_or_b32_e32 v114, 32, v132
	s_waitcnt lgkmcnt(3)
	v_mul_f32_e32 v3, 0x3d372713, v105
	v_mul_f32_e32 v3, v105, v3
	v_fma_f32 v3, v105, v3, v105
	v_mul_f32_e32 v3, 0x3f4c422a, v3
	v_add_f32_e32 v3, v3, v3
	v_mul_f32_e32 v3, 0x3fb8aa3b, v3
	v_mul_f32_e32 v2, 0x3d372713, v104
	v_exp_f32_e32 v108, v3
	v_mul_f32_e32 v3, 0x3d372713, v106
	v_mul_f32_e32 v2, v104, v2
	v_mul_f32_e32 v3, v106, v3
	v_fma_f32 v2, v104, v2, v104
	v_fma_f32 v3, v106, v3, v106
	v_mul_f32_e32 v2, 0x3f4c422a, v2
	v_mul_f32_e32 v3, 0x3f4c422a, v3
	v_add_f32_e32 v2, v2, v2
	v_add_f32_e32 v3, v3, v3
	v_mul_f32_e32 v2, 0x3fb8aa3b, v2
	v_mul_f32_e32 v3, 0x3fb8aa3b, v3
	v_exp_f32_e32 v2, v2
	v_exp_f32_e32 v3, v3
	v_ashrrev_i32_e32 v115, 31, v114
	v_lshlrev_b64 v[114:115], 5, v[114:115]
	v_or_b32_e32 v114, v114, v0
	v_pk_add_f32 v[116:117], v[2:3], 1.0 op_sel_hi:[1,0]
	v_mad_u64_u32 v[2:3], s[8:9], v114, s36, v[128:129]
	v_mad_i32_i24 v3, v115, s36, v3
	v_mul_f32_e32 v96, 0x3d372713, v107
	v_mul_f32_e32 v96, v107, v96
	v_fma_f32 v96, v107, v96, v107
	v_mul_f32_e32 v96, 0x3f4c422a, v96
	v_add_f32_e32 v96, v96, v96
	v_rcp_f32_e32 v115, v117
	s_nop 0
	v_add_f32_e32 v115, v115, v115
	v_mul_f32_e32 v96, 0x3fb8aa3b, v96
	v_exp_f32_e32 v109, v96
	s_nop 0
	v_pk_add_f32 v[108:109], v[108:109], 1.0 op_sel_hi:[1,0]
	s_waitcnt lgkmcnt(2)
; DI float geluf(float x) { float z = 0.7978845608028654f * (x + 0.044715f * x * x * x); float t = 1.f - 2.f / (1.f + __expf(2.f * z)); return 0.5f * x * (1.f + t); }
; DI void phase_s5step3(const Params& p) {
;     ...
;     EPI256_BEGIN
; #pragma unroll
;       for (int i = 0; i < 16; ++i) v[i] = geluf(v[i]);
;       store16_bf(ys + ((size_t)row * 32 + (col >> 4)) * LDP + g * 16, v);
;     EPI_END
	v_mul_f32_e32 v96, 0x3d372713, v92
	v_rcp_f32_e32 v114, v116
	s_nop 0
	v_add_f32_e32 v114, v114, v114
	v_mov_b32_e32 v116, v104
	v_mul_f32_e32 v96, v92, v96
	v_mov_b32_e32 v117, v106
	v_fma_f32 v96, v92, v96, v92
	v_mul_f32_e32 v96, 0x3f4c422a, v96
	v_pk_add_f32 v[114:115], v[114:115], 1.0 op_sel_hi:[1,0] neg_lo:[1,0] neg_hi:[1,0]
	v_add_f32_e32 v96, v96, v96
	v_pk_mul_f32 v[116:117], v[116:117], 0.5 op_sel_hi:[1,0]
	v_pk_add_f32 v[114:115], v[114:115], 1.0 op_sel_hi:[1,0]
	v_mul_f32_e32 v96, 0x3fb8aa3b, v96
	v_pk_mul_f32 v[114:115], v[116:117], v[114:115]
	v_exp_f32_e32 v110, v96
	v_mul_f32_e32 v96, 0x3d372713, v93
	v_mul_f32_e32 v96, v93, v96
	v_fma_f32 v96, v93, v96, v93
	v_mul_f32_e32 v96, 0x3f4c422a, v96
	v_add_f32_e32 v96, v96, v96
	v_mul_f32_e32 v96, 0x3fb8aa3b, v96
	v_exp_f32_e32 v112, v96
	v_mul_f32_e32 v96, 0x3d372713, v94
	v_mul_f32_e32 v96, v94, v96
	v_fma_f32 v96, v94, v96, v94
	v_mul_f32_e32 v96, 0x3f4c422a, v96
	v_rcp_f32_e32 v109, v109
	s_nop 0
	v_add_f32_e32 v109, v109, v109
	v_add_f32_e32 v96, v96, v96
	v_mul_f32_e32 v96, 0x3fb8aa3b, v96
	v_exp_f32_e32 v111, v96
	v_rcp_f32_e32 v108, v108
	s_nop 0
	v_add_f32_e32 v108, v108, v108
	v_mov_b32_e32 v106, v105
	v_pk_add_f32 v[104:105], v[110:111], 1.0 op_sel_hi:[1,0]
	v_pk_add_f32 v[108:109], v[108:109], 1.0 op_sel_hi:[1,0] neg_lo:[1,0] neg_hi:[1,0]
	v_pk_mul_f32 v[106:107], v[106:107], 0.5 op_sel_hi:[1,0]
	v_pk_add_f32 v[108:109], v[108:109], 1.0 op_sel_hi:[1,0]
	v_mul_f32_e32 v96, 0x3d372713, v95
	v_pk_mul_f32 v[106:107], v[106:107], v[108:109]
	v_mul_f32_e32 v96, v95, v96
	v_fma_f32 v96, v95, v96, v95
	v_mul_f32_e32 v96, 0x3f4c422a, v96
	v_add_f32_e32 v96, v96, v96
	v_rcp_f32_e32 v105, v105
	s_nop 0
	v_add_f32_e32 v105, v105, v105
	v_mul_f32_e32 v96, 0x3fb8aa3b, v96
	v_exp_f32_e32 v113, v96
	s_nop 0
	v_pk_add_f32 v[110:111], v[112:113], 1.0 op_sel_hi:[1,0]
	v_rcp_f32_e32 v104, v104
	s_nop 0
	v_add_f32_e32 v104, v104, v104
	v_mov_b32_e32 v108, v92
	v_mov_b32_e32 v109, v94
	v_pk_add_f32 v[104:105], v[104:105], 1.0 op_sel_hi:[1,0] neg_lo:[1,0] neg_hi:[1,0]
	v_pk_mul_f32 v[108:109], v[108:109], 0.5 op_sel_hi:[1,0]
	v_pk_add_f32 v[104:105], v[104:105], 1.0 op_sel_hi:[1,0]
	s_waitcnt lgkmcnt(1)
	v_mul_f32_e32 v96, 0x3d372713, v88
	v_pk_mul_f32 v[104:105], v[108:109], v[104:105]
	v_mul_f32_e32 v96, v88, v96
	v_fma_f32 v96, v88, v96, v88
	v_mul_f32_e32 v96, 0x3f4c422a, v96
	v_add_f32_e32 v96, v96, v96
	v_mul_f32_e32 v96, 0x3fb8aa3b, v96
	v_exp_f32_e32 v102, v96
	v_mul_f32_e32 v96, 0x3d372713, v89
	v_mul_f32_e32 v96, v89, v96
	v_fma_f32 v96, v89, v96, v89
	v_mul_f32_e32 v96, 0x3f4c422a, v96
	v_rcp_f32_e32 v109, v111
	s_nop 0
	v_add_f32_e32 v109, v109, v109
	v_add_f32_e32 v96, v96, v96
	v_mul_f32_e32 v96, 0x3fb8aa3b, v96
	v_exp_f32_e32 v100, v96
	v_mul_f32_e32 v96, 0x3d372713, v90
	v_mul_f32_e32 v96, v90, v96
	v_fma_f32 v96, v90, v96, v90
	v_mul_f32_e32 v96, 0x3f4c422a, v96
	v_add_f32_e32 v96, v96, v96
	v_rcp_f32_e32 v108, v110
	s_nop 0
	v_add_f32_e32 v108, v108, v108
	v_mul_f32_e32 v96, 0x3fb8aa3b, v96
	v_pk_add_f32 v[108:109], v[108:109], 1.0 op_sel_hi:[1,0] neg_lo:[1,0] neg_hi:[1,0]
	v_mov_b32_e32 v94, v93
	v_exp_f32_e32 v103, v96
	v_pk_mul_f32 v[92:93], v[94:95], 0.5 op_sel_hi:[1,0]
	v_pk_add_f32 v[94:95], v[108:109], 1.0 op_sel_hi:[1,0]
	v_bfe_u32 v108, v107, 16, 1
	v_pk_mul_f32 v[92:93], v[92:93], v[94:95]
	v_bfe_u32 v109, v106, 16, 1
	v_bfe_u32 v94, v93, 16, 1
	v_bfe_u32 v95, v92, 16, 1
	v_add3_u32 v107, v107, v108, s37
	v_add3_u32 v93, v93, v94, s37
	v_bfe_u32 v94, v114, 16, 1
	v_bfe_u32 v108, v104, 16, 1
	v_add3_u32 v106, v106, v109, s37
	v_add3_u32 v92, v92, v95, s37
	v_bfe_u32 v95, v115, 16, 1
	v_bfe_u32 v109, v105, 16, 1
	v_add3_u32 v104, v104, v108, s37
	v_add3_u32 v94, v114, v94, s37
	v_pk_add_f32 v[102:103], v[102:103], 1.0 op_sel_hi:[1,0]
	v_add3_u32 v105, v105, v109, s37
	v_add3_u32 v95, v115, v95, s37
	v_lshrrev_b32_e32 v108, 16, v94
	v_lshrrev_b32_e32 v94, 16, v104
	v_lshrrev_b32_e32 v109, 16, v95
	v_lshrrev_b32_e32 v95, 16, v105
	v_and_or_b32 v94, v92, s30, v94
	v_and_or_b32 v92, v106, s30, v108
	v_and_or_b32 v95, v93, s30, v95
	v_and_or_b32 v93, v107, s30, v109
	v_mul_f32_e32 v96, 0x3d372713, v91
	v_mul_f32_e32 v96, v91, v96
	v_fma_f32 v96, v91, v96, v91
	v_mul_f32_e32 v96, 0x3f4c422a, v96
	v_add_f32_e32 v96, v96, v96
	v_rcp_f32_e32 v103, v103
	s_nop 0
	v_add_f32_e32 v103, v103, v103
	v_mul_f32_e32 v96, 0x3fb8aa3b, v96
	v_exp_f32_e32 v101, v96
	s_nop 0
	v_pk_add_f32 v[100:101], v[100:101], 1.0 op_sel_hi:[1,0]
	v_rcp_f32_e32 v102, v102
	s_nop 0
	v_add_f32_e32 v102, v102, v102
	v_mov_b32_e32 v104, v88
	v_mov_b32_e32 v105, v90
	v_pk_add_f32 v[102:103], v[102:103], 1.0 op_sel_hi:[1,0] neg_lo:[1,0] neg_hi:[1,0]
	v_pk_mul_f32 v[104:105], v[104:105], 0.5 op_sel_hi:[1,0]
	v_pk_add_f32 v[102:103], v[102:103], 1.0 op_sel_hi:[1,0]
	s_waitcnt lgkmcnt(0)
; DI float geluf(float x) { float z = 0.7978845608028654f * (x + 0.044715f * x * x * x); float t = 1.f - 2.f / (1.f + __expf(2.f * z)); return 0.5f * x * (1.f + t); }
; DI void phase_s5step3(const Params& p) {
;     ...
;     EPI256_BEGIN
; #pragma unroll
;       for (int i = 0; i < 16; ++i) v[i] = geluf(v[i]);
;       store16_bf(ys + ((size_t)row * 32 + (col >> 4)) * LDP + g * 16, v);
;     EPI_END
	v_mul_f32_e32 v96, 0x3d372713, v84
	v_pk_mul_f32 v[102:103], v[104:105], v[102:103]
	v_mul_f32_e32 v97, 0x3d372713, v86
	v_mul_f32_e32 v96, v84, v96
	v_mul_f32_e32 v97, v86, v97
	v_fma_f32 v96, v84, v96, v84
	v_fma_f32 v97, v86, v97, v86
	v_mul_f32_e32 v96, 0x3f4c422a, v96
	v_mul_f32_e32 v97, 0x3f4c422a, v97
	v_rcp_f32_e32 v101, v101
	s_nop 0
	v_add_f32_e32 v101, v101, v101
	v_add_f32_e32 v96, v96, v96
	v_add_f32_e32 v97, v97, v97
	v_mul_f32_e32 v96, 0x3fb8aa3b, v96
	v_mul_f32_e32 v97, 0x3fb8aa3b, v97
	v_exp_f32_e32 v98, v96
	v_exp_f32_e32 v99, v97
	v_rcp_f32_e32 v100, v100
	s_nop 0
	v_add_f32_e32 v100, v100, v100
	v_mov_b32_e32 v90, v89
	v_pk_add_f32 v[88:89], v[98:99], 1.0 op_sel_hi:[1,0]
	v_pk_add_f32 v[100:101], v[100:101], 1.0 op_sel_hi:[1,0] neg_lo:[1,0] neg_hi:[1,0]
	v_pk_mul_f32 v[90:91], v[90:91], 0.5 op_sel_hi:[1,0]
	v_pk_add_f32 v[98:99], v[100:101], 1.0 op_sel_hi:[1,0]
	v_mul_f32_e32 v96, 0x3d372713, v85
	v_pk_mul_f32 v[90:91], v[90:91], v[98:99]
	v_mul_f32_e32 v97, 0x3d372713, v87
	v_mul_f32_e32 v96, v85, v96
	v_mul_f32_e32 v97, v87, v97
	v_fma_f32 v96, v85, v96, v85
	v_fma_f32 v97, v87, v97, v87
	v_mul_f32_e32 v96, 0x3f4c422a, v96
	v_mul_f32_e32 v97, 0x3f4c422a, v97
	v_add_f32_e32 v96, v96, v96
	v_add_f32_e32 v97, v97, v97
	v_rcp_f32_e32 v89, v89
	s_nop 0
	v_add_f32_e32 v89, v89, v89
	v_mul_f32_e32 v96, 0x3fb8aa3b, v96
	v_mul_f32_e32 v97, 0x3fb8aa3b, v97
	v_exp_f32_e32 v96, v96
	v_exp_f32_e32 v97, v97
	s_nop 0
	v_pk_add_f32 v[96:97], v[96:97], 1.0 op_sel_hi:[1,0]
	v_rcp_f32_e32 v88, v88
	s_nop 0
	v_add_f32_e32 v88, v88, v88
	v_mov_b32_e32 v98, v84
	v_div_scale_f32 v84, s[8:9], v97, v97, 2.0
	v_mov_b32_e32 v99, v86
	v_rcp_f32_e32 v86, v84
	v_pk_add_f32 v[88:89], v[88:89], 1.0 op_sel_hi:[1,0] neg_lo:[1,0] neg_hi:[1,0]
	v_pk_mul_f32 v[98:99], v[98:99], 0.5 op_sel_hi:[1,0]
	v_pk_add_f32 v[88:89], v[88:89], 1.0 op_sel_hi:[1,0]
	s_nop 0
	v_pk_mul_f32 v[88:89], v[98:99], v[88:89]
	v_fma_f32 v98, -v84, v86, 1.0
	v_fmac_f32_e32 v86, v98, v86
	v_div_scale_f32 v98, vcc, 2.0, v97, 2.0
	v_mul_f32_e32 v99, v98, v86
	v_fma_f32 v100, -v84, v99, v98
	v_fmac_f32_e32 v99, v100, v86
	v_fma_f32 v84, -v84, v99, v98
	v_div_scale_f32 v98, s[8:9], v96, v96, 2.0
	v_rcp_f32_e32 v100, v98
	v_div_fmas_f32 v84, v84, v86, v99
	v_div_fixup_f32 v97, v84, v97, 2.0
	v_fma_f32 v84, -v98, v100, 1.0
	v_fmac_f32_e32 v100, v84, v100
	v_div_scale_f32 v84, vcc, 2.0, v96, 2.0
	v_mul_f32_e32 v86, v84, v100
	v_fma_f32 v99, -v98, v86, v84
	v_fmac_f32_e32 v86, v99, v100
	v_fma_f32 v84, -v98, v86, v84
	v_div_fmas_f32 v84, v84, v100, v86
	v_div_fixup_f32 v96, v84, v96, 2.0
	v_pk_add_f32 v[96:97], v[96:97], 1.0 op_sel_hi:[1,0] neg_lo:[1,0] neg_hi:[1,0]
	v_mov_b32_e32 v86, v85
	v_pk_mul_f32 v[84:85], v[86:87], 0.5 op_sel_hi:[1,0]
	v_pk_add_f32 v[86:87], v[96:97], 1.0 op_sel_hi:[1,0]
	v_bfe_u32 v96, v91, 16, 1
	v_pk_mul_f32 v[84:85], v[84:85], v[86:87]
	v_bfe_u32 v97, v90, 16, 1
	v_bfe_u32 v86, v85, 16, 1
	v_bfe_u32 v87, v84, 16, 1
	v_add3_u32 v90, v90, v97, s37
	v_add3_u32 v91, v91, v96, s37
	v_add3_u32 v84, v84, v87, s37
	v_add3_u32 v85, v85, v86, s37
	v_bfe_u32 v86, v102, 16, 1
	v_bfe_u32 v87, v103, 16, 1
	v_bfe_u32 v96, v88, 16, 1
	v_bfe_u32 v97, v89, 16, 1
	v_add3_u32 v89, v89, v97, s37
	v_add3_u32 v88, v88, v96, s37
	v_add3_u32 v87, v103, v87, s37
	v_add3_u32 v86, v102, v86, s37
	v_lshrrev_b32_e32 v96, 16, v86
	v_lshrrev_b32_e32 v97, 16, v87
	v_lshrrev_b32_e32 v86, 16, v88
	v_lshrrev_b32_e32 v87, 16, v89
	v_and_or_b32 v87, v85, s30, v87
	v_and_or_b32 v86, v84, s30, v86
	v_and_or_b32 v85, v91, s30, v97
	v_and_or_b32 v84, v90, s30, v96
	global_store_dwordx4 v[2:3], v[92:95], off
	global_store_dwordx4 v[2:3], v[84:87], off offset:16
	ds_write2_b32 v140, v80, v76 offset1:16
	ds_write2_b32 v140, v81, v77 offset0:68 offset1:84
	ds_write2_b32 v140, v82, v78 offset0:136 offset1:152
	ds_write2_b32 v140, v83, v79 offset0:204 offset1:220
	ds_write2_b32 v140, v72, v68 offset0:32 offset1:48
	ds_write2_b32 v140, v73, v69 offset0:100 offset1:116
	ds_write2_b32 v140, v74, v70 offset0:168 offset1:184
	ds_write2_b32 v140, v75, v71 offset0:236 offset1:252
	s_waitcnt lgkmcnt(0)
	ds_read_b128 v[88:91], v141
	ds_read_b128 v[76:79], v141 offset:16
	ds_read_b128 v[72:75], v141 offset:32
	ds_read_b128 v[68:71], v141 offset:48
	v_or_b32_e32 v98, 48, v132
	s_waitcnt lgkmcnt(3)
	v_mul_f32_e32 v3, 0x3d372713, v89
	v_mul_f32_e32 v3, v89, v3
	v_fma_f32 v3, v89, v3, v89
	v_mul_f32_e32 v3, 0x3f4c422a, v3
	v_add_f32_e32 v3, v3, v3
	v_mul_f32_e32 v3, 0x3fb8aa3b, v3
	v_mul_f32_e32 v2, 0x3d372713, v88
	v_exp_f32_e32 v92, v3
	v_mul_f32_e32 v3, 0x3d372713, v90
	v_mul_f32_e32 v2, v88, v2
	v_mul_f32_e32 v3, v90, v3
	v_fma_f32 v2, v88, v2, v88
	v_fma_f32 v3, v90, v3, v90
	v_mul_f32_e32 v2, 0x3f4c422a, v2
	v_mul_f32_e32 v3, 0x3f4c422a, v3
	v_add_f32_e32 v2, v2, v2
	v_add_f32_e32 v3, v3, v3
	v_mul_f32_e32 v2, 0x3fb8aa3b, v2
	v_mul_f32_e32 v3, 0x3fb8aa3b, v3
	v_exp_f32_e32 v2, v2
	v_exp_f32_e32 v3, v3
	v_ashrrev_i32_e32 v99, 31, v98
	v_lshlrev_b64 v[98:99], 5, v[98:99]
	v_or_b32_e32 v98, v98, v0
	v_pk_add_f32 v[100:101], v[2:3], 1.0 op_sel_hi:[1,0]
	v_mad_u64_u32 v[2:3], s[8:9], v98, s36, v[128:129]
	v_mad_i32_i24 v3, v99, s36, v3
	v_mul_f32_e32 v80, 0x3d372713, v91
	v_mul_f32_e32 v80, v91, v80
	v_fma_f32 v80, v91, v80, v91
	v_mul_f32_e32 v80, 0x3f4c422a, v80
	v_add_f32_e32 v80, v80, v80
	v_rcp_f32_e32 v99, v101
	s_nop 0
	v_add_f32_e32 v99, v99, v99
	v_mul_f32_e32 v80, 0x3fb8aa3b, v80
	v_exp_f32_e32 v93, v80
	s_nop 0
	v_pk_add_f32 v[92:93], v[92:93], 1.0 op_sel_hi:[1,0]
	s_waitcnt lgkmcnt(2)
; DI float geluf(float x) { float z = 0.7978845608028654f * (x + 0.044715f * x * x * x); float t = 1.f - 2.f / (1.f + __expf(2.f * z)); return 0.5f * x * (1.f + t); }
; DI void phase_s5step3(const Params& p) {
;     ...
;     EPI256_BEGIN
; #pragma unroll
;       for (int i = 0; i < 16; ++i) v[i] = geluf(v[i]);
;       store16_bf(ys + ((size_t)row * 32 + (col >> 4)) * LDP + g * 16, v);
;     EPI_END
	v_mul_f32_e32 v80, 0x3d372713, v76
	v_rcp_f32_e32 v98, v100
	s_nop 0
	v_add_f32_e32 v98, v98, v98
	v_mov_b32_e32 v100, v88
	v_mul_f32_e32 v80, v76, v80
	v_mov_b32_e32 v101, v90
	v_fma_f32 v80, v76, v80, v76
	v_mul_f32_e32 v80, 0x3f4c422a, v80
	v_pk_add_f32 v[98:99], v[98:99], 1.0 op_sel_hi:[1,0] neg_lo:[1,0] neg_hi:[1,0]
	v_add_f32_e32 v80, v80, v80
	v_pk_mul_f32 v[100:101], v[100:101], 0.5 op_sel_hi:[1,0]
	v_pk_add_f32 v[98:99], v[98:99], 1.0 op_sel_hi:[1,0]
	v_mul_f32_e32 v80, 0x3fb8aa3b, v80
	v_pk_mul_f32 v[98:99], v[100:101], v[98:99]
	v_exp_f32_e32 v94, v80
	v_mul_f32_e32 v80, 0x3d372713, v77
	v_mul_f32_e32 v80, v77, v80
	v_fma_f32 v80, v77, v80, v77
	v_mul_f32_e32 v80, 0x3f4c422a, v80
	v_add_f32_e32 v80, v80, v80
	v_mul_f32_e32 v80, 0x3fb8aa3b, v80
	v_exp_f32_e32 v96, v80
	v_mul_f32_e32 v80, 0x3d372713, v78
	v_mul_f32_e32 v80, v78, v80
	v_fma_f32 v80, v78, v80, v78
	v_mul_f32_e32 v80, 0x3f4c422a, v80
	v_rcp_f32_e32 v93, v93
	s_nop 0
	v_add_f32_e32 v93, v93, v93
	v_add_f32_e32 v80, v80, v80
	v_mul_f32_e32 v80, 0x3fb8aa3b, v80
	v_exp_f32_e32 v95, v80
	v_rcp_f32_e32 v92, v92
	s_nop 0
	v_add_f32_e32 v92, v92, v92
	v_mov_b32_e32 v90, v89
	v_pk_add_f32 v[88:89], v[94:95], 1.0 op_sel_hi:[1,0]
	v_pk_add_f32 v[92:93], v[92:93], 1.0 op_sel_hi:[1,0] neg_lo:[1,0] neg_hi:[1,0]
	v_pk_mul_f32 v[90:91], v[90:91], 0.5 op_sel_hi:[1,0]
	v_pk_add_f32 v[92:93], v[92:93], 1.0 op_sel_hi:[1,0]
	v_mul_f32_e32 v80, 0x3d372713, v79
	v_pk_mul_f32 v[90:91], v[90:91], v[92:93]
	v_mul_f32_e32 v80, v79, v80
	v_fma_f32 v80, v79, v80, v79
	v_mul_f32_e32 v80, 0x3f4c422a, v80
	v_add_f32_e32 v80, v80, v80
	v_rcp_f32_e32 v89, v89
	s_nop 0
	v_add_f32_e32 v89, v89, v89
	v_mul_f32_e32 v80, 0x3fb8aa3b, v80
	v_exp_f32_e32 v97, v80
	s_nop 0
	v_pk_add_f32 v[94:95], v[96:97], 1.0 op_sel_hi:[1,0]
	v_rcp_f32_e32 v88, v88
	s_nop 0
	v_add_f32_e32 v88, v88, v88
	v_mov_b32_e32 v92, v76
	v_mov_b32_e32 v93, v78
	v_pk_add_f32 v[88:89], v[88:89], 1.0 op_sel_hi:[1,0] neg_lo:[1,0] neg_hi:[1,0]
	v_pk_mul_f32 v[92:93], v[92:93], 0.5 op_sel_hi:[1,0]
	v_pk_add_f32 v[88:89], v[88:89], 1.0 op_sel_hi:[1,0]
	s_waitcnt lgkmcnt(1)
	v_mul_f32_e32 v80, 0x3d372713, v72
	v_pk_mul_f32 v[88:89], v[92:93], v[88:89]
	v_mul_f32_e32 v80, v72, v80
	v_fma_f32 v80, v72, v80, v72
	v_mul_f32_e32 v80, 0x3f4c422a, v80
	v_add_f32_e32 v80, v80, v80
	v_mul_f32_e32 v80, 0x3fb8aa3b, v80
	v_exp_f32_e32 v86, v80
	v_mul_f32_e32 v80, 0x3d372713, v73
	v_mul_f32_e32 v80, v73, v80
	v_fma_f32 v80, v73, v80, v73
	v_mul_f32_e32 v80, 0x3f4c422a, v80
	v_rcp_f32_e32 v93, v95
	s_nop 0
	v_add_f32_e32 v93, v93, v93
	v_add_f32_e32 v80, v80, v80
	v_mul_f32_e32 v80, 0x3fb8aa3b, v80
	v_exp_f32_e32 v84, v80
	v_mul_f32_e32 v80, 0x3d372713, v74
	v_mul_f32_e32 v80, v74, v80
	v_fma_f32 v80, v74, v80, v74
	v_mul_f32_e32 v80, 0x3f4c422a, v80
	v_add_f32_e32 v80, v80, v80
	v_rcp_f32_e32 v92, v94
	s_nop 0
	v_add_f32_e32 v92, v92, v92
	v_mul_f32_e32 v80, 0x3fb8aa3b, v80
	v_pk_add_f32 v[92:93], v[92:93], 1.0 op_sel_hi:[1,0] neg_lo:[1,0] neg_hi:[1,0]
	v_mov_b32_e32 v78, v77
	v_exp_f32_e32 v87, v80
	v_pk_mul_f32 v[76:77], v[78:79], 0.5 op_sel_hi:[1,0]
	v_pk_add_f32 v[78:79], v[92:93], 1.0 op_sel_hi:[1,0]
	v_bfe_u32 v92, v91, 16, 1
	v_pk_mul_f32 v[76:77], v[76:77], v[78:79]
	v_bfe_u32 v93, v90, 16, 1
	v_bfe_u32 v78, v77, 16, 1
	v_bfe_u32 v79, v76, 16, 1
	v_add3_u32 v91, v91, v92, s37
	v_add3_u32 v77, v77, v78, s37
	v_bfe_u32 v78, v98, 16, 1
	v_bfe_u32 v92, v88, 16, 1
	v_add3_u32 v90, v90, v93, s37
	v_add3_u32 v76, v76, v79, s37
	v_bfe_u32 v79, v99, 16, 1
	v_bfe_u32 v93, v89, 16, 1
	v_add3_u32 v88, v88, v92, s37
	v_add3_u32 v78, v98, v78, s37
	v_pk_add_f32 v[86:87], v[86:87], 1.0 op_sel_hi:[1,0]
	v_add3_u32 v89, v89, v93, s37
	v_add3_u32 v79, v99, v79, s37
	v_lshrrev_b32_e32 v92, 16, v78
	v_lshrrev_b32_e32 v78, 16, v88
	v_lshrrev_b32_e32 v93, 16, v79
	v_lshrrev_b32_e32 v79, 16, v89
	v_and_or_b32 v78, v76, s30, v78
	v_and_or_b32 v76, v90, s30, v92
	v_and_or_b32 v79, v77, s30, v79
	v_and_or_b32 v77, v91, s30, v93
	v_mul_f32_e32 v80, 0x3d372713, v75
	v_mul_f32_e32 v80, v75, v80
	v_fma_f32 v80, v75, v80, v75
	v_mul_f32_e32 v80, 0x3f4c422a, v80
	v_add_f32_e32 v80, v80, v80
	v_rcp_f32_e32 v87, v87
	s_nop 0
	v_add_f32_e32 v87, v87, v87
	v_mul_f32_e32 v80, 0x3fb8aa3b, v80
	v_exp_f32_e32 v85, v80
	s_nop 0
	v_pk_add_f32 v[84:85], v[84:85], 1.0 op_sel_hi:[1,0]
	v_rcp_f32_e32 v86, v86
	s_nop 0
	v_add_f32_e32 v86, v86, v86
	v_mov_b32_e32 v88, v72
	v_mov_b32_e32 v89, v74
	v_pk_add_f32 v[86:87], v[86:87], 1.0 op_sel_hi:[1,0] neg_lo:[1,0] neg_hi:[1,0]
	v_pk_mul_f32 v[88:89], v[88:89], 0.5 op_sel_hi:[1,0]
	v_pk_add_f32 v[86:87], v[86:87], 1.0 op_sel_hi:[1,0]
	s_waitcnt lgkmcnt(0)
; DI float geluf(float x) { float z = 0.7978845608028654f * (x + 0.044715f * x * x * x); float t = 1.f - 2.f / (1.f + __expf(2.f * z)); return 0.5f * x * (1.f + t); }
; DI void phase_s5step3(const Params& p) {
;     ...
;     EPI256_BEGIN
; #pragma unroll
;       for (int i = 0; i < 16; ++i) v[i] = geluf(v[i]);
;       store16_bf(ys + ((size_t)row * 32 + (col >> 4)) * LDP + g * 16, v);
;     EPI_END
	v_mul_f32_e32 v80, 0x3d372713, v68
	v_pk_mul_f32 v[86:87], v[88:89], v[86:87]
	v_mul_f32_e32 v81, 0x3d372713, v70
	v_mul_f32_e32 v80, v68, v80
	v_mul_f32_e32 v81, v70, v81
	v_fma_f32 v80, v68, v80, v68
	v_fma_f32 v81, v70, v81, v70
	v_mul_f32_e32 v80, 0x3f4c422a, v80
	v_mul_f32_e32 v81, 0x3f4c422a, v81
	v_rcp_f32_e32 v85, v85
	s_nop 0
	v_add_f32_e32 v85, v85, v85
	v_add_f32_e32 v80, v80, v80
	v_add_f32_e32 v81, v81, v81
	v_mul_f32_e32 v80, 0x3fb8aa3b, v80
	v_mul_f32_e32 v81, 0x3fb8aa3b, v81
	v_exp_f32_e32 v82, v80
	v_exp_f32_e32 v83, v81
	v_rcp_f32_e32 v84, v84
	s_nop 0
	v_add_f32_e32 v84, v84, v84
	v_mov_b32_e32 v74, v73
	v_pk_add_f32 v[72:73], v[82:83], 1.0 op_sel_hi:[1,0]
	v_pk_add_f32 v[84:85], v[84:85], 1.0 op_sel_hi:[1,0] neg_lo:[1,0] neg_hi:[1,0]
	v_pk_mul_f32 v[74:75], v[74:75], 0.5 op_sel_hi:[1,0]
	v_pk_add_f32 v[82:83], v[84:85], 1.0 op_sel_hi:[1,0]
	v_mul_f32_e32 v80, 0x3d372713, v69
	v_pk_mul_f32 v[74:75], v[74:75], v[82:83]
	v_mul_f32_e32 v81, 0x3d372713, v71
	v_mul_f32_e32 v80, v69, v80
	v_mul_f32_e32 v81, v71, v81
	v_fma_f32 v80, v69, v80, v69
	v_fma_f32 v81, v71, v81, v71
	v_mul_f32_e32 v80, 0x3f4c422a, v80
	v_mul_f32_e32 v81, 0x3f4c422a, v81
	v_add_f32_e32 v80, v80, v80
	v_add_f32_e32 v81, v81, v81
	v_rcp_f32_e32 v73, v73
	s_nop 0
	v_add_f32_e32 v73, v73, v73
	v_mul_f32_e32 v80, 0x3fb8aa3b, v80
	v_mul_f32_e32 v81, 0x3fb8aa3b, v81
	v_exp_f32_e32 v80, v80
	v_exp_f32_e32 v81, v81
	s_nop 0
	v_pk_add_f32 v[80:81], v[80:81], 1.0 op_sel_hi:[1,0]
	v_rcp_f32_e32 v72, v72
	s_nop 0
	v_add_f32_e32 v72, v72, v72
	v_mov_b32_e32 v82, v68
	v_div_scale_f32 v68, s[8:9], v81, v81, 2.0
	v_mov_b32_e32 v83, v70
	v_rcp_f32_e32 v70, v68
	v_pk_add_f32 v[72:73], v[72:73], 1.0 op_sel_hi:[1,0] neg_lo:[1,0] neg_hi:[1,0]
	v_pk_mul_f32 v[82:83], v[82:83], 0.5 op_sel_hi:[1,0]
	v_pk_add_f32 v[72:73], v[72:73], 1.0 op_sel_hi:[1,0]
	s_nop 0
	v_pk_mul_f32 v[72:73], v[82:83], v[72:73]
	v_fma_f32 v82, -v68, v70, 1.0
	v_fmac_f32_e32 v70, v82, v70
	v_div_scale_f32 v82, vcc, 2.0, v81, 2.0
	v_mul_f32_e32 v83, v82, v70
	v_fma_f32 v84, -v68, v83, v82
	v_fmac_f32_e32 v83, v84, v70
	v_fma_f32 v68, -v68, v83, v82
	v_div_scale_f32 v82, s[8:9], v80, v80, 2.0
	v_rcp_f32_e32 v84, v82
	v_div_fmas_f32 v68, v68, v70, v83
	v_div_fixup_f32 v81, v68, v81, 2.0
	v_fma_f32 v68, -v82, v84, 1.0
	v_fmac_f32_e32 v84, v68, v84
	v_div_scale_f32 v68, vcc, 2.0, v80, 2.0
	v_mul_f32_e32 v70, v68, v84
	v_fma_f32 v83, -v82, v70, v68
	v_fmac_f32_e32 v70, v83, v84
	v_fma_f32 v68, -v82, v70, v68
	v_div_fmas_f32 v68, v68, v84, v70
	v_div_fixup_f32 v80, v68, v80, 2.0
	v_pk_add_f32 v[80:81], v[80:81], 1.0 op_sel_hi:[1,0] neg_lo:[1,0] neg_hi:[1,0]
	v_mov_b32_e32 v70, v69
	v_pk_mul_f32 v[68:69], v[70:71], 0.5 op_sel_hi:[1,0]
	v_pk_add_f32 v[70:71], v[80:81], 1.0 op_sel_hi:[1,0]
	v_bfe_u32 v80, v75, 16, 1
	v_pk_mul_f32 v[68:69], v[68:69], v[70:71]
	v_bfe_u32 v81, v74, 16, 1
	v_bfe_u32 v70, v69, 16, 1
	v_bfe_u32 v71, v68, 16, 1
	v_add3_u32 v74, v74, v81, s37
	v_add3_u32 v75, v75, v80, s37
	v_add3_u32 v68, v68, v71, s37
	v_add3_u32 v69, v69, v70, s37
	v_bfe_u32 v70, v86, 16, 1
	v_bfe_u32 v71, v87, 16, 1
	v_bfe_u32 v80, v72, 16, 1
	v_bfe_u32 v81, v73, 16, 1
	v_add3_u32 v73, v73, v81, s37
	v_add3_u32 v72, v72, v80, s37
	v_add3_u32 v71, v87, v71, s37
	v_add3_u32 v70, v86, v70, s37
	v_lshrrev_b32_e32 v80, 16, v70
	v_lshrrev_b32_e32 v81, 16, v71
	v_lshrrev_b32_e32 v70, 16, v72
	v_lshrrev_b32_e32 v71, 16, v73
	v_and_or_b32 v71, v69, s30, v71
	v_and_or_b32 v70, v68, s30, v70
	v_and_or_b32 v69, v75, s30, v81
	v_and_or_b32 v68, v74, s30, v80
	global_store_dwordx4 v[2:3], v[76:79], off
	global_store_dwordx4 v[2:3], v[68:71], off offset:16
	ds_write2_b32 v140, v64, v60 offset1:16
	ds_write2_b32 v140, v65, v61 offset0:68 offset1:84
	ds_write2_b32 v140, v66, v62 offset0:136 offset1:152
	ds_write2_b32 v140, v67, v63 offset0:204 offset1:220
	ds_write2_b32 v140, v56, v52 offset0:32 offset1:48
	ds_write2_b32 v140, v57, v53 offset0:100 offset1:116
	ds_write2_b32 v140, v58, v54 offset0:168 offset1:184
	ds_write2_b32 v140, v59, v55 offset0:236 offset1:252
	s_waitcnt lgkmcnt(0)
	ds_read_b128 v[72:75], v141
	ds_read_b128 v[60:63], v141 offset:16
	ds_read_b128 v[56:59], v141 offset:32
	ds_read_b128 v[52:55], v141 offset:48
	v_or_b32_e32 v82, 64, v132
	s_waitcnt lgkmcnt(3)
	v_mul_f32_e32 v3, 0x3d372713, v73
	v_mul_f32_e32 v3, v73, v3
	v_fma_f32 v3, v73, v3, v73
	v_mul_f32_e32 v3, 0x3f4c422a, v3
	v_add_f32_e32 v3, v3, v3
	v_mul_f32_e32 v3, 0x3fb8aa3b, v3
	v_mul_f32_e32 v2, 0x3d372713, v72
	v_exp_f32_e32 v76, v3
	v_mul_f32_e32 v3, 0x3d372713, v74
	v_mul_f32_e32 v2, v72, v2
	v_mul_f32_e32 v3, v74, v3
	v_fma_f32 v2, v72, v2, v72
	v_fma_f32 v3, v74, v3, v74
	v_mul_f32_e32 v2, 0x3f4c422a, v2
	v_mul_f32_e32 v3, 0x3f4c422a, v3
	v_add_f32_e32 v2, v2, v2
	v_add_f32_e32 v3, v3, v3
	v_mul_f32_e32 v2, 0x3fb8aa3b, v2
	v_mul_f32_e32 v3, 0x3fb8aa3b, v3
	v_exp_f32_e32 v2, v2
	v_exp_f32_e32 v3, v3
	v_ashrrev_i32_e32 v83, 31, v82
	v_lshlrev_b64 v[82:83], 5, v[82:83]
	v_or_b32_e32 v82, v82, v0
	v_pk_add_f32 v[84:85], v[2:3], 1.0 op_sel_hi:[1,0]
	v_mad_u64_u32 v[2:3], s[8:9], v82, s36, v[128:129]
	v_mad_i32_i24 v3, v83, s36, v3
	v_mul_f32_e32 v64, 0x3d372713, v75
	v_mul_f32_e32 v64, v75, v64
	v_fma_f32 v64, v75, v64, v75
	v_mul_f32_e32 v64, 0x3f4c422a, v64
	v_add_f32_e32 v64, v64, v64
	v_rcp_f32_e32 v83, v85
	s_nop 0
	v_add_f32_e32 v83, v83, v83
	v_mul_f32_e32 v64, 0x3fb8aa3b, v64
	v_exp_f32_e32 v77, v64
	s_nop 0
	v_pk_add_f32 v[76:77], v[76:77], 1.0 op_sel_hi:[1,0]
	s_waitcnt lgkmcnt(2)
; DI float geluf(float x) { float z = 0.7978845608028654f * (x + 0.044715f * x * x * x); float t = 1.f - 2.f / (1.f + __expf(2.f * z)); return 0.5f * x * (1.f + t); }
; DI void phase_s5step3(const Params& p) {
;     ...
;     EPI256_BEGIN
; #pragma unroll
;       for (int i = 0; i < 16; ++i) v[i] = geluf(v[i]);
;       store16_bf(ys + ((size_t)row * 32 + (col >> 4)) * LDP + g * 16, v);
;     EPI_END
	v_mul_f32_e32 v64, 0x3d372713, v60
	v_rcp_f32_e32 v82, v84
	s_nop 0
	v_add_f32_e32 v82, v82, v82
	v_mov_b32_e32 v84, v72
	v_mul_f32_e32 v64, v60, v64
	v_mov_b32_e32 v85, v74
	v_fma_f32 v64, v60, v64, v60
	v_mul_f32_e32 v64, 0x3f4c422a, v64
	v_pk_add_f32 v[82:83], v[82:83], 1.0 op_sel_hi:[1,0] neg_lo:[1,0] neg_hi:[1,0]
	v_add_f32_e32 v64, v64, v64
	v_pk_mul_f32 v[84:85], v[84:85], 0.5 op_sel_hi:[1,0]
	v_pk_add_f32 v[82:83], v[82:83], 1.0 op_sel_hi:[1,0]
	v_mul_f32_e32 v64, 0x3fb8aa3b, v64
	v_pk_mul_f32 v[82:83], v[84:85], v[82:83]
	v_exp_f32_e32 v78, v64
	v_mul_f32_e32 v64, 0x3d372713, v61
	v_mul_f32_e32 v64, v61, v64
	v_fma_f32 v64, v61, v64, v61
	v_mul_f32_e32 v64, 0x3f4c422a, v64
	v_add_f32_e32 v64, v64, v64
	v_mul_f32_e32 v64, 0x3fb8aa3b, v64
	v_exp_f32_e32 v80, v64
	v_mul_f32_e32 v64, 0x3d372713, v62
	v_mul_f32_e32 v64, v62, v64
	v_fma_f32 v64, v62, v64, v62
	v_mul_f32_e32 v64, 0x3f4c422a, v64
	v_rcp_f32_e32 v77, v77
	s_nop 0
	v_add_f32_e32 v77, v77, v77
	v_add_f32_e32 v64, v64, v64
	v_mul_f32_e32 v64, 0x3fb8aa3b, v64
	v_exp_f32_e32 v79, v64
	v_rcp_f32_e32 v76, v76
	s_nop 0
	v_add_f32_e32 v76, v76, v76
	v_mov_b32_e32 v74, v73
	v_pk_add_f32 v[72:73], v[78:79], 1.0 op_sel_hi:[1,0]
	v_pk_add_f32 v[76:77], v[76:77], 1.0 op_sel_hi:[1,0] neg_lo:[1,0] neg_hi:[1,0]
	v_pk_mul_f32 v[74:75], v[74:75], 0.5 op_sel_hi:[1,0]
	v_pk_add_f32 v[76:77], v[76:77], 1.0 op_sel_hi:[1,0]
	v_mul_f32_e32 v64, 0x3d372713, v63
	v_pk_mul_f32 v[74:75], v[74:75], v[76:77]
	v_mul_f32_e32 v64, v63, v64
	v_fma_f32 v64, v63, v64, v63
	v_mul_f32_e32 v64, 0x3f4c422a, v64
	v_add_f32_e32 v64, v64, v64
	v_rcp_f32_e32 v73, v73
	s_nop 0
	v_add_f32_e32 v73, v73, v73
	v_mul_f32_e32 v64, 0x3fb8aa3b, v64
	v_exp_f32_e32 v81, v64
	s_nop 0
	v_pk_add_f32 v[78:79], v[80:81], 1.0 op_sel_hi:[1,0]
	v_rcp_f32_e32 v72, v72
	s_nop 0
	v_add_f32_e32 v72, v72, v72
	v_mov_b32_e32 v76, v60
	v_mov_b32_e32 v77, v62
	v_pk_add_f32 v[72:73], v[72:73], 1.0 op_sel_hi:[1,0] neg_lo:[1,0] neg_hi:[1,0]
	v_pk_mul_f32 v[76:77], v[76:77], 0.5 op_sel_hi:[1,0]
	v_pk_add_f32 v[72:73], v[72:73], 1.0 op_sel_hi:[1,0]
	s_waitcnt lgkmcnt(1)
	v_mul_f32_e32 v64, 0x3d372713, v56
	v_pk_mul_f32 v[72:73], v[76:77], v[72:73]
	v_mul_f32_e32 v64, v56, v64
	v_fma_f32 v64, v56, v64, v56
	v_mul_f32_e32 v64, 0x3f4c422a, v64
	v_add_f32_e32 v64, v64, v64
	v_mul_f32_e32 v64, 0x3fb8aa3b, v64
	v_exp_f32_e32 v70, v64
	v_mul_f32_e32 v64, 0x3d372713, v57
	v_mul_f32_e32 v64, v57, v64
	v_fma_f32 v64, v57, v64, v57
	v_mul_f32_e32 v64, 0x3f4c422a, v64
	v_rcp_f32_e32 v77, v79
	s_nop 0
	v_add_f32_e32 v77, v77, v77
	v_add_f32_e32 v64, v64, v64
	v_mul_f32_e32 v64, 0x3fb8aa3b, v64
	v_exp_f32_e32 v68, v64
	v_mul_f32_e32 v64, 0x3d372713, v58
	v_mul_f32_e32 v64, v58, v64
	v_fma_f32 v64, v58, v64, v58
	v_mul_f32_e32 v64, 0x3f4c422a, v64
	v_add_f32_e32 v64, v64, v64
	v_rcp_f32_e32 v76, v78
	s_nop 0
	v_add_f32_e32 v76, v76, v76
	v_mul_f32_e32 v64, 0x3fb8aa3b, v64
	v_pk_add_f32 v[76:77], v[76:77], 1.0 op_sel_hi:[1,0] neg_lo:[1,0] neg_hi:[1,0]
	v_mov_b32_e32 v62, v61
	v_exp_f32_e32 v71, v64
	v_pk_mul_f32 v[60:61], v[62:63], 0.5 op_sel_hi:[1,0]
	v_pk_add_f32 v[62:63], v[76:77], 1.0 op_sel_hi:[1,0]
	v_bfe_u32 v76, v75, 16, 1
	v_pk_mul_f32 v[60:61], v[60:61], v[62:63]
	v_bfe_u32 v77, v74, 16, 1
	v_bfe_u32 v62, v61, 16, 1
	v_bfe_u32 v63, v60, 16, 1
	v_add3_u32 v75, v75, v76, s37
	v_add3_u32 v61, v61, v62, s37
	v_bfe_u32 v62, v82, 16, 1
	v_bfe_u32 v76, v72, 16, 1
	v_add3_u32 v74, v74, v77, s37
	v_add3_u32 v60, v60, v63, s37
	v_bfe_u32 v63, v83, 16, 1
	v_bfe_u32 v77, v73, 16, 1
	v_add3_u32 v72, v72, v76, s37
	v_add3_u32 v62, v82, v62, s37
	v_pk_add_f32 v[70:71], v[70:71], 1.0 op_sel_hi:[1,0]
	v_add3_u32 v73, v73, v77, s37
	v_add3_u32 v63, v83, v63, s37
	v_lshrrev_b32_e32 v76, 16, v62
	v_lshrrev_b32_e32 v62, 16, v72
	v_lshrrev_b32_e32 v77, 16, v63
	v_lshrrev_b32_e32 v63, 16, v73
	v_and_or_b32 v62, v60, s30, v62
	v_and_or_b32 v60, v74, s30, v76
	v_and_or_b32 v63, v61, s30, v63
	v_and_or_b32 v61, v75, s30, v77
	v_mul_f32_e32 v64, 0x3d372713, v59
	v_mul_f32_e32 v64, v59, v64
	v_fma_f32 v64, v59, v64, v59
	v_mul_f32_e32 v64, 0x3f4c422a, v64
	v_add_f32_e32 v64, v64, v64
	v_rcp_f32_e32 v71, v71
	s_nop 0
	v_add_f32_e32 v71, v71, v71
	v_mul_f32_e32 v64, 0x3fb8aa3b, v64
	v_exp_f32_e32 v69, v64
	s_nop 0
	v_pk_add_f32 v[68:69], v[68:69], 1.0 op_sel_hi:[1,0]
	v_rcp_f32_e32 v70, v70
	s_nop 0
	v_add_f32_e32 v70, v70, v70
	v_mov_b32_e32 v72, v56
	v_mov_b32_e32 v73, v58
	v_pk_add_f32 v[70:71], v[70:71], 1.0 op_sel_hi:[1,0] neg_lo:[1,0] neg_hi:[1,0]
	v_pk_mul_f32 v[72:73], v[72:73], 0.5 op_sel_hi:[1,0]
	v_pk_add_f32 v[70:71], v[70:71], 1.0 op_sel_hi:[1,0]
	s_waitcnt lgkmcnt(0)
; DI float geluf(float x) { float z = 0.7978845608028654f * (x + 0.044715f * x * x * x); float t = 1.f - 2.f / (1.f + __expf(2.f * z)); return 0.5f * x * (1.f + t); }
; DI void phase_s5step3(const Params& p) {
;     ...
;     EPI256_BEGIN
; #pragma unroll
;       for (int i = 0; i < 16; ++i) v[i] = geluf(v[i]);
;       store16_bf(ys + ((size_t)row * 32 + (col >> 4)) * LDP + g * 16, v);
;     EPI_END
	v_mul_f32_e32 v64, 0x3d372713, v52
	v_pk_mul_f32 v[70:71], v[72:73], v[70:71]
	v_mul_f32_e32 v65, 0x3d372713, v54
	v_mul_f32_e32 v64, v52, v64
	v_mul_f32_e32 v65, v54, v65
	v_fma_f32 v64, v52, v64, v52
	v_fma_f32 v65, v54, v65, v54
	v_mul_f32_e32 v64, 0x3f4c422a, v64
	v_mul_f32_e32 v65, 0x3f4c422a, v65
	v_rcp_f32_e32 v69, v69
	s_nop 0
	v_add_f32_e32 v69, v69, v69
	v_add_f32_e32 v64, v64, v64
	v_add_f32_e32 v65, v65, v65
	v_mul_f32_e32 v64, 0x3fb8aa3b, v64
	v_mul_f32_e32 v65, 0x3fb8aa3b, v65
	v_exp_f32_e32 v66, v64
	v_exp_f32_e32 v67, v65
	v_rcp_f32_e32 v68, v68
	s_nop 0
	v_add_f32_e32 v68, v68, v68
	v_mov_b32_e32 v58, v57
	v_pk_add_f32 v[56:57], v[66:67], 1.0 op_sel_hi:[1,0]
	v_pk_add_f32 v[68:69], v[68:69], 1.0 op_sel_hi:[1,0] neg_lo:[1,0] neg_hi:[1,0]
	v_pk_mul_f32 v[58:59], v[58:59], 0.5 op_sel_hi:[1,0]
	v_pk_add_f32 v[66:67], v[68:69], 1.0 op_sel_hi:[1,0]
	v_mul_f32_e32 v64, 0x3d372713, v53
	v_pk_mul_f32 v[58:59], v[58:59], v[66:67]
	v_mul_f32_e32 v65, 0x3d372713, v55
	v_mul_f32_e32 v64, v53, v64
	v_mul_f32_e32 v65, v55, v65
	v_fma_f32 v64, v53, v64, v53
	v_fma_f32 v65, v55, v65, v55
	v_mul_f32_e32 v64, 0x3f4c422a, v64
	v_mul_f32_e32 v65, 0x3f4c422a, v65
	v_add_f32_e32 v64, v64, v64
	v_add_f32_e32 v65, v65, v65
	v_rcp_f32_e32 v57, v57
	s_nop 0
	v_add_f32_e32 v57, v57, v57
	v_mul_f32_e32 v64, 0x3fb8aa3b, v64
	v_mul_f32_e32 v65, 0x3fb8aa3b, v65
	v_exp_f32_e32 v64, v64
	v_exp_f32_e32 v65, v65
	s_nop 0
	v_pk_add_f32 v[64:65], v[64:65], 1.0 op_sel_hi:[1,0]
	v_rcp_f32_e32 v56, v56
	s_nop 0
	v_add_f32_e32 v56, v56, v56
	v_mov_b32_e32 v66, v52
	v_div_scale_f32 v52, s[8:9], v65, v65, 2.0
	v_mov_b32_e32 v67, v54
	v_rcp_f32_e32 v54, v52
	v_pk_add_f32 v[56:57], v[56:57], 1.0 op_sel_hi:[1,0] neg_lo:[1,0] neg_hi:[1,0]
	v_pk_mul_f32 v[66:67], v[66:67], 0.5 op_sel_hi:[1,0]
	v_pk_add_f32 v[56:57], v[56:57], 1.0 op_sel_hi:[1,0]
	s_nop 0
	v_pk_mul_f32 v[56:57], v[66:67], v[56:57]
	v_fma_f32 v66, -v52, v54, 1.0
	v_fmac_f32_e32 v54, v66, v54
	v_div_scale_f32 v66, vcc, 2.0, v65, 2.0
	v_mul_f32_e32 v67, v66, v54
	v_fma_f32 v68, -v52, v67, v66
	v_fmac_f32_e32 v67, v68, v54
	v_fma_f32 v52, -v52, v67, v66
	v_div_scale_f32 v66, s[8:9], v64, v64, 2.0
	v_rcp_f32_e32 v68, v66
	v_div_fmas_f32 v52, v52, v54, v67
	v_div_fixup_f32 v65, v52, v65, 2.0
	v_fma_f32 v52, -v66, v68, 1.0
	v_fmac_f32_e32 v68, v52, v68
	v_div_scale_f32 v52, vcc, 2.0, v64, 2.0
	v_mul_f32_e32 v54, v52, v68
	v_fma_f32 v67, -v66, v54, v52
	v_fmac_f32_e32 v54, v67, v68
	v_fma_f32 v52, -v66, v54, v52
	v_div_fmas_f32 v52, v52, v68, v54
	v_div_fixup_f32 v64, v52, v64, 2.0
	v_pk_add_f32 v[64:65], v[64:65], 1.0 op_sel_hi:[1,0] neg_lo:[1,0] neg_hi:[1,0]
	v_mov_b32_e32 v54, v53
	v_pk_mul_f32 v[52:53], v[54:55], 0.5 op_sel_hi:[1,0]
	v_pk_add_f32 v[54:55], v[64:65], 1.0 op_sel_hi:[1,0]
	v_bfe_u32 v64, v59, 16, 1
	v_pk_mul_f32 v[52:53], v[52:53], v[54:55]
	v_bfe_u32 v65, v58, 16, 1
	v_bfe_u32 v54, v53, 16, 1
	v_bfe_u32 v55, v52, 16, 1
	v_add3_u32 v58, v58, v65, s37
	v_add3_u32 v59, v59, v64, s37
	v_add3_u32 v52, v52, v55, s37
	v_add3_u32 v53, v53, v54, s37
	v_bfe_u32 v54, v70, 16, 1
	v_bfe_u32 v55, v71, 16, 1
	v_bfe_u32 v64, v56, 16, 1
	v_bfe_u32 v65, v57, 16, 1
	v_add3_u32 v57, v57, v65, s37
	v_add3_u32 v56, v56, v64, s37
	v_add3_u32 v55, v71, v55, s37
	v_add3_u32 v54, v70, v54, s37
	v_lshrrev_b32_e32 v64, 16, v54
	v_lshrrev_b32_e32 v65, 16, v55
	v_lshrrev_b32_e32 v54, 16, v56
	v_lshrrev_b32_e32 v55, 16, v57
	v_and_or_b32 v55, v53, s30, v55
	v_and_or_b32 v54, v52, s30, v54
	v_and_or_b32 v53, v59, s30, v65
	v_and_or_b32 v52, v58, s30, v64
	global_store_dwordx4 v[2:3], v[60:63], off
	global_store_dwordx4 v[2:3], v[52:55], off offset:16
	ds_write2_b32 v140, v48, v44 offset1:16
	ds_write2_b32 v140, v49, v45 offset0:68 offset1:84
	ds_write2_b32 v140, v50, v46 offset0:136 offset1:152
	ds_write2_b32 v140, v51, v47 offset0:204 offset1:220
	ds_write2_b32 v140, v40, v36 offset0:32 offset1:48
	ds_write2_b32 v140, v41, v37 offset0:100 offset1:116
	ds_write2_b32 v140, v42, v38 offset0:168 offset1:184
	ds_write2_b32 v140, v43, v39 offset0:236 offset1:252
	s_waitcnt lgkmcnt(0)
	ds_read_b128 v[56:59], v141
	ds_read_b128 v[44:47], v141 offset:16
	ds_read_b128 v[40:43], v141 offset:32
	ds_read_b128 v[36:39], v141 offset:48
	v_or_b32_e32 v66, 0x50, v132
	s_waitcnt lgkmcnt(3)
	v_mul_f32_e32 v3, 0x3d372713, v57
	v_mul_f32_e32 v3, v57, v3
	v_fma_f32 v3, v57, v3, v57
	v_mul_f32_e32 v3, 0x3f4c422a, v3
	v_add_f32_e32 v3, v3, v3
	v_mul_f32_e32 v3, 0x3fb8aa3b, v3
	v_mul_f32_e32 v2, 0x3d372713, v56
	v_exp_f32_e32 v60, v3
	v_mul_f32_e32 v3, 0x3d372713, v58
	v_mul_f32_e32 v2, v56, v2
	v_mul_f32_e32 v3, v58, v3
	v_fma_f32 v2, v56, v2, v56
	v_fma_f32 v3, v58, v3, v58
	v_mul_f32_e32 v2, 0x3f4c422a, v2
	v_mul_f32_e32 v3, 0x3f4c422a, v3
	v_add_f32_e32 v2, v2, v2
	v_add_f32_e32 v3, v3, v3
	v_mul_f32_e32 v2, 0x3fb8aa3b, v2
	v_mul_f32_e32 v3, 0x3fb8aa3b, v3
	v_exp_f32_e32 v2, v2
	v_exp_f32_e32 v3, v3
	v_ashrrev_i32_e32 v67, 31, v66
	v_lshlrev_b64 v[66:67], 5, v[66:67]
	v_or_b32_e32 v66, v66, v0
	v_pk_add_f32 v[68:69], v[2:3], 1.0 op_sel_hi:[1,0]
	v_mad_u64_u32 v[2:3], s[8:9], v66, s36, v[128:129]
	v_mad_i32_i24 v3, v67, s36, v3
	v_mul_f32_e32 v48, 0x3d372713, v59
	v_mul_f32_e32 v48, v59, v48
	v_fma_f32 v48, v59, v48, v59
	v_mul_f32_e32 v48, 0x3f4c422a, v48
	v_add_f32_e32 v48, v48, v48
	v_rcp_f32_e32 v67, v69
	s_nop 0
	v_add_f32_e32 v67, v67, v67
	v_mul_f32_e32 v48, 0x3fb8aa3b, v48
	v_exp_f32_e32 v61, v48
	s_nop 0
	v_pk_add_f32 v[60:61], v[60:61], 1.0 op_sel_hi:[1,0]
	s_waitcnt lgkmcnt(2)
; DI float geluf(float x) { float z = 0.7978845608028654f * (x + 0.044715f * x * x * x); float t = 1.f - 2.f / (1.f + __expf(2.f * z)); return 0.5f * x * (1.f + t); }
; DI void phase_s5step3(const Params& p) {
;     ...
;     EPI256_BEGIN
; #pragma unroll
;       for (int i = 0; i < 16; ++i) v[i] = geluf(v[i]);
;       store16_bf(ys + ((size_t)row * 32 + (col >> 4)) * LDP + g * 16, v);
;     EPI_END
	v_mul_f32_e32 v48, 0x3d372713, v44
	v_rcp_f32_e32 v66, v68
	s_nop 0
	v_add_f32_e32 v66, v66, v66
	v_mov_b32_e32 v68, v56
	v_mul_f32_e32 v48, v44, v48
	v_mov_b32_e32 v69, v58
	v_fma_f32 v48, v44, v48, v44
	v_mul_f32_e32 v48, 0x3f4c422a, v48
	v_pk_add_f32 v[66:67], v[66:67], 1.0 op_sel_hi:[1,0] neg_lo:[1,0] neg_hi:[1,0]
	v_add_f32_e32 v48, v48, v48
	v_pk_mul_f32 v[68:69], v[68:69], 0.5 op_sel_hi:[1,0]
	v_pk_add_f32 v[66:67], v[66:67], 1.0 op_sel_hi:[1,0]
	v_mul_f32_e32 v48, 0x3fb8aa3b, v48
	v_pk_mul_f32 v[66:67], v[68:69], v[66:67]
	v_exp_f32_e32 v62, v48
	v_mul_f32_e32 v48, 0x3d372713, v45
	v_mul_f32_e32 v48, v45, v48
	v_fma_f32 v48, v45, v48, v45
	v_mul_f32_e32 v48, 0x3f4c422a, v48
	v_add_f32_e32 v48, v48, v48
	v_mul_f32_e32 v48, 0x3fb8aa3b, v48
	v_exp_f32_e32 v64, v48
	v_mul_f32_e32 v48, 0x3d372713, v46
	v_mul_f32_e32 v48, v46, v48
	v_fma_f32 v48, v46, v48, v46
	v_mul_f32_e32 v48, 0x3f4c422a, v48
	v_rcp_f32_e32 v61, v61
	s_nop 0
	v_add_f32_e32 v61, v61, v61
	v_add_f32_e32 v48, v48, v48
	v_mul_f32_e32 v48, 0x3fb8aa3b, v48
	v_exp_f32_e32 v63, v48
	v_rcp_f32_e32 v60, v60
	s_nop 0
	v_add_f32_e32 v60, v60, v60
	v_mov_b32_e32 v58, v57
	v_pk_add_f32 v[56:57], v[62:63], 1.0 op_sel_hi:[1,0]
	v_pk_add_f32 v[60:61], v[60:61], 1.0 op_sel_hi:[1,0] neg_lo:[1,0] neg_hi:[1,0]
	v_pk_mul_f32 v[58:59], v[58:59], 0.5 op_sel_hi:[1,0]
	v_pk_add_f32 v[60:61], v[60:61], 1.0 op_sel_hi:[1,0]
	v_mul_f32_e32 v48, 0x3d372713, v47
	v_pk_mul_f32 v[58:59], v[58:59], v[60:61]
	v_mul_f32_e32 v48, v47, v48
	v_fma_f32 v48, v47, v48, v47
	v_mul_f32_e32 v48, 0x3f4c422a, v48
	v_add_f32_e32 v48, v48, v48
	v_rcp_f32_e32 v57, v57
	s_nop 0
	v_add_f32_e32 v57, v57, v57
	v_mul_f32_e32 v48, 0x3fb8aa3b, v48
	v_exp_f32_e32 v65, v48
	s_nop 0
	v_pk_add_f32 v[62:63], v[64:65], 1.0 op_sel_hi:[1,0]
	v_rcp_f32_e32 v56, v56
	s_nop 0
	v_add_f32_e32 v56, v56, v56
	v_mov_b32_e32 v60, v44
	v_mov_b32_e32 v61, v46
	v_pk_add_f32 v[56:57], v[56:57], 1.0 op_sel_hi:[1,0] neg_lo:[1,0] neg_hi:[1,0]
	v_pk_mul_f32 v[60:61], v[60:61], 0.5 op_sel_hi:[1,0]
	v_pk_add_f32 v[56:57], v[56:57], 1.0 op_sel_hi:[1,0]
	s_waitcnt lgkmcnt(1)
	v_mul_f32_e32 v48, 0x3d372713, v40
	v_pk_mul_f32 v[56:57], v[60:61], v[56:57]
	v_mul_f32_e32 v48, v40, v48
	v_fma_f32 v48, v40, v48, v40
	v_mul_f32_e32 v48, 0x3f4c422a, v48
	v_add_f32_e32 v48, v48, v48
	v_mul_f32_e32 v48, 0x3fb8aa3b, v48
	v_exp_f32_e32 v54, v48
	v_mul_f32_e32 v48, 0x3d372713, v41
	v_mul_f32_e32 v48, v41, v48
	v_fma_f32 v48, v41, v48, v41
	v_mul_f32_e32 v48, 0x3f4c422a, v48
	v_rcp_f32_e32 v61, v63
	s_nop 0
	v_add_f32_e32 v61, v61, v61
	v_add_f32_e32 v48, v48, v48
	v_mul_f32_e32 v48, 0x3fb8aa3b, v48
	v_exp_f32_e32 v52, v48
	v_mul_f32_e32 v48, 0x3d372713, v42
	v_mul_f32_e32 v48, v42, v48
	v_fma_f32 v48, v42, v48, v42
	v_mul_f32_e32 v48, 0x3f4c422a, v48
	v_add_f32_e32 v48, v48, v48
	v_rcp_f32_e32 v60, v62
	s_nop 0
	v_add_f32_e32 v60, v60, v60
	v_mul_f32_e32 v48, 0x3fb8aa3b, v48
	v_pk_add_f32 v[60:61], v[60:61], 1.0 op_sel_hi:[1,0] neg_lo:[1,0] neg_hi:[1,0]
	v_mov_b32_e32 v46, v45
	v_exp_f32_e32 v55, v48
	v_pk_mul_f32 v[44:45], v[46:47], 0.5 op_sel_hi:[1,0]
	v_pk_add_f32 v[46:47], v[60:61], 1.0 op_sel_hi:[1,0]
	v_bfe_u32 v60, v59, 16, 1
	v_pk_mul_f32 v[44:45], v[44:45], v[46:47]
	v_bfe_u32 v61, v58, 16, 1
	v_bfe_u32 v46, v45, 16, 1
	v_bfe_u32 v47, v44, 16, 1
	v_add3_u32 v59, v59, v60, s37
	v_add3_u32 v45, v45, v46, s37
	v_bfe_u32 v46, v66, 16, 1
	v_bfe_u32 v60, v56, 16, 1
	v_add3_u32 v58, v58, v61, s37
	v_add3_u32 v44, v44, v47, s37
	v_bfe_u32 v47, v67, 16, 1
	v_bfe_u32 v61, v57, 16, 1
	v_add3_u32 v56, v56, v60, s37
	v_add3_u32 v46, v66, v46, s37
	v_pk_add_f32 v[54:55], v[54:55], 1.0 op_sel_hi:[1,0]
	v_add3_u32 v57, v57, v61, s37
	v_add3_u32 v47, v67, v47, s37
	v_lshrrev_b32_e32 v60, 16, v46
	v_lshrrev_b32_e32 v46, 16, v56
	v_lshrrev_b32_e32 v61, 16, v47
	v_lshrrev_b32_e32 v47, 16, v57
	v_and_or_b32 v46, v44, s30, v46
	v_and_or_b32 v44, v58, s30, v60
	v_and_or_b32 v47, v45, s30, v47
	v_and_or_b32 v45, v59, s30, v61
	v_mul_f32_e32 v48, 0x3d372713, v43
	v_mul_f32_e32 v48, v43, v48
	v_fma_f32 v48, v43, v48, v43
	v_mul_f32_e32 v48, 0x3f4c422a, v48
	v_add_f32_e32 v48, v48, v48
	v_rcp_f32_e32 v55, v55
	s_nop 0
	v_add_f32_e32 v55, v55, v55
	v_mul_f32_e32 v48, 0x3fb8aa3b, v48
	v_exp_f32_e32 v53, v48
	s_nop 0
	v_pk_add_f32 v[52:53], v[52:53], 1.0 op_sel_hi:[1,0]
	v_rcp_f32_e32 v54, v54
	s_nop 0
	v_add_f32_e32 v54, v54, v54
	v_mov_b32_e32 v56, v40
	v_mov_b32_e32 v57, v42
	v_pk_add_f32 v[54:55], v[54:55], 1.0 op_sel_hi:[1,0] neg_lo:[1,0] neg_hi:[1,0]
	v_pk_mul_f32 v[56:57], v[56:57], 0.5 op_sel_hi:[1,0]
	v_pk_add_f32 v[54:55], v[54:55], 1.0 op_sel_hi:[1,0]
	s_waitcnt lgkmcnt(0)
; DI float geluf(float x) { float z = 0.7978845608028654f * (x + 0.044715f * x * x * x); float t = 1.f - 2.f / (1.f + __expf(2.f * z)); return 0.5f * x * (1.f + t); }
; DI void phase_s5step3(const Params& p) {
;     ...
;     EPI256_BEGIN
; #pragma unroll
;       for (int i = 0; i < 16; ++i) v[i] = geluf(v[i]);
;       store16_bf(ys + ((size_t)row * 32 + (col >> 4)) * LDP + g * 16, v);
;     EPI_END
	v_mul_f32_e32 v48, 0x3d372713, v36
	v_pk_mul_f32 v[54:55], v[56:57], v[54:55]
	v_mul_f32_e32 v49, 0x3d372713, v38
	v_mul_f32_e32 v48, v36, v48
	v_mul_f32_e32 v49, v38, v49
	v_fma_f32 v48, v36, v48, v36
	v_fma_f32 v49, v38, v49, v38
	v_mul_f32_e32 v48, 0x3f4c422a, v48
	v_mul_f32_e32 v49, 0x3f4c422a, v49
	v_rcp_f32_e32 v53, v53
	s_nop 0
	v_add_f32_e32 v53, v53, v53
	v_add_f32_e32 v48, v48, v48
	v_add_f32_e32 v49, v49, v49
	v_mul_f32_e32 v48, 0x3fb8aa3b, v48
	v_mul_f32_e32 v49, 0x3fb8aa3b, v49
	v_exp_f32_e32 v50, v48
	v_exp_f32_e32 v51, v49
	v_rcp_f32_e32 v52, v52
	s_nop 0
	v_add_f32_e32 v52, v52, v52
	v_mov_b32_e32 v42, v41
	v_pk_add_f32 v[40:41], v[50:51], 1.0 op_sel_hi:[1,0]
	v_pk_add_f32 v[52:53], v[52:53], 1.0 op_sel_hi:[1,0] neg_lo:[1,0] neg_hi:[1,0]
	v_pk_mul_f32 v[42:43], v[42:43], 0.5 op_sel_hi:[1,0]
	v_pk_add_f32 v[50:51], v[52:53], 1.0 op_sel_hi:[1,0]
	v_mul_f32_e32 v48, 0x3d372713, v37
	v_pk_mul_f32 v[42:43], v[42:43], v[50:51]
	v_mul_f32_e32 v49, 0x3d372713, v39
	v_mul_f32_e32 v48, v37, v48
	v_mul_f32_e32 v49, v39, v49
	v_fma_f32 v48, v37, v48, v37
	v_fma_f32 v49, v39, v49, v39
	v_mul_f32_e32 v48, 0x3f4c422a, v48
	v_mul_f32_e32 v49, 0x3f4c422a, v49
	v_add_f32_e32 v48, v48, v48
	v_add_f32_e32 v49, v49, v49
	v_rcp_f32_e32 v41, v41
	s_nop 0
	v_add_f32_e32 v41, v41, v41
	v_mul_f32_e32 v48, 0x3fb8aa3b, v48
	v_mul_f32_e32 v49, 0x3fb8aa3b, v49
	v_exp_f32_e32 v48, v48
	v_exp_f32_e32 v49, v49
	s_nop 0
	v_pk_add_f32 v[48:49], v[48:49], 1.0 op_sel_hi:[1,0]
	v_rcp_f32_e32 v40, v40
	s_nop 0
	v_add_f32_e32 v40, v40, v40
	v_mov_b32_e32 v50, v36
	v_div_scale_f32 v36, s[8:9], v49, v49, 2.0
	v_mov_b32_e32 v51, v38
	v_rcp_f32_e32 v38, v36
	v_pk_add_f32 v[40:41], v[40:41], 1.0 op_sel_hi:[1,0] neg_lo:[1,0] neg_hi:[1,0]
	v_pk_mul_f32 v[50:51], v[50:51], 0.5 op_sel_hi:[1,0]
	v_pk_add_f32 v[40:41], v[40:41], 1.0 op_sel_hi:[1,0]
	s_nop 0
	v_pk_mul_f32 v[40:41], v[50:51], v[40:41]
	v_fma_f32 v50, -v36, v38, 1.0
	v_fmac_f32_e32 v38, v50, v38
	v_div_scale_f32 v50, vcc, 2.0, v49, 2.0
	v_mul_f32_e32 v51, v50, v38
	v_fma_f32 v52, -v36, v51, v50
	v_fmac_f32_e32 v51, v52, v38
	v_fma_f32 v36, -v36, v51, v50
	v_div_scale_f32 v50, s[8:9], v48, v48, 2.0
	v_rcp_f32_e32 v52, v50
	v_div_fmas_f32 v36, v36, v38, v51
	v_div_fixup_f32 v49, v36, v49, 2.0
	v_fma_f32 v36, -v50, v52, 1.0
	v_fmac_f32_e32 v52, v36, v52
	v_div_scale_f32 v36, vcc, 2.0, v48, 2.0
	v_mul_f32_e32 v38, v36, v52
	v_fma_f32 v51, -v50, v38, v36
	v_fmac_f32_e32 v38, v51, v52
	v_fma_f32 v36, -v50, v38, v36
	v_div_fmas_f32 v36, v36, v52, v38
	v_div_fixup_f32 v48, v36, v48, 2.0
	v_pk_add_f32 v[48:49], v[48:49], 1.0 op_sel_hi:[1,0] neg_lo:[1,0] neg_hi:[1,0]
	v_mov_b32_e32 v38, v37
	v_pk_mul_f32 v[36:37], v[38:39], 0.5 op_sel_hi:[1,0]
	v_pk_add_f32 v[38:39], v[48:49], 1.0 op_sel_hi:[1,0]
	v_bfe_u32 v48, v43, 16, 1
	v_pk_mul_f32 v[36:37], v[36:37], v[38:39]
	v_bfe_u32 v49, v42, 16, 1
	v_bfe_u32 v38, v37, 16, 1
	v_bfe_u32 v39, v36, 16, 1
	v_add3_u32 v42, v42, v49, s37
	v_add3_u32 v43, v43, v48, s37
	v_add3_u32 v36, v36, v39, s37
	v_add3_u32 v37, v37, v38, s37
	v_bfe_u32 v38, v54, 16, 1
	v_bfe_u32 v39, v55, 16, 1
	v_bfe_u32 v48, v40, 16, 1
	v_bfe_u32 v49, v41, 16, 1
	v_add3_u32 v41, v41, v49, s37
	v_add3_u32 v40, v40, v48, s37
	v_add3_u32 v39, v55, v39, s37
	v_add3_u32 v38, v54, v38, s37
	v_lshrrev_b32_e32 v48, 16, v38
	v_lshrrev_b32_e32 v49, 16, v39
	v_lshrrev_b32_e32 v38, 16, v40
	v_lshrrev_b32_e32 v39, 16, v41
	v_and_or_b32 v39, v37, s30, v39
	v_and_or_b32 v38, v36, s30, v38
	v_and_or_b32 v37, v43, s30, v49
	v_and_or_b32 v36, v42, s30, v48
	global_store_dwordx4 v[2:3], v[44:47], off
	global_store_dwordx4 v[2:3], v[36:39], off offset:16
	ds_write2_b32 v140, v32, v28 offset1:16
	ds_write2_b32 v140, v33, v29 offset0:68 offset1:84
	ds_write2_b32 v140, v34, v30 offset0:136 offset1:152
	ds_write2_b32 v140, v35, v31 offset0:204 offset1:220
	ds_write2_b32 v140, v24, v20 offset0:32 offset1:48
	ds_write2_b32 v140, v25, v21 offset0:100 offset1:116
	ds_write2_b32 v140, v26, v22 offset0:168 offset1:184
	ds_write2_b32 v140, v27, v23 offset0:236 offset1:252
	s_waitcnt lgkmcnt(0)
	ds_read_b128 v[40:43], v141
	ds_read_b128 v[28:31], v141 offset:16
	ds_read_b128 v[24:27], v141 offset:32
	ds_read_b128 v[20:23], v141 offset:48
	v_or_b32_e32 v50, 0x60, v132
	s_waitcnt lgkmcnt(3)
	v_mul_f32_e32 v3, 0x3d372713, v41
	v_mul_f32_e32 v3, v41, v3
	v_fma_f32 v3, v41, v3, v41
	v_mul_f32_e32 v3, 0x3f4c422a, v3
	v_add_f32_e32 v3, v3, v3
	v_mul_f32_e32 v3, 0x3fb8aa3b, v3
	v_mul_f32_e32 v2, 0x3d372713, v40
	v_exp_f32_e32 v44, v3
	v_mul_f32_e32 v3, 0x3d372713, v42
	v_mul_f32_e32 v2, v40, v2
	v_mul_f32_e32 v3, v42, v3
	v_fma_f32 v2, v40, v2, v40
	v_fma_f32 v3, v42, v3, v42
	v_mul_f32_e32 v2, 0x3f4c422a, v2
	v_mul_f32_e32 v3, 0x3f4c422a, v3
	v_add_f32_e32 v2, v2, v2
	v_add_f32_e32 v3, v3, v3
	v_mul_f32_e32 v2, 0x3fb8aa3b, v2
	v_mul_f32_e32 v3, 0x3fb8aa3b, v3
	v_exp_f32_e32 v2, v2
	v_exp_f32_e32 v3, v3
	v_ashrrev_i32_e32 v51, 31, v50
	v_lshlrev_b64 v[50:51], 5, v[50:51]
	v_or_b32_e32 v50, v50, v0
	v_pk_add_f32 v[52:53], v[2:3], 1.0 op_sel_hi:[1,0]
	v_mad_u64_u32 v[2:3], s[8:9], v50, s36, v[128:129]
	v_mad_i32_i24 v3, v51, s36, v3
	v_mul_f32_e32 v32, 0x3d372713, v43
	v_mul_f32_e32 v32, v43, v32
	v_fma_f32 v32, v43, v32, v43
	v_mul_f32_e32 v32, 0x3f4c422a, v32
	v_add_f32_e32 v32, v32, v32
	v_rcp_f32_e32 v51, v53
	s_nop 0
	v_add_f32_e32 v51, v51, v51
	v_mul_f32_e32 v32, 0x3fb8aa3b, v32
	v_exp_f32_e32 v45, v32
	s_nop 0
	v_pk_add_f32 v[44:45], v[44:45], 1.0 op_sel_hi:[1,0]
	s_waitcnt lgkmcnt(2)
; DI float geluf(float x) { float z = 0.7978845608028654f * (x + 0.044715f * x * x * x); float t = 1.f - 2.f / (1.f + __expf(2.f * z)); return 0.5f * x * (1.f + t); }
; DI void phase_s5step3(const Params& p) {
;     ...
;     EPI256_BEGIN
; #pragma unroll
;       for (int i = 0; i < 16; ++i) v[i] = geluf(v[i]);
;       store16_bf(ys + ((size_t)row * 32 + (col >> 4)) * LDP + g * 16, v);
;     EPI_END
	v_mul_f32_e32 v32, 0x3d372713, v28
	v_rcp_f32_e32 v50, v52
	s_nop 0
	v_add_f32_e32 v50, v50, v50
	v_mov_b32_e32 v52, v40
	v_mul_f32_e32 v32, v28, v32
	v_mov_b32_e32 v53, v42
	v_fma_f32 v32, v28, v32, v28
	v_mul_f32_e32 v32, 0x3f4c422a, v32
	v_pk_add_f32 v[50:51], v[50:51], 1.0 op_sel_hi:[1,0] neg_lo:[1,0] neg_hi:[1,0]
	v_add_f32_e32 v32, v32, v32
	v_pk_mul_f32 v[52:53], v[52:53], 0.5 op_sel_hi:[1,0]
	v_pk_add_f32 v[50:51], v[50:51], 1.0 op_sel_hi:[1,0]
	v_mul_f32_e32 v32, 0x3fb8aa3b, v32
	v_pk_mul_f32 v[50:51], v[52:53], v[50:51]
	v_exp_f32_e32 v46, v32
	v_mul_f32_e32 v32, 0x3d372713, v29
	v_mul_f32_e32 v32, v29, v32
	v_fma_f32 v32, v29, v32, v29
	v_mul_f32_e32 v32, 0x3f4c422a, v32
	v_add_f32_e32 v32, v32, v32
	v_mul_f32_e32 v32, 0x3fb8aa3b, v32
	v_exp_f32_e32 v48, v32
	v_mul_f32_e32 v32, 0x3d372713, v30
	v_mul_f32_e32 v32, v30, v32
	v_fma_f32 v32, v30, v32, v30
	v_mul_f32_e32 v32, 0x3f4c422a, v32
	v_rcp_f32_e32 v45, v45
	s_nop 0
	v_add_f32_e32 v45, v45, v45
	v_add_f32_e32 v32, v32, v32
	v_mul_f32_e32 v32, 0x3fb8aa3b, v32
	v_exp_f32_e32 v47, v32
	v_rcp_f32_e32 v44, v44
	s_nop 0
	v_add_f32_e32 v44, v44, v44
	v_mov_b32_e32 v42, v41
	v_pk_add_f32 v[40:41], v[46:47], 1.0 op_sel_hi:[1,0]
	v_pk_add_f32 v[44:45], v[44:45], 1.0 op_sel_hi:[1,0] neg_lo:[1,0] neg_hi:[1,0]
	v_pk_mul_f32 v[42:43], v[42:43], 0.5 op_sel_hi:[1,0]
	v_pk_add_f32 v[44:45], v[44:45], 1.0 op_sel_hi:[1,0]
	v_mul_f32_e32 v32, 0x3d372713, v31
	v_pk_mul_f32 v[42:43], v[42:43], v[44:45]
	v_mul_f32_e32 v32, v31, v32
	v_fma_f32 v32, v31, v32, v31
	v_mul_f32_e32 v32, 0x3f4c422a, v32
	v_add_f32_e32 v32, v32, v32
	v_rcp_f32_e32 v41, v41
	s_nop 0
	v_add_f32_e32 v41, v41, v41
	v_mul_f32_e32 v32, 0x3fb8aa3b, v32
	v_exp_f32_e32 v49, v32
	s_nop 0
	v_pk_add_f32 v[46:47], v[48:49], 1.0 op_sel_hi:[1,0]
	v_rcp_f32_e32 v40, v40
	s_nop 0
	v_add_f32_e32 v40, v40, v40
	v_mov_b32_e32 v44, v28
	v_mov_b32_e32 v45, v30
	v_pk_add_f32 v[40:41], v[40:41], 1.0 op_sel_hi:[1,0] neg_lo:[1,0] neg_hi:[1,0]
	v_pk_mul_f32 v[44:45], v[44:45], 0.5 op_sel_hi:[1,0]
	v_pk_add_f32 v[40:41], v[40:41], 1.0 op_sel_hi:[1,0]
	s_waitcnt lgkmcnt(1)
	v_mul_f32_e32 v32, 0x3d372713, v24
	v_pk_mul_f32 v[40:41], v[44:45], v[40:41]
	v_mul_f32_e32 v32, v24, v32
	v_fma_f32 v32, v24, v32, v24
	v_mul_f32_e32 v32, 0x3f4c422a, v32
	v_add_f32_e32 v32, v32, v32
	v_mul_f32_e32 v32, 0x3fb8aa3b, v32
	v_exp_f32_e32 v38, v32
	v_mul_f32_e32 v32, 0x3d372713, v25
	v_mul_f32_e32 v32, v25, v32
	v_fma_f32 v32, v25, v32, v25
	v_mul_f32_e32 v32, 0x3f4c422a, v32
	v_rcp_f32_e32 v45, v47
	s_nop 0
	v_add_f32_e32 v45, v45, v45
	v_add_f32_e32 v32, v32, v32
	v_mul_f32_e32 v32, 0x3fb8aa3b, v32
	v_exp_f32_e32 v36, v32
	v_mul_f32_e32 v32, 0x3d372713, v26
	v_mul_f32_e32 v32, v26, v32
	v_fma_f32 v32, v26, v32, v26
	v_mul_f32_e32 v32, 0x3f4c422a, v32
	v_add_f32_e32 v32, v32, v32
	v_rcp_f32_e32 v44, v46
	s_nop 0
	v_add_f32_e32 v44, v44, v44
	v_mul_f32_e32 v32, 0x3fb8aa3b, v32
	v_pk_add_f32 v[44:45], v[44:45], 1.0 op_sel_hi:[1,0] neg_lo:[1,0] neg_hi:[1,0]
	v_mov_b32_e32 v30, v29
	v_exp_f32_e32 v39, v32
	v_pk_mul_f32 v[28:29], v[30:31], 0.5 op_sel_hi:[1,0]
	v_pk_add_f32 v[30:31], v[44:45], 1.0 op_sel_hi:[1,0]
	v_bfe_u32 v44, v43, 16, 1
	v_pk_mul_f32 v[28:29], v[28:29], v[30:31]
	v_bfe_u32 v45, v42, 16, 1
	v_bfe_u32 v30, v29, 16, 1
	v_bfe_u32 v31, v28, 16, 1
	v_add3_u32 v43, v43, v44, s37
	v_add3_u32 v29, v29, v30, s37
	v_bfe_u32 v30, v50, 16, 1
	v_bfe_u32 v44, v40, 16, 1
	v_add3_u32 v42, v42, v45, s37
	v_add3_u32 v28, v28, v31, s37
	v_bfe_u32 v31, v51, 16, 1
	v_bfe_u32 v45, v41, 16, 1
	v_add3_u32 v40, v40, v44, s37
	v_add3_u32 v30, v50, v30, s37
	v_pk_add_f32 v[38:39], v[38:39], 1.0 op_sel_hi:[1,0]
	v_add3_u32 v41, v41, v45, s37
	v_add3_u32 v31, v51, v31, s37
	v_lshrrev_b32_e32 v44, 16, v30
	v_lshrrev_b32_e32 v30, 16, v40
	v_lshrrev_b32_e32 v45, 16, v31
	v_lshrrev_b32_e32 v31, 16, v41
	v_and_or_b32 v30, v28, s30, v30
	v_and_or_b32 v28, v42, s30, v44
	v_and_or_b32 v31, v29, s30, v31
	v_and_or_b32 v29, v43, s30, v45
	v_mul_f32_e32 v32, 0x3d372713, v27
	v_mul_f32_e32 v32, v27, v32
	v_fma_f32 v32, v27, v32, v27
	v_mul_f32_e32 v32, 0x3f4c422a, v32
	v_add_f32_e32 v32, v32, v32
	v_rcp_f32_e32 v39, v39
	s_nop 0
	v_add_f32_e32 v39, v39, v39
	v_mul_f32_e32 v32, 0x3fb8aa3b, v32
	v_exp_f32_e32 v37, v32
	s_nop 0
	v_pk_add_f32 v[36:37], v[36:37], 1.0 op_sel_hi:[1,0]
	v_rcp_f32_e32 v38, v38
	s_nop 0
	v_add_f32_e32 v38, v38, v38
	v_mov_b32_e32 v40, v24
	v_mov_b32_e32 v41, v26
	v_pk_add_f32 v[38:39], v[38:39], 1.0 op_sel_hi:[1,0] neg_lo:[1,0] neg_hi:[1,0]
	v_pk_mul_f32 v[40:41], v[40:41], 0.5 op_sel_hi:[1,0]
	v_pk_add_f32 v[38:39], v[38:39], 1.0 op_sel_hi:[1,0]
	s_waitcnt lgkmcnt(0)
; DI unsigned pack2(float a, float b) { return (unsigned)f2bf(a) | ((unsigned)f2bf(b) << 16); }
; DI float geluf(float x) { float z = 0.7978845608028654f * (x + 0.044715f * x * x * x); float t = 1.f - 2.f / (1.f + __expf(2.f * z)); return 0.5f * x * (1.f + t); }
;   const int lane = tid & 63, wid = tid >> 6, fr = lane & 15, fq = lane >> 4;
;   float* stg = (float*)(smem + PATCH) + wid * (16 * 68);
;   asm volatile("" ::: "memory");
; #pragma unroll
;   for (int n = 0; n < 4; ++n)
; #pragma unroll
;     for (int j = 0; j < 4; ++j) stg[(fq * 4 + j) * 68 + n * 16 + fr] = am[n][j];
;   asm volatile("s_waitcnt lgkmcnt(0)" ::: "memory");
;   const float* rp = stg + (lane >> 2) * 68 + (lane & 3) * 16;
; #pragma unroll
;   for (int i = 0; i < 4; ++i) { f32x4 t = *(const f32x4*)(rp + i * 4); v[4 * i] = t[0]; v[4 * i + 1] = t[1]; v[4 * i + 2] = t[2]; v[4 * i + 3] = t[3]; }
;   asm volatile("" ::: "memory");
; }
; DI void store16_bf(bft* dst, const float (&v)[16]) {
;   u32x4 o0 = {pack2(v[0], v[1]), pack2(v[2], v[3]), pack2(v[4], v[5]), pack2(v[6], v[7])}, o1 = {pack2(v[8], v[9]), pack2(v[10], v[11]), pack2(v[12], v[13]), pack2(v[14], v[15])};
;   *(u32x4*)dst = o0; *(u32x4*)(dst + 8) = o1;
; }
; DI void phase_s5step3(const Params& p) {
;     ...
;     EPI256_BEGIN
; #pragma unroll
;       for (int i = 0; i < 16; ++i) v[i] = geluf(v[i]);
;       store16_bf(ys + ((size_t)row * 32 + (col >> 4)) * LDP + g * 16, v);
;     EPI_END
	v_mul_f32_e32 v32, 0x3d372713, v20
	v_pk_mul_f32 v[38:39], v[40:41], v[38:39]
	v_mul_f32_e32 v33, 0x3d372713, v22
	v_mul_f32_e32 v32, v20, v32
	v_mul_f32_e32 v33, v22, v33
	v_fma_f32 v32, v20, v32, v20
	v_fma_f32 v33, v22, v33, v22
	v_mul_f32_e32 v32, 0x3f4c422a, v32
	v_mul_f32_e32 v33, 0x3f4c422a, v33
	v_rcp_f32_e32 v37, v37
	s_nop 0
	v_add_f32_e32 v37, v37, v37
	v_add_f32_e32 v32, v32, v32
	v_add_f32_e32 v33, v33, v33
	v_mul_f32_e32 v32, 0x3fb8aa3b, v32
	v_mul_f32_e32 v33, 0x3fb8aa3b, v33
	v_exp_f32_e32 v34, v32
	v_exp_f32_e32 v35, v33
	v_rcp_f32_e32 v36, v36
	s_nop 0
	v_add_f32_e32 v36, v36, v36
	v_mov_b32_e32 v26, v25
	v_pk_add_f32 v[24:25], v[34:35], 1.0 op_sel_hi:[1,0]
	v_pk_add_f32 v[36:37], v[36:37], 1.0 op_sel_hi:[1,0] neg_lo:[1,0] neg_hi:[1,0]
	v_pk_mul_f32 v[26:27], v[26:27], 0.5 op_sel_hi:[1,0]
	v_pk_add_f32 v[34:35], v[36:37], 1.0 op_sel_hi:[1,0]
	v_mul_f32_e32 v32, 0x3d372713, v21
	v_pk_mul_f32 v[26:27], v[26:27], v[34:35]
	v_mul_f32_e32 v33, 0x3d372713, v23
	v_mul_f32_e32 v32, v21, v32
	v_mul_f32_e32 v33, v23, v33
	v_fma_f32 v32, v21, v32, v21
	v_fma_f32 v33, v23, v33, v23
	v_mul_f32_e32 v32, 0x3f4c422a, v32
	v_mul_f32_e32 v33, 0x3f4c422a, v33
	v_add_f32_e32 v32, v32, v32
	v_add_f32_e32 v33, v33, v33
	v_rcp_f32_e32 v25, v25
	s_nop 0
	v_add_f32_e32 v25, v25, v25
	v_mul_f32_e32 v32, 0x3fb8aa3b, v32
	v_mul_f32_e32 v33, 0x3fb8aa3b, v33
	v_exp_f32_e32 v32, v32
	v_exp_f32_e32 v33, v33
	s_nop 0
	v_pk_add_f32 v[32:33], v[32:33], 1.0 op_sel_hi:[1,0]
	v_rcp_f32_e32 v24, v24
	s_nop 0
	v_add_f32_e32 v24, v24, v24
	v_mov_b32_e32 v34, v20
	v_div_scale_f32 v20, s[8:9], v33, v33, 2.0
	v_mov_b32_e32 v35, v22
	v_rcp_f32_e32 v22, v20
	v_pk_add_f32 v[24:25], v[24:25], 1.0 op_sel_hi:[1,0] neg_lo:[1,0] neg_hi:[1,0]
	v_pk_mul_f32 v[34:35], v[34:35], 0.5 op_sel_hi:[1,0]
	v_pk_add_f32 v[24:25], v[24:25], 1.0 op_sel_hi:[1,0]
	s_nop 0
	v_pk_mul_f32 v[24:25], v[34:35], v[24:25]
	v_fma_f32 v34, -v20, v22, 1.0
	v_fmac_f32_e32 v22, v34, v22
	v_div_scale_f32 v34, vcc, 2.0, v33, 2.0
	v_mul_f32_e32 v35, v34, v22
	v_fma_f32 v36, -v20, v35, v34
	v_fmac_f32_e32 v35, v36, v22
	v_fma_f32 v20, -v20, v35, v34
	v_div_scale_f32 v34, s[8:9], v32, v32, 2.0
	v_rcp_f32_e32 v36, v34
	v_div_fmas_f32 v20, v20, v22, v35
	v_div_fixup_f32 v33, v20, v33, 2.0
	v_fma_f32 v20, -v34, v36, 1.0
	v_fmac_f32_e32 v36, v20, v36
	v_div_scale_f32 v20, vcc, 2.0, v32, 2.0
	v_mul_f32_e32 v22, v20, v36
	v_fma_f32 v35, -v34, v22, v20
	v_fmac_f32_e32 v22, v35, v36
	v_fma_f32 v20, -v34, v22, v20
	v_div_fmas_f32 v20, v20, v36, v22
	v_div_fixup_f32 v32, v20, v32, 2.0
	v_pk_add_f32 v[32:33], v[32:33], 1.0 op_sel_hi:[1,0] neg_lo:[1,0] neg_hi:[1,0]
	v_mov_b32_e32 v22, v21
	v_pk_mul_f32 v[20:21], v[22:23], 0.5 op_sel_hi:[1,0]
	v_pk_add_f32 v[22:23], v[32:33], 1.0 op_sel_hi:[1,0]
	v_bfe_u32 v32, v27, 16, 1
	v_pk_mul_f32 v[20:21], v[20:21], v[22:23]
	v_bfe_u32 v33, v26, 16, 1
	v_bfe_u32 v22, v21, 16, 1
	v_bfe_u32 v23, v20, 16, 1
	v_add3_u32 v26, v26, v33, s37
	v_add3_u32 v27, v27, v32, s37
	v_add3_u32 v20, v20, v23, s37
	v_add3_u32 v21, v21, v22, s37
	v_bfe_u32 v22, v38, 16, 1
	v_bfe_u32 v23, v39, 16, 1
	v_bfe_u32 v32, v24, 16, 1
	v_bfe_u32 v33, v25, 16, 1
	v_add3_u32 v25, v25, v33, s37
	v_add3_u32 v24, v24, v32, s37
	v_add3_u32 v23, v39, v23, s37
	v_add3_u32 v22, v38, v22, s37
	v_lshrrev_b32_e32 v32, 16, v22
	v_lshrrev_b32_e32 v33, 16, v23
	v_lshrrev_b32_e32 v22, 16, v24
	v_lshrrev_b32_e32 v23, 16, v25
	v_and_or_b32 v23, v21, s30, v23
	v_and_or_b32 v22, v20, s30, v22
	v_and_or_b32 v21, v27, s30, v33
	v_and_or_b32 v20, v26, s30, v32
	global_store_dwordx4 v[2:3], v[28:31], off
	global_store_dwordx4 v[2:3], v[20:23], off offset:16
	ds_write2_b32 v140, v16, v12 offset1:16
	ds_write2_b32 v140, v17, v13 offset0:68 offset1:84
	ds_write2_b32 v140, v18, v14 offset0:136 offset1:152
	ds_write2_b32 v140, v19, v15 offset0:204 offset1:220
	ds_write2_b32 v140, v8, v4 offset0:32 offset1:48
	ds_write2_b32 v140, v9, v5 offset0:100 offset1:116
	ds_write2_b32 v140, v10, v6 offset0:168 offset1:184
	ds_write2_b32 v140, v11, v7 offset0:236 offset1:252
	s_waitcnt lgkmcnt(0)
	ds_read_b128 v[24:27], v141
	ds_read_b128 v[10:13], v141 offset:16
	ds_read_b128 v[6:9], v141 offset:32
	ds_read_b128 v[2:5], v141 offset:48
	v_or_b32_e32 v34, 0x70, v132
	s_waitcnt lgkmcnt(3)
	v_mul_f32_e32 v15, 0x3d372713, v25
	v_mul_f32_e32 v15, v25, v15
	v_fma_f32 v15, v25, v15, v25
	v_mul_f32_e32 v15, 0x3f4c422a, v15
	v_add_f32_e32 v15, v15, v15
	v_mul_f32_e32 v15, 0x3fb8aa3b, v15
	v_mul_f32_e32 v14, 0x3d372713, v24
	v_exp_f32_e32 v28, v15
	v_mul_f32_e32 v15, 0x3d372713, v26
	v_mul_f32_e32 v14, v24, v14
	v_mul_f32_e32 v15, v26, v15
	v_fma_f32 v14, v24, v14, v24
	v_fma_f32 v15, v26, v15, v26
	v_mul_f32_e32 v14, 0x3f4c422a, v14
	v_mul_f32_e32 v15, 0x3f4c422a, v15
	v_add_f32_e32 v14, v14, v14
	v_add_f32_e32 v15, v15, v15
	v_mul_f32_e32 v14, 0x3fb8aa3b, v14
	v_mul_f32_e32 v15, 0x3fb8aa3b, v15
	v_exp_f32_e32 v14, v14
	v_exp_f32_e32 v15, v15
	v_ashrrev_i32_e32 v35, 31, v34
	v_lshlrev_b64 v[34:35], 5, v[34:35]
	v_or_b32_e32 v0, v34, v0
	v_pk_add_f32 v[36:37], v[14:15], 1.0 op_sel_hi:[1,0]
	v_mad_u64_u32 v[14:15], s[8:9], v0, s36, v[128:129]
	v_mad_i32_i24 v15, v35, s36, v15
	v_mul_f32_e32 v16, 0x3d372713, v27
	v_mul_f32_e32 v16, v27, v16
	v_fma_f32 v16, v27, v16, v27
	v_mul_f32_e32 v16, 0x3f4c422a, v16
	v_add_f32_e32 v16, v16, v16
	v_rcp_f32_e32 v35, v37
	s_nop 0
	v_add_f32_e32 v35, v35, v35
	v_mul_f32_e32 v16, 0x3fb8aa3b, v16
	v_exp_f32_e32 v29, v16
	s_waitcnt lgkmcnt(2)
; DI float geluf(float x) { float z = 0.7978845608028654f * (x + 0.044715f * x * x * x); float t = 1.f - 2.f / (1.f + __expf(2.f * z)); return 0.5f * x * (1.f + t); }
; DI void phase_s5step3(const Params& p) {
;     ...
;     EPI256_BEGIN
; #pragma unroll
;       for (int i = 0; i < 16; ++i) v[i] = geluf(v[i]);
;       store16_bf(ys + ((size_t)row * 32 + (col >> 4)) * LDP + g * 16, v);
;     EPI_END
	v_mul_f32_e32 v16, 0x3d372713, v10
	v_pk_add_f32 v[28:29], v[28:29], 1.0 op_sel_hi:[1,0]
	v_mul_f32_e32 v16, v10, v16
	v_rcp_f32_e32 v34, v36
	s_nop 0
	v_add_f32_e32 v34, v34, v34
	v_fma_f32 v16, v10, v16, v10
	v_mov_b32_e32 v36, v24
	v_mul_f32_e32 v16, 0x3f4c422a, v16
	v_add_f32_e32 v16, v16, v16
	v_mul_f32_e32 v16, 0x3fb8aa3b, v16
	v_exp_f32_e32 v30, v16
	v_mul_f32_e32 v16, 0x3d372713, v11
	v_pk_add_f32 v[34:35], v[34:35], 1.0 op_sel_hi:[1,0] neg_lo:[1,0] neg_hi:[1,0]
	v_mov_b32_e32 v37, v26
	v_mul_f32_e32 v16, v11, v16
	v_pk_mul_f32 v[36:37], v[36:37], 0.5 op_sel_hi:[1,0]
	v_pk_add_f32 v[34:35], v[34:35], 1.0 op_sel_hi:[1,0]
	v_fma_f32 v16, v11, v16, v11
	v_pk_mul_f32 v[34:35], v[36:37], v[34:35]
	v_mul_f32_e32 v16, 0x3f4c422a, v16
	v_add_f32_e32 v16, v16, v16
	v_mul_f32_e32 v16, 0x3fb8aa3b, v16
	v_exp_f32_e32 v32, v16
	v_mul_f32_e32 v16, 0x3d372713, v12
	v_mul_f32_e32 v16, v12, v16
	v_fma_f32 v16, v12, v16, v12
	v_mul_f32_e32 v16, 0x3f4c422a, v16
	v_add_f32_e32 v16, v16, v16
	v_rcp_f32_e32 v29, v29
	s_nop 0
	v_add_f32_e32 v29, v29, v29
	v_mul_f32_e32 v16, 0x3fb8aa3b, v16
	v_exp_f32_e32 v31, v16
	v_mov_b32_e32 v26, v25
	v_pk_add_f32 v[24:25], v[30:31], 1.0 op_sel_hi:[1,0]
	v_rcp_f32_e32 v28, v28
	s_nop 0
	v_add_f32_e32 v28, v28, v28
	v_pk_add_f32 v[28:29], v[28:29], 1.0 op_sel_hi:[1,0] neg_lo:[1,0] neg_hi:[1,0]
	v_pk_mul_f32 v[26:27], v[26:27], 0.5 op_sel_hi:[1,0]
	v_pk_add_f32 v[28:29], v[28:29], 1.0 op_sel_hi:[1,0]
	v_mul_f32_e32 v16, 0x3d372713, v13
	v_pk_mul_f32 v[26:27], v[26:27], v[28:29]
	v_mul_f32_e32 v16, v13, v16
	v_fma_f32 v16, v13, v16, v13
	v_mul_f32_e32 v16, 0x3f4c422a, v16
	v_add_f32_e32 v16, v16, v16
	v_rcp_f32_e32 v25, v25
	s_nop 0
	v_add_f32_e32 v25, v25, v25
	v_mul_f32_e32 v16, 0x3fb8aa3b, v16
	v_exp_f32_e32 v33, v16
	s_nop 0
	v_pk_add_f32 v[30:31], v[32:33], 1.0 op_sel_hi:[1,0]
	v_rcp_f32_e32 v24, v24
	s_nop 0
	v_add_f32_e32 v24, v24, v24
	v_mov_b32_e32 v28, v10
	v_pk_add_f32 v[24:25], v[24:25], 1.0 op_sel_hi:[1,0] neg_lo:[1,0] neg_hi:[1,0]
	v_mov_b32_e32 v29, v12
	v_pk_mul_f32 v[28:29], v[28:29], 0.5 op_sel_hi:[1,0]
	v_pk_add_f32 v[24:25], v[24:25], 1.0 op_sel_hi:[1,0]
	s_waitcnt lgkmcnt(1)
	v_mul_f32_e32 v16, 0x3d372713, v6
	v_pk_mul_f32 v[24:25], v[28:29], v[24:25]
	v_mul_f32_e32 v16, v6, v16
	v_fma_f32 v16, v6, v16, v6
	v_mul_f32_e32 v16, 0x3f4c422a, v16
	v_add_f32_e32 v16, v16, v16
	v_mul_f32_e32 v16, 0x3fb8aa3b, v16
	v_exp_f32_e32 v22, v16
	v_mul_f32_e32 v16, 0x3d372713, v7
	v_mul_f32_e32 v16, v7, v16
	v_fma_f32 v16, v7, v16, v7
	v_rcp_f32_e32 v29, v31
	s_nop 0
	v_add_f32_e32 v29, v29, v29
	v_mul_f32_e32 v16, 0x3f4c422a, v16
	v_add_f32_e32 v16, v16, v16
	v_mul_f32_e32 v16, 0x3fb8aa3b, v16
	v_exp_f32_e32 v20, v16
	v_mul_f32_e32 v16, 0x3d372713, v8
	v_mul_f32_e32 v16, v8, v16
	v_fma_f32 v16, v8, v16, v8
	v_mul_f32_e32 v16, 0x3f4c422a, v16
	v_rcp_f32_e32 v28, v30
	s_nop 0
	v_add_f32_e32 v28, v28, v28
	v_add_f32_e32 v16, v16, v16
	v_pk_add_f32 v[28:29], v[28:29], 1.0 op_sel_hi:[1,0] neg_lo:[1,0] neg_hi:[1,0]
	v_mov_b32_e32 v12, v11
	v_mul_f32_e32 v16, 0x3fb8aa3b, v16
	v_pk_mul_f32 v[10:11], v[12:13], 0.5 op_sel_hi:[1,0]
	v_pk_add_f32 v[12:13], v[28:29], 1.0 op_sel_hi:[1,0]
	v_exp_f32_e32 v23, v16
	v_pk_mul_f32 v[10:11], v[10:11], v[12:13]
	v_bfe_u32 v13, v27, 16, 1
	v_bfe_u32 v0, v11, 16, 1
	v_bfe_u32 v12, v10, 16, 1
	v_bfe_u32 v28, v26, 16, 1
	v_add3_u32 v26, v26, v28, s37
	v_add3_u32 v27, v27, v13, s37
	v_add3_u32 v10, v10, v12, s37
	v_add3_u32 v0, v11, v0, s37
	v_bfe_u32 v11, v34, 16, 1
	v_bfe_u32 v12, v35, 16, 1
	v_bfe_u32 v13, v24, 16, 1
	v_bfe_u32 v28, v25, 16, 1
	v_add3_u32 v25, v25, v28, s37
	v_add3_u32 v13, v24, v13, s37
	v_add3_u32 v12, v35, v12, s37
	v_add3_u32 v11, v34, v11, s37
	v_lshrrev_b32_e32 v24, 16, v11
	v_lshrrev_b32_e32 v11, 16, v12
	v_lshrrev_b32_e32 v12, 16, v13
	v_lshrrev_b32_e32 v13, 16, v25
	v_pk_add_f32 v[22:23], v[22:23], 1.0 op_sel_hi:[1,0]
	v_and_or_b32 v13, v0, s30, v13
	v_and_or_b32 v12, v10, s30, v12
	v_and_or_b32 v10, v26, s30, v24
	v_and_or_b32 v11, v27, s30, v11
	v_mul_f32_e32 v16, 0x3d372713, v9
	v_mul_f32_e32 v16, v9, v16
	v_fma_f32 v16, v9, v16, v9
	v_mul_f32_e32 v16, 0x3f4c422a, v16
	v_add_f32_e32 v16, v16, v16
	v_rcp_f32_e32 v23, v23
	s_nop 0
	v_add_f32_e32 v23, v23, v23
	v_mul_f32_e32 v16, 0x3fb8aa3b, v16
	v_exp_f32_e32 v21, v16
	s_nop 0
	v_pk_add_f32 v[20:21], v[20:21], 1.0 op_sel_hi:[1,0]
	v_rcp_f32_e32 v22, v22
	s_nop 0
	v_add_f32_e32 v22, v22, v22
	v_mov_b32_e32 v24, v6
	v_pk_add_f32 v[22:23], v[22:23], 1.0 op_sel_hi:[1,0] neg_lo:[1,0] neg_hi:[1,0]
	v_mov_b32_e32 v25, v8
	v_pk_mul_f32 v[24:25], v[24:25], 0.5 op_sel_hi:[1,0]
	v_pk_add_f32 v[22:23], v[22:23], 1.0 op_sel_hi:[1,0]
	v_pk_mul_f32 v[22:23], v[24:25], v[22:23]
	s_waitcnt lgkmcnt(0)
; DI unsigned pack2(float a, float b) { return (unsigned)f2bf(a) | ((unsigned)f2bf(b) << 16); }
; DI float geluf(float x) { float z = 0.7978845608028654f * (x + 0.044715f * x * x * x); float t = 1.f - 2.f / (1.f + __expf(2.f * z)); return 0.5f * x * (1.f + t); }
; DI void store16_bf(bft* dst, const float (&v)[16]) {
;   u32x4 o0 = {pack2(v[0], v[1]), pack2(v[2], v[3]), pack2(v[4], v[5]), pack2(v[6], v[7])}, o1 = {pack2(v[8], v[9]), pack2(v[10], v[11]), pack2(v[12], v[13]), pack2(v[14], v[15])};
;   *(u32x4*)dst = o0; *(u32x4*)(dst + 8) = o1;
; }
; DI void phase_s5step3(const Params& p) {
;     ...
;     EPI256_BEGIN
; #pragma unroll
;       for (int i = 0; i < 16; ++i) v[i] = geluf(v[i]);
;       store16_bf(ys + ((size_t)row * 32 + (col >> 4)) * LDP + g * 16, v);
;     EPI_END
	v_mul_f32_e32 v16, 0x3d372713, v2
	v_mul_f32_e32 v17, 0x3d372713, v4
	v_mul_f32_e32 v16, v2, v16
	v_mul_f32_e32 v17, v4, v17
	v_fma_f32 v16, v2, v16, v2
	v_fma_f32 v17, v4, v17, v4
	v_mul_f32_e32 v16, 0x3f4c422a, v16
	v_mul_f32_e32 v17, 0x3f4c422a, v17
	v_add_f32_e32 v16, v16, v16
	v_add_f32_e32 v17, v17, v17
	v_rcp_f32_e32 v21, v21
	s_nop 0
	v_add_f32_e32 v21, v21, v21
	v_mul_f32_e32 v16, 0x3fb8aa3b, v16
	v_mul_f32_e32 v17, 0x3fb8aa3b, v17
	v_exp_f32_e32 v18, v16
	v_exp_f32_e32 v19, v17
	v_mov_b32_e32 v8, v7
	v_pk_add_f32 v[6:7], v[18:19], 1.0 op_sel_hi:[1,0]
	v_rcp_f32_e32 v20, v20
	s_nop 0
	v_add_f32_e32 v20, v20, v20
	v_pk_add_f32 v[20:21], v[20:21], 1.0 op_sel_hi:[1,0] neg_lo:[1,0] neg_hi:[1,0]
	v_pk_mul_f32 v[8:9], v[8:9], 0.5 op_sel_hi:[1,0]
	v_pk_add_f32 v[18:19], v[20:21], 1.0 op_sel_hi:[1,0]
	v_mul_f32_e32 v16, 0x3d372713, v3
	v_pk_mul_f32 v[8:9], v[8:9], v[18:19]
	v_mul_f32_e32 v17, 0x3d372713, v5
	v_mul_f32_e32 v16, v3, v16
	v_mul_f32_e32 v17, v5, v17
	v_fma_f32 v16, v3, v16, v3
	v_fma_f32 v17, v5, v17, v5
	v_mul_f32_e32 v16, 0x3f4c422a, v16
	v_mul_f32_e32 v17, 0x3f4c422a, v17
	v_add_f32_e32 v16, v16, v16
	v_add_f32_e32 v17, v17, v17
	v_rcp_f32_e32 v7, v7
	s_nop 0
	v_add_f32_e32 v7, v7, v7
	v_mul_f32_e32 v16, 0x3fb8aa3b, v16
	v_mul_f32_e32 v17, 0x3fb8aa3b, v17
	v_exp_f32_e32 v16, v16
	v_exp_f32_e32 v17, v17
	s_nop 0
	v_pk_add_f32 v[16:17], v[16:17], 1.0 op_sel_hi:[1,0]
	v_rcp_f32_e32 v6, v6
	s_nop 0
	v_add_f32_e32 v6, v6, v6
	v_mov_b32_e32 v18, v2
	v_pk_add_f32 v[6:7], v[6:7], 1.0 op_sel_hi:[1,0] neg_lo:[1,0] neg_hi:[1,0]
	v_mov_b32_e32 v19, v4
	v_pk_mul_f32 v[18:19], v[18:19], 0.5 op_sel_hi:[1,0]
	v_pk_add_f32 v[6:7], v[6:7], 1.0 op_sel_hi:[1,0]
	v_pk_mul_f32 v[6:7], v[18:19], v[6:7]
	v_div_scale_f32 v4, s[8:9], v16, v16, 2.0
	v_rcp_f32_e32 v19, v4
	v_rcp_f32_e32 v17, v17
	s_nop 0
	v_add_f32_e32 v17, v17, v17
	v_fma_f32 v0, -v4, v19, 1.0
	v_fmac_f32_e32 v19, v0, v19
	v_div_scale_f32 v0, vcc, 2.0, v16, 2.0
	v_mul_f32_e32 v2, v0, v19
	v_fma_f32 v18, -v4, v2, v0
	v_fmac_f32_e32 v2, v18, v19
	v_fma_f32 v0, -v4, v2, v0
	v_div_fmas_f32 v0, v0, v19, v2
	v_div_fixup_f32 v16, v0, v16, 2.0
	v_pk_add_f32 v[16:17], v[16:17], 1.0 op_sel_hi:[1,0] neg_lo:[1,0] neg_hi:[1,0]
	v_mov_b32_e32 v4, v3
	v_pk_mul_f32 v[2:3], v[4:5], 0.5 op_sel_hi:[1,0]
	v_pk_add_f32 v[4:5], v[16:17], 1.0 op_sel_hi:[1,0]
	v_bfe_u32 v16, v8, 16, 1
	v_pk_mul_f32 v[2:3], v[2:3], v[4:5]
	v_bfe_u32 v5, v9, 16, 1
	v_bfe_u32 v0, v3, 16, 1
	v_bfe_u32 v4, v2, 16, 1
	v_add3_u32 v8, v8, v16, s37
	v_add3_u32 v9, v9, v5, s37
	v_add3_u32 v2, v2, v4, s37
	v_add3_u32 v0, v3, v0, s37
	v_bfe_u32 v3, v22, 16, 1
	v_bfe_u32 v4, v23, 16, 1
	v_bfe_u32 v5, v6, 16, 1
	v_bfe_u32 v16, v7, 16, 1
	v_add3_u32 v7, v7, v16, s37
	v_add3_u32 v5, v6, v5, s37
	v_add3_u32 v4, v23, v4, s37
	v_add3_u32 v3, v22, v3, s37
	v_lshrrev_b32_e32 v6, 16, v3
	v_lshrrev_b32_e32 v3, 16, v4
	v_lshrrev_b32_e32 v4, 16, v5
	v_lshrrev_b32_e32 v5, 16, v7
	s_mov_b64 s[8:9], 0
	v_and_or_b32 v5, v0, s30, v5
	v_and_or_b32 v4, v2, s30, v4
	v_and_or_b32 v3, v9, s30, v3
	v_and_or_b32 v2, v8, s30, v6
	global_store_dwordx4 v[14:15], v[10:13], off
	global_store_dwordx4 v[14:15], v[2:5], off offset:16

; DI float sigm(float x) { return 1.f / (1.f + __expf(-x)); }
; DI void phase_glu(const Params& p) {
;     ...
;     float b[16]; load16_f(p.s5_glu_b + bcol + ((tid >> 6) & 3) * 64 + (tid & 3) * 16, b);
;     EPI256_BEGIN
;       float y[16], g[16]; load16_bf(ys + (size_t)row * LDP + col, y); bft* gp = G0 + (size_t)row * 2048 + col; load16_bf(gp, g);
; #pragma unroll
;       for (int i = 0; i < 16; ++i) v[i] = y[i] * sigm(v[i] + b[i]) * g[i];
;       store16_bf(gp, v);
.LBB0_892:
	s_lshl_b32 s0, s26, 2
	s_add_u32 s0, s6, s0
	v_and_b32_e32 v148, 0xc0, v165
	s_addc_u32 s1, s7, 0
	v_lshlrev_b32_e32 v0, 2, v148
	v_and_b32_e32 v149, 48, v166
	v_lshl_add_u64 v[2:3], s[0:1], 0, v[0:1]
	v_lshlrev_b32_e32 v0, 2, v149
	v_lshl_add_u64 v[2:3], v[2:3], 0, v[0:1]
	s_waitcnt vmcnt(0)
	s_barrier
	global_load_dwordx4 v[48:51], v[2:3], off
	global_load_dwordx4 v[44:47], v[2:3], off offset:16
	global_load_dwordx4 v[24:27], v[2:3], off offset:32
	global_load_dwordx4 v[20:23], v[2:3], off offset:48
	v_lshrrev_b32_e32 v2, 6, v165
	v_lshrrev_b32_e32 v150, 2, v165
	v_and_b32_e32 v3, 15, v165
	v_mul_lo_u32 v2, v2, s23
	v_and_b32_e32 v150, 12, v150
	v_bfe_u32 v151, v165, 2, 4
	v_ashrrev_i32_e32 v152, 1, v165
	v_lshlrev_b32_e32 v3, 2, v3
	v_or3_b32 v148, v148, s26, v149
	v_add_u32_e32 v149, s33, v2
	v_mul_u32_u24_e32 v2, 0x110, v150
	v_mul_u32_u24_e32 v153, 0x110, v151
	v_and_b32_e32 v152, 0xffffff80, v152
	v_add3_u32 v155, v149, v3, v2
	v_add_u32_e32 v150, s25, v152
	v_add3_u32 v154, v149, v0, v153
	v_lshlrev_b32_e32 v0, 1, v148
	ds_write2_b32 v155, v144, v140 offset1:16
	ds_write2_b32 v155, v145, v141 offset0:68 offset1:84
	ds_write2_b32 v155, v146, v142 offset0:136 offset1:152
	ds_write2_b32 v155, v147, v143 offset0:204 offset1:220
	ds_write2_b32 v155, v136, v132 offset0:32 offset1:48
	ds_write2_b32 v155, v137, v133 offset0:100 offset1:116
	ds_write2_b32 v155, v138, v134 offset0:168 offset1:184
	ds_write2_b32 v155, v139, v135 offset0:236 offset1:252
	v_or_b32_e32 v2, v150, v151
	v_lshl_add_u64 v[148:149], s[8:9], 0, v[0:1]
	s_waitcnt lgkmcnt(0)
	v_ashrrev_i32_e32 v3, 31, v2
	v_mad_i64_i32 v[132:133], s[0:1], v2, s4, v[148:149]
	ds_read_b128 v[144:147], v154
	ds_read_b128 v[150:153], v154 offset:16
	ds_read_b128 v[156:159], v154 offset:32
	ds_read_b128 v[160:163], v154 offset:48
	global_load_dwordx4 v[166:169], v[132:133], off
	v_lshl_add_u64 v[140:141], s[10:11], 0, v[0:1]
	v_lshlrev_b64 v[134:135], 12, v[2:3]
	v_lshl_add_u64 v[142:143], v[140:141], 0, v[134:135]
	global_load_dwordx4 v[170:173], v[142:143], off
	global_load_dwordx4 v[136:139], v[132:133], off offset:16
	s_nop 0
	global_load_dwordx4 v[132:135], v[142:143], off offset:16
	s_add_i32 s2, s2, 1
	s_add_i32 s3, s3, 1
	s_waitcnt vmcnt(7) lgkmcnt(3)
	v_add_f32_e32 v0, v48, v144
	v_add_f32_e32 v3, v49, v145
	v_add_f32_e32 v144, v50, v146
	v_add_f32_e32 v145, v51, v147
	s_waitcnt vmcnt(6) lgkmcnt(2)
	v_add_f32_e32 v146, v44, v150
	v_add_f32_e32 v147, v45, v151
	v_add_f32_e32 v150, v46, v152
	v_add_f32_e32 v151, v47, v153
	s_waitcnt vmcnt(5) lgkmcnt(1)
	v_add_f32_e32 v153, v25, v157
	v_mul_f32_e32 v0, 0xbfb8aa3b, v0
	v_add_f32_e32 v152, v24, v156
	v_mul_f32_e32 v150, 0xbfb8aa3b, v150
	v_exp_f32_e32 v156, v0
	v_mul_f32_e32 v0, 0xbfb8aa3b, v153
	v_exp_f32_e32 v177, v150
	v_exp_f32_e32 v150, v0
	v_add_f32_e32 v0, v26, v158
	v_mul_f32_e32 v0, 0xbfb8aa3b, v0
	v_exp_f32_e32 v153, v0
	v_add_f32_e32 v0, v27, v159
	v_mul_f32_e32 v151, 0xbfb8aa3b, v151
	v_mul_f32_e32 v0, 0xbfb8aa3b, v0
	v_exp_f32_e32 v179, v151
	v_exp_f32_e32 v151, v0
	s_waitcnt vmcnt(4) lgkmcnt(0)
	v_add_f32_e32 v0, v20, v160
	v_mul_f32_e32 v146, 0xbfb8aa3b, v146
	v_mul_f32_e32 v0, 0xbfb8aa3b, v0
	v_mul_f32_e32 v144, 0xbfb8aa3b, v144
	v_exp_f32_e32 v176, v146
	v_exp_f32_e32 v146, v0
	v_add_f32_e32 v0, v21, v161
	v_exp_f32_e32 v157, v144
	v_mul_f32_e32 v0, 0xbfb8aa3b, v0
	v_exp_f32_e32 v144, v0
	v_add_f32_e32 v0, v22, v162
	v_mul_f32_e32 v147, 0xbfb8aa3b, v147
	v_mul_f32_e32 v0, 0xbfb8aa3b, v0
	v_exp_f32_e32 v178, v147
	v_exp_f32_e32 v147, v0
	v_add_f32_e32 v0, v23, v163
	v_mul_f32_e32 v145, 0xbfb8aa3b, v145
	v_mul_f32_e32 v0, 0xbfb8aa3b, v0
	v_pk_add_f32 v[156:157], v[156:157], 1.0 op_sel_hi:[1,0]
	v_mul_f32_e32 v3, 0xbfb8aa3b, v3
	v_exp_f32_e32 v175, v145
	v_exp_f32_e32 v145, v0
	v_exp_f32_e32 v174, v3
	s_waitcnt vmcnt(3)
	v_lshlrev_b32_e32 v158, 16, v166
	v_and_b32_e32 v160, 0xffff0000, v166
	s_waitcnt vmcnt(2)
	v_lshlrev_b32_e32 v162, 16, v170
	v_and_b32_e32 v166, 0xffff0000, v170
	v_lshlrev_b32_e32 v159, 16, v167
	v_and_b32_e32 v161, 0xffff0000, v167
	v_lshlrev_b32_e32 v163, 16, v171
	v_and_b32_e32 v167, 0xffff0000, v171
	v_rcp_f32_e32 v157, v157
	v_mul_f32_e32 v152, 0xbfb8aa3b, v152
	v_pk_add_f32 v[170:171], v[174:175], 1.0 op_sel_hi:[1,0]
	v_rcp_f32_e32 v156, v156
	s_nop 0
	v_pk_mul_f32 v[156:157], v[156:157], v[158:159]
	v_exp_f32_e32 v152, v152
	v_pk_mul_f32 v[156:157], v[156:157], v[162:163]
	v_rcp_f32_e32 v159, v171
	v_and_b32_e32 v171, 0xffff0000, v173
	v_rcp_f32_e32 v158, v170
	s_nop 0
	v_pk_mul_f32 v[158:159], v[158:159], v[160:161]
	v_lshlrev_b32_e32 v161, 16, v169
	v_lshlrev_b32_e32 v160, 16, v168
	v_and_b32_e32 v163, 0xffff0000, v169
	v_and_b32_e32 v162, 0xffff0000, v168
	v_pk_add_f32 v[168:169], v[176:177], 1.0 op_sel_hi:[1,0]
	v_pk_mul_f32 v[158:159], v[158:159], v[166:167]
	v_lshlrev_b32_e32 v166, 16, v172
	v_and_b32_e32 v170, 0xffff0000, v172
	v_lshlrev_b32_e32 v167, 16, v173
	v_rcp_f32_e32 v169, v169
	v_pk_add_f32 v[152:153], v[152:153], 1.0 op_sel_hi:[1,0]
	v_pk_add_f32 v[172:173], v[178:179], 1.0 op_sel_hi:[1,0]
	v_rcp_f32_e32 v168, v168
	s_nop 0
	v_pk_mul_f32 v[160:161], v[168:169], v[160:161]
	v_pk_add_f32 v[150:151], v[150:151], 1.0 op_sel_hi:[1,0]
	v_pk_mul_f32 v[160:161], v[160:161], v[166:167]
	v_rcp_f32_e32 v167, v173
	v_pk_add_f32 v[146:147], v[146:147], 1.0 op_sel_hi:[1,0]
	v_rcp_f32_e32 v166, v172
	s_nop 0
	v_pk_mul_f32 v[162:163], v[166:167], v[162:163]
	v_bfe_u32 v165, v159, 16, 1
	v_pk_mul_f32 v[162:163], v[162:163], v[170:171]
	v_bfe_u32 v166, v158, 16, 1
	v_bfe_u32 v0, v163, 16, 1
	v_bfe_u32 v3, v162, 16, 1
	v_add3_u32 v0, v163, v0, s24
	v_bfe_u32 v163, v161, 16, 1
	v_add3_u32 v165, v159, v165, s24
	v_add3_u32 v3, v162, v3, s24
	v_bfe_u32 v159, v157, 16, 1
	v_bfe_u32 v162, v160, 16, 1
	v_add3_u32 v161, v161, v163, s24
	v_add3_u32 v166, v158, v166, s24
	v_bfe_u32 v158, v156, 16, 1
	v_add3_u32 v160, v160, v162, s24
	v_add3_u32 v157, v157, v159, s24
	v_lshrrev_b32_e32 v159, 16, v161
	v_add3_u32 v156, v156, v158, s24
	v_lshrrev_b32_e32 v158, 16, v160
	v_and_or_b32 v159, v0, s22, v159
	v_and_or_b32 v158, v3, s22, v158
	v_lshrrev_b32_e32 v157, 16, v157
	v_and_or_b32 v157, v165, s22, v157
	v_lshrrev_b32_e32 v156, 16, v156
	v_and_or_b32 v156, v166, s22, v156
	v_rcp_f32_e32 v153, v153
	s_waitcnt vmcnt(1)
; DI float sigm(float x) { return 1.f / (1.f + __expf(-x)); }
; DI void phase_glu(const Params& p) {
;     ...
;     float b[16]; load16_f(p.s5_glu_b + bcol + ((tid >> 6) & 3) * 64 + (tid & 3) * 16, b);
;     EPI256_BEGIN
;       float y[16], g[16]; load16_bf(ys + (size_t)row * LDP + col, y); bft* gp = G0 + (size_t)row * 2048 + col; load16_bf(gp, g);
; #pragma unroll
;       for (int i = 0; i < 16; ++i) v[i] = y[i] * sigm(v[i] + b[i]) * g[i];
;       store16_bf(gp, v);
	v_lshlrev_b32_e32 v161, 16, v137
	v_rcp_f32_e32 v152, v152
	v_lshlrev_b32_e32 v160, 16, v136
	v_pk_mul_f32 v[152:153], v[152:153], v[160:161]
	v_rcp_f32_e32 v151, v151
	s_waitcnt vmcnt(0)
	v_lshlrev_b32_e32 v163, 16, v133
	v_lshlrev_b32_e32 v162, 16, v132
	v_pk_mul_f32 v[152:153], v[152:153], v[162:163]
	v_rcp_f32_e32 v150, v150
	v_pk_add_f32 v[144:145], v[144:145], 1.0 op_sel_hi:[1,0]
	v_and_b32_e32 v137, 0xffff0000, v137
	v_and_b32_e32 v136, 0xffff0000, v136
	v_rcp_f32_e32 v147, v147
	v_and_b32_e32 v133, 0xffff0000, v133
	v_div_scale_f32 v3, s[0:1], v145, v145, 1.0
	v_rcp_f32_e32 v160, v3
	v_and_b32_e32 v132, 0xffff0000, v132
	v_pk_mul_f32 v[136:137], v[150:151], v[136:137]
	v_rcp_f32_e32 v146, v146
	v_fma_f32 v0, -v3, v160, 1.0
	v_pk_mul_f32 v[132:133], v[136:137], v[132:133]
	v_lshlrev_b32_e32 v137, 16, v139
	v_lshlrev_b32_e32 v136, 16, v138
	v_fmac_f32_e32 v160, v0, v160
	v_div_scale_f32 v0, vcc, 1.0, v145, 1.0
	v_pk_mul_f32 v[136:137], v[146:147], v[136:137]
	v_mul_f32_e32 v146, v0, v160
	v_fma_f32 v147, -v3, v146, v0
	v_fmac_f32_e32 v146, v147, v160
	v_fma_f32 v0, -v3, v146, v0
	v_div_scale_f32 v3, s[0:1], v144, v144, 1.0
	v_rcp_f32_e32 v147, v3
	v_div_fmas_f32 v0, v0, v160, v146
	v_div_fixup_f32 v145, v0, v145, 1.0
	v_lshlrev_b32_e32 v151, 16, v135
	v_fma_f32 v0, -v3, v147, 1.0
	v_fmac_f32_e32 v147, v0, v147
	v_div_scale_f32 v0, vcc, 1.0, v144, 1.0
	v_lshlrev_b32_e32 v150, 16, v134
	v_mul_f32_e32 v146, v0, v147
	v_pk_mul_f32 v[136:137], v[136:137], v[150:151]
	v_fma_f32 v150, -v3, v146, v0
	v_fmac_f32_e32 v146, v150, v147
	v_fma_f32 v0, -v3, v146, v0
	v_div_fmas_f32 v0, v0, v147, v146
	v_and_b32_e32 v139, 0xffff0000, v139
	v_and_b32_e32 v138, 0xffff0000, v138
	v_div_fixup_f32 v144, v0, v144, 1.0
	v_and_b32_e32 v135, 0xffff0000, v135
	v_and_b32_e32 v134, 0xffff0000, v134
	v_pk_mul_f32 v[138:139], v[144:145], v[138:139]
	s_nop 0
	v_pk_mul_f32 v[134:135], v[138:139], v[134:135]
	v_bfe_u32 v138, v133, 16, 1
	v_bfe_u32 v0, v135, 16, 1
	v_bfe_u32 v3, v134, 16, 1
	v_bfe_u32 v139, v132, 16, 1
	v_add3_u32 v132, v132, v139, s24
	v_add3_u32 v133, v133, v138, s24
	v_add3_u32 v3, v134, v3, s24
	v_add3_u32 v0, v135, v0, s24
	v_bfe_u32 v134, v152, 16, 1
	v_bfe_u32 v135, v153, 16, 1
	v_bfe_u32 v138, v136, 16, 1
	v_bfe_u32 v139, v137, 16, 1
	v_add3_u32 v137, v137, v139, s24
	v_add3_u32 v136, v136, v138, s24
	v_add3_u32 v135, v153, v135, s24
	v_add3_u32 v134, v152, v134, s24
	v_lshrrev_b32_e32 v138, 16, v134
	v_lshrrev_b32_e32 v139, 16, v135
	v_lshrrev_b32_e32 v134, 16, v136
	v_lshrrev_b32_e32 v135, 16, v137
	v_and_or_b32 v135, v0, s22, v135
	v_and_or_b32 v134, v3, s22, v134
	v_and_or_b32 v133, v133, s22, v139
	v_and_or_b32 v132, v132, s22, v138
	global_store_dwordx4 v[142:143], v[156:159], off
	global_store_dwordx4 v[142:143], v[132:135], off offset:16
	ds_write2_b32 v155, v128, v124 offset1:16
	ds_write2_b32 v155, v129, v125 offset0:68 offset1:84
	ds_write2_b32 v155, v130, v126 offset0:136 offset1:152
	ds_write2_b32 v155, v131, v127 offset0:204 offset1:220
	ds_write2_b32 v155, v120, v116 offset0:32 offset1:48
	ds_write2_b32 v155, v121, v117 offset0:100 offset1:116
	ds_write2_b32 v155, v122, v118 offset0:168 offset1:184
	ds_write2_b32 v155, v123, v119 offset0:236 offset1:252
	s_waitcnt lgkmcnt(0)
	v_or_b32_e32 v116, 16, v2
	ds_read_b128 v[126:129], v154
	ds_read_b128 v[130:133], v154 offset:16
	ds_read_b128 v[134:137], v154 offset:32
	ds_read_b128 v[142:145], v154 offset:48
	v_mad_i64_i32 v[118:119], s[0:1], v116, s4, v[148:149]
	global_load_dwordx4 v[150:153], v[118:119], off
	v_ashrrev_i32_e32 v117, 31, v116
	v_lshlrev_b64 v[116:117], 12, v[116:117]
	v_lshl_add_u64 v[124:125], v[140:141], 0, v[116:117]
	global_load_dwordx4 v[156:159], v[124:125], off
	global_load_dwordx4 v[120:123], v[118:119], off offset:16
	s_nop 0
	global_load_dwordx4 v[116:119], v[124:125], off offset:16
	s_waitcnt lgkmcnt(3)
	v_add_f32_e32 v0, v48, v126
	v_mul_f32_e32 v0, 0xbfb8aa3b, v0
	v_exp_f32_e32 v138, v0
	v_add_f32_e32 v0, v49, v127
	v_mul_f32_e32 v0, 0xbfb8aa3b, v0
	v_exp_f32_e32 v146, v0
	v_add_f32_e32 v0, v50, v128
	v_mul_f32_e32 v0, 0xbfb8aa3b, v0
	v_exp_f32_e32 v139, v0
	v_add_f32_e32 v0, v51, v129
	v_mul_f32_e32 v0, 0xbfb8aa3b, v0
	v_exp_f32_e32 v147, v0
	s_waitcnt lgkmcnt(2)
	v_add_f32_e32 v0, v44, v130
	v_mul_f32_e32 v0, 0xbfb8aa3b, v0
	v_exp_f32_e32 v160, v0
	v_add_f32_e32 v0, v45, v131
	v_mul_f32_e32 v0, 0xbfb8aa3b, v0
	v_exp_f32_e32 v162, v0
	v_add_f32_e32 v0, v46, v132
	v_mul_f32_e32 v0, 0xbfb8aa3b, v0
	v_exp_f32_e32 v161, v0
	v_add_f32_e32 v0, v47, v133
	v_mul_f32_e32 v0, 0xbfb8aa3b, v0
	v_exp_f32_e32 v163, v0
	s_waitcnt lgkmcnt(1)
	v_add_f32_e32 v0, v24, v134
	v_mul_f32_e32 v0, 0xbfb8aa3b, v0
	v_exp_f32_e32 v132, v0
	v_add_f32_e32 v0, v25, v135
	v_mul_f32_e32 v0, 0xbfb8aa3b, v0
	v_exp_f32_e32 v130, v0
	v_add_f32_e32 v0, v26, v136
	v_mul_f32_e32 v0, 0xbfb8aa3b, v0
	v_exp_f32_e32 v133, v0
	v_add_f32_e32 v0, v27, v137
	v_mul_f32_e32 v0, 0xbfb8aa3b, v0
	v_exp_f32_e32 v131, v0
	s_waitcnt lgkmcnt(0)
	v_add_f32_e32 v0, v20, v142
	v_mul_f32_e32 v0, 0xbfb8aa3b, v0
	v_exp_f32_e32 v128, v0
	v_add_f32_e32 v0, v21, v143
	v_mul_f32_e32 v0, 0xbfb8aa3b, v0
	v_exp_f32_e32 v126, v0
	v_add_f32_e32 v0, v22, v144
	v_mul_f32_e32 v0, 0xbfb8aa3b, v0
	v_exp_f32_e32 v129, v0
	v_add_f32_e32 v0, v23, v145
	v_mul_f32_e32 v0, 0xbfb8aa3b, v0
	v_pk_add_f32 v[138:139], v[138:139], 1.0 op_sel_hi:[1,0]
	v_exp_f32_e32 v127, v0
	v_pk_add_f32 v[146:147], v[146:147], 1.0 op_sel_hi:[1,0]
	v_pk_add_f32 v[132:133], v[132:133], 1.0 op_sel_hi:[1,0]
	v_pk_add_f32 v[130:131], v[130:131], 1.0 op_sel_hi:[1,0]
	v_pk_add_f32 v[128:129], v[128:129], 1.0 op_sel_hi:[1,0]
	v_pk_add_f32 v[126:127], v[126:127], 1.0 op_sel_hi:[1,0]
	s_waitcnt vmcnt(3)
; DI float sigm(float x) { return 1.f / (1.f + __expf(-x)); }
; DI void phase_glu(const Params& p) {
;     ...
;     float b[16]; load16_f(p.s5_glu_b + bcol + ((tid >> 6) & 3) * 64 + (tid & 3) * 16, b);
;     EPI256_BEGIN
;       float y[16], g[16]; load16_bf(ys + (size_t)row * LDP + col, y); bft* gp = G0 + (size_t)row * 2048 + col; load16_bf(gp, g);
; #pragma unroll
;       for (int i = 0; i < 16; ++i) v[i] = y[i] * sigm(v[i] + b[i]) * g[i];
;       store16_bf(gp, v);
	v_lshlrev_b32_e32 v134, 16, v150
	v_and_b32_e32 v136, 0xffff0000, v150
	v_lshlrev_b32_e32 v135, 16, v151
	v_and_b32_e32 v137, 0xffff0000, v151
	s_waitcnt vmcnt(2)
	v_lshlrev_b32_e32 v142, 16, v156
	v_and_b32_e32 v144, 0xffff0000, v156
	v_rcp_f32_e32 v139, v139
	v_lshlrev_b32_e32 v143, 16, v157
	v_rcp_f32_e32 v138, v138
	s_nop 0
	v_pk_mul_f32 v[134:135], v[138:139], v[134:135]
	v_and_b32_e32 v145, 0xffff0000, v157
	v_pk_mul_f32 v[134:135], v[134:135], v[142:143]
	v_rcp_f32_e32 v139, v147
	v_and_b32_e32 v151, 0xffff0000, v159
	v_rcp_f32_e32 v138, v146
	v_pk_add_f32 v[146:147], v[160:161], 1.0 op_sel_hi:[1,0]
	v_pk_mul_f32 v[136:137], v[138:139], v[136:137]
	v_lshlrev_b32_e32 v138, 16, v152
	v_and_b32_e32 v142, 0xffff0000, v152
	v_lshlrev_b32_e32 v139, 16, v153
	v_and_b32_e32 v143, 0xffff0000, v153
	v_rcp_f32_e32 v147, v147
	v_pk_mul_f32 v[136:137], v[136:137], v[144:145]
	v_pk_add_f32 v[152:153], v[162:163], 1.0 op_sel_hi:[1,0]
	v_rcp_f32_e32 v146, v146
	v_lshlrev_b32_e32 v145, 16, v159
	v_lshlrev_b32_e32 v144, 16, v158
	v_pk_mul_f32 v[138:139], v[146:147], v[138:139]
	v_pk_mul_f32 v[138:139], v[138:139], v[144:145]
	v_rcp_f32_e32 v145, v153
	v_and_b32_e32 v150, 0xffff0000, v158
	v_rcp_f32_e32 v144, v152
	s_nop 0
	v_pk_mul_f32 v[142:143], v[144:145], v[142:143]
	v_bfe_u32 v144, v137, 16, 1
	v_pk_mul_f32 v[142:143], v[142:143], v[150:151]
	v_bfe_u32 v145, v136, 16, 1
	v_bfe_u32 v0, v143, 16, 1
	v_bfe_u32 v3, v142, 16, 1
	v_add3_u32 v0, v143, v0, s24
	v_bfe_u32 v143, v139, 16, 1
	v_add3_u32 v144, v137, v144, s24
	v_add3_u32 v3, v142, v3, s24
	v_bfe_u32 v137, v135, 16, 1
	v_bfe_u32 v142, v138, 16, 1
	v_add3_u32 v139, v139, v143, s24
	v_add3_u32 v145, v136, v145, s24
	v_bfe_u32 v136, v134, 16, 1
	v_add3_u32 v138, v138, v142, s24
	v_add3_u32 v135, v135, v137, s24
	v_lshrrev_b32_e32 v137, 16, v139
	v_add3_u32 v134, v134, v136, s24
	v_lshrrev_b32_e32 v136, 16, v138
	v_and_or_b32 v137, v0, s22, v137
	v_and_or_b32 v136, v3, s22, v136
	v_lshrrev_b32_e32 v135, 16, v135
	v_and_or_b32 v135, v144, s22, v135
	v_lshrrev_b32_e32 v134, 16, v134
	v_and_or_b32 v134, v145, s22, v134
	v_rcp_f32_e32 v133, v133
	s_waitcnt vmcnt(1)
	v_lshlrev_b32_e32 v139, 16, v121
	v_rcp_f32_e32 v132, v132
	v_lshlrev_b32_e32 v138, 16, v120
	v_pk_mul_f32 v[132:133], v[132:133], v[138:139]
	v_rcp_f32_e32 v131, v131
	s_waitcnt vmcnt(0)
	v_lshlrev_b32_e32 v143, 16, v117
	v_lshlrev_b32_e32 v142, 16, v116
	v_pk_mul_f32 v[132:133], v[132:133], v[142:143]
	v_rcp_f32_e32 v130, v130
	v_and_b32_e32 v121, 0xffff0000, v121
	v_and_b32_e32 v120, 0xffff0000, v120
	v_and_b32_e32 v117, 0xffff0000, v117
	v_rcp_f32_e32 v129, v129
	v_and_b32_e32 v116, 0xffff0000, v116
	v_div_scale_f32 v3, s[0:1], v127, v127, 1.0
	v_rcp_f32_e32 v138, v3
	v_pk_mul_f32 v[120:121], v[130:131], v[120:121]
	v_rcp_f32_e32 v128, v128
	v_pk_mul_f32 v[116:117], v[120:121], v[116:117]
	v_fma_f32 v0, -v3, v138, 1.0
	v_lshlrev_b32_e32 v121, 16, v123
	v_lshlrev_b32_e32 v120, 16, v122
	v_fmac_f32_e32 v138, v0, v138
	v_div_scale_f32 v0, vcc, 1.0, v127, 1.0
	v_pk_mul_f32 v[120:121], v[128:129], v[120:121]
	v_mul_f32_e32 v128, v0, v138
	v_fma_f32 v129, -v3, v128, v0
	v_fmac_f32_e32 v128, v129, v138
	v_fma_f32 v0, -v3, v128, v0
	v_div_scale_f32 v3, s[0:1], v126, v126, 1.0
	v_rcp_f32_e32 v129, v3
	v_div_fmas_f32 v0, v0, v138, v128
	v_div_fixup_f32 v127, v0, v127, 1.0
	v_lshlrev_b32_e32 v131, 16, v119
	v_fma_f32 v0, -v3, v129, 1.0
	v_fmac_f32_e32 v129, v0, v129
	v_div_scale_f32 v0, vcc, 1.0, v126, 1.0
	v_lshlrev_b32_e32 v130, 16, v118
	v_mul_f32_e32 v128, v0, v129
	v_pk_mul_f32 v[120:121], v[120:121], v[130:131]
	v_fma_f32 v130, -v3, v128, v0
	v_fmac_f32_e32 v128, v130, v129
	v_fma_f32 v0, -v3, v128, v0
	v_div_fmas_f32 v0, v0, v129, v128
	v_and_b32_e32 v123, 0xffff0000, v123
	v_and_b32_e32 v122, 0xffff0000, v122
	v_div_fixup_f32 v126, v0, v126, 1.0
	v_and_b32_e32 v119, 0xffff0000, v119
	v_and_b32_e32 v118, 0xffff0000, v118
	v_pk_mul_f32 v[122:123], v[126:127], v[122:123]
	s_nop 0
	v_pk_mul_f32 v[118:119], v[122:123], v[118:119]
	v_bfe_u32 v122, v117, 16, 1
	v_bfe_u32 v0, v119, 16, 1
	v_bfe_u32 v3, v118, 16, 1
	v_bfe_u32 v123, v116, 16, 1
	v_add3_u32 v116, v116, v123, s24
	v_add3_u32 v117, v117, v122, s24
	v_add3_u32 v3, v118, v3, s24
	v_add3_u32 v0, v119, v0, s24
	v_bfe_u32 v118, v132, 16, 1
	v_bfe_u32 v119, v133, 16, 1
	v_bfe_u32 v122, v120, 16, 1
	v_bfe_u32 v123, v121, 16, 1
	v_add3_u32 v121, v121, v123, s24
	v_add3_u32 v120, v120, v122, s24
	v_add3_u32 v119, v133, v119, s24
	v_add3_u32 v118, v132, v118, s24
	v_lshrrev_b32_e32 v122, 16, v118
	v_lshrrev_b32_e32 v123, 16, v119
	v_lshrrev_b32_e32 v118, 16, v120
	v_lshrrev_b32_e32 v119, 16, v121
	v_and_or_b32 v119, v0, s22, v119
	v_and_or_b32 v118, v3, s22, v118
	v_and_or_b32 v117, v117, s22, v123
	v_and_or_b32 v116, v116, s22, v122
	global_store_dwordx4 v[124:125], v[134:137], off
	global_store_dwordx4 v[124:125], v[116:119], off offset:16
	ds_write2_b32 v155, v112, v108 offset1:16
	ds_write2_b32 v155, v113, v109 offset0:68 offset1:84
	ds_write2_b32 v155, v114, v110 offset0:136 offset1:152
	ds_write2_b32 v155, v115, v111 offset0:204 offset1:220
	ds_write2_b32 v155, v104, v100 offset0:32 offset1:48
	ds_write2_b32 v155, v105, v101 offset0:100 offset1:116
	ds_write2_b32 v155, v106, v102 offset0:168 offset1:184
	ds_write2_b32 v155, v107, v103 offset0:236 offset1:252
	s_waitcnt lgkmcnt(0)
; DI float sigm(float x) { return 1.f / (1.f + __expf(-x)); }
; DI void phase_glu(const Params& p) {
;     ...
;     float b[16]; load16_f(p.s5_glu_b + bcol + ((tid >> 6) & 3) * 64 + (tid & 3) * 16, b);
;     EPI256_BEGIN
;       float y[16], g[16]; load16_bf(ys + (size_t)row * LDP + col, y); bft* gp = G0 + (size_t)row * 2048 + col; load16_bf(gp, g);
; #pragma unroll
;       for (int i = 0; i < 16; ++i) v[i] = y[i] * sigm(v[i] + b[i]) * g[i];
;       store16_bf(gp, v);
	v_or_b32_e32 v100, 32, v2
	ds_read_b128 v[110:113], v154
	ds_read_b128 v[114:117], v154 offset:16
	ds_read_b128 v[118:121], v154 offset:32
	ds_read_b128 v[122:125], v154 offset:48
	v_mad_i64_i32 v[102:103], s[0:1], v100, s4, v[148:149]
	v_ashrrev_i32_e32 v101, 31, v100
	global_load_dwordx4 v[126:129], v[102:103], off
	v_lshlrev_b64 v[100:101], 12, v[100:101]
	v_lshl_add_u64 v[108:109], v[140:141], 0, v[100:101]
	global_load_dwordx4 v[130:133], v[108:109], off
	global_load_dwordx4 v[104:107], v[102:103], off offset:16
	s_nop 0
	global_load_dwordx4 v[100:103], v[108:109], off offset:16
	s_waitcnt lgkmcnt(3)
	v_add_f32_e32 v0, v48, v110
	v_mul_f32_e32 v0, 0xbfb8aa3b, v0
	v_exp_f32_e32 v134, v0
	v_add_f32_e32 v0, v49, v111
	v_mul_f32_e32 v0, 0xbfb8aa3b, v0
	v_exp_f32_e32 v136, v0
	v_add_f32_e32 v0, v50, v112
	v_mul_f32_e32 v0, 0xbfb8aa3b, v0
	v_exp_f32_e32 v135, v0
	v_add_f32_e32 v0, v51, v113
	v_mul_f32_e32 v0, 0xbfb8aa3b, v0
	v_exp_f32_e32 v137, v0
	s_waitcnt lgkmcnt(2)
	v_add_f32_e32 v0, v44, v114
	v_mul_f32_e32 v0, 0xbfb8aa3b, v0
	v_exp_f32_e32 v138, v0
	v_add_f32_e32 v0, v45, v115
	v_mul_f32_e32 v0, 0xbfb8aa3b, v0
	v_exp_f32_e32 v142, v0
	v_add_f32_e32 v0, v46, v116
	v_mul_f32_e32 v0, 0xbfb8aa3b, v0
	v_exp_f32_e32 v139, v0
	v_add_f32_e32 v0, v47, v117
	v_mul_f32_e32 v0, 0xbfb8aa3b, v0
	v_exp_f32_e32 v143, v0
	s_waitcnt lgkmcnt(1)
	v_add_f32_e32 v0, v24, v118
	v_mul_f32_e32 v0, 0xbfb8aa3b, v0
	v_exp_f32_e32 v116, v0
	v_add_f32_e32 v0, v25, v119
	v_mul_f32_e32 v0, 0xbfb8aa3b, v0
	v_exp_f32_e32 v114, v0
	v_add_f32_e32 v0, v26, v120
	v_mul_f32_e32 v0, 0xbfb8aa3b, v0
	v_exp_f32_e32 v117, v0
	v_add_f32_e32 v0, v27, v121
	v_mul_f32_e32 v0, 0xbfb8aa3b, v0
	v_exp_f32_e32 v115, v0
	s_waitcnt lgkmcnt(0)
	v_add_f32_e32 v0, v20, v122
	v_mul_f32_e32 v0, 0xbfb8aa3b, v0
	v_exp_f32_e32 v112, v0
	v_add_f32_e32 v0, v21, v123
	v_mul_f32_e32 v0, 0xbfb8aa3b, v0
	v_exp_f32_e32 v110, v0
	v_add_f32_e32 v0, v22, v124
	v_mul_f32_e32 v0, 0xbfb8aa3b, v0
	v_exp_f32_e32 v113, v0
	v_add_f32_e32 v0, v23, v125
	v_mul_f32_e32 v0, 0xbfb8aa3b, v0
	v_pk_add_f32 v[124:125], v[134:135], 1.0 op_sel_hi:[1,0]
	v_exp_f32_e32 v111, v0
	v_pk_add_f32 v[116:117], v[116:117], 1.0 op_sel_hi:[1,0]
	v_pk_add_f32 v[114:115], v[114:115], 1.0 op_sel_hi:[1,0]
	v_pk_add_f32 v[112:113], v[112:113], 1.0 op_sel_hi:[1,0]
	v_pk_add_f32 v[110:111], v[110:111], 1.0 op_sel_hi:[1,0]
	s_waitcnt vmcnt(3)
	v_lshlrev_b32_e32 v118, 16, v126
	v_and_b32_e32 v120, 0xffff0000, v126
	s_waitcnt vmcnt(2)
	v_lshlrev_b32_e32 v122, 16, v130
	v_and_b32_e32 v126, 0xffff0000, v130
	v_lshlrev_b32_e32 v119, 16, v127
	v_and_b32_e32 v121, 0xffff0000, v127
	v_lshlrev_b32_e32 v123, 16, v131
	v_and_b32_e32 v127, 0xffff0000, v131
	v_rcp_f32_e32 v125, v125
	v_pk_add_f32 v[130:131], v[136:137], 1.0 op_sel_hi:[1,0]
	v_rcp_f32_e32 v124, v124
	s_nop 0
	v_pk_mul_f32 v[118:119], v[124:125], v[118:119]
	v_pk_mul_f32 v[118:119], v[118:119], v[122:123]
	v_rcp_f32_e32 v123, v131
	v_and_b32_e32 v131, 0xffff0000, v133
	v_rcp_f32_e32 v122, v130
	s_nop 0
	v_pk_mul_f32 v[120:121], v[122:123], v[120:121]
	v_lshlrev_b32_e32 v123, 16, v129
	v_lshlrev_b32_e32 v122, 16, v128
	v_and_b32_e32 v125, 0xffff0000, v129
	v_and_b32_e32 v124, 0xffff0000, v128
	v_pk_add_f32 v[128:129], v[138:139], 1.0 op_sel_hi:[1,0]
	v_pk_mul_f32 v[120:121], v[120:121], v[126:127]
	v_lshlrev_b32_e32 v126, 16, v132
	v_and_b32_e32 v130, 0xffff0000, v132
	v_lshlrev_b32_e32 v127, 16, v133
	v_rcp_f32_e32 v129, v129
	v_pk_add_f32 v[132:133], v[142:143], 1.0 op_sel_hi:[1,0]
	v_rcp_f32_e32 v128, v128
	s_nop 0
	v_pk_mul_f32 v[122:123], v[128:129], v[122:123]
	v_pk_mul_f32 v[122:123], v[122:123], v[126:127]
	v_rcp_f32_e32 v127, v133
	v_rcp_f32_e32 v126, v132
	s_nop 0
	v_pk_mul_f32 v[124:125], v[126:127], v[124:125]
	v_bfe_u32 v126, v121, 16, 1
	v_pk_mul_f32 v[124:125], v[124:125], v[130:131]
	v_bfe_u32 v127, v120, 16, 1
	v_bfe_u32 v0, v125, 16, 1
	v_bfe_u32 v3, v124, 16, 1
	v_add3_u32 v0, v125, v0, s24
	v_bfe_u32 v125, v123, 16, 1
	v_add3_u32 v126, v121, v126, s24
	v_add3_u32 v3, v124, v3, s24
	v_bfe_u32 v121, v119, 16, 1
	v_bfe_u32 v124, v122, 16, 1
	v_add3_u32 v123, v123, v125, s24
	v_add3_u32 v127, v120, v127, s24
	v_bfe_u32 v120, v118, 16, 1
	v_add3_u32 v122, v122, v124, s24
	v_add3_u32 v119, v119, v121, s24
	v_lshrrev_b32_e32 v121, 16, v123
	v_add3_u32 v118, v118, v120, s24
	v_lshrrev_b32_e32 v120, 16, v122
	v_and_or_b32 v121, v0, s22, v121
	v_and_or_b32 v120, v3, s22, v120
	v_lshrrev_b32_e32 v119, 16, v119
	v_and_or_b32 v119, v126, s22, v119
	v_lshrrev_b32_e32 v118, 16, v118
	v_and_or_b32 v118, v127, s22, v118
	v_rcp_f32_e32 v117, v117
	s_waitcnt vmcnt(1)
	v_lshlrev_b32_e32 v123, 16, v105
	v_rcp_f32_e32 v116, v116
	v_lshlrev_b32_e32 v122, 16, v104
	v_pk_mul_f32 v[116:117], v[116:117], v[122:123]
	v_rcp_f32_e32 v115, v115
	s_waitcnt vmcnt(0)
; DI float sigm(float x) { return 1.f / (1.f + __expf(-x)); }
; DI void phase_glu(const Params& p) {
;     ...
;     float b[16]; load16_f(p.s5_glu_b + bcol + ((tid >> 6) & 3) * 64 + (tid & 3) * 16, b);
;     EPI256_BEGIN
;       float y[16], g[16]; load16_bf(ys + (size_t)row * LDP + col, y); bft* gp = G0 + (size_t)row * 2048 + col; load16_bf(gp, g);
; #pragma unroll
;       for (int i = 0; i < 16; ++i) v[i] = y[i] * sigm(v[i] + b[i]) * g[i];
;       store16_bf(gp, v);
	v_lshlrev_b32_e32 v125, 16, v101
	v_lshlrev_b32_e32 v124, 16, v100
	v_pk_mul_f32 v[116:117], v[116:117], v[124:125]
	v_rcp_f32_e32 v114, v114
	v_and_b32_e32 v105, 0xffff0000, v105
	v_and_b32_e32 v104, 0xffff0000, v104
	v_and_b32_e32 v101, 0xffff0000, v101
	v_rcp_f32_e32 v113, v113
	v_and_b32_e32 v100, 0xffff0000, v100
	v_div_scale_f32 v3, s[0:1], v111, v111, 1.0
	v_rcp_f32_e32 v122, v3
	v_pk_mul_f32 v[104:105], v[114:115], v[104:105]
	v_rcp_f32_e32 v112, v112
	v_pk_mul_f32 v[100:101], v[104:105], v[100:101]
	v_fma_f32 v0, -v3, v122, 1.0
	v_lshlrev_b32_e32 v105, 16, v107
	v_lshlrev_b32_e32 v104, 16, v106
	v_fmac_f32_e32 v122, v0, v122
	v_div_scale_f32 v0, vcc, 1.0, v111, 1.0
	v_pk_mul_f32 v[104:105], v[112:113], v[104:105]
	v_mul_f32_e32 v112, v0, v122
	v_fma_f32 v113, -v3, v112, v0
	v_fmac_f32_e32 v112, v113, v122
	v_fma_f32 v0, -v3, v112, v0
	v_div_scale_f32 v3, s[0:1], v110, v110, 1.0
	v_rcp_f32_e32 v113, v3
	v_div_fmas_f32 v0, v0, v122, v112
	v_div_fixup_f32 v111, v0, v111, 1.0
	v_lshlrev_b32_e32 v115, 16, v103
	v_fma_f32 v0, -v3, v113, 1.0
	v_fmac_f32_e32 v113, v0, v113
	v_div_scale_f32 v0, vcc, 1.0, v110, 1.0
	v_lshlrev_b32_e32 v114, 16, v102
	v_mul_f32_e32 v112, v0, v113
	v_pk_mul_f32 v[104:105], v[104:105], v[114:115]
	v_fma_f32 v114, -v3, v112, v0
	v_fmac_f32_e32 v112, v114, v113
	v_fma_f32 v0, -v3, v112, v0
	v_div_fmas_f32 v0, v0, v113, v112
	v_and_b32_e32 v107, 0xffff0000, v107
	v_and_b32_e32 v106, 0xffff0000, v106
	v_div_fixup_f32 v110, v0, v110, 1.0
	v_and_b32_e32 v103, 0xffff0000, v103
	v_and_b32_e32 v102, 0xffff0000, v102
	v_pk_mul_f32 v[106:107], v[110:111], v[106:107]
	s_nop 0
	v_pk_mul_f32 v[102:103], v[106:107], v[102:103]
	v_bfe_u32 v106, v101, 16, 1
	v_bfe_u32 v0, v103, 16, 1
	v_bfe_u32 v3, v102, 16, 1
	v_bfe_u32 v107, v100, 16, 1
	v_add3_u32 v100, v100, v107, s24
	v_add3_u32 v101, v101, v106, s24
	v_add3_u32 v3, v102, v3, s24
	v_add3_u32 v0, v103, v0, s24
	v_bfe_u32 v102, v116, 16, 1
	v_bfe_u32 v103, v117, 16, 1
	v_bfe_u32 v106, v104, 16, 1
	v_bfe_u32 v107, v105, 16, 1
	v_add3_u32 v105, v105, v107, s24
	v_add3_u32 v104, v104, v106, s24
	v_add3_u32 v103, v117, v103, s24
	v_add3_u32 v102, v116, v102, s24
	v_lshrrev_b32_e32 v106, 16, v102
	v_lshrrev_b32_e32 v107, 16, v103
	v_lshrrev_b32_e32 v102, 16, v104
	v_lshrrev_b32_e32 v103, 16, v105
	v_and_or_b32 v103, v0, s22, v103
	v_and_or_b32 v102, v3, s22, v102
	v_and_or_b32 v101, v101, s22, v107
	v_and_or_b32 v100, v100, s22, v106
	global_store_dwordx4 v[108:109], v[118:121], off
	global_store_dwordx4 v[108:109], v[100:103], off offset:16
	ds_write2_b32 v155, v96, v92 offset1:16
	ds_write2_b32 v155, v97, v93 offset0:68 offset1:84
	ds_write2_b32 v155, v98, v94 offset0:136 offset1:152
	ds_write2_b32 v155, v99, v95 offset0:204 offset1:220
	ds_write2_b32 v155, v88, v84 offset0:32 offset1:48
	ds_write2_b32 v155, v89, v85 offset0:100 offset1:116
	ds_write2_b32 v155, v90, v86 offset0:168 offset1:184
	ds_write2_b32 v155, v91, v87 offset0:236 offset1:252
	s_waitcnt lgkmcnt(0)
	v_or_b32_e32 v84, 48, v2
	ds_read_b128 v[94:97], v154
	ds_read_b128 v[98:101], v154 offset:16
	ds_read_b128 v[102:105], v154 offset:32
	ds_read_b128 v[106:109], v154 offset:48
	v_mad_i64_i32 v[86:87], s[0:1], v84, s4, v[148:149]
	v_ashrrev_i32_e32 v85, 31, v84
	global_load_dwordx4 v[110:113], v[86:87], off
	v_lshlrev_b64 v[84:85], 12, v[84:85]
	v_lshl_add_u64 v[92:93], v[140:141], 0, v[84:85]
	global_load_dwordx4 v[114:117], v[92:93], off
	global_load_dwordx4 v[88:91], v[86:87], off offset:16
	s_nop 0
	global_load_dwordx4 v[84:87], v[92:93], off offset:16
	s_waitcnt lgkmcnt(3)
	v_add_f32_e32 v0, v48, v94
	v_mul_f32_e32 v0, 0xbfb8aa3b, v0
	v_exp_f32_e32 v118, v0
	v_add_f32_e32 v0, v49, v95
	v_mul_f32_e32 v0, 0xbfb8aa3b, v0
	v_exp_f32_e32 v120, v0
	v_add_f32_e32 v0, v50, v96
	v_mul_f32_e32 v0, 0xbfb8aa3b, v0
	v_exp_f32_e32 v119, v0
	v_add_f32_e32 v0, v51, v97
	v_mul_f32_e32 v0, 0xbfb8aa3b, v0
	v_exp_f32_e32 v121, v0
	s_waitcnt lgkmcnt(2)
	v_add_f32_e32 v0, v44, v98
	v_mul_f32_e32 v0, 0xbfb8aa3b, v0
	v_exp_f32_e32 v122, v0
	v_add_f32_e32 v0, v45, v99
	v_mul_f32_e32 v0, 0xbfb8aa3b, v0
	v_exp_f32_e32 v124, v0
	v_add_f32_e32 v0, v46, v100
	v_mul_f32_e32 v0, 0xbfb8aa3b, v0
	v_exp_f32_e32 v123, v0
	v_add_f32_e32 v0, v47, v101
	v_mul_f32_e32 v0, 0xbfb8aa3b, v0
	v_exp_f32_e32 v125, v0
	s_waitcnt lgkmcnt(1)
	v_add_f32_e32 v0, v24, v102
	v_mul_f32_e32 v0, 0xbfb8aa3b, v0
	v_exp_f32_e32 v100, v0
	v_add_f32_e32 v0, v25, v103
	v_mul_f32_e32 v0, 0xbfb8aa3b, v0
	v_exp_f32_e32 v98, v0
	v_add_f32_e32 v0, v26, v104
	v_mul_f32_e32 v0, 0xbfb8aa3b, v0
	v_exp_f32_e32 v101, v0
	v_add_f32_e32 v0, v27, v105
	v_mul_f32_e32 v0, 0xbfb8aa3b, v0
	v_exp_f32_e32 v99, v0
	s_waitcnt lgkmcnt(0)
	v_add_f32_e32 v0, v20, v106
	v_mul_f32_e32 v0, 0xbfb8aa3b, v0
	v_exp_f32_e32 v96, v0
	v_add_f32_e32 v0, v21, v107
	v_mul_f32_e32 v0, 0xbfb8aa3b, v0
	v_exp_f32_e32 v94, v0
	v_add_f32_e32 v0, v22, v108
	v_mul_f32_e32 v0, 0xbfb8aa3b, v0
	v_exp_f32_e32 v97, v0
	v_add_f32_e32 v0, v23, v109
	v_mul_f32_e32 v0, 0xbfb8aa3b, v0
	v_pk_add_f32 v[108:109], v[118:119], 1.0 op_sel_hi:[1,0]
	v_exp_f32_e32 v95, v0
	v_pk_add_f32 v[100:101], v[100:101], 1.0 op_sel_hi:[1,0]
	v_pk_add_f32 v[98:99], v[98:99], 1.0 op_sel_hi:[1,0]
	v_pk_add_f32 v[96:97], v[96:97], 1.0 op_sel_hi:[1,0]
	v_pk_add_f32 v[94:95], v[94:95], 1.0 op_sel_hi:[1,0]
	s_waitcnt vmcnt(3)
	v_lshlrev_b32_e32 v102, 16, v110
	v_and_b32_e32 v104, 0xffff0000, v110
	s_waitcnt vmcnt(2)
; DI float sigm(float x) { return 1.f / (1.f + __expf(-x)); }
; DI void phase_glu(const Params& p) {
;     ...
;     float b[16]; load16_f(p.s5_glu_b + bcol + ((tid >> 6) & 3) * 64 + (tid & 3) * 16, b);
;     EPI256_BEGIN
;       float y[16], g[16]; load16_bf(ys + (size_t)row * LDP + col, y); bft* gp = G0 + (size_t)row * 2048 + col; load16_bf(gp, g);
; #pragma unroll
;       for (int i = 0; i < 16; ++i) v[i] = y[i] * sigm(v[i] + b[i]) * g[i];
;       store16_bf(gp, v);
	v_lshlrev_b32_e32 v106, 16, v114
	v_and_b32_e32 v110, 0xffff0000, v114
	v_lshlrev_b32_e32 v103, 16, v111
	v_and_b32_e32 v105, 0xffff0000, v111
	v_lshlrev_b32_e32 v107, 16, v115
	v_and_b32_e32 v111, 0xffff0000, v115
	v_rcp_f32_e32 v109, v109
	v_pk_add_f32 v[114:115], v[120:121], 1.0 op_sel_hi:[1,0]
	v_rcp_f32_e32 v108, v108
	s_nop 0
	v_pk_mul_f32 v[102:103], v[108:109], v[102:103]
	v_pk_mul_f32 v[102:103], v[102:103], v[106:107]
	v_rcp_f32_e32 v107, v115
	v_and_b32_e32 v115, 0xffff0000, v117
	v_rcp_f32_e32 v106, v114
	s_nop 0
	v_pk_mul_f32 v[104:105], v[106:107], v[104:105]
	v_lshlrev_b32_e32 v107, 16, v113
	v_lshlrev_b32_e32 v106, 16, v112
	v_and_b32_e32 v109, 0xffff0000, v113
	v_and_b32_e32 v108, 0xffff0000, v112
	v_pk_add_f32 v[112:113], v[122:123], 1.0 op_sel_hi:[1,0]
	v_pk_mul_f32 v[104:105], v[104:105], v[110:111]
	v_lshlrev_b32_e32 v110, 16, v116
	v_and_b32_e32 v114, 0xffff0000, v116
	v_lshlrev_b32_e32 v111, 16, v117
	v_rcp_f32_e32 v113, v113
	v_pk_add_f32 v[116:117], v[124:125], 1.0 op_sel_hi:[1,0]
	v_rcp_f32_e32 v112, v112
	s_nop 0
	v_pk_mul_f32 v[106:107], v[112:113], v[106:107]
	v_pk_mul_f32 v[106:107], v[106:107], v[110:111]
	v_rcp_f32_e32 v111, v117
	v_rcp_f32_e32 v110, v116
	s_nop 0
	v_pk_mul_f32 v[108:109], v[110:111], v[108:109]
	v_bfe_u32 v110, v105, 16, 1
	v_pk_mul_f32 v[108:109], v[108:109], v[114:115]
	v_bfe_u32 v111, v104, 16, 1
	v_bfe_u32 v0, v109, 16, 1
	v_bfe_u32 v3, v108, 16, 1
	v_add3_u32 v0, v109, v0, s24
	v_bfe_u32 v109, v107, 16, 1
	v_add3_u32 v110, v105, v110, s24
	v_add3_u32 v3, v108, v3, s24
	v_bfe_u32 v105, v103, 16, 1
	v_bfe_u32 v108, v106, 16, 1
	v_add3_u32 v107, v107, v109, s24
	v_add3_u32 v111, v104, v111, s24
	v_bfe_u32 v104, v102, 16, 1
	v_add3_u32 v106, v106, v108, s24
	v_add3_u32 v103, v103, v105, s24
	v_lshrrev_b32_e32 v105, 16, v107
	v_add3_u32 v102, v102, v104, s24
	v_lshrrev_b32_e32 v104, 16, v106
	v_and_or_b32 v105, v0, s22, v105
	v_and_or_b32 v104, v3, s22, v104
	v_lshrrev_b32_e32 v103, 16, v103
	v_and_or_b32 v103, v110, s22, v103
	v_lshrrev_b32_e32 v102, 16, v102
	v_and_or_b32 v102, v111, s22, v102
	v_rcp_f32_e32 v101, v101
	s_waitcnt vmcnt(1)
	v_lshlrev_b32_e32 v107, 16, v89
	v_rcp_f32_e32 v100, v100
	v_lshlrev_b32_e32 v106, 16, v88
	v_pk_mul_f32 v[100:101], v[100:101], v[106:107]
	v_rcp_f32_e32 v99, v99
	s_waitcnt vmcnt(0)
	v_lshlrev_b32_e32 v109, 16, v85
	v_lshlrev_b32_e32 v108, 16, v84
	v_pk_mul_f32 v[100:101], v[100:101], v[108:109]
	v_rcp_f32_e32 v98, v98
	v_and_b32_e32 v89, 0xffff0000, v89
	v_and_b32_e32 v88, 0xffff0000, v88
	v_and_b32_e32 v85, 0xffff0000, v85
	v_rcp_f32_e32 v97, v97
	v_and_b32_e32 v84, 0xffff0000, v84
	v_div_scale_f32 v3, s[0:1], v95, v95, 1.0
	v_rcp_f32_e32 v106, v3
	v_pk_mul_f32 v[88:89], v[98:99], v[88:89]
	v_rcp_f32_e32 v96, v96
	v_pk_mul_f32 v[84:85], v[88:89], v[84:85]
	v_fma_f32 v0, -v3, v106, 1.0
	v_lshlrev_b32_e32 v89, 16, v91
	v_lshlrev_b32_e32 v88, 16, v90
	v_fmac_f32_e32 v106, v0, v106
	v_div_scale_f32 v0, vcc, 1.0, v95, 1.0
	v_pk_mul_f32 v[88:89], v[96:97], v[88:89]
	v_mul_f32_e32 v96, v0, v106
	v_fma_f32 v97, -v3, v96, v0
	v_fmac_f32_e32 v96, v97, v106
	v_fma_f32 v0, -v3, v96, v0
	v_div_scale_f32 v3, s[0:1], v94, v94, 1.0
	v_rcp_f32_e32 v97, v3
	v_div_fmas_f32 v0, v0, v106, v96
	v_div_fixup_f32 v95, v0, v95, 1.0
	v_lshlrev_b32_e32 v99, 16, v87
	v_fma_f32 v0, -v3, v97, 1.0
	v_fmac_f32_e32 v97, v0, v97
	v_div_scale_f32 v0, vcc, 1.0, v94, 1.0
	v_lshlrev_b32_e32 v98, 16, v86
	v_mul_f32_e32 v96, v0, v97
	v_pk_mul_f32 v[88:89], v[88:89], v[98:99]
	v_fma_f32 v98, -v3, v96, v0
	v_fmac_f32_e32 v96, v98, v97
	v_fma_f32 v0, -v3, v96, v0
	v_div_fmas_f32 v0, v0, v97, v96
	v_and_b32_e32 v91, 0xffff0000, v91
	v_and_b32_e32 v90, 0xffff0000, v90
	v_div_fixup_f32 v94, v0, v94, 1.0
	v_and_b32_e32 v87, 0xffff0000, v87
	v_and_b32_e32 v86, 0xffff0000, v86
	v_pk_mul_f32 v[90:91], v[94:95], v[90:91]
	s_nop 0
	v_pk_mul_f32 v[86:87], v[90:91], v[86:87]
	v_bfe_u32 v90, v85, 16, 1
	v_bfe_u32 v0, v87, 16, 1
	v_bfe_u32 v3, v86, 16, 1
	v_bfe_u32 v91, v84, 16, 1
	v_add3_u32 v84, v84, v91, s24
	v_add3_u32 v85, v85, v90, s24
	v_add3_u32 v3, v86, v3, s24
	v_add3_u32 v0, v87, v0, s24
	v_bfe_u32 v86, v100, 16, 1
	v_bfe_u32 v87, v101, 16, 1
	v_bfe_u32 v90, v88, 16, 1
	v_bfe_u32 v91, v89, 16, 1
	v_add3_u32 v89, v89, v91, s24
	v_add3_u32 v88, v88, v90, s24
	v_add3_u32 v87, v101, v87, s24
	v_add3_u32 v86, v100, v86, s24
	v_lshrrev_b32_e32 v90, 16, v86
	v_lshrrev_b32_e32 v91, 16, v87
	v_lshrrev_b32_e32 v86, 16, v88
	v_lshrrev_b32_e32 v87, 16, v89
	v_and_or_b32 v87, v0, s22, v87
	v_and_or_b32 v86, v3, s22, v86
	v_and_or_b32 v85, v85, s22, v91
	v_and_or_b32 v84, v84, s22, v90
	global_store_dwordx4 v[92:93], v[102:105], off
	global_store_dwordx4 v[92:93], v[84:87], off offset:16
	ds_write2_b32 v155, v76, v80 offset1:16
	ds_write2_b32 v155, v77, v81 offset0:68 offset1:84
	ds_write2_b32 v155, v78, v82 offset0:136 offset1:152
	ds_write2_b32 v155, v79, v83 offset0:204 offset1:220
	ds_write2_b32 v155, v68, v72 offset0:32 offset1:48
	ds_write2_b32 v155, v69, v73 offset0:100 offset1:116
	ds_write2_b32 v155, v70, v74 offset0:168 offset1:184
	ds_write2_b32 v155, v71, v75 offset0:236 offset1:252
	s_waitcnt lgkmcnt(0)
	v_or_b32_e32 v68, 64, v2
	ds_read_b128 v[78:81], v154
	ds_read_b128 v[82:85], v154 offset:16
	ds_read_b128 v[86:89], v154 offset:32
	ds_read_b128 v[90:93], v154 offset:48
	v_mad_i64_i32 v[70:71], s[0:1], v68, s4, v[148:149]
	v_ashrrev_i32_e32 v69, 31, v68
	global_load_dwordx4 v[94:97], v[70:71], off
	v_lshlrev_b64 v[68:69], 12, v[68:69]
	v_lshl_add_u64 v[76:77], v[140:141], 0, v[68:69]
	global_load_dwordx4 v[98:101], v[76:77], off
	global_load_dwordx4 v[72:75], v[70:71], off offset:16
	s_nop 0
	global_load_dwordx4 v[68:71], v[76:77], off offset:16
	s_waitcnt lgkmcnt(3)
; DI float sigm(float x) { return 1.f / (1.f + __expf(-x)); }
; DI void phase_glu(const Params& p) {
;     ...
;     float b[16]; load16_f(p.s5_glu_b + bcol + ((tid >> 6) & 3) * 64 + (tid & 3) * 16, b);
;     EPI256_BEGIN
;       float y[16], g[16]; load16_bf(ys + (size_t)row * LDP + col, y); bft* gp = G0 + (size_t)row * 2048 + col; load16_bf(gp, g);
; #pragma unroll
;       for (int i = 0; i < 16; ++i) v[i] = y[i] * sigm(v[i] + b[i]) * g[i];
;       store16_bf(gp, v);
	v_add_f32_e32 v0, v48, v78
	v_mul_f32_e32 v0, 0xbfb8aa3b, v0
	v_exp_f32_e32 v102, v0
	v_add_f32_e32 v0, v49, v79
	v_mul_f32_e32 v0, 0xbfb8aa3b, v0
	v_exp_f32_e32 v104, v0
	v_add_f32_e32 v0, v50, v80
	v_mul_f32_e32 v0, 0xbfb8aa3b, v0
	v_exp_f32_e32 v103, v0
	v_add_f32_e32 v0, v51, v81
	v_mul_f32_e32 v0, 0xbfb8aa3b, v0
	v_exp_f32_e32 v105, v0
	s_waitcnt lgkmcnt(2)
	v_add_f32_e32 v0, v44, v82
	v_mul_f32_e32 v0, 0xbfb8aa3b, v0
	v_exp_f32_e32 v106, v0
	v_add_f32_e32 v0, v45, v83
	v_mul_f32_e32 v0, 0xbfb8aa3b, v0
	v_exp_f32_e32 v108, v0
	v_add_f32_e32 v0, v46, v84
	v_mul_f32_e32 v0, 0xbfb8aa3b, v0
	v_exp_f32_e32 v107, v0
	v_add_f32_e32 v0, v47, v85
	v_mul_f32_e32 v0, 0xbfb8aa3b, v0
	v_exp_f32_e32 v109, v0
	s_waitcnt lgkmcnt(1)
	v_add_f32_e32 v0, v24, v86
	v_mul_f32_e32 v0, 0xbfb8aa3b, v0
	v_exp_f32_e32 v84, v0
	v_add_f32_e32 v0, v25, v87
	v_mul_f32_e32 v0, 0xbfb8aa3b, v0
	v_exp_f32_e32 v82, v0
	v_add_f32_e32 v0, v26, v88
	v_mul_f32_e32 v0, 0xbfb8aa3b, v0
	v_exp_f32_e32 v85, v0
	v_add_f32_e32 v0, v27, v89
	v_mul_f32_e32 v0, 0xbfb8aa3b, v0
	v_exp_f32_e32 v83, v0
	s_waitcnt lgkmcnt(0)
	v_add_f32_e32 v0, v20, v90
	v_mul_f32_e32 v0, 0xbfb8aa3b, v0
	v_exp_f32_e32 v80, v0
	v_add_f32_e32 v0, v21, v91
	v_mul_f32_e32 v0, 0xbfb8aa3b, v0
	v_exp_f32_e32 v78, v0
	v_add_f32_e32 v0, v22, v92
	v_mul_f32_e32 v0, 0xbfb8aa3b, v0
	v_exp_f32_e32 v81, v0
	v_add_f32_e32 v0, v23, v93
	v_mul_f32_e32 v0, 0xbfb8aa3b, v0
	v_pk_add_f32 v[92:93], v[102:103], 1.0 op_sel_hi:[1,0]
	v_exp_f32_e32 v79, v0
	v_pk_add_f32 v[84:85], v[84:85], 1.0 op_sel_hi:[1,0]
	v_pk_add_f32 v[82:83], v[82:83], 1.0 op_sel_hi:[1,0]
	v_pk_add_f32 v[80:81], v[80:81], 1.0 op_sel_hi:[1,0]
	v_pk_add_f32 v[78:79], v[78:79], 1.0 op_sel_hi:[1,0]
	s_waitcnt vmcnt(3)
	v_lshlrev_b32_e32 v86, 16, v94
	v_and_b32_e32 v88, 0xffff0000, v94
	s_waitcnt vmcnt(2)
	v_lshlrev_b32_e32 v90, 16, v98
	v_and_b32_e32 v94, 0xffff0000, v98
	v_lshlrev_b32_e32 v87, 16, v95
	v_and_b32_e32 v89, 0xffff0000, v95
	v_lshlrev_b32_e32 v91, 16, v99
	v_and_b32_e32 v95, 0xffff0000, v99
	v_rcp_f32_e32 v93, v93
	v_pk_add_f32 v[98:99], v[104:105], 1.0 op_sel_hi:[1,0]
	v_rcp_f32_e32 v92, v92
	s_nop 0
	v_pk_mul_f32 v[86:87], v[92:93], v[86:87]
	v_pk_mul_f32 v[86:87], v[86:87], v[90:91]
	v_rcp_f32_e32 v91, v99
	v_and_b32_e32 v99, 0xffff0000, v101
	v_rcp_f32_e32 v90, v98
	s_nop 0
	v_pk_mul_f32 v[88:89], v[90:91], v[88:89]
	v_lshlrev_b32_e32 v91, 16, v97
	v_lshlrev_b32_e32 v90, 16, v96
	v_and_b32_e32 v93, 0xffff0000, v97
	v_and_b32_e32 v92, 0xffff0000, v96
	v_pk_add_f32 v[96:97], v[106:107], 1.0 op_sel_hi:[1,0]
	v_pk_mul_f32 v[88:89], v[88:89], v[94:95]
	v_lshlrev_b32_e32 v94, 16, v100
	v_and_b32_e32 v98, 0xffff0000, v100
	v_lshlrev_b32_e32 v95, 16, v101
	v_rcp_f32_e32 v97, v97
	v_pk_add_f32 v[100:101], v[108:109], 1.0 op_sel_hi:[1,0]
	v_rcp_f32_e32 v96, v96
	s_nop 0
	v_pk_mul_f32 v[90:91], v[96:97], v[90:91]
	v_pk_mul_f32 v[90:91], v[90:91], v[94:95]
	v_rcp_f32_e32 v95, v101
	v_rcp_f32_e32 v94, v100
	s_nop 0
	v_pk_mul_f32 v[92:93], v[94:95], v[92:93]
	v_bfe_u32 v94, v89, 16, 1
	v_pk_mul_f32 v[92:93], v[92:93], v[98:99]
	v_bfe_u32 v95, v88, 16, 1
	v_bfe_u32 v0, v93, 16, 1
	v_bfe_u32 v3, v92, 16, 1
	v_add3_u32 v0, v93, v0, s24
	v_bfe_u32 v93, v91, 16, 1
	v_add3_u32 v94, v89, v94, s24
	v_add3_u32 v3, v92, v3, s24
	v_bfe_u32 v89, v87, 16, 1
	v_bfe_u32 v92, v90, 16, 1
	v_add3_u32 v91, v91, v93, s24
	v_add3_u32 v95, v88, v95, s24
	v_bfe_u32 v88, v86, 16, 1
	v_add3_u32 v90, v90, v92, s24
	v_add3_u32 v87, v87, v89, s24
	v_lshrrev_b32_e32 v89, 16, v91
	v_add3_u32 v86, v86, v88, s24
	v_lshrrev_b32_e32 v88, 16, v90
	v_and_or_b32 v89, v0, s22, v89
	v_and_or_b32 v88, v3, s22, v88
	v_lshrrev_b32_e32 v87, 16, v87
	v_and_or_b32 v87, v94, s22, v87
	v_lshrrev_b32_e32 v86, 16, v86
	v_and_or_b32 v86, v95, s22, v86
	v_rcp_f32_e32 v85, v85
	s_waitcnt vmcnt(1)
	v_lshlrev_b32_e32 v91, 16, v73
	v_rcp_f32_e32 v84, v84
	v_lshlrev_b32_e32 v90, 16, v72
	v_pk_mul_f32 v[84:85], v[84:85], v[90:91]
	v_rcp_f32_e32 v83, v83
	s_waitcnt vmcnt(0)
	v_lshlrev_b32_e32 v93, 16, v69
	v_lshlrev_b32_e32 v92, 16, v68
	v_pk_mul_f32 v[84:85], v[84:85], v[92:93]
	v_rcp_f32_e32 v82, v82
	v_and_b32_e32 v73, 0xffff0000, v73
	v_and_b32_e32 v72, 0xffff0000, v72
	v_and_b32_e32 v69, 0xffff0000, v69
	v_rcp_f32_e32 v81, v81
	v_and_b32_e32 v68, 0xffff0000, v68
	v_div_scale_f32 v3, s[0:1], v79, v79, 1.0
	v_rcp_f32_e32 v90, v3
	v_pk_mul_f32 v[72:73], v[82:83], v[72:73]
	v_rcp_f32_e32 v80, v80
	v_pk_mul_f32 v[68:69], v[72:73], v[68:69]
	v_fma_f32 v0, -v3, v90, 1.0
	v_lshlrev_b32_e32 v73, 16, v75
	v_lshlrev_b32_e32 v72, 16, v74
	v_fmac_f32_e32 v90, v0, v90
	v_div_scale_f32 v0, vcc, 1.0, v79, 1.0
	v_pk_mul_f32 v[72:73], v[80:81], v[72:73]
	v_mul_f32_e32 v80, v0, v90
	v_fma_f32 v81, -v3, v80, v0
	v_fmac_f32_e32 v80, v81, v90
	v_fma_f32 v0, -v3, v80, v0
	v_div_scale_f32 v3, s[0:1], v78, v78, 1.0
	v_rcp_f32_e32 v81, v3
	v_div_fmas_f32 v0, v0, v90, v80
	v_div_fixup_f32 v79, v0, v79, 1.0
	v_lshlrev_b32_e32 v83, 16, v71
	v_fma_f32 v0, -v3, v81, 1.0
	v_fmac_f32_e32 v81, v0, v81
	v_div_scale_f32 v0, vcc, 1.0, v78, 1.0
	v_lshlrev_b32_e32 v82, 16, v70
	v_mul_f32_e32 v80, v0, v81
	v_pk_mul_f32 v[72:73], v[72:73], v[82:83]
	v_fma_f32 v82, -v3, v80, v0
	v_fmac_f32_e32 v80, v82, v81
	v_fma_f32 v0, -v3, v80, v0
	v_div_fmas_f32 v0, v0, v81, v80
	v_and_b32_e32 v75, 0xffff0000, v75
	v_and_b32_e32 v74, 0xffff0000, v74
	v_div_fixup_f32 v78, v0, v78, 1.0
	v_and_b32_e32 v71, 0xffff0000, v71
	v_and_b32_e32 v70, 0xffff0000, v70
	v_pk_mul_f32 v[74:75], v[78:79], v[74:75]
	s_nop 0
	v_pk_mul_f32 v[70:71], v[74:75], v[70:71]
	v_bfe_u32 v74, v69, 16, 1
	v_bfe_u32 v0, v71, 16, 1
	v_bfe_u32 v3, v70, 16, 1
	v_bfe_u32 v75, v68, 16, 1
	v_add3_u32 v68, v68, v75, s24
	v_add3_u32 v69, v69, v74, s24
	v_add3_u32 v3, v70, v3, s24
	v_add3_u32 v0, v71, v0, s24
	v_bfe_u32 v70, v84, 16, 1
	v_bfe_u32 v71, v85, 16, 1
	v_bfe_u32 v74, v72, 16, 1
	v_bfe_u32 v75, v73, 16, 1
	v_add3_u32 v73, v73, v75, s24
	v_add3_u32 v72, v72, v74, s24
	v_add3_u32 v71, v85, v71, s24
	v_add3_u32 v70, v84, v70, s24
	v_lshrrev_b32_e32 v74, 16, v70
	v_lshrrev_b32_e32 v75, 16, v71
	v_lshrrev_b32_e32 v70, 16, v72
	v_lshrrev_b32_e32 v71, 16, v73
	v_and_or_b32 v71, v0, s22, v71
	v_and_or_b32 v70, v3, s22, v70
	v_and_or_b32 v69, v69, s22, v75
	v_and_or_b32 v68, v68, s22, v74
	global_store_dwordx4 v[76:77], v[86:89], off
	global_store_dwordx4 v[76:77], v[68:71], off offset:16
	ds_write2_b32 v155, v60, v64 offset1:16
	ds_write2_b32 v155, v61, v65 offset0:68 offset1:84
	ds_write2_b32 v155, v62, v66 offset0:136 offset1:152
	ds_write2_b32 v155, v63, v67 offset0:204 offset1:220
	ds_write2_b32 v155, v52, v56 offset0:32 offset1:48
	ds_write2_b32 v155, v53, v57 offset0:100 offset1:116
	ds_write2_b32 v155, v54, v58 offset0:168 offset1:184
	ds_write2_b32 v155, v55, v59 offset0:236 offset1:252
	s_waitcnt lgkmcnt(0)
; DI float sigm(float x) { return 1.f / (1.f + __expf(-x)); }
; DI void phase_glu(const Params& p) {
;     ...
;     float b[16]; load16_f(p.s5_glu_b + bcol + ((tid >> 6) & 3) * 64 + (tid & 3) * 16, b);
;     EPI256_BEGIN
;       float y[16], g[16]; load16_bf(ys + (size_t)row * LDP + col, y); bft* gp = G0 + (size_t)row * 2048 + col; load16_bf(gp, g);
; #pragma unroll
;       for (int i = 0; i < 16; ++i) v[i] = y[i] * sigm(v[i] + b[i]) * g[i];
;       store16_bf(gp, v);
	v_or_b32_e32 v52, 0x50, v2
	ds_read_b128 v[62:65], v154
	ds_read_b128 v[66:69], v154 offset:16
	ds_read_b128 v[70:73], v154 offset:32
	ds_read_b128 v[74:77], v154 offset:48
	v_mad_i64_i32 v[54:55], s[0:1], v52, s4, v[148:149]
	v_ashrrev_i32_e32 v53, 31, v52
	global_load_dwordx4 v[78:81], v[54:55], off
	v_lshlrev_b64 v[52:53], 12, v[52:53]
	v_lshl_add_u64 v[60:61], v[140:141], 0, v[52:53]
	global_load_dwordx4 v[82:85], v[60:61], off
	global_load_dwordx4 v[56:59], v[54:55], off offset:16
	s_nop 0
	global_load_dwordx4 v[52:55], v[60:61], off offset:16
	s_waitcnt lgkmcnt(3)
	v_add_f32_e32 v0, v48, v62
	v_mul_f32_e32 v0, 0xbfb8aa3b, v0
	v_exp_f32_e32 v86, v0
	v_add_f32_e32 v0, v49, v63
	v_mul_f32_e32 v0, 0xbfb8aa3b, v0
	v_exp_f32_e32 v88, v0
	v_add_f32_e32 v0, v50, v64
	v_mul_f32_e32 v0, 0xbfb8aa3b, v0
	v_exp_f32_e32 v87, v0
	v_add_f32_e32 v0, v51, v65
	v_mul_f32_e32 v0, 0xbfb8aa3b, v0
	v_exp_f32_e32 v89, v0
	s_waitcnt lgkmcnt(2)
	v_add_f32_e32 v0, v44, v66
	v_mul_f32_e32 v0, 0xbfb8aa3b, v0
	v_exp_f32_e32 v90, v0
	v_add_f32_e32 v0, v45, v67
	v_mul_f32_e32 v0, 0xbfb8aa3b, v0
	v_exp_f32_e32 v92, v0
	v_add_f32_e32 v0, v46, v68
	v_mul_f32_e32 v0, 0xbfb8aa3b, v0
	v_exp_f32_e32 v91, v0
	v_add_f32_e32 v0, v47, v69
	v_mul_f32_e32 v0, 0xbfb8aa3b, v0
	v_exp_f32_e32 v93, v0
	s_waitcnt lgkmcnt(1)
	v_add_f32_e32 v0, v24, v70
	v_mul_f32_e32 v0, 0xbfb8aa3b, v0
	v_exp_f32_e32 v68, v0
	v_add_f32_e32 v0, v25, v71
	v_mul_f32_e32 v0, 0xbfb8aa3b, v0
	v_exp_f32_e32 v66, v0
	v_add_f32_e32 v0, v26, v72
	v_mul_f32_e32 v0, 0xbfb8aa3b, v0
	v_exp_f32_e32 v69, v0
	v_add_f32_e32 v0, v27, v73
	v_mul_f32_e32 v0, 0xbfb8aa3b, v0
	v_exp_f32_e32 v67, v0
	s_waitcnt lgkmcnt(0)
	v_add_f32_e32 v0, v20, v74
	v_mul_f32_e32 v0, 0xbfb8aa3b, v0
	v_exp_f32_e32 v64, v0
	v_add_f32_e32 v0, v21, v75
	v_mul_f32_e32 v0, 0xbfb8aa3b, v0
	v_exp_f32_e32 v62, v0
	v_add_f32_e32 v0, v22, v76
	v_mul_f32_e32 v0, 0xbfb8aa3b, v0
	v_exp_f32_e32 v65, v0
	v_add_f32_e32 v0, v23, v77
	v_mul_f32_e32 v0, 0xbfb8aa3b, v0
	v_pk_add_f32 v[76:77], v[86:87], 1.0 op_sel_hi:[1,0]
	v_exp_f32_e32 v63, v0
	v_pk_add_f32 v[68:69], v[68:69], 1.0 op_sel_hi:[1,0]
	v_pk_add_f32 v[66:67], v[66:67], 1.0 op_sel_hi:[1,0]
	v_pk_add_f32 v[64:65], v[64:65], 1.0 op_sel_hi:[1,0]
	v_pk_add_f32 v[62:63], v[62:63], 1.0 op_sel_hi:[1,0]
	s_waitcnt vmcnt(3)
	v_lshlrev_b32_e32 v70, 16, v78
	v_and_b32_e32 v72, 0xffff0000, v78
	s_waitcnt vmcnt(2)
	v_lshlrev_b32_e32 v74, 16, v82
	v_and_b32_e32 v78, 0xffff0000, v82
	v_lshlrev_b32_e32 v71, 16, v79
	v_and_b32_e32 v73, 0xffff0000, v79
	v_lshlrev_b32_e32 v75, 16, v83
	v_and_b32_e32 v79, 0xffff0000, v83
	v_rcp_f32_e32 v77, v77
	v_pk_add_f32 v[82:83], v[88:89], 1.0 op_sel_hi:[1,0]
	v_rcp_f32_e32 v76, v76
	s_nop 0
	v_pk_mul_f32 v[70:71], v[76:77], v[70:71]
	v_pk_mul_f32 v[70:71], v[70:71], v[74:75]
	v_rcp_f32_e32 v75, v83
	v_and_b32_e32 v83, 0xffff0000, v85
	v_rcp_f32_e32 v74, v82
	s_nop 0
	v_pk_mul_f32 v[72:73], v[74:75], v[72:73]
	v_lshlrev_b32_e32 v75, 16, v81
	v_lshlrev_b32_e32 v74, 16, v80
	v_and_b32_e32 v77, 0xffff0000, v81
	v_and_b32_e32 v76, 0xffff0000, v80
	v_pk_add_f32 v[80:81], v[90:91], 1.0 op_sel_hi:[1,0]
	v_pk_mul_f32 v[72:73], v[72:73], v[78:79]
	v_lshlrev_b32_e32 v78, 16, v84
	v_and_b32_e32 v82, 0xffff0000, v84
	v_lshlrev_b32_e32 v79, 16, v85
	v_rcp_f32_e32 v81, v81
	v_pk_add_f32 v[84:85], v[92:93], 1.0 op_sel_hi:[1,0]
	v_rcp_f32_e32 v80, v80
	s_nop 0
	v_pk_mul_f32 v[74:75], v[80:81], v[74:75]
	v_pk_mul_f32 v[74:75], v[74:75], v[78:79]
	v_rcp_f32_e32 v79, v85
	v_rcp_f32_e32 v78, v84
	s_nop 0
	v_pk_mul_f32 v[76:77], v[78:79], v[76:77]
	v_bfe_u32 v78, v73, 16, 1
	v_pk_mul_f32 v[76:77], v[76:77], v[82:83]
	v_bfe_u32 v79, v72, 16, 1
	v_bfe_u32 v0, v77, 16, 1
	v_bfe_u32 v3, v76, 16, 1
	v_add3_u32 v0, v77, v0, s24
	v_bfe_u32 v77, v75, 16, 1
	v_add3_u32 v78, v73, v78, s24
	v_add3_u32 v3, v76, v3, s24
	v_bfe_u32 v73, v71, 16, 1
	v_bfe_u32 v76, v74, 16, 1
	v_add3_u32 v75, v75, v77, s24
	v_add3_u32 v79, v72, v79, s24
	v_bfe_u32 v72, v70, 16, 1
	v_add3_u32 v74, v74, v76, s24
	v_add3_u32 v71, v71, v73, s24
	v_lshrrev_b32_e32 v73, 16, v75
	v_add3_u32 v70, v70, v72, s24
	v_lshrrev_b32_e32 v72, 16, v74
	v_and_or_b32 v73, v0, s22, v73
	v_and_or_b32 v72, v3, s22, v72
	v_lshrrev_b32_e32 v71, 16, v71
	v_and_or_b32 v71, v78, s22, v71
	v_lshrrev_b32_e32 v70, 16, v70
	v_and_or_b32 v70, v79, s22, v70
	v_rcp_f32_e32 v69, v69
	s_waitcnt vmcnt(1)
	v_lshlrev_b32_e32 v75, 16, v57
	v_rcp_f32_e32 v68, v68
	v_lshlrev_b32_e32 v74, 16, v56
	v_pk_mul_f32 v[68:69], v[68:69], v[74:75]
	v_rcp_f32_e32 v67, v67
	s_waitcnt vmcnt(0)
; DI float sigm(float x) { return 1.f / (1.f + __expf(-x)); }
; DI void phase_glu(const Params& p) {
;     ...
;     float b[16]; load16_f(p.s5_glu_b + bcol + ((tid >> 6) & 3) * 64 + (tid & 3) * 16, b);
;     EPI256_BEGIN
;       float y[16], g[16]; load16_bf(ys + (size_t)row * LDP + col, y); bft* gp = G0 + (size_t)row * 2048 + col; load16_bf(gp, g);
; #pragma unroll
;       for (int i = 0; i < 16; ++i) v[i] = y[i] * sigm(v[i] + b[i]) * g[i];
;       store16_bf(gp, v);
	v_lshlrev_b32_e32 v77, 16, v53
	v_lshlrev_b32_e32 v76, 16, v52
	v_pk_mul_f32 v[68:69], v[68:69], v[76:77]
	v_rcp_f32_e32 v66, v66
	v_and_b32_e32 v57, 0xffff0000, v57
	v_and_b32_e32 v56, 0xffff0000, v56
	v_and_b32_e32 v53, 0xffff0000, v53
	v_rcp_f32_e32 v65, v65
	v_and_b32_e32 v52, 0xffff0000, v52
	v_div_scale_f32 v3, s[0:1], v63, v63, 1.0
	v_rcp_f32_e32 v74, v3
	v_pk_mul_f32 v[56:57], v[66:67], v[56:57]
	v_rcp_f32_e32 v64, v64
	v_pk_mul_f32 v[52:53], v[56:57], v[52:53]
	v_fma_f32 v0, -v3, v74, 1.0
	v_lshlrev_b32_e32 v57, 16, v59
	v_lshlrev_b32_e32 v56, 16, v58
	v_fmac_f32_e32 v74, v0, v74
	v_div_scale_f32 v0, vcc, 1.0, v63, 1.0
	v_pk_mul_f32 v[56:57], v[64:65], v[56:57]
	v_mul_f32_e32 v64, v0, v74
	v_fma_f32 v65, -v3, v64, v0
	v_fmac_f32_e32 v64, v65, v74
	v_fma_f32 v0, -v3, v64, v0
	v_div_scale_f32 v3, s[0:1], v62, v62, 1.0
	v_rcp_f32_e32 v65, v3
	v_div_fmas_f32 v0, v0, v74, v64
	v_div_fixup_f32 v63, v0, v63, 1.0
	v_lshlrev_b32_e32 v67, 16, v55
	v_fma_f32 v0, -v3, v65, 1.0
	v_fmac_f32_e32 v65, v0, v65
	v_div_scale_f32 v0, vcc, 1.0, v62, 1.0
	v_lshlrev_b32_e32 v66, 16, v54
	v_mul_f32_e32 v64, v0, v65
	v_pk_mul_f32 v[56:57], v[56:57], v[66:67]
	v_fma_f32 v66, -v3, v64, v0
	v_fmac_f32_e32 v64, v66, v65
	v_fma_f32 v0, -v3, v64, v0
	v_div_fmas_f32 v0, v0, v65, v64
	v_and_b32_e32 v59, 0xffff0000, v59
	v_and_b32_e32 v58, 0xffff0000, v58
	v_div_fixup_f32 v62, v0, v62, 1.0
	v_and_b32_e32 v55, 0xffff0000, v55
	v_and_b32_e32 v54, 0xffff0000, v54
	v_pk_mul_f32 v[58:59], v[62:63], v[58:59]
	s_nop 0
	v_pk_mul_f32 v[54:55], v[58:59], v[54:55]
	v_bfe_u32 v58, v53, 16, 1
	v_bfe_u32 v0, v55, 16, 1
	v_bfe_u32 v3, v54, 16, 1
	v_bfe_u32 v59, v52, 16, 1
	v_add3_u32 v52, v52, v59, s24
	v_add3_u32 v53, v53, v58, s24
	v_add3_u32 v3, v54, v3, s24
	v_add3_u32 v0, v55, v0, s24
	v_bfe_u32 v54, v68, 16, 1
	v_bfe_u32 v55, v69, 16, 1
	v_bfe_u32 v58, v56, 16, 1
	v_bfe_u32 v59, v57, 16, 1
	v_add3_u32 v57, v57, v59, s24
	v_add3_u32 v56, v56, v58, s24
	v_add3_u32 v55, v69, v55, s24
	v_add3_u32 v54, v68, v54, s24
	v_lshrrev_b32_e32 v58, 16, v54
	v_lshrrev_b32_e32 v59, 16, v55
	v_lshrrev_b32_e32 v54, 16, v56
	v_lshrrev_b32_e32 v55, 16, v57
	v_and_or_b32 v55, v0, s22, v55
	v_and_or_b32 v54, v3, s22, v54
	v_and_or_b32 v53, v53, s22, v59
	v_and_or_b32 v52, v52, s22, v58
	global_store_dwordx4 v[60:61], v[70:73], off
	global_store_dwordx4 v[60:61], v[52:55], off offset:16
	ds_write2_b32 v155, v36, v40 offset1:16
	ds_write2_b32 v155, v37, v41 offset0:68 offset1:84
	ds_write2_b32 v155, v38, v42 offset0:136 offset1:152
	ds_write2_b32 v155, v39, v43 offset0:204 offset1:220
	ds_write2_b32 v155, v28, v32 offset0:32 offset1:48
	ds_write2_b32 v155, v29, v33 offset0:100 offset1:116
	ds_write2_b32 v155, v30, v34 offset0:168 offset1:184
	ds_write2_b32 v155, v31, v35 offset0:236 offset1:252
	s_waitcnt lgkmcnt(0)
	v_or_b32_e32 v28, 0x60, v2
	ds_read_b128 v[38:41], v154
	ds_read_b128 v[52:55], v154 offset:16
	ds_read_b128 v[56:59], v154 offset:32
	ds_read_b128 v[60:63], v154 offset:48
	v_mad_i64_i32 v[30:31], s[0:1], v28, s4, v[148:149]
	global_load_dwordx4 v[64:67], v[30:31], off
	v_ashrrev_i32_e32 v29, 31, v28
	v_lshlrev_b64 v[28:29], 12, v[28:29]
	v_lshl_add_u64 v[36:37], v[140:141], 0, v[28:29]
	global_load_dwordx4 v[68:71], v[36:37], off
	global_load_dwordx4 v[32:35], v[30:31], off offset:16
	s_nop 0
	global_load_dwordx4 v[28:31], v[36:37], off offset:16
	s_waitcnt lgkmcnt(3)
	v_add_f32_e32 v0, v48, v38
	v_mul_f32_e32 v0, 0xbfb8aa3b, v0
	v_exp_f32_e32 v72, v0
	v_add_f32_e32 v0, v49, v39
	v_mul_f32_e32 v0, 0xbfb8aa3b, v0
	v_exp_f32_e32 v74, v0
	v_add_f32_e32 v0, v50, v40
	v_mul_f32_e32 v0, 0xbfb8aa3b, v0
	v_exp_f32_e32 v73, v0
	v_add_f32_e32 v0, v51, v41
	v_mul_f32_e32 v0, 0xbfb8aa3b, v0
	v_exp_f32_e32 v75, v0
	s_waitcnt lgkmcnt(2)
	v_add_f32_e32 v0, v44, v52
	v_mul_f32_e32 v0, 0xbfb8aa3b, v0
	v_exp_f32_e32 v76, v0
	v_add_f32_e32 v0, v45, v53
	v_mul_f32_e32 v0, 0xbfb8aa3b, v0
	v_exp_f32_e32 v78, v0
	v_add_f32_e32 v0, v46, v54
	v_mul_f32_e32 v0, 0xbfb8aa3b, v0
	v_exp_f32_e32 v77, v0
	v_add_f32_e32 v0, v47, v55
	v_mul_f32_e32 v0, 0xbfb8aa3b, v0
	v_exp_f32_e32 v79, v0
	s_waitcnt lgkmcnt(1)
	v_add_f32_e32 v0, v24, v56
	v_mul_f32_e32 v0, 0xbfb8aa3b, v0
	v_exp_f32_e32 v52, v0
	v_add_f32_e32 v0, v25, v57
	v_mul_f32_e32 v0, 0xbfb8aa3b, v0
	v_exp_f32_e32 v42, v0
	v_add_f32_e32 v0, v26, v58
	v_mul_f32_e32 v0, 0xbfb8aa3b, v0
	v_exp_f32_e32 v53, v0
	v_add_f32_e32 v0, v27, v59
	v_mul_f32_e32 v0, 0xbfb8aa3b, v0
	v_exp_f32_e32 v43, v0
	s_waitcnt lgkmcnt(0)
	v_add_f32_e32 v0, v20, v60
	v_mul_f32_e32 v0, 0xbfb8aa3b, v0
	v_exp_f32_e32 v40, v0
	v_add_f32_e32 v0, v21, v61
	v_mul_f32_e32 v0, 0xbfb8aa3b, v0
	v_exp_f32_e32 v38, v0
	v_add_f32_e32 v0, v22, v62
	v_mul_f32_e32 v0, 0xbfb8aa3b, v0
	v_exp_f32_e32 v41, v0
	v_add_f32_e32 v0, v23, v63
	v_mul_f32_e32 v0, 0xbfb8aa3b, v0
	v_pk_add_f32 v[60:61], v[72:73], 1.0 op_sel_hi:[1,0]
	v_exp_f32_e32 v39, v0
	v_pk_add_f32 v[52:53], v[52:53], 1.0 op_sel_hi:[1,0]
	v_pk_add_f32 v[42:43], v[42:43], 1.0 op_sel_hi:[1,0]
	v_pk_add_f32 v[40:41], v[40:41], 1.0 op_sel_hi:[1,0]
	v_pk_add_f32 v[38:39], v[38:39], 1.0 op_sel_hi:[1,0]
	v_or_b32_e32 v2, 0x70, v2
	s_waitcnt vmcnt(3)
	v_lshlrev_b32_e32 v54, 16, v64
	v_and_b32_e32 v56, 0xffff0000, v64
	v_lshlrev_b32_e32 v55, 16, v65
	v_and_b32_e32 v57, 0xffff0000, v65
	s_waitcnt vmcnt(2)
; DI float sigm(float x) { return 1.f / (1.f + __expf(-x)); }
; DI void phase_glu(const Params& p) {
;     ...
;     float b[16]; load16_f(p.s5_glu_b + bcol + ((tid >> 6) & 3) * 64 + (tid & 3) * 16, b);
;     EPI256_BEGIN
;       float y[16], g[16]; load16_bf(ys + (size_t)row * LDP + col, y); bft* gp = G0 + (size_t)row * 2048 + col; load16_bf(gp, g);
; #pragma unroll
;       for (int i = 0; i < 16; ++i) v[i] = y[i] * sigm(v[i] + b[i]) * g[i];
;       store16_bf(gp, v);
	v_lshlrev_b32_e32 v58, 16, v68
	v_and_b32_e32 v62, 0xffff0000, v68
	v_rcp_f32_e32 v61, v61
	v_lshlrev_b32_e32 v59, 16, v69
	v_pk_add_f32 v[64:65], v[74:75], 1.0 op_sel_hi:[1,0]
	v_rcp_f32_e32 v60, v60
	s_nop 0
	v_pk_mul_f32 v[54:55], v[60:61], v[54:55]
	v_and_b32_e32 v63, 0xffff0000, v69
	v_pk_mul_f32 v[54:55], v[54:55], v[58:59]
	v_rcp_f32_e32 v59, v65
	v_rcp_f32_e32 v58, v64
	v_pk_add_f32 v[64:65], v[76:77], 1.0 op_sel_hi:[1,0]
	v_pk_mul_f32 v[56:57], v[58:59], v[56:57]
	v_pk_mul_f32 v[56:57], v[56:57], v[62:63]
	v_lshlrev_b32_e32 v58, 16, v66
	v_and_b32_e32 v60, 0xffff0000, v66
	v_lshlrev_b32_e32 v62, 16, v70
	v_and_b32_e32 v66, 0xffff0000, v70
	v_rcp_f32_e32 v65, v65
	v_lshlrev_b32_e32 v59, 16, v67
	v_pk_add_f32 v[68:69], v[78:79], 1.0 op_sel_hi:[1,0]
	v_rcp_f32_e32 v64, v64
	v_lshlrev_b32_e32 v63, 16, v71
	v_pk_mul_f32 v[58:59], v[64:65], v[58:59]
	v_pk_mul_f32 v[58:59], v[58:59], v[62:63]
	v_rcp_f32_e32 v63, v69
	v_and_b32_e32 v61, 0xffff0000, v67
	v_rcp_f32_e32 v62, v68
	v_and_b32_e32 v67, 0xffff0000, v71
	v_pk_mul_f32 v[60:61], v[62:63], v[60:61]
	v_bfe_u32 v62, v57, 16, 1
	v_pk_mul_f32 v[60:61], v[60:61], v[66:67]
	v_bfe_u32 v63, v56, 16, 1
	v_bfe_u32 v0, v61, 16, 1
	v_bfe_u32 v3, v60, 16, 1
	v_add3_u32 v0, v61, v0, s24
	v_bfe_u32 v61, v59, 16, 1
	v_add3_u32 v62, v57, v62, s24
	v_add3_u32 v3, v60, v3, s24
	v_bfe_u32 v57, v55, 16, 1
	v_bfe_u32 v60, v58, 16, 1
	v_add3_u32 v59, v59, v61, s24
	v_add3_u32 v63, v56, v63, s24
	v_bfe_u32 v56, v54, 16, 1
	v_add3_u32 v58, v58, v60, s24
	v_add3_u32 v55, v55, v57, s24
	v_lshrrev_b32_e32 v57, 16, v59
	v_add3_u32 v54, v54, v56, s24
	v_lshrrev_b32_e32 v56, 16, v58
	v_and_or_b32 v57, v0, s22, v57
	v_and_or_b32 v56, v3, s22, v56
	v_lshrrev_b32_e32 v55, 16, v55
	v_and_or_b32 v55, v62, s22, v55
	v_lshrrev_b32_e32 v54, 16, v54
	v_and_or_b32 v54, v63, s22, v54
	v_rcp_f32_e32 v53, v53
	s_waitcnt vmcnt(1)
	v_lshlrev_b32_e32 v59, 16, v33
	v_rcp_f32_e32 v52, v52
	v_lshlrev_b32_e32 v58, 16, v32
	v_pk_mul_f32 v[52:53], v[52:53], v[58:59]
	v_rcp_f32_e32 v43, v43
	s_waitcnt vmcnt(0)
	v_lshlrev_b32_e32 v61, 16, v29
	v_lshlrev_b32_e32 v60, 16, v28
	v_pk_mul_f32 v[52:53], v[52:53], v[60:61]
	v_rcp_f32_e32 v42, v42
	v_and_b32_e32 v33, 0xffff0000, v33
	v_and_b32_e32 v32, 0xffff0000, v32
	v_and_b32_e32 v29, 0xffff0000, v29
	v_rcp_f32_e32 v41, v41
	v_and_b32_e32 v28, 0xffff0000, v28
	v_div_scale_f32 v3, s[0:1], v39, v39, 1.0
	v_rcp_f32_e32 v58, v3
	v_pk_mul_f32 v[32:33], v[42:43], v[32:33]
	v_rcp_f32_e32 v40, v40
	v_pk_mul_f32 v[28:29], v[32:33], v[28:29]
	v_fma_f32 v0, -v3, v58, 1.0
	v_lshlrev_b32_e32 v33, 16, v35
	v_lshlrev_b32_e32 v32, 16, v34
	v_fmac_f32_e32 v58, v0, v58
	v_div_scale_f32 v0, vcc, 1.0, v39, 1.0
	v_pk_mul_f32 v[32:33], v[40:41], v[32:33]
	v_mul_f32_e32 v40, v0, v58
	v_fma_f32 v41, -v3, v40, v0
	v_fmac_f32_e32 v40, v41, v58
	v_fma_f32 v0, -v3, v40, v0
	v_div_scale_f32 v3, s[0:1], v38, v38, 1.0
	v_rcp_f32_e32 v41, v3
	v_div_fmas_f32 v0, v0, v58, v40
	v_div_fixup_f32 v39, v0, v39, 1.0
	v_lshlrev_b32_e32 v43, 16, v31
	v_fma_f32 v0, -v3, v41, 1.0
	v_fmac_f32_e32 v41, v0, v41
	v_div_scale_f32 v0, vcc, 1.0, v38, 1.0
	v_lshlrev_b32_e32 v42, 16, v30
	v_mul_f32_e32 v40, v0, v41
	v_pk_mul_f32 v[32:33], v[32:33], v[42:43]
	v_fma_f32 v42, -v3, v40, v0
	v_fmac_f32_e32 v40, v42, v41
	v_fma_f32 v0, -v3, v40, v0
	v_div_fmas_f32 v0, v0, v41, v40
	v_and_b32_e32 v35, 0xffff0000, v35
	v_and_b32_e32 v34, 0xffff0000, v34
	v_div_fixup_f32 v38, v0, v38, 1.0
	v_and_b32_e32 v31, 0xffff0000, v31
	v_and_b32_e32 v30, 0xffff0000, v30
	v_pk_mul_f32 v[34:35], v[38:39], v[34:35]
	s_nop 0
	v_pk_mul_f32 v[30:31], v[34:35], v[30:31]
	v_bfe_u32 v34, v29, 16, 1
	v_bfe_u32 v0, v31, 16, 1
	v_bfe_u32 v3, v30, 16, 1
	v_bfe_u32 v35, v28, 16, 1
	v_add3_u32 v28, v28, v35, s24
	v_add3_u32 v29, v29, v34, s24
	v_add3_u32 v3, v30, v3, s24
	v_add3_u32 v0, v31, v0, s24
	v_bfe_u32 v30, v52, 16, 1
	v_bfe_u32 v31, v53, 16, 1
	v_bfe_u32 v34, v32, 16, 1
	v_bfe_u32 v35, v33, 16, 1
	v_add3_u32 v33, v33, v35, s24
	v_add3_u32 v32, v32, v34, s24
	v_add3_u32 v31, v53, v31, s24
	v_add3_u32 v30, v52, v30, s24
	v_lshrrev_b32_e32 v34, 16, v30
	v_lshrrev_b32_e32 v35, 16, v31
	v_lshrrev_b32_e32 v30, 16, v32
	v_lshrrev_b32_e32 v31, 16, v33
	v_and_or_b32 v31, v0, s22, v31
	v_and_or_b32 v30, v3, s22, v30
	v_and_or_b32 v29, v29, s22, v35
	v_and_or_b32 v28, v28, s22, v34
	global_store_dwordx4 v[36:37], v[54:57], off
	global_store_dwordx4 v[36:37], v[28:31], off offset:16
	ds_write2_b32 v155, v12, v16 offset1:16
	ds_write2_b32 v155, v13, v17 offset0:68 offset1:84
	ds_write2_b32 v155, v14, v18 offset0:136 offset1:152
	ds_write2_b32 v155, v15, v19 offset0:204 offset1:220
	ds_write2_b32 v155, v4, v8 offset0:32 offset1:48
	ds_write2_b32 v155, v5, v9 offset0:100 offset1:116
	ds_write2_b32 v155, v6, v10 offset0:168 offset1:184
	ds_write2_b32 v155, v7, v11 offset0:236 offset1:252
	s_waitcnt lgkmcnt(0)
	ds_read_b128 v[12:15], v154
	ds_read_b128 v[16:19], v154 offset:16
	ds_read_b128 v[28:31], v154 offset:32
	ds_read_b128 v[32:35], v154 offset:48
	v_mad_i64_i32 v[4:5], s[0:1], v2, s4, v[148:149]
	global_load_dwordx4 v[36:39], v[4:5], off
	v_ashrrev_i32_e32 v3, 31, v2
	v_lshlrev_b64 v[2:3], 12, v[2:3]
	v_lshl_add_u64 v[10:11], v[140:141], 0, v[2:3]
	global_load_dwordx4 v[40:43], v[10:11], off
	global_load_dwordx4 v[6:9], v[4:5], off offset:16
	s_nop 0
	global_load_dwordx4 v[2:5], v[10:11], off offset:16
	s_waitcnt lgkmcnt(3)
	v_add_f32_e32 v0, v48, v12
	v_mul_f32_e32 v0, 0xbfb8aa3b, v0
	v_exp_f32_e32 v48, v0
	v_add_f32_e32 v0, v49, v13
	v_mul_f32_e32 v0, 0xbfb8aa3b, v0
	v_exp_f32_e32 v52, v0
	v_add_f32_e32 v0, v50, v14
	v_mul_f32_e32 v0, 0xbfb8aa3b, v0
	v_exp_f32_e32 v49, v0
	v_add_f32_e32 v0, v51, v15
	v_mul_f32_e32 v0, 0xbfb8aa3b, v0
	v_exp_f32_e32 v53, v0
	s_waitcnt lgkmcnt(2)
; DI float sigm(float x) { return 1.f / (1.f + __expf(-x)); }
; DI void phase_glu(const Params& p) {
;     ...
;     float b[16]; load16_f(p.s5_glu_b + bcol + ((tid >> 6) & 3) * 64 + (tid & 3) * 16, b);
;     EPI256_BEGIN
;       float y[16], g[16]; load16_bf(ys + (size_t)row * LDP + col, y); bft* gp = G0 + (size_t)row * 2048 + col; load16_bf(gp, g);
; #pragma unroll
;       for (int i = 0; i < 16; ++i) v[i] = y[i] * sigm(v[i] + b[i]) * g[i];
;       store16_bf(gp, v);
;     EPI_END
	v_add_f32_e32 v0, v44, v16
	v_mul_f32_e32 v0, 0xbfb8aa3b, v0
	v_exp_f32_e32 v44, v0
	v_add_f32_e32 v0, v45, v17
	v_mul_f32_e32 v0, 0xbfb8aa3b, v0
	v_exp_f32_e32 v50, v0
	v_add_f32_e32 v0, v46, v18
	v_mul_f32_e32 v0, 0xbfb8aa3b, v0
	v_exp_f32_e32 v45, v0
	v_add_f32_e32 v0, v47, v19
	v_mul_f32_e32 v0, 0xbfb8aa3b, v0
	v_exp_f32_e32 v51, v0
	s_waitcnt lgkmcnt(1)
	v_add_f32_e32 v0, v24, v28
	v_mul_f32_e32 v0, 0xbfb8aa3b, v0
	v_exp_f32_e32 v18, v0
	v_add_f32_e32 v0, v25, v29
	v_mul_f32_e32 v0, 0xbfb8aa3b, v0
	v_exp_f32_e32 v16, v0
	v_add_f32_e32 v0, v26, v30
	v_mul_f32_e32 v0, 0xbfb8aa3b, v0
	v_exp_f32_e32 v19, v0
	v_add_f32_e32 v0, v27, v31
	v_mul_f32_e32 v0, 0xbfb8aa3b, v0
	v_exp_f32_e32 v17, v0
	s_waitcnt lgkmcnt(0)
	v_add_f32_e32 v0, v20, v32
	v_mul_f32_e32 v0, 0xbfb8aa3b, v0
	v_exp_f32_e32 v14, v0
	v_add_f32_e32 v0, v21, v33
	v_mul_f32_e32 v0, 0xbfb8aa3b, v0
	v_exp_f32_e32 v12, v0
	v_add_f32_e32 v0, v22, v34
	v_mul_f32_e32 v0, 0xbfb8aa3b, v0
	v_exp_f32_e32 v15, v0
	v_add_f32_e32 v0, v23, v35
	v_mul_f32_e32 v0, 0xbfb8aa3b, v0
	v_pk_add_f32 v[26:27], v[48:49], 1.0 op_sel_hi:[1,0]
	v_exp_f32_e32 v13, v0
	v_pk_add_f32 v[18:19], v[18:19], 1.0 op_sel_hi:[1,0]
	v_pk_add_f32 v[16:17], v[16:17], 1.0 op_sel_hi:[1,0]
	v_pk_add_f32 v[14:15], v[14:15], 1.0 op_sel_hi:[1,0]
	v_rcp_f32_e32 v27, v27
	v_pk_add_f32 v[12:13], v[12:13], 1.0 op_sel_hi:[1,0]
	v_pk_add_f32 v[30:31], v[52:53], 1.0 op_sel_hi:[1,0]
	s_waitcnt vmcnt(3)
	v_lshlrev_b32_e32 v21, 16, v37
	v_lshlrev_b32_e32 v20, 16, v36
	v_rcp_f32_e32 v26, v26
	s_waitcnt vmcnt(2)
	v_lshlrev_b32_e32 v25, 16, v41
	v_lshlrev_b32_e32 v24, 16, v40
	v_pk_mul_f32 v[20:21], v[26:27], v[20:21]
	v_pk_mul_f32 v[20:21], v[20:21], v[24:25]
	v_rcp_f32_e32 v25, v31
	v_rcp_f32_e32 v24, v30
	v_pk_add_f32 v[30:31], v[44:45], 1.0 op_sel_hi:[1,0]
	v_and_b32_e32 v22, 0xffff0000, v36
	v_and_b32_e32 v23, 0xffff0000, v37
	v_and_b32_e32 v29, 0xffff0000, v41
	v_and_b32_e32 v28, 0xffff0000, v40
	v_rcp_f32_e32 v31, v31
	v_pk_mul_f32 v[22:23], v[24:25], v[22:23]
	v_pk_add_f32 v[34:35], v[50:51], 1.0 op_sel_hi:[1,0]
	v_lshlrev_b32_e32 v25, 16, v39
	v_lshlrev_b32_e32 v24, 16, v38
	v_rcp_f32_e32 v30, v30
	v_pk_mul_f32 v[22:23], v[22:23], v[28:29]
	v_lshlrev_b32_e32 v29, 16, v43
	v_lshlrev_b32_e32 v28, 16, v42
	v_pk_mul_f32 v[24:25], v[30:31], v[24:25]
	v_pk_mul_f32 v[24:25], v[24:25], v[28:29]
	v_rcp_f32_e32 v29, v35
	v_and_b32_e32 v27, 0xffff0000, v39
	v_and_b32_e32 v26, 0xffff0000, v38
	v_rcp_f32_e32 v28, v34
	v_and_b32_e32 v33, 0xffff0000, v43
	v_and_b32_e32 v32, 0xffff0000, v42
	v_pk_mul_f32 v[26:27], v[28:29], v[26:27]
	v_bfe_u32 v30, v22, 16, 1
	v_pk_mul_f32 v[26:27], v[26:27], v[32:33]
	v_bfe_u32 v29, v23, 16, 1
	v_bfe_u32 v28, v26, 16, 1
	v_add3_u32 v30, v22, v30, s24
	v_add3_u32 v22, v26, v28, s24
	v_bfe_u32 v28, v25, 16, 1
	v_bfe_u32 v0, v27, 16, 1
	v_add3_u32 v29, v23, v29, s24
	v_bfe_u32 v23, v20, 16, 1
	v_add3_u32 v25, v25, v28, s24
	v_add3_u32 v0, v27, v0, s24
	v_add3_u32 v20, v20, v23, s24
	v_lshrrev_b32_e32 v23, 16, v25
	v_and_or_b32 v23, v0, s22, v23
	v_bfe_u32 v26, v21, 16, 1
	v_add3_u32 v21, v21, v26, s24
	v_lshrrev_b32_e32 v21, 16, v21
	v_and_or_b32 v21, v29, s22, v21
	v_lshrrev_b32_e32 v20, 16, v20
	v_and_or_b32 v20, v30, s22, v20
	v_rcp_f32_e32 v19, v19
	v_bfe_u32 v27, v24, 16, 1
	v_add3_u32 v24, v24, v27, s24
	v_lshrrev_b32_e32 v24, 16, v24
	v_rcp_f32_e32 v18, v18
	v_and_or_b32 v22, v22, s22, v24
	s_waitcnt vmcnt(1)
	v_lshlrev_b32_e32 v25, 16, v7
	v_lshlrev_b32_e32 v24, 16, v6
	v_pk_mul_f32 v[18:19], v[18:19], v[24:25]
	s_waitcnt vmcnt(0)
	v_lshlrev_b32_e32 v27, 16, v3
	v_lshlrev_b32_e32 v26, 16, v2
	v_pk_mul_f32 v[18:19], v[18:19], v[26:27]
	v_rcp_f32_e32 v17, v17
	v_rcp_f32_e32 v16, v16
	v_and_b32_e32 v7, 0xffff0000, v7
	v_and_b32_e32 v6, 0xffff0000, v6
	v_and_b32_e32 v3, 0xffff0000, v3
	v_rcp_f32_e32 v15, v15
	v_and_b32_e32 v2, 0xffff0000, v2
	v_pk_mul_f32 v[6:7], v[16:17], v[6:7]
	v_rcp_f32_e32 v14, v14
	v_pk_mul_f32 v[2:3], v[6:7], v[2:3]
	v_lshlrev_b32_e32 v7, 16, v9
	v_lshlrev_b32_e32 v6, 16, v8
	v_pk_mul_f32 v[6:7], v[14:15], v[6:7]
	v_lshlrev_b32_e32 v17, 16, v5
	v_lshlrev_b32_e32 v16, 16, v4
	v_div_scale_f32 v15, s[0:1], v12, v12, 1.0
	v_pk_mul_f32 v[6:7], v[6:7], v[16:17]
	v_rcp_f32_e32 v16, v15
	v_rcp_f32_e32 v13, v13
	v_fma_f32 v0, -v15, v16, 1.0
	v_fmac_f32_e32 v16, v0, v16
	v_div_scale_f32 v0, vcc, 1.0, v12, 1.0
	v_mul_f32_e32 v14, v0, v16
	v_fma_f32 v17, -v15, v14, v0
	v_fmac_f32_e32 v14, v17, v16
	v_fma_f32 v0, -v15, v14, v0
	v_div_fmas_f32 v0, v0, v16, v14
	v_and_b32_e32 v9, 0xffff0000, v9
	v_and_b32_e32 v8, 0xffff0000, v8
	v_div_fixup_f32 v12, v0, v12, 1.0
	v_and_b32_e32 v5, 0xffff0000, v5
	v_and_b32_e32 v4, 0xffff0000, v4
	v_pk_mul_f32 v[8:9], v[12:13], v[8:9]
	v_bfe_u32 v12, v2, 16, 1
	v_pk_mul_f32 v[4:5], v[8:9], v[4:5]
	v_bfe_u32 v9, v3, 16, 1
	v_bfe_u32 v0, v5, 16, 1
	v_bfe_u32 v8, v4, 16, 1
	v_add3_u32 v2, v2, v12, s24
	v_add3_u32 v3, v3, v9, s24
	v_add3_u32 v4, v4, v8, s24
	v_add3_u32 v0, v5, v0, s24
	v_bfe_u32 v5, v18, 16, 1
	v_bfe_u32 v8, v19, 16, 1
	v_bfe_u32 v9, v6, 16, 1
	v_bfe_u32 v12, v7, 16, 1
	v_add3_u32 v7, v7, v12, s24
	v_add3_u32 v6, v6, v9, s24
	v_add3_u32 v8, v19, v8, s24
	v_add3_u32 v5, v18, v5, s24
	v_lshrrev_b32_e32 v9, 16, v5
	v_lshrrev_b32_e32 v8, 16, v8
	v_lshrrev_b32_e32 v6, 16, v6
	v_lshrrev_b32_e32 v5, 16, v7
	s_mov_b64 s[0:1], 0
	v_and_or_b32 v5, v0, s22, v5
	v_and_or_b32 v4, v4, s22, v6
	v_and_or_b32 v3, v3, s22, v8
	v_and_or_b32 v2, v2, s22, v9
	global_store_dwordx4 v[10:11], v[20:23], off
	global_store_dwordx4 v[10:11], v[2:5], off offset:16

; DI float sigm(float x) { return 1.f / (1.f + __expf(-x)); }
; DI void phase_ple(const Params& p, int layer, const bft* hbin, bft* hbout, int ldo, float* ssq) {
;     ...
;     EPI_BEGIN
;       float v2[16]; epi_stage(tid, acc2[m], v2); float h[16]; float* hp = p.out + (size_t)row * 1024 + col; load16_f(hp, h); float ss = 0.f;
; #pragma unroll
;       for (int i = 0; i < 16; ++i) { h[i] += sigm(v[i]) * v2[i]; ss += h[i] * h[i]; }
;       store16_f(hp, h); if (hbout) store16_bf(hbout + (size_t)row * ldo + col, h);
;       ss += __shfl_xor(ss, 1); ss += __shfl_xor(ss, 2);
;       if ((lane & 3) == 0) atomicAdd(ssq + row, ss);
.LBB0_1046:
	v_lshrrev_b32_e32 v129, 6, v143
	s_movk_i32 s0, 0x1100
	v_lshrrev_b32_e32 v130, 2, v143
	v_mul_lo_u32 v129, v129, s0
	v_and_b32_e32 v130, 12, v130
	v_add_u32_e32 v129, s39, v129
	v_lshlrev_b32_e32 v131, 2, v148
	v_mul_u32_u24_e32 v130, 0x110, v130
	v_add3_u32 v140, v129, v131, v130
	v_bfe_u32 v130, v143, 2, 4
	v_and_b32_e32 v132, 48, v144
	v_mul_u32_u24_e32 v131, 0x110, v130
	v_lshlrev_b32_e32 v132, 2, v132
	v_add3_u32 v141, v129, v131, v132
	v_ashrrev_i32_e32 v129, 1, v143
	v_and_b32_e32 v129, 0xffffffc0, v129
	s_waitcnt vmcnt(0)
	s_barrier
	v_add_u32_e32 v129, s27, v129
	v_and_b32_e32 v138, 3, v143
	ds_write2_b32 v140, v92, v88 offset1:16
	ds_write2_b32 v140, v93, v89 offset0:68 offset1:84
	ds_write2_b32 v140, v94, v90 offset0:136 offset1:152
	ds_write2_b32 v140, v95, v91 offset0:204 offset1:220
	ds_write2_b32 v140, v84, v80 offset0:32 offset1:48
	ds_write2_b32 v140, v85, v81 offset0:100 offset1:116
	ds_write2_b32 v140, v86, v82 offset0:168 offset1:184
	ds_write2_b32 v140, v87, v83 offset0:236 offset1:252
	v_and_b32_e32 v128, 64, v143
	v_or_b32_e32 v136, v129, v130
	v_lshlrev_b32_e32 v129, 4, v138
	s_waitcnt lgkmcnt(0)
	v_or3_b32 v139, v129, v128, s26
	ds_read_b128 v[84:87], v141
	ds_read_b128 v[144:147], v141 offset:16
	ds_read_b128 v[128:131], v141 offset:32
	ds_read_b128 v[92:95], v141 offset:48
	v_ashrrev_i32_e32 v137, 31, v136
	v_lshlrev_b32_e32 v132, 1, v139
	ds_write2_b32 v140, v124, v120 offset1:16
	ds_write2_b32 v140, v125, v121 offset0:68 offset1:84
	ds_write2_b32 v140, v126, v122 offset0:136 offset1:152
	ds_write2_b32 v140, v127, v123 offset0:204 offset1:220
	ds_write2_b32 v140, v116, v112 offset0:32 offset1:48
	ds_write2_b32 v140, v117, v113 offset0:100 offset1:116
	ds_write2_b32 v140, v118, v114 offset0:168 offset1:184
	ds_write2_b32 v140, v119, v115 offset0:236 offset1:252
	v_lshlrev_b64 v[88:89], 12, v[136:137]
	v_lshl_add_u64 v[134:135], s[16:17], 0, v[132:133]
	s_waitcnt lgkmcnt(0)
	v_lshl_add_u64 v[88:89], s[12:13], 0, v[88:89]
	v_lshlrev_b32_e32 v132, 2, v139
	ds_read_b128 v[120:123], v141
	ds_read_b128 v[148:151], v141 offset:16
	ds_read_b128 v[112:115], v141 offset:32
	ds_read_b128 v[80:83], v141 offset:48
	v_lshl_add_u64 v[124:125], v[88:89], 0, v[132:133]
	global_load_dwordx4 v[152:155], v[124:125], off
	global_load_dwordx4 v[156:159], v[124:125], off offset:16
	s_waitcnt lgkmcnt(14)
	v_mul_f32_e32 v84, 0xbfb8aa3b, v84
	v_mul_f32_e32 v85, 0xbfb8aa3b, v85
	v_exp_f32_e32 v84, v84
	v_exp_f32_e32 v85, v85
	v_cmp_eq_u32_e64 s[8:9], 0, v138
	v_mul_f32_e32 v86, 0xbfb8aa3b, v86
	v_mul_f32_e32 v87, 0xbfb8aa3b, v87
	v_pk_add_f32 v[84:85], v[84:85], 1.0 op_sel_hi:[1,0]
	v_exp_f32_e32 v86, v86
	v_exp_f32_e32 v87, v87
	global_load_dwordx4 v[88:91], v[124:125], off offset:48
	global_load_dwordx4 v[116:119], v[124:125], off offset:32
	s_waitcnt lgkmcnt(13)
	v_mul_f32_e32 v128, 0xbfb8aa3b, v128
	v_rcp_f32_e32 v85, v85
	v_pk_add_f32 v[86:87], v[86:87], 1.0 op_sel_hi:[1,0]
	v_rcp_f32_e32 v84, v84
	v_mul_f32_e32 v129, 0xbfb8aa3b, v129
	v_exp_f32_e32 v128, v128
	v_exp_f32_e32 v129, v129
	v_mul_f32_e32 v130, 0xbfb8aa3b, v130
	v_mul_f32_e32 v131, 0xbfb8aa3b, v131
	v_exp_f32_e32 v130, v130
	v_pk_add_f32 v[128:129], v[128:129], 1.0 op_sel_hi:[1,0]
	v_exp_f32_e32 v131, v131
	s_waitcnt lgkmcnt(12)
	v_mul_f32_e32 v92, 0xbfb8aa3b, v92
	v_mul_f32_e32 v93, 0xbfb8aa3b, v93
	v_exp_f32_e32 v92, v92
	v_pk_add_f32 v[130:131], v[130:131], 1.0 op_sel_hi:[1,0]
	v_exp_f32_e32 v93, v93
	v_mul_f32_e32 v94, 0xbfb8aa3b, v94
	v_mul_f32_e32 v95, 0xbfb8aa3b, v95
	v_exp_f32_e32 v94, v94
	v_pk_add_f32 v[92:93], v[92:93], 1.0 op_sel_hi:[1,0]
	v_exp_f32_e32 v95, v95
	s_waitcnt vmcnt(3) lgkmcnt(3)
	v_pk_fma_f32 v[84:85], v[84:85], v[120:121], v[152:153]
	v_rcp_f32_e32 v87, v87
	v_mul_f32_e32 v120, 0xbfb8aa3b, v144
	v_mul_f32_e32 v121, 0xbfb8aa3b, v145
	v_exp_f32_e32 v120, v120
	v_exp_f32_e32 v121, v121
	v_rcp_f32_e32 v86, v86
	v_pk_add_f32 v[120:121], v[120:121], 1.0 op_sel_hi:[1,0]
	v_pk_fma_f32 v[86:87], v[86:87], v[122:123], v[154:155]
	v_pk_add_f32 v[94:95], v[94:95], 1.0 op_sel_hi:[1,0]
	v_pk_mul_f32 v[126:127], v[84:85], v[84:85]
	v_pk_mul_f32 v[138:139], v[86:87], v[86:87]
	v_rcp_f32_e32 v121, v121
	v_mul_f32_e32 v122, 0xbfb8aa3b, v146
	v_mul_f32_e32 v123, 0xbfb8aa3b, v147
	v_exp_f32_e32 v122, v122
	v_exp_f32_e32 v123, v123
	v_rcp_f32_e32 v120, v120
	v_pk_add_f32 v[122:123], v[122:123], 1.0 op_sel_hi:[1,0]
	s_waitcnt vmcnt(2) lgkmcnt(2)
	v_pk_fma_f32 v[120:121], v[120:121], v[148:149], v[156:157]
	v_pk_mul_f32 v[144:145], v[120:121], v[120:121]
	v_rcp_f32_e32 v123, v123
	v_rcp_f32_e32 v122, v122
	s_nop 0
	v_pk_fma_f32 v[122:123], v[122:123], v[150:151], v[158:159]
	v_rcp_f32_e32 v129, v129
	v_pk_mul_f32 v[146:147], v[122:123], v[122:123]
	v_rcp_f32_e32 v128, v128
	s_waitcnt vmcnt(0) lgkmcnt(1)
	v_pk_fma_f32 v[112:113], v[128:129], v[112:113], v[116:117]
	v_rcp_f32_e32 v129, v131
	v_pk_mul_f32 v[116:117], v[112:113], v[112:113]
	v_rcp_f32_e32 v128, v130
	s_nop 0
	v_pk_fma_f32 v[114:115], v[128:129], v[114:115], v[118:119]
	v_rcp_f32_e32 v93, v93
	v_pk_mul_f32 v[118:119], v[114:115], v[114:115]
	v_div_scale_f32 v129, s[0:1], v95, v95, 1.0
	v_rcp_f32_e32 v130, v129
	v_rcp_f32_e32 v92, v92
	s_waitcnt lgkmcnt(0)
; DI float sigm(float x) { return 1.f / (1.f + __expf(-x)); }
; DI void phase_ple(const Params& p, int layer, const bft* hbin, bft* hbout, int ldo, float* ssq) {
;     ...
;       float v2[16]; epi_stage(tid, acc2[m], v2); float h[16]; float* hp = p.out + (size_t)row * 1024 + col; load16_f(hp, h); float ss = 0.f;
; #pragma unroll
;       for (int i = 0; i < 16; ++i) { h[i] += sigm(v[i]) * v2[i]; ss += h[i] * h[i]; }
;       store16_f(hp, h); if (hbout) store16_bf(hbout + (size_t)row * ldo + col, h);
;       ss += __shfl_xor(ss, 1); ss += __shfl_xor(ss, 2);
;       if ((lane & 3) == 0) atomicAdd(ssq + row, ss);
;     EPI_END
	v_pk_fma_f32 v[80:81], v[92:93], v[80:81], v[88:89]
	v_fma_f32 v92, -v129, v130, 1.0
	v_fmac_f32_e32 v130, v92, v130
	v_div_scale_f32 v92, vcc, 1.0, v95, 1.0
	v_mul_f32_e32 v93, v92, v130
	v_fma_f32 v128, -v129, v93, v92
	v_fmac_f32_e32 v93, v128, v130
	v_div_scale_f32 v128, s[0:1], v94, v94, 1.0
	v_fma_f32 v92, -v129, v93, v92
	v_rcp_f32_e32 v129, v128
	v_div_fmas_f32 v92, v92, v130, v93
	v_div_fixup_f32 v93, v92, v95, 1.0
	v_pk_mul_f32 v[88:89], v[80:81], v[80:81]
	v_fma_f32 v92, -v128, v129, 1.0
	v_fmac_f32_e32 v129, v92, v129
	v_div_scale_f32 v92, vcc, 1.0, v94, 1.0
	v_mul_f32_e32 v95, v92, v129
	v_fma_f32 v130, -v128, v95, v92
	v_fmac_f32_e32 v95, v130, v129
	v_fma_f32 v92, -v128, v95, v92
	v_div_fmas_f32 v92, v92, v129, v95
	v_div_fixup_f32 v92, v92, v94, 1.0
	v_pk_fma_f32 v[82:83], v[92:93], v[82:83], v[90:91]
	v_add_f32_e32 v92, v126, v127
	v_add_f32_e32 v92, v138, v92
	v_add_f32_e32 v92, v139, v92
	v_add_f32_e32 v92, v144, v92
	v_add_f32_e32 v92, v145, v92
	v_add_f32_e32 v92, v146, v92
	v_add_f32_e32 v92, v147, v92
	v_add_f32_e32 v92, v116, v92
	v_add_f32_e32 v92, v117, v92
	v_add_f32_e32 v92, v118, v92
	v_add_f32_e32 v92, v119, v92
	v_add_f32_e32 v88, v88, v92
	v_pk_mul_f32 v[90:91], v[82:83], v[82:83]
	v_add_f32_e32 v88, v89, v88
	v_add_f32_e32 v88, v90, v88
	v_add_f32_e32 v89, v91, v88
	v_bfe_u32 v90, v85, 16, 1
	v_bfe_u32 v91, v123, 16, 1
	v_bfe_u32 v94, v87, 16, 1
	global_store_dwordx4 v[124:125], v[84:87], off
	global_store_dwordx4 v[124:125], v[120:123], off offset:16
	global_store_dwordx4 v[124:125], v[112:115], off offset:32
	global_store_dwordx4 v[124:125], v[80:83], off offset:48
	v_add3_u32 v94, v87, v94, s24
	v_add3_u32 v87, v123, v91, s24
	v_add3_u32 v85, v85, v90, s24
	v_bfe_u32 v90, v86, 16, 1
	v_bfe_u32 v91, v122, 16, 1
	v_bfe_u32 v95, v84, 16, 1
	v_bfe_u32 v116, v120, 16, 1
	v_bfe_u32 v88, v121, 16, 1
	v_add3_u32 v116, v120, v116, s24
	v_add3_u32 v84, v84, v95, s24
	v_add3_u32 v91, v122, v91, s24
	v_add3_u32 v86, v86, v90, s24
	v_add3_u32 v88, v121, v88, s24
	v_lshrrev_b32_e32 v90, 16, v86
	v_lshrrev_b32_e32 v91, 16, v91
	v_lshrrev_b32_e32 v84, 16, v84
	v_lshrrev_b32_e32 v86, 16, v116
	v_and_or_b32 v86, v88, s25, v86
	v_and_or_b32 v84, v85, s25, v84
	v_and_or_b32 v87, v87, s25, v91
	v_and_or_b32 v85, v94, s25, v90
	v_bfe_u32 v88, v81, 16, 1
	v_bfe_u32 v90, v113, 16, 1
	v_bfe_u32 v91, v83, 16, 1
	v_add3_u32 v83, v83, v91, s24
	v_add3_u32 v91, v113, v90, s24
	v_add3_u32 v81, v81, v88, s24
	v_bfe_u32 v88, v114, 16, 1
	v_bfe_u32 v90, v82, 16, 1
	v_bfe_u32 v95, v112, 16, 1
	v_bfe_u32 v113, v80, 16, 1
	v_add3_u32 v82, v82, v90, s24
	v_add3_u32 v88, v114, v88, s24
	v_and_b32_e32 v90, 64, v181
	v_add3_u32 v80, v80, v113, s24
	v_add3_u32 v95, v112, v95, s24
	v_lshrrev_b32_e32 v112, 16, v88
	v_xor_b32_e32 v88, 1, v181
	v_add_u32_e32 v113, 64, v90
	v_cmp_lt_i32_e32 vcc, v88, v113
	v_lshrrev_b32_e32 v80, 16, v80
	v_and_or_b32 v90, v81, s25, v80
	v_cndmask_b32_e32 v88, v181, v88, vcc
	v_lshlrev_b32_e32 v119, 2, v88
	ds_bpermute_b32 v114, v119, v89
	v_xor_b32_e32 v81, 2, v181
	v_cmp_lt_i32_e32 vcc, v81, v113
	v_bfe_u32 v94, v115, 16, 1
	v_mad_i64_i32 v[92:93], s[0:1], v136, s4, v[134:135]
	v_cndmask_b32_e32 v81, v181, v81, vcc
	s_waitcnt lgkmcnt(0)
	v_add_f32_e32 v80, v89, v114
	v_lshlrev_b32_e32 v118, 2, v81
	ds_bpermute_b32 v81, v118, v80
	v_add3_u32 v94, v115, v94, s24
	v_lshrrev_b32_e32 v82, 16, v82
	v_lshrrev_b32_e32 v88, 16, v95
	v_and_or_b32 v88, v91, s25, v88
	v_and_or_b32 v91, v83, s25, v82
	v_and_or_b32 v89, v94, s25, v112
	global_store_dwordx4 v[92:93], v[84:87], off
	global_store_dwordx4 v[92:93], v[88:91], off offset:16
	s_and_saveexec_b64 s[0:1], s[8:9]
	s_cbranch_execz .LBB0_1048
	s_waitcnt lgkmcnt(0)
	v_add_f32_e32 v82, v80, v81
	v_lshl_add_u64 v[80:81], v[136:137], 2, s[18:19]
	global_atomic_add_f32 v[80:81], v82, off
.LBB0_1048:
	s_or_b64 exec, exec, s[0:1]
	ds_write2_b32 v140, v76, v72 offset1:16
	ds_write2_b32 v140, v77, v73 offset0:68 offset1:84
	ds_write2_b32 v140, v78, v74 offset0:136 offset1:152
	ds_write2_b32 v140, v79, v75 offset0:204 offset1:220
	ds_write2_b32 v140, v68, v64 offset0:32 offset1:48
	ds_write2_b32 v140, v69, v65 offset0:100 offset1:116
	ds_write2_b32 v140, v70, v66 offset0:168 offset1:184
	ds_write2_b32 v140, v71, v67 offset0:236 offset1:252
	s_waitcnt lgkmcnt(0)
	v_or_b32_e32 v116, 16, v136
	ds_read_b128 v[120:123], v141
	ds_read_b128 v[112:115], v141 offset:16
	ds_read_b128 v[88:91], v141 offset:32
	ds_read_b128 v[76:79], v141 offset:48
	v_ashrrev_i32_e32 v117, 31, v116
	ds_write2_b32 v140, v108, v104 offset1:16
	ds_write2_b32 v140, v109, v105 offset0:68 offset1:84
	ds_write2_b32 v140, v110, v106 offset0:136 offset1:152
	ds_write2_b32 v140, v111, v107 offset0:204 offset1:220
	ds_write2_b32 v140, v100, v96 offset0:32 offset1:48
	ds_write2_b32 v140, v101, v97 offset0:100 offset1:116
	ds_write2_b32 v140, v102, v98 offset0:168 offset1:184
	ds_write2_b32 v140, v103, v99 offset0:236 offset1:252
	v_lshlrev_b64 v[68:69], 12, v[116:117]
	s_waitcnt lgkmcnt(0)
	v_lshl_add_u64 v[68:69], s[12:13], 0, v[68:69]
	ds_read_b128 v[72:75], v141
	ds_read_b128 v[92:95], v141 offset:16
	s_waitcnt lgkmcnt(14)
	ds_read_b128 v[80:83], v141 offset:32
	ds_read_b128 v[64:67], v141 offset:48
	v_lshl_add_u64 v[104:105], v[68:69], 0, v[132:133]
	global_load_dwordx4 v[68:71], v[104:105], off offset:48
	global_load_dwordx4 v[84:87], v[104:105], off offset:32
	global_load_dwordx4 v[96:99], v[104:105], off offset:16
	global_load_dwordx4 v[100:103], v[104:105], off
	s_waitcnt lgkmcnt(14)
	v_mul_f32_e32 v106, 0xbfb8aa3b, v120
	v_mul_f32_e32 v107, 0xbfb8aa3b, v121
	v_exp_f32_e32 v106, v106
	v_exp_f32_e32 v107, v107
	s_waitcnt lgkmcnt(13)
; DI float sigm(float x) { return 1.f / (1.f + __expf(-x)); }
; DI void phase_ple(const Params& p, int layer, const bft* hbin, bft* hbout, int ldo, float* ssq) {
;     ...
;       float v2[16]; epi_stage(tid, acc2[m], v2); float h[16]; float* hp = p.out + (size_t)row * 1024 + col; load16_f(hp, h); float ss = 0.f;
; #pragma unroll
;       for (int i = 0; i < 16; ++i) { h[i] += sigm(v[i]) * v2[i]; ss += h[i] * h[i]; }
;       store16_f(hp, h); if (hbout) store16_bf(hbout + (size_t)row * ldo + col, h);
;       ss += __shfl_xor(ss, 1); ss += __shfl_xor(ss, 2);
;       if ((lane & 3) == 0) atomicAdd(ssq + row, ss);
	v_mul_f32_e32 v88, 0xbfb8aa3b, v88
	v_mul_f32_e32 v89, 0xbfb8aa3b, v89
	v_exp_f32_e32 v88, v88
	v_pk_add_f32 v[106:107], v[106:107], 1.0 op_sel_hi:[1,0]
	v_exp_f32_e32 v89, v89
	s_nop 0
	v_pk_add_f32 v[88:89], v[88:89], 1.0 op_sel_hi:[1,0]
	s_waitcnt lgkmcnt(12)
	v_mul_f32_e32 v76, 0xbfb8aa3b, v76
	v_mul_f32_e32 v77, 0xbfb8aa3b, v77
	v_rcp_f32_e32 v107, v107
	v_exp_f32_e32 v76, v76
	v_exp_f32_e32 v77, v77
	v_rcp_f32_e32 v106, v106
	v_pk_add_f32 v[76:77], v[76:77], 1.0 op_sel_hi:[1,0]
	s_waitcnt vmcnt(0) lgkmcnt(3)
	v_pk_fma_f32 v[72:73], v[106:107], v[72:73], v[100:101]
	v_mul_f32_e32 v106, 0xbfb8aa3b, v122
	v_mul_f32_e32 v107, 0xbfb8aa3b, v123
	v_exp_f32_e32 v106, v106
	v_exp_f32_e32 v107, v107
	v_pk_mul_f32 v[100:101], v[72:73], v[72:73]
	v_pk_add_f32 v[106:107], v[106:107], 1.0 op_sel_hi:[1,0]
	s_nop 0
	s_nop 0
	v_rcp_f32_e32 v107, v107
	s_nop 0
	v_rcp_f32_e32 v106, v106
	s_nop 0
	v_pk_fma_f32 v[74:75], v[106:107], v[74:75], v[102:103]
	v_mul_f32_e32 v106, 0xbfb8aa3b, v112
	v_mul_f32_e32 v107, 0xbfb8aa3b, v113
	v_exp_f32_e32 v106, v106
	v_exp_f32_e32 v107, v107
	v_pk_mul_f32 v[102:103], v[74:75], v[74:75]
	v_pk_add_f32 v[106:107], v[106:107], 1.0 op_sel_hi:[1,0]
	s_nop 0
	s_nop 0
	v_rcp_f32_e32 v107, v107
	s_nop 0
	v_rcp_f32_e32 v106, v106
	s_waitcnt lgkmcnt(2)
	v_pk_fma_f32 v[92:93], v[106:107], v[92:93], v[96:97]
	v_mul_f32_e32 v106, 0xbfb8aa3b, v114
	v_mul_f32_e32 v107, 0xbfb8aa3b, v115
	v_exp_f32_e32 v106, v106
	v_exp_f32_e32 v107, v107
	v_pk_mul_f32 v[96:97], v[92:93], v[92:93]
	v_pk_add_f32 v[106:107], v[106:107], 1.0 op_sel_hi:[1,0]
	s_nop 0
	s_nop 0
	v_rcp_f32_e32 v107, v107
	s_nop 0
	v_rcp_f32_e32 v106, v106
	s_nop 0
	v_pk_fma_f32 v[94:95], v[106:107], v[94:95], v[98:99]
	v_pk_mul_f32 v[98:99], v[94:95], v[94:95]
	v_rcp_f32_e32 v89, v89
	s_nop 0
	v_rcp_f32_e32 v88, v88
	s_waitcnt lgkmcnt(1)
	v_pk_fma_f32 v[80:81], v[88:89], v[80:81], v[84:85]
	v_mul_f32_e32 v88, 0xbfb8aa3b, v90
	v_mul_f32_e32 v89, 0xbfb8aa3b, v91
	v_exp_f32_e32 v88, v88
	v_exp_f32_e32 v89, v89
	v_pk_mul_f32 v[84:85], v[80:81], v[80:81]
	v_pk_add_f32 v[88:89], v[88:89], 1.0 op_sel_hi:[1,0]
	s_nop 0
	s_nop 0
	v_rcp_f32_e32 v89, v89
	s_nop 0
	v_rcp_f32_e32 v88, v88
	s_nop 0
	v_pk_fma_f32 v[82:83], v[88:89], v[82:83], v[86:87]
	v_pk_mul_f32 v[86:87], v[82:83], v[82:83]
	v_rcp_f32_e32 v77, v77
	s_nop 0
	v_rcp_f32_e32 v76, v76
	s_waitcnt lgkmcnt(0)
	v_pk_fma_f32 v[64:65], v[76:77], v[64:65], v[68:69]
	v_mul_f32_e32 v76, 0xbfb8aa3b, v78
	v_mul_f32_e32 v77, 0xbfb8aa3b, v79
	v_exp_f32_e32 v76, v76
	v_exp_f32_e32 v77, v77
	v_pk_mul_f32 v[68:69], v[64:65], v[64:65]
	v_pk_add_f32 v[76:77], v[76:77], 1.0 op_sel_hi:[1,0]
	s_nop 0
	s_nop 0
	v_rcp_f32_e32 v77, v77
	v_div_scale_f32 v78, s[0:1], v76, v76, 1.0
	v_rcp_f32_e32 v79, v78
	s_nop 0
	v_fma_f32 v88, -v78, v79, 1.0
	v_fmac_f32_e32 v79, v88, v79
	v_div_scale_f32 v88, vcc, 1.0, v76, 1.0
	v_mul_f32_e32 v89, v88, v79
	v_fma_f32 v90, -v78, v89, v88
	v_fmac_f32_e32 v89, v90, v79
	v_fma_f32 v78, -v78, v89, v88
	v_div_fmas_f32 v78, v78, v79, v89
	v_div_fixup_f32 v76, v78, v76, 1.0
	v_pk_fma_f32 v[66:67], v[76:77], v[66:67], v[70:71]
	v_add_f32_e32 v76, v100, v101
	v_add_f32_e32 v76, v102, v76
	v_add_f32_e32 v76, v103, v76
	v_add_f32_e32 v76, v96, v76
	v_add_f32_e32 v76, v97, v76
	v_add_f32_e32 v76, v98, v76
	v_add_f32_e32 v76, v99, v76
	v_add_f32_e32 v76, v84, v76
	v_add_f32_e32 v76, v85, v76
	v_add_f32_e32 v76, v86, v76
	v_add_f32_e32 v76, v87, v76
	v_add_f32_e32 v68, v68, v76
	v_pk_mul_f32 v[70:71], v[66:67], v[66:67]
	v_add_f32_e32 v68, v69, v68
	v_add_f32_e32 v68, v70, v68
	v_bfe_u32 v69, v73, 16, 1
	v_add_f32_e32 v78, v71, v68
	global_store_dwordx4 v[104:105], v[72:75], off
	global_store_dwordx4 v[104:105], v[92:95], off offset:16
	global_store_dwordx4 v[104:105], v[80:83], off offset:32
	global_store_dwordx4 v[104:105], v[64:67], off offset:48
	v_bfe_u32 v70, v95, 16, 1
	v_bfe_u32 v71, v75, 16, 1
	v_add3_u32 v69, v73, v69, s24
	v_bfe_u32 v73, v94, 16, 1
	v_add3_u32 v75, v75, v71, s24
	v_add3_u32 v71, v95, v70, s24
	v_bfe_u32 v70, v74, 16, 1
	v_bfe_u32 v79, v72, 16, 1
	v_bfe_u32 v84, v92, 16, 1
	v_add3_u32 v73, v94, v73, s24
	v_bfe_u32 v68, v93, 16, 1
	v_add3_u32 v84, v92, v84, s24
	v_add3_u32 v72, v72, v79, s24
	v_add3_u32 v70, v74, v70, s24
	v_lshrrev_b32_e32 v73, 16, v73
	v_add3_u32 v68, v93, v68, s24
	v_lshrrev_b32_e32 v74, 16, v70
	v_lshrrev_b32_e32 v72, 16, v72
	v_lshrrev_b32_e32 v70, 16, v84
	v_and_or_b32 v71, v71, s25, v73
	v_bfe_u32 v73, v81, 16, 1
	v_and_or_b32 v70, v68, s25, v70
	v_and_or_b32 v68, v69, s25, v72
	v_and_or_b32 v69, v75, s25, v74
	v_bfe_u32 v72, v65, 16, 1
	v_bfe_u32 v74, v67, 16, 1
	v_add3_u32 v73, v81, v73, s24
	v_bfe_u32 v79, v80, 16, 1
	v_bfe_u32 v81, v64, 16, 1
	v_add3_u32 v67, v67, v74, s24
	v_add3_u32 v65, v65, v72, s24
	v_bfe_u32 v72, v82, 16, 1
	v_bfe_u32 v74, v66, 16, 1
	v_add3_u32 v64, v64, v81, s24
	v_add3_u32 v79, v80, v79, s24
	v_bfe_u32 v75, v83, 16, 1
	v_add3_u32 v66, v66, v74, s24
	v_add3_u32 v72, v82, v72, s24
	v_lshrrev_b32_e32 v79, 16, v79
	v_lshrrev_b32_e32 v64, 16, v64
	v_mad_i64_i32 v[76:77], s[0:1], v116, s4, v[134:135]
	v_add3_u32 v75, v83, v75, s24
	v_lshrrev_b32_e32 v72, 16, v72
	v_lshrrev_b32_e32 v74, 16, v66
	v_and_or_b32 v66, v65, s25, v64
	v_and_or_b32 v64, v73, s25, v79
	v_and_or_b32 v67, v67, s25, v74
	v_and_or_b32 v65, v75, s25, v72
	global_store_dwordx4 v[76:77], v[68:71], off
	global_store_dwordx4 v[76:77], v[64:67], off offset:16
	ds_bpermute_b32 v64, v119, v78
	s_waitcnt lgkmcnt(0)
	v_add_f32_e32 v64, v78, v64
	ds_bpermute_b32 v65, v118, v64
	s_and_saveexec_b64 s[0:1], s[8:9]
	s_cbranch_execz .LBB0_1050
	s_waitcnt lgkmcnt(0)
	v_add_f32_e32 v66, v64, v65
	v_lshl_add_u64 v[64:65], v[116:117], 2, s[18:19]
	global_atomic_add_f32 v[64:65], v66, off
; DI float sigm(float x) { return 1.f / (1.f + __expf(-x)); }
; DI void phase_ple(const Params& p, int layer, const bft* hbin, bft* hbout, int ldo, float* ssq) {
;     ...
;       float v2[16]; epi_stage(tid, acc2[m], v2); float h[16]; float* hp = p.out + (size_t)row * 1024 + col; load16_f(hp, h); float ss = 0.f;
; #pragma unroll
;       for (int i = 0; i < 16; ++i) { h[i] += sigm(v[i]) * v2[i]; ss += h[i] * h[i]; }
;       store16_f(hp, h); if (hbout) store16_bf(hbout + (size_t)row * ldo + col, h);
;       ss += __shfl_xor(ss, 1); ss += __shfl_xor(ss, 2);
;       if ((lane & 3) == 0) atomicAdd(ssq + row, ss);
.LBB0_1050:
	s_or_b64 exec, exec, s[0:1]
	ds_write2_b32 v140, v44, v40 offset1:16
	ds_write2_b32 v140, v45, v41 offset0:68 offset1:84
	ds_write2_b32 v140, v46, v42 offset0:136 offset1:152
	ds_write2_b32 v140, v47, v43 offset0:204 offset1:220
	ds_write2_b32 v140, v36, v32 offset0:32 offset1:48
	ds_write2_b32 v140, v37, v33 offset0:100 offset1:116
	ds_write2_b32 v140, v38, v34 offset0:168 offset1:184
	ds_write2_b32 v140, v39, v35 offset0:236 offset1:252
	s_waitcnt lgkmcnt(0)
	v_or_b32_e32 v76, 32, v136
	ds_read_b128 v[80:83], v141
	ds_read_b128 v[68:71], v141 offset:16
	s_waitcnt lgkmcnt(10)
	ds_read_b128 v[64:67], v141 offset:32
	ds_read_b128 v[44:47], v141 offset:48
	v_ashrrev_i32_e32 v77, 31, v76
	ds_write2_b32 v140, v60, v56 offset1:16
	ds_write2_b32 v140, v61, v57 offset0:68 offset1:84
	ds_write2_b32 v140, v62, v58 offset0:136 offset1:152
	ds_write2_b32 v140, v63, v59 offset0:204 offset1:220
	ds_write2_b32 v140, v52, v48 offset0:32 offset1:48
	ds_write2_b32 v140, v53, v49 offset0:100 offset1:116
	ds_write2_b32 v140, v54, v50 offset0:168 offset1:184
	ds_write2_b32 v140, v55, v51 offset0:236 offset1:252
	v_lshlrev_b64 v[36:37], 12, v[76:77]
	s_waitcnt lgkmcnt(0)
	v_lshl_add_u64 v[36:37], s[12:13], 0, v[36:37]
	ds_read_b128 v[40:43], v141
	ds_read_b128 v[56:59], v141 offset:16
	ds_read_b128 v[48:51], v141 offset:32
	ds_read_b128 v[32:35], v141 offset:48
	v_lshl_add_u64 v[78:79], v[36:37], 0, v[132:133]
	global_load_dwordx4 v[36:39], v[78:79], off offset:48
	global_load_dwordx4 v[52:55], v[78:79], off offset:32
	global_load_dwordx4 v[60:63], v[78:79], off offset:16
	global_load_dwordx4 v[72:75], v[78:79], off
	s_waitcnt lgkmcnt(14)
	v_mul_f32_e32 v80, 0xbfb8aa3b, v80
	v_mul_f32_e32 v81, 0xbfb8aa3b, v81
	v_exp_f32_e32 v80, v80
	v_exp_f32_e32 v81, v81
	v_mul_f32_e32 v68, 0xbfb8aa3b, v68
	v_mul_f32_e32 v69, 0xbfb8aa3b, v69
	v_exp_f32_e32 v68, v68
	v_pk_add_f32 v[80:81], v[80:81], 1.0 op_sel_hi:[1,0]
	v_exp_f32_e32 v69, v69
	s_nop 0
	v_pk_add_f32 v[68:69], v[68:69], 1.0 op_sel_hi:[1,0]
	s_waitcnt lgkmcnt(13)
	v_mul_f32_e32 v64, 0xbfb8aa3b, v64
	v_mul_f32_e32 v65, 0xbfb8aa3b, v65
	v_rcp_f32_e32 v81, v81
	v_exp_f32_e32 v64, v64
	v_exp_f32_e32 v65, v65
	s_waitcnt lgkmcnt(12)
	v_mul_f32_e32 v44, 0xbfb8aa3b, v44
	v_rcp_f32_e32 v80, v80
	v_pk_add_f32 v[64:65], v[64:65], 1.0 op_sel_hi:[1,0]
	v_mul_f32_e32 v45, 0xbfb8aa3b, v45
	v_exp_f32_e32 v44, v44
	v_exp_f32_e32 v45, v45
	s_waitcnt vmcnt(0) lgkmcnt(3)
	v_pk_fma_f32 v[40:41], v[80:81], v[40:41], v[72:73]
	v_mul_f32_e32 v80, 0xbfb8aa3b, v82
	v_mul_f32_e32 v81, 0xbfb8aa3b, v83
	v_exp_f32_e32 v80, v80
	v_exp_f32_e32 v81, v81
	v_pk_add_f32 v[44:45], v[44:45], 1.0 op_sel_hi:[1,0]
	v_pk_mul_f32 v[72:73], v[40:41], v[40:41]
	v_pk_add_f32 v[80:81], v[80:81], 1.0 op_sel_hi:[1,0]
	s_nop 0
	s_nop 0
	v_rcp_f32_e32 v81, v81
	s_nop 0
	v_rcp_f32_e32 v80, v80
	s_nop 0
	v_pk_fma_f32 v[42:43], v[80:81], v[42:43], v[74:75]
	v_pk_mul_f32 v[74:75], v[42:43], v[42:43]
	v_rcp_f32_e32 v69, v69
	s_nop 0
	v_rcp_f32_e32 v68, v68
	s_waitcnt lgkmcnt(2)
	v_pk_fma_f32 v[56:57], v[68:69], v[56:57], v[60:61]
	v_mul_f32_e32 v68, 0xbfb8aa3b, v70
	v_mul_f32_e32 v69, 0xbfb8aa3b, v71
	v_exp_f32_e32 v68, v68
	v_exp_f32_e32 v69, v69
	v_pk_mul_f32 v[60:61], v[56:57], v[56:57]
	v_pk_add_f32 v[68:69], v[68:69], 1.0 op_sel_hi:[1,0]
	s_nop 0
	s_nop 0
	v_rcp_f32_e32 v69, v69
	s_nop 0
	v_rcp_f32_e32 v68, v68
	s_nop 0
	v_pk_fma_f32 v[58:59], v[68:69], v[58:59], v[62:63]
	v_pk_mul_f32 v[62:63], v[58:59], v[58:59]
	v_rcp_f32_e32 v65, v65
	s_nop 0
	v_rcp_f32_e32 v64, v64
	s_waitcnt lgkmcnt(1)
	v_pk_fma_f32 v[48:49], v[64:65], v[48:49], v[52:53]
	v_mul_f32_e32 v64, 0xbfb8aa3b, v66
	v_mul_f32_e32 v65, 0xbfb8aa3b, v67
	v_exp_f32_e32 v64, v64
	v_exp_f32_e32 v65, v65
	v_pk_mul_f32 v[52:53], v[48:49], v[48:49]
	v_pk_add_f32 v[64:65], v[64:65], 1.0 op_sel_hi:[1,0]
	s_nop 0
	s_nop 0
	v_rcp_f32_e32 v65, v65
	s_nop 0
	v_rcp_f32_e32 v64, v64
	s_nop 0
	v_pk_fma_f32 v[50:51], v[64:65], v[50:51], v[54:55]
	v_pk_mul_f32 v[54:55], v[50:51], v[50:51]
	v_rcp_f32_e32 v45, v45
	s_nop 0
	v_rcp_f32_e32 v44, v44
	s_waitcnt lgkmcnt(0)
	v_pk_fma_f32 v[32:33], v[44:45], v[32:33], v[36:37]
	v_mul_f32_e32 v44, 0xbfb8aa3b, v46
	v_mul_f32_e32 v45, 0xbfb8aa3b, v47
	v_exp_f32_e32 v44, v44
	v_exp_f32_e32 v45, v45
	v_pk_mul_f32 v[36:37], v[32:33], v[32:33]
	v_pk_add_f32 v[44:45], v[44:45], 1.0 op_sel_hi:[1,0]
	s_nop 0
	s_nop 0
	v_rcp_f32_e32 v45, v45
	v_div_scale_f32 v46, s[0:1], v44, v44, 1.0
	v_rcp_f32_e32 v47, v46
	s_nop 0
	v_fma_f32 v64, -v46, v47, 1.0
	v_fmac_f32_e32 v47, v64, v47
	v_div_scale_f32 v64, vcc, 1.0, v44, 1.0
	v_mul_f32_e32 v65, v64, v47
	v_fma_f32 v66, -v46, v65, v64
	v_fmac_f32_e32 v65, v66, v47
	v_fma_f32 v46, -v46, v65, v64
	v_div_fmas_f32 v46, v46, v47, v65
	v_div_fixup_f32 v44, v46, v44, 1.0
	v_pk_fma_f32 v[34:35], v[44:45], v[34:35], v[38:39]
	v_add_f32_e32 v44, v72, v73
	v_add_f32_e32 v44, v74, v44
	v_add_f32_e32 v44, v75, v44
	v_add_f32_e32 v44, v60, v44
	v_add_f32_e32 v44, v61, v44
	v_add_f32_e32 v44, v62, v44
	v_add_f32_e32 v44, v63, v44
	v_add_f32_e32 v44, v52, v44
	v_add_f32_e32 v44, v53, v44
	v_add_f32_e32 v44, v54, v44
	v_add_f32_e32 v44, v55, v44
	v_add_f32_e32 v36, v36, v44
	v_pk_mul_f32 v[38:39], v[34:35], v[34:35]
	v_add_f32_e32 v36, v37, v36
	v_add_f32_e32 v36, v38, v36
	v_bfe_u32 v37, v41, 16, 1
	v_add_f32_e32 v46, v39, v36
	global_store_dwordx4 v[78:79], v[40:43], off
	global_store_dwordx4 v[78:79], v[56:59], off offset:16
	global_store_dwordx4 v[78:79], v[48:51], off offset:32
	global_store_dwordx4 v[78:79], v[32:35], off offset:48
	v_bfe_u32 v38, v59, 16, 1
	v_bfe_u32 v39, v43, 16, 1
	v_add3_u32 v37, v41, v37, s24
	v_bfe_u32 v41, v58, 16, 1
; DI float sigm(float x) { return 1.f / (1.f + __expf(-x)); }
; DI void phase_ple(const Params& p, int layer, const bft* hbin, bft* hbout, int ldo, float* ssq) {
;     ...
;       float v2[16]; epi_stage(tid, acc2[m], v2); float h[16]; float* hp = p.out + (size_t)row * 1024 + col; load16_f(hp, h); float ss = 0.f;
; #pragma unroll
;       for (int i = 0; i < 16; ++i) { h[i] += sigm(v[i]) * v2[i]; ss += h[i] * h[i]; }
;       store16_f(hp, h); if (hbout) store16_bf(hbout + (size_t)row * ldo + col, h);
;       ss += __shfl_xor(ss, 1); ss += __shfl_xor(ss, 2);
;       if ((lane & 3) == 0) atomicAdd(ssq + row, ss);
	v_add3_u32 v43, v43, v39, s24
	v_add3_u32 v39, v59, v38, s24
	v_bfe_u32 v38, v42, 16, 1
	v_bfe_u32 v47, v40, 16, 1
	v_bfe_u32 v52, v56, 16, 1
	v_add3_u32 v41, v58, v41, s24
	v_bfe_u32 v36, v57, 16, 1
	v_add3_u32 v52, v56, v52, s24
	v_add3_u32 v40, v40, v47, s24
	v_add3_u32 v38, v42, v38, s24
	v_lshrrev_b32_e32 v41, 16, v41
	v_add3_u32 v36, v57, v36, s24
	v_lshrrev_b32_e32 v42, 16, v38
	v_lshrrev_b32_e32 v40, 16, v40
	v_lshrrev_b32_e32 v38, 16, v52
	v_and_or_b32 v39, v39, s25, v41
	v_bfe_u32 v41, v49, 16, 1
	v_and_or_b32 v38, v36, s25, v38
	v_and_or_b32 v36, v37, s25, v40
	v_and_or_b32 v37, v43, s25, v42
	v_bfe_u32 v40, v33, 16, 1
	v_bfe_u32 v42, v35, 16, 1
	v_add3_u32 v41, v49, v41, s24
	v_bfe_u32 v47, v48, 16, 1
	v_bfe_u32 v49, v32, 16, 1
	v_add3_u32 v35, v35, v42, s24
	v_add3_u32 v33, v33, v40, s24
	v_bfe_u32 v40, v50, 16, 1
	v_bfe_u32 v42, v34, 16, 1
	v_add3_u32 v32, v32, v49, s24
	v_add3_u32 v47, v48, v47, s24
	v_bfe_u32 v43, v51, 16, 1
	v_add3_u32 v34, v34, v42, s24
	v_add3_u32 v40, v50, v40, s24
	v_lshrrev_b32_e32 v47, 16, v47
	v_lshrrev_b32_e32 v32, 16, v32
	v_mad_i64_i32 v[44:45], s[0:1], v76, s4, v[134:135]
	v_add3_u32 v43, v51, v43, s24
	v_lshrrev_b32_e32 v40, 16, v40
	v_lshrrev_b32_e32 v42, 16, v34
	v_and_or_b32 v34, v33, s25, v32
	v_and_or_b32 v32, v41, s25, v47
	v_and_or_b32 v35, v35, s25, v42
	v_and_or_b32 v33, v43, s25, v40
	global_store_dwordx4 v[44:45], v[36:39], off
	global_store_dwordx4 v[44:45], v[32:35], off offset:16
	ds_bpermute_b32 v32, v119, v46
	s_waitcnt lgkmcnt(0)
	v_add_f32_e32 v32, v46, v32
	ds_bpermute_b32 v33, v118, v32
	s_and_saveexec_b64 s[0:1], s[8:9]
	s_cbranch_execz .LBB0_1052
	s_waitcnt lgkmcnt(0)
	v_add_f32_e32 v34, v32, v33
	v_lshl_add_u64 v[32:33], v[76:77], 2, s[18:19]
	global_atomic_add_f32 v[32:33], v34, off
.LBB0_1052:
	s_or_b64 exec, exec, s[0:1]
	ds_write2_b32 v140, v8, v4 offset1:16
	ds_write2_b32 v140, v9, v5 offset0:68 offset1:84
	ds_write2_b32 v140, v10, v6 offset0:136 offset1:152
	ds_write2_b32 v140, v11, v7 offset0:204 offset1:220
	ds_write2_b32 v140, v0, v12 offset0:32 offset1:48
	ds_write2_b32 v140, v1, v13 offset0:100 offset1:116
	ds_write2_b32 v140, v2, v14 offset0:168 offset1:184
	ds_write2_b32 v140, v3, v15 offset0:236 offset1:252
	s_waitcnt lgkmcnt(0)
	v_or_b32_e32 v44, 48, v136
	ds_read_b128 v[48:51], v141
	ds_read_b128 v[36:39], v141 offset:16
	s_waitcnt lgkmcnt(10)
	ds_read_b128 v[32:35], v141 offset:32
	ds_read_b128 v[12:15], v141 offset:48
	v_ashrrev_i32_e32 v45, 31, v44
	ds_write2_b32 v140, v24, v20 offset1:16
	ds_write2_b32 v140, v25, v21 offset0:68 offset1:84
	ds_write2_b32 v140, v26, v22 offset0:136 offset1:152
	ds_write2_b32 v140, v27, v23 offset0:204 offset1:220
	ds_write2_b32 v140, v16, v28 offset0:32 offset1:48
	ds_write2_b32 v140, v17, v29 offset0:100 offset1:116
	ds_write2_b32 v140, v18, v30 offset0:168 offset1:184
	ds_write2_b32 v140, v19, v31 offset0:236 offset1:252
	v_lshlrev_b64 v[4:5], 12, v[44:45]
	s_waitcnt lgkmcnt(0)
	v_lshl_add_u64 v[4:5], s[12:13], 0, v[4:5]
	ds_read_b128 v[8:11], v141
	ds_read_b128 v[24:27], v141 offset:16
	ds_read_b128 v[16:19], v141 offset:32
	ds_read_b128 v[0:3], v141 offset:48
	v_lshl_add_u64 v[46:47], v[4:5], 0, v[132:133]
	global_load_dwordx4 v[4:7], v[46:47], off offset:48
	global_load_dwordx4 v[20:23], v[46:47], off offset:32
	global_load_dwordx4 v[28:31], v[46:47], off offset:16
	global_load_dwordx4 v[40:43], v[46:47], off
	s_waitcnt lgkmcnt(14)
	v_mul_f32_e32 v48, 0xbfb8aa3b, v48
	v_mul_f32_e32 v49, 0xbfb8aa3b, v49
	v_exp_f32_e32 v48, v48
	v_exp_f32_e32 v49, v49
	v_mul_f32_e32 v36, 0xbfb8aa3b, v36
	v_mul_f32_e32 v37, 0xbfb8aa3b, v37
	v_exp_f32_e32 v36, v36
	v_pk_add_f32 v[48:49], v[48:49], 1.0 op_sel_hi:[1,0]
	v_exp_f32_e32 v37, v37
	s_nop 0
	v_pk_add_f32 v[36:37], v[36:37], 1.0 op_sel_hi:[1,0]
	s_waitcnt lgkmcnt(13)
	v_mul_f32_e32 v32, 0xbfb8aa3b, v32
	v_mul_f32_e32 v33, 0xbfb8aa3b, v33
	v_rcp_f32_e32 v49, v49
	v_exp_f32_e32 v32, v32
	v_exp_f32_e32 v33, v33
	s_waitcnt lgkmcnt(12)
	v_mul_f32_e32 v12, 0xbfb8aa3b, v12
	v_rcp_f32_e32 v48, v48
	v_pk_add_f32 v[32:33], v[32:33], 1.0 op_sel_hi:[1,0]
	v_mul_f32_e32 v13, 0xbfb8aa3b, v13
	v_exp_f32_e32 v12, v12
	v_exp_f32_e32 v13, v13
	s_waitcnt vmcnt(0) lgkmcnt(3)
	v_pk_fma_f32 v[8:9], v[48:49], v[8:9], v[40:41]
	v_mul_f32_e32 v48, 0xbfb8aa3b, v50
	v_mul_f32_e32 v49, 0xbfb8aa3b, v51
	v_exp_f32_e32 v48, v48
	v_exp_f32_e32 v49, v49
	v_pk_add_f32 v[12:13], v[12:13], 1.0 op_sel_hi:[1,0]
	v_pk_mul_f32 v[40:41], v[8:9], v[8:9]
	v_pk_add_f32 v[48:49], v[48:49], 1.0 op_sel_hi:[1,0]
	s_nop 0
	s_nop 0
	v_rcp_f32_e32 v49, v49
	s_nop 0
	v_rcp_f32_e32 v48, v48
	s_nop 0
	v_pk_fma_f32 v[10:11], v[48:49], v[10:11], v[42:43]
	v_pk_mul_f32 v[42:43], v[10:11], v[10:11]
	v_rcp_f32_e32 v37, v37
	s_nop 0
	v_rcp_f32_e32 v36, v36
	s_waitcnt lgkmcnt(2)
; DI float sigm(float x) { return 1.f / (1.f + __expf(-x)); }
; DI void phase_ple(const Params& p, int layer, const bft* hbin, bft* hbout, int ldo, float* ssq) {
;     ...
;       float v2[16]; epi_stage(tid, acc2[m], v2); float h[16]; float* hp = p.out + (size_t)row * 1024 + col; load16_f(hp, h); float ss = 0.f;
; #pragma unroll
;       for (int i = 0; i < 16; ++i) { h[i] += sigm(v[i]) * v2[i]; ss += h[i] * h[i]; }
;       store16_f(hp, h); if (hbout) store16_bf(hbout + (size_t)row * ldo + col, h);
;       ss += __shfl_xor(ss, 1); ss += __shfl_xor(ss, 2);
;       if ((lane & 3) == 0) atomicAdd(ssq + row, ss);
;     EPI_END
	v_pk_fma_f32 v[24:25], v[36:37], v[24:25], v[28:29]
	v_mul_f32_e32 v36, 0xbfb8aa3b, v38
	v_mul_f32_e32 v37, 0xbfb8aa3b, v39
	v_exp_f32_e32 v36, v36
	v_exp_f32_e32 v37, v37
	v_pk_mul_f32 v[28:29], v[24:25], v[24:25]
	v_pk_add_f32 v[36:37], v[36:37], 1.0 op_sel_hi:[1,0]
	s_nop 0
	s_nop 0
	v_rcp_f32_e32 v37, v37
	s_nop 0
	v_rcp_f32_e32 v36, v36
	s_nop 0
	v_pk_fma_f32 v[26:27], v[36:37], v[26:27], v[30:31]
	v_pk_mul_f32 v[30:31], v[26:27], v[26:27]
	v_rcp_f32_e32 v33, v33
	s_nop 0
	v_rcp_f32_e32 v32, v32
	s_waitcnt lgkmcnt(1)
	v_pk_fma_f32 v[16:17], v[32:33], v[16:17], v[20:21]
	v_mul_f32_e32 v32, 0xbfb8aa3b, v34
	v_mul_f32_e32 v33, 0xbfb8aa3b, v35
	v_exp_f32_e32 v32, v32
	v_exp_f32_e32 v33, v33
	v_pk_mul_f32 v[20:21], v[16:17], v[16:17]
	v_pk_add_f32 v[32:33], v[32:33], 1.0 op_sel_hi:[1,0]
	s_nop 0
	s_nop 0
	v_rcp_f32_e32 v33, v33
	s_nop 0
	v_rcp_f32_e32 v32, v32
	s_nop 0
	v_pk_fma_f32 v[18:19], v[32:33], v[18:19], v[22:23]
	v_pk_mul_f32 v[22:23], v[18:19], v[18:19]
	v_rcp_f32_e32 v13, v13
	s_nop 0
	v_rcp_f32_e32 v12, v12
	s_waitcnt lgkmcnt(0)
	v_pk_fma_f32 v[0:1], v[12:13], v[0:1], v[4:5]
	v_mul_f32_e32 v12, 0xbfb8aa3b, v14
	v_mul_f32_e32 v13, 0xbfb8aa3b, v15
	v_exp_f32_e32 v12, v12
	v_exp_f32_e32 v13, v13
	v_pk_mul_f32 v[4:5], v[0:1], v[0:1]
	v_pk_add_f32 v[12:13], v[12:13], 1.0 op_sel_hi:[1,0]
	s_nop 0
	s_nop 0
	v_rcp_f32_e32 v13, v13
	v_div_scale_f32 v14, s[0:1], v12, v12, 1.0
	v_rcp_f32_e32 v15, v14
	s_nop 0
	v_fma_f32 v32, -v14, v15, 1.0
	v_fmac_f32_e32 v15, v32, v15
	v_div_scale_f32 v32, vcc, 1.0, v12, 1.0
	v_mul_f32_e32 v33, v32, v15
	v_fma_f32 v34, -v14, v33, v32
	v_fmac_f32_e32 v33, v34, v15
	v_fma_f32 v14, -v14, v33, v32
	v_div_fmas_f32 v14, v14, v15, v33
	v_div_fixup_f32 v12, v14, v12, 1.0
	v_pk_fma_f32 v[2:3], v[12:13], v[2:3], v[6:7]
	v_add_f32_e32 v12, v40, v41
	v_add_f32_e32 v12, v42, v12
	v_add_f32_e32 v12, v43, v12
	v_add_f32_e32 v12, v28, v12
	v_add_f32_e32 v12, v29, v12
	v_add_f32_e32 v12, v30, v12
	v_add_f32_e32 v12, v31, v12
	v_add_f32_e32 v12, v20, v12
	v_add_f32_e32 v12, v21, v12
	v_add_f32_e32 v12, v22, v12
	v_add_f32_e32 v12, v23, v12
	v_add_f32_e32 v4, v4, v12
	v_pk_mul_f32 v[6:7], v[2:3], v[2:3]
	v_add_f32_e32 v4, v5, v4
	v_add_f32_e32 v4, v6, v4
	v_bfe_u32 v5, v9, 16, 1
	v_add_f32_e32 v14, v7, v4
	global_store_dwordx4 v[46:47], v[8:11], off
	global_store_dwordx4 v[46:47], v[24:27], off offset:16
	global_store_dwordx4 v[46:47], v[16:19], off offset:32
	global_store_dwordx4 v[46:47], v[0:3], off offset:48
	v_bfe_u32 v6, v27, 16, 1
	v_bfe_u32 v7, v11, 16, 1
	v_add3_u32 v5, v9, v5, s24
	v_bfe_u32 v9, v26, 16, 1
	v_add3_u32 v11, v11, v7, s24
	v_add3_u32 v7, v27, v6, s24
	v_bfe_u32 v6, v10, 16, 1
	v_bfe_u32 v15, v8, 16, 1
	v_bfe_u32 v20, v24, 16, 1
	v_add3_u32 v9, v26, v9, s24
	v_bfe_u32 v4, v25, 16, 1
	v_add3_u32 v20, v24, v20, s24
	v_add3_u32 v8, v8, v15, s24
	v_add3_u32 v6, v10, v6, s24
	v_lshrrev_b32_e32 v9, 16, v9
	v_add3_u32 v4, v25, v4, s24
	v_lshrrev_b32_e32 v10, 16, v6
	v_lshrrev_b32_e32 v8, 16, v8
	v_lshrrev_b32_e32 v6, 16, v20
	v_and_or_b32 v7, v7, s25, v9
	v_bfe_u32 v9, v17, 16, 1
	v_and_or_b32 v6, v4, s25, v6
	v_and_or_b32 v4, v5, s25, v8
	v_and_or_b32 v5, v11, s25, v10
	v_bfe_u32 v8, v1, 16, 1
	v_bfe_u32 v10, v3, 16, 1
	v_add3_u32 v9, v17, v9, s24
	v_bfe_u32 v15, v16, 16, 1
	v_bfe_u32 v17, v0, 16, 1
	v_add3_u32 v3, v3, v10, s24
	v_add3_u32 v1, v1, v8, s24
	v_bfe_u32 v8, v18, 16, 1
	v_bfe_u32 v10, v2, 16, 1
	v_add3_u32 v0, v0, v17, s24
	v_add3_u32 v15, v16, v15, s24
	v_bfe_u32 v11, v19, 16, 1
	v_add3_u32 v2, v2, v10, s24
	v_add3_u32 v8, v18, v8, s24
	v_lshrrev_b32_e32 v15, 16, v15
	v_lshrrev_b32_e32 v0, 16, v0
	v_mad_i64_i32 v[12:13], s[0:1], v44, s4, v[134:135]
	v_add3_u32 v11, v19, v11, s24
	v_lshrrev_b32_e32 v8, 16, v8
	v_lshrrev_b32_e32 v10, 16, v2
	v_and_or_b32 v2, v1, s25, v0
	v_and_or_b32 v0, v9, s25, v15
	v_and_or_b32 v3, v3, s25, v10
	v_and_or_b32 v1, v11, s25, v8
	global_store_dwordx4 v[12:13], v[4:7], off
	global_store_dwordx4 v[12:13], v[0:3], off offset:16
	ds_bpermute_b32 v0, v119, v14
	s_waitcnt lgkmcnt(0)
	v_add_f32_e32 v0, v14, v0
	ds_bpermute_b32 v1, v118, v0
	s_and_saveexec_b64 s[0:1], s[8:9]
	s_cbranch_execz .LBB0_1027
	s_waitcnt lgkmcnt(0)
	v_add_f32_e32 v2, v0, v1
	v_lshl_add_u64 v[0:1], v[44:45], 2, s[18:19]
	global_atomic_add_f32 v[0:1], v2, off
	s_branch .LBB0_1027

; DI float sigm(float x) { return 1.f / (1.f + __expf(-x)); }
; DI float siluf(float x) { return x * sigm(x); }
; DI void phase_inproj1(const Params& p, int ch) {
;     ...
;     const bool isgate = bcol >= 768;
;     EPI256_BEGIN
;       float rs = rsqrtf(ssq1[row] * (1.f / 1024) + EPS);
; #pragma unroll
;       for (int i = 0; i < 16; ++i) { v[i] *= rs; if (isgate) v[i] = siluf(v[i]); }
;       store16_bf(Z + (size_t)row * 1024 + col, v);
.LBB0_1277:
	v_mul_f32_e32 v128, 0xbfb8aa3b, v3
	v_exp_f32_e32 v128, v128
	s_nop 0
	v_add_f32_e32 v128, 1.0, v128
	v_rcp_f32_e32 v128, v128
	s_nop 0
	v_mul_f32_e32 v3, v3, v128
	s_and_b64 vcc, exec, s[8:9]
	v_mul_f32_e32 v128, v130, v136
	s_cbranch_vccnz .LBB0_1145
.LBB0_1278:
	v_mul_f32_e32 v129, 0xbfb8aa3b, v128
	v_exp_f32_e32 v129, v129
	s_nop 0
	v_add_f32_e32 v129, 1.0, v129
	v_rcp_f32_e32 v129, v129
	s_nop 0
	v_mul_f32_e32 v128, v128, v129
	s_and_b64 vcc, exec, s[8:9]
	v_mul_f32_e32 v129, v131, v136
	s_cbranch_vccnz .LBB0_1146
.LBB0_1279:
	v_mul_f32_e32 v130, 0xbfb8aa3b, v129
	v_exp_f32_e32 v130, v130
	s_nop 0
	v_add_f32_e32 v130, 1.0, v130
	v_rcp_f32_e32 v130, v130
	s_nop 0
	v_mul_f32_e32 v129, v129, v130
	s_and_b64 vcc, exec, s[8:9]
	s_waitcnt lgkmcnt(2)
	v_mul_f32_e32 v124, v124, v136
	s_cbranch_vccnz .LBB0_1147
.LBB0_1280:
	v_mul_f32_e32 v130, 0xbfb8aa3b, v124
	v_exp_f32_e32 v130, v130
	s_nop 0
	v_add_f32_e32 v130, 1.0, v130
	v_rcp_f32_e32 v130, v130
	s_nop 0
	v_mul_f32_e32 v124, v124, v130
	s_and_b64 vcc, exec, s[8:9]
	v_mul_f32_e32 v125, v125, v136
	s_cbranch_vccnz .LBB0_1148
.LBB0_1281:
	v_mul_f32_e32 v130, 0xbfb8aa3b, v125
	v_exp_f32_e32 v130, v130
	s_nop 0
	v_add_f32_e32 v130, 1.0, v130
	v_rcp_f32_e32 v130, v130
	s_nop 0
	v_mul_f32_e32 v125, v125, v130
	s_and_b64 vcc, exec, s[8:9]
	v_mul_f32_e32 v126, v126, v136
	s_cbranch_vccnz .LBB0_1149
.LBB0_1282:
	v_mul_f32_e32 v130, 0xbfb8aa3b, v126
	v_exp_f32_e32 v130, v130
	s_nop 0
	v_add_f32_e32 v130, 1.0, v130
	v_rcp_f32_e32 v130, v130
	s_nop 0
	v_mul_f32_e32 v126, v126, v130
	s_and_b64 vcc, exec, s[8:9]
	v_mul_f32_e32 v127, v127, v136
	s_cbranch_vccnz .LBB0_1150
.LBB0_1283:
	v_mul_f32_e32 v130, 0xbfb8aa3b, v127
	v_exp_f32_e32 v130, v130
	s_nop 0
	v_add_f32_e32 v130, 1.0, v130
	v_rcp_f32_e32 v130, v130
	s_nop 0
	v_mul_f32_e32 v127, v127, v130
	s_and_b64 vcc, exec, s[8:9]
	s_waitcnt lgkmcnt(1)
	v_mul_f32_e32 v120, v120, v136
	s_cbranch_vccnz .LBB0_1151
.LBB0_1284:
	v_mul_f32_e32 v130, 0xbfb8aa3b, v120
	v_exp_f32_e32 v130, v130
	s_nop 0
	v_add_f32_e32 v130, 1.0, v130
	v_rcp_f32_e32 v130, v130
	s_nop 0
	v_mul_f32_e32 v120, v120, v130
	s_and_b64 vcc, exec, s[8:9]
	v_mul_f32_e32 v121, v121, v136
	s_cbranch_vccnz .LBB0_1152
.LBB0_1285:
	v_mul_f32_e32 v130, 0xbfb8aa3b, v121
	v_exp_f32_e32 v130, v130
	s_nop 0
	v_add_f32_e32 v130, 1.0, v130
	v_rcp_f32_e32 v130, v130
	s_nop 0
	v_mul_f32_e32 v121, v121, v130
	s_and_b64 vcc, exec, s[8:9]
	v_mul_f32_e32 v122, v122, v136
	s_cbranch_vccnz .LBB0_1153
.LBB0_1286:
	v_mul_f32_e32 v130, 0xbfb8aa3b, v122
	v_exp_f32_e32 v130, v130
	s_nop 0
	v_add_f32_e32 v130, 1.0, v130
	v_rcp_f32_e32 v130, v130
	s_nop 0
	v_mul_f32_e32 v122, v122, v130
	s_and_b64 vcc, exec, s[8:9]
	v_mul_f32_e32 v123, v123, v136
	s_cbranch_vccnz .LBB0_1154
.LBB0_1287:
	v_mul_f32_e32 v130, 0xbfb8aa3b, v123
	v_exp_f32_e32 v130, v130
	s_nop 0
	v_add_f32_e32 v130, 1.0, v130
	v_rcp_f32_e32 v130, v130
	s_nop 0
	v_mul_f32_e32 v123, v123, v130
	s_and_b64 vcc, exec, s[8:9]
	s_waitcnt lgkmcnt(0)
	v_mul_f32_e32 v130, v116, v136
	s_cbranch_vccnz .LBB0_1155
.LBB0_1288:
	v_mul_f32_e32 v116, 0xbfb8aa3b, v130
	v_exp_f32_e32 v116, v116
	s_nop 0
	v_add_f32_e32 v116, 1.0, v116
	v_rcp_f32_e32 v116, v116
	s_nop 0
	v_mul_f32_e32 v130, v130, v116
	s_and_b64 vcc, exec, s[8:9]
	v_mul_f32_e32 v131, v117, v136
	s_cbranch_vccnz .LBB0_1156
.LBB0_1289:
	v_mul_f32_e32 v116, 0xbfb8aa3b, v131
	v_exp_f32_e32 v116, v116
	s_nop 0
	v_add_f32_e32 v116, 1.0, v116
	v_rcp_f32_e32 v116, v116
	s_nop 0
	v_mul_f32_e32 v131, v131, v116
	s_and_b64 vcc, exec, s[8:9]
	v_mul_f32_e32 v118, v118, v136
	s_cbranch_vccnz .LBB0_1157
.LBB0_1290:
	v_mul_f32_e32 v116, 0xbfb8aa3b, v118
	v_exp_f32_e32 v116, v116
	s_nop 0
	v_add_f32_e32 v116, 1.0, v116
	v_rcp_f32_e32 v116, v116
	s_nop 0
	v_mul_f32_e32 v118, v118, v116
	s_and_b64 vcc, exec, s[8:9]
	v_mul_f32_e32 v119, v119, v136
	s_cbranch_vccz .LBB0_1158
	s_branch .LBB0_1159
.LBB0_1291:
	v_mul_f32_e32 v112, 0xbfb8aa3b, v0
	v_exp_f32_e32 v112, v112
	s_nop 0
	v_add_f32_e32 v112, 1.0, v112
	v_rcp_f32_e32 v112, v112
	s_nop 0
	v_mul_f32_e32 v0, v0, v112
	s_and_b64 vcc, exec, s[8:9]
	v_mul_f32_e32 v112, v113, v118
	s_cbranch_vccnz .LBB0_1161
.LBB0_1292:
	v_mul_f32_e32 v113, 0xbfb8aa3b, v112
	v_exp_f32_e32 v113, v113
	s_nop 0
	v_add_f32_e32 v113, 1.0, v113
	v_rcp_f32_e32 v113, v113
	s_nop 0
	v_mul_f32_e32 v112, v112, v113
	s_and_b64 vcc, exec, s[8:9]
	v_mul_f32_e32 v113, v114, v118
	s_cbranch_vccnz .LBB0_1162
.LBB0_1293:
	v_mul_f32_e32 v114, 0xbfb8aa3b, v113
	v_exp_f32_e32 v114, v114
	s_nop 0
	v_add_f32_e32 v114, 1.0, v114
	v_rcp_f32_e32 v114, v114
	s_nop 0
	v_mul_f32_e32 v113, v113, v114
	s_and_b64 vcc, exec, s[8:9]
	v_mul_f32_e32 v114, v115, v118
	s_cbranch_vccnz .LBB0_1163
.LBB0_1294:
	v_mul_f32_e32 v115, 0xbfb8aa3b, v114
	v_exp_f32_e32 v115, v115
	s_nop 0
	v_add_f32_e32 v115, 1.0, v115
	v_rcp_f32_e32 v115, v115
	s_nop 0
	v_mul_f32_e32 v114, v114, v115
	s_and_b64 vcc, exec, s[8:9]
	s_waitcnt lgkmcnt(2)
	v_mul_f32_e32 v108, v108, v118
	s_cbranch_vccnz .LBB0_1164
.LBB0_1295:
	v_mul_f32_e32 v115, 0xbfb8aa3b, v108
	v_exp_f32_e32 v115, v115
	s_nop 0
	v_add_f32_e32 v115, 1.0, v115
	v_rcp_f32_e32 v115, v115
	s_nop 0
	v_mul_f32_e32 v108, v108, v115
	s_and_b64 vcc, exec, s[8:9]
	v_mul_f32_e32 v109, v109, v118
	s_cbranch_vccnz .LBB0_1165
.LBB0_1296:
	v_mul_f32_e32 v115, 0xbfb8aa3b, v109
	v_exp_f32_e32 v115, v115
	s_nop 0
	v_add_f32_e32 v115, 1.0, v115
	v_rcp_f32_e32 v115, v115
	s_nop 0
	v_mul_f32_e32 v109, v109, v115
	s_and_b64 vcc, exec, s[8:9]
	v_mul_f32_e32 v110, v110, v118
	s_cbranch_vccnz .LBB0_1166
; DI float sigm(float x) { return 1.f / (1.f + __expf(-x)); }
; DI float siluf(float x) { return x * sigm(x); }
; DI void phase_inproj1(const Params& p, int ch) {
;     ...
;     const bool isgate = bcol >= 768;
;     EPI256_BEGIN
;       float rs = rsqrtf(ssq1[row] * (1.f / 1024) + EPS);
; #pragma unroll
;       for (int i = 0; i < 16; ++i) { v[i] *= rs; if (isgate) v[i] = siluf(v[i]); }
;       store16_bf(Z + (size_t)row * 1024 + col, v);
.LBB0_1297:
	v_mul_f32_e32 v115, 0xbfb8aa3b, v110
	v_exp_f32_e32 v115, v115
	s_nop 0
	v_add_f32_e32 v115, 1.0, v115
	v_rcp_f32_e32 v115, v115
	s_nop 0
	v_mul_f32_e32 v110, v110, v115
	s_and_b64 vcc, exec, s[8:9]
	v_mul_f32_e32 v111, v111, v118
	s_cbranch_vccnz .LBB0_1167
.LBB0_1298:
	v_mul_f32_e32 v115, 0xbfb8aa3b, v111
	v_exp_f32_e32 v115, v115
	s_nop 0
	v_add_f32_e32 v115, 1.0, v115
	v_rcp_f32_e32 v115, v115
	s_nop 0
	v_mul_f32_e32 v111, v111, v115
	s_and_b64 vcc, exec, s[8:9]
	s_waitcnt lgkmcnt(1)
	v_mul_f32_e32 v104, v104, v118
	s_cbranch_vccnz .LBB0_1168
.LBB0_1299:
	v_mul_f32_e32 v115, 0xbfb8aa3b, v104
	v_exp_f32_e32 v115, v115
	s_nop 0
	v_add_f32_e32 v115, 1.0, v115
	v_rcp_f32_e32 v115, v115
	s_nop 0
	v_mul_f32_e32 v104, v104, v115
	s_and_b64 vcc, exec, s[8:9]
	v_mul_f32_e32 v105, v105, v118
	s_cbranch_vccnz .LBB0_1169
.LBB0_1300:
	v_mul_f32_e32 v115, 0xbfb8aa3b, v105
	v_exp_f32_e32 v115, v115
	s_nop 0
	v_add_f32_e32 v115, 1.0, v115
	v_rcp_f32_e32 v115, v115
	s_nop 0
	v_mul_f32_e32 v105, v105, v115
	s_and_b64 vcc, exec, s[8:9]
	v_mul_f32_e32 v106, v106, v118
	s_cbranch_vccnz .LBB0_1170
.LBB0_1301:
	v_mul_f32_e32 v115, 0xbfb8aa3b, v106
	v_exp_f32_e32 v115, v115
	s_nop 0
	v_add_f32_e32 v115, 1.0, v115
	v_rcp_f32_e32 v115, v115
	s_nop 0
	v_mul_f32_e32 v106, v106, v115
	s_and_b64 vcc, exec, s[8:9]
	v_mul_f32_e32 v107, v107, v118
	s_cbranch_vccnz .LBB0_1171
.LBB0_1302:
	v_mul_f32_e32 v115, 0xbfb8aa3b, v107
	v_exp_f32_e32 v115, v115
	s_nop 0
	v_add_f32_e32 v115, 1.0, v115
	v_rcp_f32_e32 v115, v115
	s_nop 0
	v_mul_f32_e32 v107, v107, v115
	s_and_b64 vcc, exec, s[8:9]
	s_waitcnt lgkmcnt(0)
	v_mul_f32_e32 v100, v100, v118
	s_cbranch_vccnz .LBB0_1172
.LBB0_1303:
	v_mul_f32_e32 v115, 0xbfb8aa3b, v100
	v_exp_f32_e32 v115, v115
	s_nop 0
	v_add_f32_e32 v115, 1.0, v115
	v_rcp_f32_e32 v115, v115
	s_nop 0
	v_mul_f32_e32 v100, v100, v115
	s_and_b64 vcc, exec, s[8:9]
	v_mul_f32_e32 v101, v101, v118
	s_cbranch_vccnz .LBB0_1173
.LBB0_1304:
	v_mul_f32_e32 v115, 0xbfb8aa3b, v101
	v_exp_f32_e32 v115, v115
	s_nop 0
	v_add_f32_e32 v115, 1.0, v115
	v_rcp_f32_e32 v115, v115
	s_nop 0
	v_mul_f32_e32 v101, v101, v115
	s_and_b64 vcc, exec, s[8:9]
	v_mul_f32_e32 v102, v102, v118
	s_cbranch_vccnz .LBB0_1174
.LBB0_1305:
	v_mul_f32_e32 v115, 0xbfb8aa3b, v102
	v_exp_f32_e32 v115, v115
	s_nop 0
	v_add_f32_e32 v115, 1.0, v115
	v_rcp_f32_e32 v115, v115
	s_nop 0
	v_mul_f32_e32 v102, v102, v115
	s_and_b64 vcc, exec, s[8:9]
	v_mul_f32_e32 v103, v103, v118
	s_cbranch_vccz .LBB0_1175
	s_branch .LBB0_1176
.LBB0_1306:
	v_mul_f32_e32 v96, 0xbfb8aa3b, v0
	v_exp_f32_e32 v96, v96
	s_nop 0
	v_add_f32_e32 v96, 1.0, v96
	v_rcp_f32_e32 v96, v96
	s_nop 0
	v_mul_f32_e32 v0, v0, v96
	s_and_b64 vcc, exec, s[8:9]
	v_mul_f32_e32 v96, v97, v100
	s_cbranch_vccnz .LBB0_1178
.LBB0_1307:
	v_mul_f32_e32 v97, 0xbfb8aa3b, v96
	v_exp_f32_e32 v97, v97
	s_nop 0
	v_add_f32_e32 v97, 1.0, v97
	v_rcp_f32_e32 v97, v97
	s_nop 0
	v_mul_f32_e32 v96, v96, v97
	s_and_b64 vcc, exec, s[8:9]
	v_mul_f32_e32 v97, v98, v100
	s_cbranch_vccnz .LBB0_1179
.LBB0_1308:
	v_mul_f32_e32 v98, 0xbfb8aa3b, v97
	v_exp_f32_e32 v98, v98
	s_nop 0
	v_add_f32_e32 v98, 1.0, v98
	v_rcp_f32_e32 v98, v98
	s_nop 0
	v_mul_f32_e32 v97, v97, v98
	s_and_b64 vcc, exec, s[8:9]
	v_mul_f32_e32 v98, v99, v100
	s_cbranch_vccnz .LBB0_1180
.LBB0_1309:
	v_mul_f32_e32 v99, 0xbfb8aa3b, v98
	v_exp_f32_e32 v99, v99
	s_nop 0
	v_add_f32_e32 v99, 1.0, v99
	v_rcp_f32_e32 v99, v99
	s_nop 0
	v_mul_f32_e32 v98, v98, v99
	s_and_b64 vcc, exec, s[8:9]
	s_waitcnt lgkmcnt(2)
	v_mul_f32_e32 v92, v92, v100
	s_cbranch_vccnz .LBB0_1181
.LBB0_1310:
	v_mul_f32_e32 v99, 0xbfb8aa3b, v92
	v_exp_f32_e32 v99, v99
	s_nop 0
	v_add_f32_e32 v99, 1.0, v99
	v_rcp_f32_e32 v99, v99
	s_nop 0
	v_mul_f32_e32 v92, v92, v99
	s_and_b64 vcc, exec, s[8:9]
	v_mul_f32_e32 v93, v93, v100
	s_cbranch_vccnz .LBB0_1182
.LBB0_1311:
	v_mul_f32_e32 v99, 0xbfb8aa3b, v93
	v_exp_f32_e32 v99, v99
	s_nop 0
	v_add_f32_e32 v99, 1.0, v99
	v_rcp_f32_e32 v99, v99
	s_nop 0
	v_mul_f32_e32 v93, v93, v99
	s_and_b64 vcc, exec, s[8:9]
	v_mul_f32_e32 v94, v94, v100
	s_cbranch_vccnz .LBB0_1183
.LBB0_1312:
	v_mul_f32_e32 v99, 0xbfb8aa3b, v94
	v_exp_f32_e32 v99, v99
	s_nop 0
	v_add_f32_e32 v99, 1.0, v99
	v_rcp_f32_e32 v99, v99
	s_nop 0
	v_mul_f32_e32 v94, v94, v99
	s_and_b64 vcc, exec, s[8:9]
	v_mul_f32_e32 v95, v95, v100
	s_cbranch_vccnz .LBB0_1184
.LBB0_1313:
	v_mul_f32_e32 v99, 0xbfb8aa3b, v95
	v_exp_f32_e32 v99, v99
	s_nop 0
	v_add_f32_e32 v99, 1.0, v99
	v_rcp_f32_e32 v99, v99
	s_nop 0
	v_mul_f32_e32 v95, v95, v99
	s_and_b64 vcc, exec, s[8:9]
	s_waitcnt lgkmcnt(1)
	v_mul_f32_e32 v88, v88, v100
	s_cbranch_vccnz .LBB0_1185
.LBB0_1314:
	v_mul_f32_e32 v99, 0xbfb8aa3b, v88
	v_exp_f32_e32 v99, v99
	s_nop 0
	v_add_f32_e32 v99, 1.0, v99
	v_rcp_f32_e32 v99, v99
	s_nop 0
	v_mul_f32_e32 v88, v88, v99
	s_and_b64 vcc, exec, s[8:9]
	v_mul_f32_e32 v89, v89, v100
	s_cbranch_vccnz .LBB0_1186
.LBB0_1315:
	v_mul_f32_e32 v99, 0xbfb8aa3b, v89
	v_exp_f32_e32 v99, v99
	s_nop 0
	v_add_f32_e32 v99, 1.0, v99
	v_rcp_f32_e32 v99, v99
	s_nop 0
	v_mul_f32_e32 v89, v89, v99
	s_and_b64 vcc, exec, s[8:9]
	v_mul_f32_e32 v90, v90, v100
	s_cbranch_vccnz .LBB0_1187
.LBB0_1316:
	v_mul_f32_e32 v99, 0xbfb8aa3b, v90
	v_exp_f32_e32 v99, v99
	s_nop 0
	v_add_f32_e32 v99, 1.0, v99
	v_rcp_f32_e32 v99, v99
	s_nop 0
	v_mul_f32_e32 v90, v90, v99
	s_and_b64 vcc, exec, s[8:9]
	v_mul_f32_e32 v91, v91, v100
	s_cbranch_vccnz .LBB0_1188
.LBB0_1317:
	v_mul_f32_e32 v99, 0xbfb8aa3b, v91
	v_exp_f32_e32 v99, v99
	s_nop 0
	v_add_f32_e32 v99, 1.0, v99
	v_rcp_f32_e32 v99, v99
	s_nop 0
	v_mul_f32_e32 v91, v91, v99
	s_and_b64 vcc, exec, s[8:9]
	s_waitcnt lgkmcnt(0)
	v_mul_f32_e32 v84, v84, v100
	s_cbranch_vccnz .LBB0_1189
; DI float sigm(float x) { return 1.f / (1.f + __expf(-x)); }
; DI float siluf(float x) { return x * sigm(x); }
; DI void phase_inproj1(const Params& p, int ch) {
;     ...
;     const bool isgate = bcol >= 768;
;     EPI256_BEGIN
;       float rs = rsqrtf(ssq1[row] * (1.f / 1024) + EPS);
; #pragma unroll
;       for (int i = 0; i < 16; ++i) { v[i] *= rs; if (isgate) v[i] = siluf(v[i]); }
;       store16_bf(Z + (size_t)row * 1024 + col, v);
.LBB0_1318:
	v_mul_f32_e32 v99, 0xbfb8aa3b, v84
	v_exp_f32_e32 v99, v99
	s_nop 0
	v_add_f32_e32 v99, 1.0, v99
	v_rcp_f32_e32 v99, v99
	s_nop 0
	v_mul_f32_e32 v84, v84, v99
	s_and_b64 vcc, exec, s[8:9]
	v_mul_f32_e32 v85, v85, v100
	s_cbranch_vccnz .LBB0_1190
.LBB0_1319:
	v_mul_f32_e32 v99, 0xbfb8aa3b, v85
	v_exp_f32_e32 v99, v99
	s_nop 0
	v_add_f32_e32 v99, 1.0, v99
	v_rcp_f32_e32 v99, v99
	s_nop 0
	v_mul_f32_e32 v85, v85, v99
	s_and_b64 vcc, exec, s[8:9]
	v_mul_f32_e32 v86, v86, v100
	s_cbranch_vccnz .LBB0_1191
.LBB0_1320:
	v_mul_f32_e32 v99, 0xbfb8aa3b, v86
	v_exp_f32_e32 v99, v99
	s_nop 0
	v_add_f32_e32 v99, 1.0, v99
	v_rcp_f32_e32 v99, v99
	s_nop 0
	v_mul_f32_e32 v86, v86, v99
	s_and_b64 vcc, exec, s[8:9]
	v_mul_f32_e32 v87, v87, v100
	s_cbranch_vccz .LBB0_1192
	s_branch .LBB0_1193
.LBB0_1321:
	v_mul_f32_e32 v80, 0xbfb8aa3b, v0
	v_exp_f32_e32 v80, v80
	s_nop 0
	v_add_f32_e32 v80, 1.0, v80
	v_rcp_f32_e32 v80, v80
	s_nop 0
	v_mul_f32_e32 v0, v0, v80
	s_and_b64 vcc, exec, s[8:9]
	v_mul_f32_e32 v80, v81, v84
	s_cbranch_vccnz .LBB0_1195
.LBB0_1322:
	v_mul_f32_e32 v81, 0xbfb8aa3b, v80
	v_exp_f32_e32 v81, v81
	s_nop 0
	v_add_f32_e32 v81, 1.0, v81
	v_rcp_f32_e32 v81, v81
	s_nop 0
	v_mul_f32_e32 v80, v80, v81
	s_and_b64 vcc, exec, s[8:9]
	v_mul_f32_e32 v81, v82, v84
	s_cbranch_vccnz .LBB0_1196
.LBB0_1323:
	v_mul_f32_e32 v82, 0xbfb8aa3b, v81
	v_exp_f32_e32 v82, v82
	s_nop 0
	v_add_f32_e32 v82, 1.0, v82
	v_rcp_f32_e32 v82, v82
	s_nop 0
	v_mul_f32_e32 v81, v81, v82
	s_and_b64 vcc, exec, s[8:9]
	v_mul_f32_e32 v82, v83, v84
	s_cbranch_vccnz .LBB0_1197
.LBB0_1324:
	v_mul_f32_e32 v83, 0xbfb8aa3b, v82
	v_exp_f32_e32 v83, v83
	s_nop 0
	v_add_f32_e32 v83, 1.0, v83
	v_rcp_f32_e32 v83, v83
	s_nop 0
	v_mul_f32_e32 v82, v82, v83
	s_and_b64 vcc, exec, s[8:9]
	s_waitcnt lgkmcnt(2)
	v_mul_f32_e32 v76, v76, v84
	s_cbranch_vccnz .LBB0_1198
.LBB0_1325:
	v_mul_f32_e32 v83, 0xbfb8aa3b, v76
	v_exp_f32_e32 v83, v83
	s_nop 0
	v_add_f32_e32 v83, 1.0, v83
	v_rcp_f32_e32 v83, v83
	s_nop 0
	v_mul_f32_e32 v76, v76, v83
	s_and_b64 vcc, exec, s[8:9]
	v_mul_f32_e32 v77, v77, v84
	s_cbranch_vccnz .LBB0_1199
.LBB0_1326:
	v_mul_f32_e32 v83, 0xbfb8aa3b, v77
	v_exp_f32_e32 v83, v83
	s_nop 0
	v_add_f32_e32 v83, 1.0, v83
	v_rcp_f32_e32 v83, v83
	s_nop 0
	v_mul_f32_e32 v77, v77, v83
	s_and_b64 vcc, exec, s[8:9]
	v_mul_f32_e32 v78, v78, v84
	s_cbranch_vccnz .LBB0_1200
.LBB0_1327:
	v_mul_f32_e32 v83, 0xbfb8aa3b, v78
	v_exp_f32_e32 v83, v83
	s_nop 0
	v_add_f32_e32 v83, 1.0, v83
	v_rcp_f32_e32 v83, v83
	s_nop 0
	v_mul_f32_e32 v78, v78, v83
	s_and_b64 vcc, exec, s[8:9]
	v_mul_f32_e32 v79, v79, v84
	s_cbranch_vccnz .LBB0_1201
.LBB0_1328:
	v_mul_f32_e32 v83, 0xbfb8aa3b, v79
	v_exp_f32_e32 v83, v83
	s_nop 0
	v_add_f32_e32 v83, 1.0, v83
	v_rcp_f32_e32 v83, v83
	s_nop 0
	v_mul_f32_e32 v79, v79, v83
	s_and_b64 vcc, exec, s[8:9]
	s_waitcnt lgkmcnt(1)
	v_mul_f32_e32 v72, v72, v84
	s_cbranch_vccnz .LBB0_1202
.LBB0_1329:
	v_mul_f32_e32 v83, 0xbfb8aa3b, v72
	v_exp_f32_e32 v83, v83
	s_nop 0
	v_add_f32_e32 v83, 1.0, v83
	v_rcp_f32_e32 v83, v83
	s_nop 0
	v_mul_f32_e32 v72, v72, v83
	s_and_b64 vcc, exec, s[8:9]
	v_mul_f32_e32 v73, v73, v84
	s_cbranch_vccnz .LBB0_1203
.LBB0_1330:
	v_mul_f32_e32 v83, 0xbfb8aa3b, v73
	v_exp_f32_e32 v83, v83
	s_nop 0
	v_add_f32_e32 v83, 1.0, v83
	v_rcp_f32_e32 v83, v83
	s_nop 0
	v_mul_f32_e32 v73, v73, v83
	s_and_b64 vcc, exec, s[8:9]
	v_mul_f32_e32 v74, v74, v84
	s_cbranch_vccnz .LBB0_1204
.LBB0_1331:
	v_mul_f32_e32 v83, 0xbfb8aa3b, v74
	v_exp_f32_e32 v83, v83
	s_nop 0
	v_add_f32_e32 v83, 1.0, v83
	v_rcp_f32_e32 v83, v83
	s_nop 0
	v_mul_f32_e32 v74, v74, v83
	s_and_b64 vcc, exec, s[8:9]
	v_mul_f32_e32 v75, v75, v84
	s_cbranch_vccnz .LBB0_1205
.LBB0_1332:
	v_mul_f32_e32 v83, 0xbfb8aa3b, v75
	v_exp_f32_e32 v83, v83
	s_nop 0
	v_add_f32_e32 v83, 1.0, v83
	v_rcp_f32_e32 v83, v83
	s_nop 0
	v_mul_f32_e32 v75, v75, v83
	s_and_b64 vcc, exec, s[8:9]
	s_waitcnt lgkmcnt(0)
	v_mul_f32_e32 v68, v68, v84
	s_cbranch_vccnz .LBB0_1206
.LBB0_1333:
	v_mul_f32_e32 v83, 0xbfb8aa3b, v68
	v_exp_f32_e32 v83, v83
	s_nop 0
	v_add_f32_e32 v83, 1.0, v83
	v_rcp_f32_e32 v83, v83
	s_nop 0
	v_mul_f32_e32 v68, v68, v83
	s_and_b64 vcc, exec, s[8:9]
	v_mul_f32_e32 v69, v69, v84
	s_cbranch_vccnz .LBB0_1207
.LBB0_1334:
	v_mul_f32_e32 v83, 0xbfb8aa3b, v69
	v_exp_f32_e32 v83, v83
	s_nop 0
	v_add_f32_e32 v83, 1.0, v83
	v_rcp_f32_e32 v83, v83
	s_nop 0
	v_mul_f32_e32 v69, v69, v83
	s_and_b64 vcc, exec, s[8:9]
	v_mul_f32_e32 v70, v70, v84
	s_cbranch_vccnz .LBB0_1208
.LBB0_1335:
	v_mul_f32_e32 v83, 0xbfb8aa3b, v70
	v_exp_f32_e32 v83, v83
	s_nop 0
	v_add_f32_e32 v83, 1.0, v83
	v_rcp_f32_e32 v83, v83
	s_nop 0
	v_mul_f32_e32 v70, v70, v83
	s_and_b64 vcc, exec, s[8:9]
	v_mul_f32_e32 v71, v71, v84
	s_cbranch_vccz .LBB0_1209
	s_branch .LBB0_1210
.LBB0_1336:
	v_mul_f32_e32 v64, 0xbfb8aa3b, v0
	v_exp_f32_e32 v64, v64
	s_nop 0
	v_add_f32_e32 v64, 1.0, v64
	v_rcp_f32_e32 v64, v64
	s_nop 0
	v_mul_f32_e32 v0, v0, v64
	s_and_b64 vcc, exec, s[8:9]
	v_mul_f32_e32 v64, v65, v68
	s_cbranch_vccnz .LBB0_1212
.LBB0_1337:
	v_mul_f32_e32 v65, 0xbfb8aa3b, v64
	v_exp_f32_e32 v65, v65
	s_nop 0
	v_add_f32_e32 v65, 1.0, v65
	v_rcp_f32_e32 v65, v65
	s_nop 0
	v_mul_f32_e32 v64, v64, v65
	s_and_b64 vcc, exec, s[8:9]
	v_mul_f32_e32 v65, v66, v68
	s_cbranch_vccnz .LBB0_1213
.LBB0_1338:
	v_mul_f32_e32 v66, 0xbfb8aa3b, v65
	v_exp_f32_e32 v66, v66
	s_nop 0
	v_add_f32_e32 v66, 1.0, v66
	v_rcp_f32_e32 v66, v66
	s_nop 0
	v_mul_f32_e32 v65, v65, v66
	s_and_b64 vcc, exec, s[8:9]
	v_mul_f32_e32 v66, v67, v68
	s_cbranch_vccnz .LBB0_1214
; DI float sigm(float x) { return 1.f / (1.f + __expf(-x)); }
; DI float siluf(float x) { return x * sigm(x); }
; DI void phase_inproj1(const Params& p, int ch) {
;     ...
;     const bool isgate = bcol >= 768;
;     EPI256_BEGIN
;       float rs = rsqrtf(ssq1[row] * (1.f / 1024) + EPS);
; #pragma unroll
;       for (int i = 0; i < 16; ++i) { v[i] *= rs; if (isgate) v[i] = siluf(v[i]); }
;       store16_bf(Z + (size_t)row * 1024 + col, v);
.LBB0_1339:
	v_mul_f32_e32 v67, 0xbfb8aa3b, v66
	v_exp_f32_e32 v67, v67
	s_nop 0
	v_add_f32_e32 v67, 1.0, v67
	v_rcp_f32_e32 v67, v67
	s_nop 0
	v_mul_f32_e32 v66, v66, v67
	s_and_b64 vcc, exec, s[8:9]
	s_waitcnt lgkmcnt(2)
	v_mul_f32_e32 v60, v60, v68
	s_cbranch_vccnz .LBB0_1215
.LBB0_1340:
	v_mul_f32_e32 v67, 0xbfb8aa3b, v60
	v_exp_f32_e32 v67, v67
	s_nop 0
	v_add_f32_e32 v67, 1.0, v67
	v_rcp_f32_e32 v67, v67
	s_nop 0
	v_mul_f32_e32 v60, v60, v67
	s_and_b64 vcc, exec, s[8:9]
	v_mul_f32_e32 v61, v61, v68
	s_cbranch_vccnz .LBB0_1216
.LBB0_1341:
	v_mul_f32_e32 v67, 0xbfb8aa3b, v61
	v_exp_f32_e32 v67, v67
	s_nop 0
	v_add_f32_e32 v67, 1.0, v67
	v_rcp_f32_e32 v67, v67
	s_nop 0
	v_mul_f32_e32 v61, v61, v67
	s_and_b64 vcc, exec, s[8:9]
	v_mul_f32_e32 v62, v62, v68
	s_cbranch_vccnz .LBB0_1217
.LBB0_1342:
	v_mul_f32_e32 v67, 0xbfb8aa3b, v62
	v_exp_f32_e32 v67, v67
	s_nop 0
	v_add_f32_e32 v67, 1.0, v67
	v_rcp_f32_e32 v67, v67
	s_nop 0
	v_mul_f32_e32 v62, v62, v67
	s_and_b64 vcc, exec, s[8:9]
	v_mul_f32_e32 v63, v63, v68
	s_cbranch_vccnz .LBB0_1218
.LBB0_1343:
	v_mul_f32_e32 v67, 0xbfb8aa3b, v63
	v_exp_f32_e32 v67, v67
	s_nop 0
	v_add_f32_e32 v67, 1.0, v67
	v_rcp_f32_e32 v67, v67
	s_nop 0
	v_mul_f32_e32 v63, v63, v67
	s_and_b64 vcc, exec, s[8:9]
	s_waitcnt lgkmcnt(1)
	v_mul_f32_e32 v56, v56, v68
	s_cbranch_vccnz .LBB0_1219
.LBB0_1344:
	v_mul_f32_e32 v67, 0xbfb8aa3b, v56
	v_exp_f32_e32 v67, v67
	s_nop 0
	v_add_f32_e32 v67, 1.0, v67
	v_rcp_f32_e32 v67, v67
	s_nop 0
	v_mul_f32_e32 v56, v56, v67
	s_and_b64 vcc, exec, s[8:9]
	v_mul_f32_e32 v57, v57, v68
	s_cbranch_vccnz .LBB0_1220
.LBB0_1345:
	v_mul_f32_e32 v67, 0xbfb8aa3b, v57
	v_exp_f32_e32 v67, v67
	s_nop 0
	v_add_f32_e32 v67, 1.0, v67
	v_rcp_f32_e32 v67, v67
	s_nop 0
	v_mul_f32_e32 v57, v57, v67
	s_and_b64 vcc, exec, s[8:9]
	v_mul_f32_e32 v58, v58, v68
	s_cbranch_vccnz .LBB0_1221
.LBB0_1346:
	v_mul_f32_e32 v67, 0xbfb8aa3b, v58
	v_exp_f32_e32 v67, v67
	s_nop 0
	v_add_f32_e32 v67, 1.0, v67
	v_rcp_f32_e32 v67, v67
	s_nop 0
	v_mul_f32_e32 v58, v58, v67
	s_and_b64 vcc, exec, s[8:9]
	v_mul_f32_e32 v59, v59, v68
	s_cbranch_vccnz .LBB0_1222
.LBB0_1347:
	v_mul_f32_e32 v67, 0xbfb8aa3b, v59
	v_exp_f32_e32 v67, v67
	s_nop 0
	v_add_f32_e32 v67, 1.0, v67
	v_rcp_f32_e32 v67, v67
	s_nop 0
	v_mul_f32_e32 v59, v59, v67
	s_and_b64 vcc, exec, s[8:9]
	s_waitcnt lgkmcnt(0)
	v_mul_f32_e32 v52, v52, v68
	s_cbranch_vccnz .LBB0_1223
.LBB0_1348:
	v_mul_f32_e32 v67, 0xbfb8aa3b, v52
	v_exp_f32_e32 v67, v67
	s_nop 0
	v_add_f32_e32 v67, 1.0, v67
	v_rcp_f32_e32 v67, v67
	s_nop 0
	v_mul_f32_e32 v52, v52, v67
	s_and_b64 vcc, exec, s[8:9]
	v_mul_f32_e32 v53, v53, v68
	s_cbranch_vccnz .LBB0_1224
.LBB0_1349:
	v_mul_f32_e32 v67, 0xbfb8aa3b, v53
	v_exp_f32_e32 v67, v67
	s_nop 0
	v_add_f32_e32 v67, 1.0, v67
	v_rcp_f32_e32 v67, v67
	s_nop 0
	v_mul_f32_e32 v53, v53, v67
	s_and_b64 vcc, exec, s[8:9]
	v_mul_f32_e32 v54, v54, v68
	s_cbranch_vccnz .LBB0_1225
.LBB0_1350:
	v_mul_f32_e32 v67, 0xbfb8aa3b, v54
	v_exp_f32_e32 v67, v67
	s_nop 0
	v_add_f32_e32 v67, 1.0, v67
	v_rcp_f32_e32 v67, v67
	s_nop 0
	v_mul_f32_e32 v54, v54, v67
	s_and_b64 vcc, exec, s[8:9]
	v_mul_f32_e32 v55, v55, v68
	s_cbranch_vccz .LBB0_1226
	s_branch .LBB0_1227
.LBB0_1351:
	v_mul_f32_e32 v48, 0xbfb8aa3b, v0
	v_exp_f32_e32 v48, v48
	s_nop 0
	v_add_f32_e32 v48, 1.0, v48
	v_rcp_f32_e32 v48, v48
	s_nop 0
	v_mul_f32_e32 v0, v0, v48
	s_and_b64 vcc, exec, s[8:9]
	v_mul_f32_e32 v48, v49, v52
	s_cbranch_vccnz .LBB0_1229
.LBB0_1352:
	v_mul_f32_e32 v49, 0xbfb8aa3b, v48
	v_exp_f32_e32 v49, v49
	s_nop 0
	v_add_f32_e32 v49, 1.0, v49
	v_rcp_f32_e32 v49, v49
	s_nop 0
	v_mul_f32_e32 v48, v48, v49
	s_and_b64 vcc, exec, s[8:9]
	v_mul_f32_e32 v49, v50, v52
	s_cbranch_vccnz .LBB0_1230
.LBB0_1353:
	v_mul_f32_e32 v50, 0xbfb8aa3b, v49
	v_exp_f32_e32 v50, v50
	s_nop 0
	v_add_f32_e32 v50, 1.0, v50
	v_rcp_f32_e32 v50, v50
	s_nop 0
	v_mul_f32_e32 v49, v49, v50
	s_and_b64 vcc, exec, s[8:9]
	v_mul_f32_e32 v50, v51, v52
	s_cbranch_vccnz .LBB0_1231
.LBB0_1354:
	v_mul_f32_e32 v51, 0xbfb8aa3b, v50
	v_exp_f32_e32 v51, v51
	s_nop 0
	v_add_f32_e32 v51, 1.0, v51
	v_rcp_f32_e32 v51, v51
	s_nop 0
	v_mul_f32_e32 v50, v50, v51
	s_and_b64 vcc, exec, s[8:9]
	s_waitcnt lgkmcnt(2)
	v_mul_f32_e32 v44, v44, v52
	s_cbranch_vccnz .LBB0_1232
.LBB0_1355:
	v_mul_f32_e32 v51, 0xbfb8aa3b, v44
	v_exp_f32_e32 v51, v51
	s_nop 0
	v_add_f32_e32 v51, 1.0, v51
	v_rcp_f32_e32 v51, v51
	s_nop 0
	v_mul_f32_e32 v44, v44, v51
	s_and_b64 vcc, exec, s[8:9]
	v_mul_f32_e32 v45, v45, v52
	s_cbranch_vccnz .LBB0_1233
.LBB0_1356:
	v_mul_f32_e32 v51, 0xbfb8aa3b, v45
	v_exp_f32_e32 v51, v51
	s_nop 0
	v_add_f32_e32 v51, 1.0, v51
	v_rcp_f32_e32 v51, v51
	s_nop 0
	v_mul_f32_e32 v45, v45, v51
	s_and_b64 vcc, exec, s[8:9]
	v_mul_f32_e32 v46, v46, v52
	s_cbranch_vccnz .LBB0_1234
.LBB0_1357:
	v_mul_f32_e32 v51, 0xbfb8aa3b, v46
	v_exp_f32_e32 v51, v51
	s_nop 0
	v_add_f32_e32 v51, 1.0, v51
	v_rcp_f32_e32 v51, v51
	s_nop 0
	v_mul_f32_e32 v46, v46, v51
	s_and_b64 vcc, exec, s[8:9]
	v_mul_f32_e32 v47, v47, v52
	s_cbranch_vccnz .LBB0_1235
.LBB0_1358:
	v_mul_f32_e32 v51, 0xbfb8aa3b, v47
	v_exp_f32_e32 v51, v51
	s_nop 0
	v_add_f32_e32 v51, 1.0, v51
	v_rcp_f32_e32 v51, v51
	s_nop 0
	v_mul_f32_e32 v47, v47, v51
	s_and_b64 vcc, exec, s[8:9]
	s_waitcnt lgkmcnt(1)
	v_mul_f32_e32 v40, v40, v52
	s_cbranch_vccnz .LBB0_1236
.LBB0_1359:
	v_mul_f32_e32 v51, 0xbfb8aa3b, v40
	v_exp_f32_e32 v51, v51
	s_nop 0
	v_add_f32_e32 v51, 1.0, v51
	v_rcp_f32_e32 v51, v51
	s_nop 0
	v_mul_f32_e32 v40, v40, v51
	s_and_b64 vcc, exec, s[8:9]
	v_mul_f32_e32 v41, v41, v52
	s_cbranch_vccnz .LBB0_1237
; DI float siluf(float x) { return x * sigm(x); }
; DI void phase_inproj1(const Params& p, int ch) {
;     ...
;       float rs = rsqrtf(ssq1[row] * (1.f / 1024) + EPS);
; #pragma unroll
;       for (int i = 0; i < 16; ++i) { v[i] *= rs; if (isgate) v[i] = siluf(v[i]); }
.LBB0_1360:
	v_mul_f32_e32 v51, 0xbfb8aa3b, v41
	v_exp_f32_e32 v51, v51
	s_nop 0
	v_add_f32_e32 v51, 1.0, v51
	v_rcp_f32_e32 v51, v51
	s_nop 0
	v_mul_f32_e32 v41, v41, v51
	s_and_b64 vcc, exec, s[8:9]
	v_mul_f32_e32 v42, v42, v52
	s_cbranch_vccnz .LBB0_1238
.LBB0_1361:
	v_mul_f32_e32 v51, 0xbfb8aa3b, v42
	v_exp_f32_e32 v51, v51
	s_nop 0
	v_add_f32_e32 v51, 1.0, v51
	v_rcp_f32_e32 v51, v51
	s_nop 0
	v_mul_f32_e32 v42, v42, v51
	s_and_b64 vcc, exec, s[8:9]
	v_mul_f32_e32 v43, v43, v52
	s_cbranch_vccnz .LBB0_1239
.LBB0_1362:
	v_mul_f32_e32 v51, 0xbfb8aa3b, v43
	v_exp_f32_e32 v51, v51
	s_nop 0
	v_add_f32_e32 v51, 1.0, v51
	v_rcp_f32_e32 v51, v51
	s_nop 0
	v_mul_f32_e32 v43, v43, v51
	s_and_b64 vcc, exec, s[8:9]
	s_waitcnt lgkmcnt(0)
	v_mul_f32_e32 v36, v36, v52
	s_cbranch_vccnz .LBB0_1240
.LBB0_1363:
	v_mul_f32_e32 v51, 0xbfb8aa3b, v36
	v_exp_f32_e32 v51, v51
	s_nop 0
	v_add_f32_e32 v51, 1.0, v51
	v_rcp_f32_e32 v51, v51
	s_nop 0
	v_mul_f32_e32 v36, v36, v51
	s_and_b64 vcc, exec, s[8:9]
	v_mul_f32_e32 v37, v37, v52
	s_cbranch_vccnz .LBB0_1241
.LBB0_1364:
	v_mul_f32_e32 v51, 0xbfb8aa3b, v37
	v_exp_f32_e32 v51, v51
	s_nop 0
	v_add_f32_e32 v51, 1.0, v51
	v_rcp_f32_e32 v51, v51
	s_nop 0
	v_mul_f32_e32 v37, v37, v51
	s_and_b64 vcc, exec, s[8:9]
	v_mul_f32_e32 v38, v38, v52
	s_cbranch_vccnz .LBB0_1242
.LBB0_1365:
	v_mul_f32_e32 v51, 0xbfb8aa3b, v38
	v_exp_f32_e32 v51, v51
	s_nop 0
	v_add_f32_e32 v51, 1.0, v51
	v_rcp_f32_e32 v51, v51
	s_nop 0
	v_mul_f32_e32 v38, v38, v51
	s_and_b64 vcc, exec, s[8:9]
	v_mul_f32_e32 v39, v39, v52
	s_cbranch_vccz .LBB0_1243
	s_branch .LBB0_1244
.LBB0_1366:
	v_mul_f32_e32 v32, 0xbfb8aa3b, v0
	v_exp_f32_e32 v32, v32
	s_nop 0
	v_add_f32_e32 v32, 1.0, v32
	v_rcp_f32_e32 v32, v32
	s_nop 0
	v_mul_f32_e32 v0, v0, v32
	s_and_b64 vcc, exec, s[8:9]
	v_mul_f32_e32 v32, v33, v36
	s_cbranch_vccnz .LBB0_1246
.LBB0_1367:
	v_mul_f32_e32 v33, 0xbfb8aa3b, v32
	v_exp_f32_e32 v33, v33
	s_nop 0
	v_add_f32_e32 v33, 1.0, v33
	v_rcp_f32_e32 v33, v33
	s_nop 0
	v_mul_f32_e32 v32, v32, v33
	s_and_b64 vcc, exec, s[8:9]
	v_mul_f32_e32 v33, v34, v36
	s_cbranch_vccnz .LBB0_1247
.LBB0_1368:
	v_mul_f32_e32 v34, 0xbfb8aa3b, v33
	v_exp_f32_e32 v34, v34
	s_nop 0
	v_add_f32_e32 v34, 1.0, v34
	v_rcp_f32_e32 v34, v34
	s_nop 0
	v_mul_f32_e32 v33, v33, v34
	s_and_b64 vcc, exec, s[8:9]
	v_mul_f32_e32 v34, v35, v36
	s_cbranch_vccnz .LBB0_1248
.LBB0_1369:
	v_mul_f32_e32 v35, 0xbfb8aa3b, v34
	v_exp_f32_e32 v35, v35
	s_nop 0
	v_add_f32_e32 v35, 1.0, v35
	v_rcp_f32_e32 v35, v35
	s_nop 0
	v_mul_f32_e32 v34, v34, v35
	s_and_b64 vcc, exec, s[8:9]
	s_waitcnt lgkmcnt(2)
	v_mul_f32_e32 v28, v28, v36
	s_cbranch_vccnz .LBB0_1249
.LBB0_1370:
	v_mul_f32_e32 v35, 0xbfb8aa3b, v28
	v_exp_f32_e32 v35, v35
	s_nop 0
	v_add_f32_e32 v35, 1.0, v35
	v_rcp_f32_e32 v35, v35
	s_nop 0
	v_mul_f32_e32 v28, v28, v35
	s_and_b64 vcc, exec, s[8:9]
	v_mul_f32_e32 v29, v29, v36
	s_cbranch_vccnz .LBB0_1250
.LBB0_1371:
	v_mul_f32_e32 v35, 0xbfb8aa3b, v29
	v_exp_f32_e32 v35, v35
	s_nop 0
	v_add_f32_e32 v35, 1.0, v35
	v_rcp_f32_e32 v35, v35
	s_nop 0
	v_mul_f32_e32 v29, v29, v35
	s_and_b64 vcc, exec, s[8:9]
	v_mul_f32_e32 v30, v30, v36
	s_cbranch_vccnz .LBB0_1251
.LBB0_1372:
	v_mul_f32_e32 v35, 0xbfb8aa3b, v30
	v_exp_f32_e32 v35, v35
	s_nop 0
	v_add_f32_e32 v35, 1.0, v35
	v_rcp_f32_e32 v35, v35
	s_nop 0
	v_mul_f32_e32 v30, v30, v35
	s_and_b64 vcc, exec, s[8:9]
	v_mul_f32_e32 v31, v31, v36
	s_cbranch_vccnz .LBB0_1252
.LBB0_1373:
	v_mul_f32_e32 v35, 0xbfb8aa3b, v31
	v_exp_f32_e32 v35, v35
	s_nop 0
	v_add_f32_e32 v35, 1.0, v35
	v_rcp_f32_e32 v35, v35
	s_nop 0
	v_mul_f32_e32 v31, v31, v35
	s_and_b64 vcc, exec, s[8:9]
	s_waitcnt lgkmcnt(1)
	v_mul_f32_e32 v24, v24, v36
	s_cbranch_vccnz .LBB0_1253
.LBB0_1374:
	v_mul_f32_e32 v35, 0xbfb8aa3b, v24
	v_exp_f32_e32 v35, v35
	s_nop 0
	v_add_f32_e32 v35, 1.0, v35
	v_rcp_f32_e32 v35, v35
	s_nop 0
	v_mul_f32_e32 v24, v24, v35
	s_and_b64 vcc, exec, s[8:9]
	v_mul_f32_e32 v25, v25, v36
	s_cbranch_vccnz .LBB0_1254
.LBB0_1375:
	v_mul_f32_e32 v35, 0xbfb8aa3b, v25
	v_exp_f32_e32 v35, v35
	s_nop 0
	v_add_f32_e32 v35, 1.0, v35
	v_rcp_f32_e32 v35, v35
	s_nop 0
	v_mul_f32_e32 v25, v25, v35
	s_and_b64 vcc, exec, s[8:9]
	v_mul_f32_e32 v26, v26, v36
	s_cbranch_vccnz .LBB0_1255
.LBB0_1376:
	v_mul_f32_e32 v35, 0xbfb8aa3b, v26
	v_exp_f32_e32 v35, v35
	s_nop 0
	v_add_f32_e32 v35, 1.0, v35
	v_rcp_f32_e32 v35, v35
	s_nop 0
	v_mul_f32_e32 v26, v26, v35
	s_and_b64 vcc, exec, s[8:9]
	v_mul_f32_e32 v27, v27, v36
	s_cbranch_vccnz .LBB0_1256
.LBB0_1377:
	v_mul_f32_e32 v35, 0xbfb8aa3b, v27
	v_exp_f32_e32 v35, v35
	s_nop 0
	v_add_f32_e32 v35, 1.0, v35
	v_rcp_f32_e32 v35, v35
	s_nop 0
	v_mul_f32_e32 v27, v27, v35
	s_and_b64 vcc, exec, s[8:9]
	s_waitcnt lgkmcnt(0)
	v_mul_f32_e32 v20, v20, v36
	s_cbranch_vccnz .LBB0_1257
; DI float siluf(float x) { return x * sigm(x); }
; DI void phase_inproj1(const Params& p, int ch) {
;     ...
;       float rs = rsqrtf(ssq1[row] * (1.f / 1024) + EPS);
; #pragma unroll
;       for (int i = 0; i < 16; ++i) { v[i] *= rs; if (isgate) v[i] = siluf(v[i]); }
.LBB0_1378:
	v_mul_f32_e32 v35, 0xbfb8aa3b, v20
	v_exp_f32_e32 v35, v35
	s_nop 0
	v_add_f32_e32 v35, 1.0, v35
	v_rcp_f32_e32 v35, v35
	s_nop 0
	v_mul_f32_e32 v20, v20, v35
	s_and_b64 vcc, exec, s[8:9]
	v_mul_f32_e32 v21, v21, v36
	s_cbranch_vccnz .LBB0_1258
.LBB0_1379:
	v_mul_f32_e32 v35, 0xbfb8aa3b, v21
	v_exp_f32_e32 v35, v35
	s_nop 0
	v_add_f32_e32 v35, 1.0, v35
	v_rcp_f32_e32 v35, v35
	s_nop 0
	v_mul_f32_e32 v21, v21, v35
	s_and_b64 vcc, exec, s[8:9]
	v_mul_f32_e32 v22, v22, v36
	s_cbranch_vccnz .LBB0_1259
.LBB0_1380:
	v_mul_f32_e32 v35, 0xbfb8aa3b, v22
	v_exp_f32_e32 v35, v35
	s_nop 0
	v_add_f32_e32 v35, 1.0, v35
	v_rcp_f32_e32 v35, v35
	s_nop 0
	v_mul_f32_e32 v22, v22, v35
	s_and_b64 vcc, exec, s[8:9]
	v_mul_f32_e32 v23, v23, v36
	s_cbranch_vccz .LBB0_1260
	s_branch .LBB0_1261
.LBB0_1381:
	v_mul_f32_e32 v14, 0xbfb8aa3b, v0
	v_exp_f32_e32 v14, v14
	s_nop 0
	v_add_f32_e32 v14, 1.0, v14
	v_rcp_f32_e32 v14, v14
	s_nop 0
	v_mul_f32_e32 v0, v0, v14
	s_and_b64 vcc, exec, s[8:9]
	v_mul_f32_e32 v14, v15, v20
	s_cbranch_vccnz .LBB0_1263
.LBB0_1382:
	v_mul_f32_e32 v15, 0xbfb8aa3b, v14
	v_exp_f32_e32 v15, v15
	s_nop 0
	v_add_f32_e32 v15, 1.0, v15
	v_rcp_f32_e32 v15, v15
	s_nop 0
	v_mul_f32_e32 v14, v14, v15
	s_and_b64 vcc, exec, s[8:9]
	v_mul_f32_e32 v15, v16, v20
	s_cbranch_vccnz .LBB0_1264
.LBB0_1383:
	v_mul_f32_e32 v16, 0xbfb8aa3b, v15
	v_exp_f32_e32 v16, v16
	s_nop 0
	v_add_f32_e32 v16, 1.0, v16
	v_rcp_f32_e32 v16, v16
	s_nop 0
	v_mul_f32_e32 v15, v15, v16
	s_and_b64 vcc, exec, s[8:9]
	v_mul_f32_e32 v16, v17, v20
	s_cbranch_vccnz .LBB0_1265
.LBB0_1384:
	v_mul_f32_e32 v17, 0xbfb8aa3b, v16
	v_exp_f32_e32 v17, v17
	s_nop 0
	v_add_f32_e32 v17, 1.0, v17
	v_rcp_f32_e32 v17, v17
	s_nop 0
	v_mul_f32_e32 v16, v16, v17
	s_and_b64 vcc, exec, s[8:9]
	s_waitcnt lgkmcnt(2)
	v_mul_f32_e32 v10, v10, v20
	s_cbranch_vccnz .LBB0_1266
.LBB0_1385:
	v_mul_f32_e32 v17, 0xbfb8aa3b, v10
	v_exp_f32_e32 v17, v17
	s_nop 0
	v_add_f32_e32 v17, 1.0, v17
	v_rcp_f32_e32 v17, v17
	s_nop 0
	v_mul_f32_e32 v10, v10, v17
	s_and_b64 vcc, exec, s[8:9]
	v_mul_f32_e32 v11, v11, v20
	s_cbranch_vccnz .LBB0_1267
.LBB0_1386:
	v_mul_f32_e32 v17, 0xbfb8aa3b, v11
	v_exp_f32_e32 v17, v17
	s_nop 0
	v_add_f32_e32 v17, 1.0, v17
	v_rcp_f32_e32 v17, v17
	s_nop 0
	v_mul_f32_e32 v11, v11, v17
	s_and_b64 vcc, exec, s[8:9]
	v_mul_f32_e32 v12, v12, v20
	s_cbranch_vccnz .LBB0_1268
.LBB0_1387:
	v_mul_f32_e32 v17, 0xbfb8aa3b, v12
	v_exp_f32_e32 v17, v17
	s_nop 0
	v_add_f32_e32 v17, 1.0, v17
	v_rcp_f32_e32 v17, v17
	s_nop 0
	v_mul_f32_e32 v12, v12, v17
	s_and_b64 vcc, exec, s[8:9]
	v_mul_f32_e32 v13, v13, v20
	s_cbranch_vccnz .LBB0_1269
.LBB0_1388:
	v_mul_f32_e32 v17, 0xbfb8aa3b, v13
	v_exp_f32_e32 v17, v17
	s_nop 0
	v_add_f32_e32 v17, 1.0, v17
	v_rcp_f32_e32 v17, v17
	s_nop 0
	v_mul_f32_e32 v13, v13, v17
	s_and_b64 vcc, exec, s[8:9]
	s_waitcnt lgkmcnt(1)
	v_mul_f32_e32 v6, v6, v20
	s_cbranch_vccnz .LBB0_1270
.LBB0_1389:
	v_mul_f32_e32 v17, 0xbfb8aa3b, v6
	v_exp_f32_e32 v17, v17
	s_nop 0
	v_add_f32_e32 v17, 1.0, v17
	v_rcp_f32_e32 v17, v17
	s_nop 0
	v_mul_f32_e32 v6, v6, v17
	s_and_b64 vcc, exec, s[8:9]
	v_mul_f32_e32 v7, v7, v20
	s_cbranch_vccnz .LBB0_1271
.LBB0_1390:
	v_mul_f32_e32 v17, 0xbfb8aa3b, v7
	v_exp_f32_e32 v17, v17
	s_nop 0
	v_add_f32_e32 v17, 1.0, v17
	v_rcp_f32_e32 v17, v17
	s_nop 0
	v_mul_f32_e32 v7, v7, v17
	s_and_b64 vcc, exec, s[8:9]
	v_mul_f32_e32 v8, v8, v20
	s_cbranch_vccnz .LBB0_1272
.LBB0_1391:
	v_mul_f32_e32 v17, 0xbfb8aa3b, v8
	v_exp_f32_e32 v17, v17
	s_nop 0
	v_add_f32_e32 v17, 1.0, v17
	v_rcp_f32_e32 v17, v17
	s_nop 0
	v_mul_f32_e32 v8, v8, v17
	s_and_b64 vcc, exec, s[8:9]
	v_mul_f32_e32 v9, v9, v20
	s_cbranch_vccnz .LBB0_1273
.LBB0_1392:
	v_mul_f32_e32 v17, 0xbfb8aa3b, v9
	v_exp_f32_e32 v17, v17
	s_nop 0
	v_add_f32_e32 v17, 1.0, v17
	v_rcp_f32_e32 v17, v17
	s_nop 0
	v_mul_f32_e32 v9, v9, v17
	s_and_b64 vcc, exec, s[8:9]
	s_waitcnt lgkmcnt(0)
	v_mul_f32_e32 v2, v2, v20
	s_cbranch_vccnz .LBB0_1274
.LBB0_1393:
	v_mul_f32_e32 v17, 0xbfb8aa3b, v2
	v_exp_f32_e32 v17, v17
	s_nop 0
	v_add_f32_e32 v17, 1.0, v17
	v_rcp_f32_e32 v17, v17
	s_nop 0
	v_mul_f32_e32 v2, v2, v17
	s_and_b64 vcc, exec, s[8:9]
	v_mul_f32_e32 v3, v3, v20
	s_cbranch_vccnz .LBB0_1275
.LBB0_1394:
	v_mul_f32_e32 v17, 0xbfb8aa3b, v3
	v_exp_f32_e32 v17, v17
	s_nop 0
	v_add_f32_e32 v17, 1.0, v17
	v_rcp_f32_e32 v17, v17
	s_nop 0
	v_mul_f32_e32 v3, v3, v17
	s_and_b64 vcc, exec, s[8:9]
	v_mul_f32_e32 v4, v4, v20
	s_cbranch_vccnz .LBB0_1276
.LBB0_1395:
	v_mul_f32_e32 v17, 0xbfb8aa3b, v4
	v_exp_f32_e32 v17, v17
	s_nop 0
	v_add_f32_e32 v17, 1.0, v17
	v_rcp_f32_e32 v17, v17
	s_nop 0
	v_mul_f32_e32 v4, v4, v17
	s_and_b64 vcc, exec, s[8:9]
	v_mul_f32_e32 v5, v5, v20
	s_cbranch_vccnz .LBB0_1128

; DI float sigm(float x) { return 1.f / (1.f + __expf(-x)); }
; DI void phase_ple(const Params& p, int layer, const bft* hbin, bft* hbout, int ldo, float* ssq) {
;     ...
;       float v2[16]; epi_stage(tid, acc2[m], v2); float h[16]; float* hp = p.out + (size_t)row * 1024 + col; load16_f(hp, h); float ss = 0.f;
; #pragma unroll
;       for (int i = 0; i < 16; ++i) { h[i] += sigm(v[i]) * v2[i]; ss += h[i] * h[i]; }
;       store16_f(hp, h); if (hbout) store16_bf(hbout + (size_t)row * ldo + col, h);
;       ss += __shfl_xor(ss, 1); ss += __shfl_xor(ss, 2);
;       if ((lane & 3) == 0) atomicAdd(ssq + row, ss);
.LBB0_1852:
	v_lshrrev_b32_e32 v129, 6, v143
	v_lshrrev_b32_e32 v130, 2, v143
	v_mul_lo_u32 v129, v129, s25
	v_and_b32_e32 v130, 12, v130
	v_add_u32_e32 v129, s83, v129
	v_lshlrev_b32_e32 v131, 2, v148
	v_mul_u32_u24_e32 v130, 0x110, v130
	v_add3_u32 v138, v129, v131, v130
	v_bfe_u32 v130, v143, 2, 4
	v_and_b32_e32 v132, 48, v144
	v_mul_u32_u24_e32 v131, 0x110, v130
	v_lshlrev_b32_e32 v132, 2, v132
	v_add3_u32 v139, v129, v131, v132
	v_ashrrev_i32_e32 v129, 1, v143
	v_and_b32_e32 v129, 0xffffffc0, v129
	s_waitcnt vmcnt(0)
	s_barrier
	v_and_b32_e32 v128, 64, v143
	v_add_u32_e32 v129, s11, v129
	v_and_b32_e32 v143, 3, v143
	ds_write2_b32 v138, v92, v88 offset1:16
	ds_write2_b32 v138, v93, v89 offset0:68 offset1:84
	ds_write2_b32 v138, v94, v90 offset0:136 offset1:152
	ds_write2_b32 v138, v95, v91 offset0:204 offset1:220
	ds_write2_b32 v138, v84, v80 offset0:32 offset1:48
	ds_write2_b32 v138, v85, v81 offset0:100 offset1:116
	ds_write2_b32 v138, v86, v82 offset0:168 offset1:184
	ds_write2_b32 v138, v87, v83 offset0:236 offset1:252
	v_or_b32_e32 v134, v129, v130
	v_lshlrev_b32_e32 v129, 4, v143
	s_waitcnt lgkmcnt(0)
	v_or3_b32 v132, v129, v128, s10
	ds_read_b128 v[84:87], v139
	ds_read_b128 v[144:147], v139 offset:16
	ds_read_b128 v[128:131], v139 offset:32
	ds_read_b128 v[92:95], v139 offset:48
	v_ashrrev_i32_e32 v135, 31, v134
	ds_write2_b32 v138, v124, v120 offset1:16
	ds_write2_b32 v138, v125, v121 offset0:68 offset1:84
	ds_write2_b32 v138, v126, v122 offset0:136 offset1:152
	ds_write2_b32 v138, v127, v123 offset0:204 offset1:220
	ds_write2_b32 v138, v116, v112 offset0:32 offset1:48
	ds_write2_b32 v138, v117, v113 offset0:100 offset1:116
	ds_write2_b32 v138, v118, v114 offset0:168 offset1:184
	ds_write2_b32 v138, v119, v115 offset0:236 offset1:252
	v_lshlrev_b64 v[88:89], 12, v[134:135]
	s_waitcnt lgkmcnt(0)
	v_lshl_add_u64 v[88:89], s[16:17], 0, v[88:89]
	v_lshlrev_b32_e32 v132, 2, v132
	ds_read_b128 v[120:123], v139
	ds_read_b128 v[148:151], v139 offset:16
	ds_read_b128 v[112:115], v139 offset:32
	ds_read_b128 v[80:83], v139 offset:48
	v_lshl_add_u64 v[124:125], v[88:89], 0, v[132:133]
	global_load_dwordx4 v[152:155], v[124:125], off
	s_waitcnt lgkmcnt(14)
	v_mul_f32_e32 v84, 0xbfb8aa3b, v84
	v_mul_f32_e32 v85, 0xbfb8aa3b, v85
	v_exp_f32_e32 v84, v84
	v_exp_f32_e32 v85, v85
	global_load_dwordx4 v[156:159], v[124:125], off offset:16
	global_load_dwordx4 v[88:91], v[124:125], off offset:48
	global_load_dwordx4 v[116:119], v[124:125], off offset:32
	v_mul_f32_e32 v86, 0xbfb8aa3b, v86
	v_mul_f32_e32 v87, 0xbfb8aa3b, v87
	v_pk_add_f32 v[84:85], v[84:85], 1.0 op_sel_hi:[1,0]
	v_exp_f32_e32 v86, v86
	v_exp_f32_e32 v87, v87
	s_waitcnt lgkmcnt(13)
	v_mul_f32_e32 v128, 0xbfb8aa3b, v128
	v_mul_f32_e32 v129, 0xbfb8aa3b, v129
	v_rcp_f32_e32 v85, v85
	v_pk_add_f32 v[86:87], v[86:87], 1.0 op_sel_hi:[1,0]
	v_rcp_f32_e32 v84, v84
	v_exp_f32_e32 v128, v128
	v_exp_f32_e32 v129, v129
	v_mul_f32_e32 v130, 0xbfb8aa3b, v130
	v_mul_f32_e32 v131, 0xbfb8aa3b, v131
	v_exp_f32_e32 v130, v130
	v_pk_add_f32 v[128:129], v[128:129], 1.0 op_sel_hi:[1,0]
	v_exp_f32_e32 v131, v131
	s_waitcnt lgkmcnt(12)
	v_mul_f32_e32 v92, 0xbfb8aa3b, v92
	v_mul_f32_e32 v93, 0xbfb8aa3b, v93
	v_exp_f32_e32 v92, v92
	v_pk_add_f32 v[130:131], v[130:131], 1.0 op_sel_hi:[1,0]
	v_exp_f32_e32 v93, v93
	v_mul_f32_e32 v94, 0xbfb8aa3b, v94
	v_mul_f32_e32 v95, 0xbfb8aa3b, v95
	v_exp_f32_e32 v94, v94
	v_pk_add_f32 v[92:93], v[92:93], 1.0 op_sel_hi:[1,0]
	v_exp_f32_e32 v95, v95
	v_cmp_eq_u32_e64 s[8:9], 0, v143
	v_pk_add_f32 v[94:95], v[94:95], 1.0 op_sel_hi:[1,0]
	s_waitcnt vmcnt(3) lgkmcnt(3)
	v_pk_fma_f32 v[84:85], v[84:85], v[120:121], v[152:153]
	v_rcp_f32_e32 v87, v87
	v_mul_f32_e32 v120, 0xbfb8aa3b, v144
	v_mul_f32_e32 v121, 0xbfb8aa3b, v145
	v_exp_f32_e32 v120, v120
	v_exp_f32_e32 v121, v121
	v_rcp_f32_e32 v86, v86
	v_pk_add_f32 v[120:121], v[120:121], 1.0 op_sel_hi:[1,0]
	v_pk_fma_f32 v[86:87], v[86:87], v[122:123], v[154:155]
	v_pk_mul_f32 v[126:127], v[84:85], v[84:85]
	v_pk_mul_f32 v[136:137], v[86:87], v[86:87]
	v_rcp_f32_e32 v121, v121
	v_mul_f32_e32 v122, 0xbfb8aa3b, v146
	v_mul_f32_e32 v123, 0xbfb8aa3b, v147
	v_exp_f32_e32 v122, v122
	v_exp_f32_e32 v123, v123
	v_rcp_f32_e32 v120, v120
	v_pk_add_f32 v[122:123], v[122:123], 1.0 op_sel_hi:[1,0]
	s_waitcnt vmcnt(2) lgkmcnt(2)
	v_pk_fma_f32 v[120:121], v[120:121], v[148:149], v[156:157]
	v_pk_mul_f32 v[140:141], v[120:121], v[120:121]
	v_rcp_f32_e32 v123, v123
	v_rcp_f32_e32 v122, v122
	s_nop 0
	v_pk_fma_f32 v[122:123], v[122:123], v[150:151], v[158:159]
	v_rcp_f32_e32 v129, v129
	v_pk_mul_f32 v[144:145], v[122:123], v[122:123]
	v_rcp_f32_e32 v128, v128
	s_waitcnt vmcnt(0) lgkmcnt(1)
	v_pk_fma_f32 v[116:117], v[128:129], v[112:113], v[116:117]
	v_rcp_f32_e32 v129, v131
	v_pk_mul_f32 v[112:113], v[116:117], v[116:117]
	v_rcp_f32_e32 v128, v130
	s_nop 0
	v_pk_fma_f32 v[118:119], v[128:129], v[114:115], v[118:119]
	v_rcp_f32_e32 v93, v93
	v_pk_mul_f32 v[114:115], v[118:119], v[118:119]
	v_rcp_f32_e32 v92, v92
	s_waitcnt lgkmcnt(0)
	v_pk_fma_f32 v[88:89], v[92:93], v[80:81], v[88:89]
	v_rcp_f32_e32 v93, v95
	v_pk_mul_f32 v[80:81], v[88:89], v[88:89]
	v_rcp_f32_e32 v92, v94
	s_nop 0
	v_pk_fma_f32 v[90:91], v[92:93], v[82:83], v[90:91]
	v_add_f32_e32 v92, v126, v127
	v_add_f32_e32 v92, v136, v92
	v_add_f32_e32 v92, v137, v92
	v_add_f32_e32 v92, v140, v92
	v_add_f32_e32 v92, v141, v92
	v_add_f32_e32 v92, v144, v92
	v_add_f32_e32 v92, v145, v92
	v_add_f32_e32 v92, v112, v92
	v_add_f32_e32 v92, v113, v92
	v_add_f32_e32 v92, v114, v92
	v_add_f32_e32 v92, v115, v92
	v_add_f32_e32 v80, v80, v92
	v_pk_mul_f32 v[82:83], v[90:91], v[90:91]
	v_add_f32_e32 v80, v81, v80
	v_add_f32_e32 v80, v82, v80
	v_and_b32_e32 v82, 64, v181
	v_xor_b32_e32 v81, 1, v181
	v_add_u32_e32 v82, 64, v82
	v_cmp_lt_i32_e32 vcc, v81, v82
	v_add_f32_e32 v80, v83, v80
	global_store_dwordx4 v[124:125], v[84:87], off
	global_store_dwordx4 v[124:125], v[120:123], off offset:16
	global_store_dwordx4 v[124:125], v[116:119], off offset:32
	global_store_dwordx4 v[124:125], v[88:91], off offset:48
	v_cndmask_b32_e32 v81, v181, v81, vcc
	v_lshlrev_b32_e32 v114, 2, v81
	ds_bpermute_b32 v81, v114, v80
	s_waitcnt lgkmcnt(0)
	v_add_f32_e32 v80, v80, v81
	v_xor_b32_e32 v81, 2, v181
	v_cmp_lt_i32_e32 vcc, v81, v82
	s_nop 1
	v_cndmask_b32_e32 v81, v181, v81, vcc
	v_lshlrev_b32_e32 v115, 2, v81
	ds_bpermute_b32 v81, v115, v80
	s_and_saveexec_b64 s[0:1], s[8:9]
	s_cbranch_execz .LBB0_1854
	s_waitcnt lgkmcnt(0)
	v_add_f32_e32 v82, v80, v81
	v_lshl_add_u64 v[80:81], v[134:135], 2, s[14:15]
	global_atomic_add_f32 v[80:81], v82, off
; DI float sigm(float x) { return 1.f / (1.f + __expf(-x)); }
; DI void phase_ple(const Params& p, int layer, const bft* hbin, bft* hbout, int ldo, float* ssq) {
;     ...
;       float v2[16]; epi_stage(tid, acc2[m], v2); float h[16]; float* hp = p.out + (size_t)row * 1024 + col; load16_f(hp, h); float ss = 0.f;
; #pragma unroll
;       for (int i = 0; i < 16; ++i) { h[i] += sigm(v[i]) * v2[i]; ss += h[i] * h[i]; }
;       store16_f(hp, h); if (hbout) store16_bf(hbout + (size_t)row * ldo + col, h);
;       ss += __shfl_xor(ss, 1); ss += __shfl_xor(ss, 2);
;       if ((lane & 3) == 0) atomicAdd(ssq + row, ss);
.LBB0_1854:
	s_or_b64 exec, exec, s[0:1]
	ds_write2_b32 v138, v60, v56 offset1:16
	ds_write2_b32 v138, v61, v57 offset0:68 offset1:84
	ds_write2_b32 v138, v62, v58 offset0:136 offset1:152
	ds_write2_b32 v138, v63, v59 offset0:204 offset1:220
	ds_write2_b32 v138, v52, v48 offset0:32 offset1:48
	ds_write2_b32 v138, v53, v49 offset0:100 offset1:116
	ds_write2_b32 v138, v54, v50 offset0:168 offset1:184
	ds_write2_b32 v138, v55, v51 offset0:236 offset1:252
	s_waitcnt lgkmcnt(0)
	v_or_b32_e32 v112, 16, v134
	ds_read_b128 v[56:59], v139
	ds_read_b128 v[92:95], v139 offset:16
	ds_read_b128 v[84:87], v139 offset:32
	ds_read_b128 v[52:55], v139 offset:48
	v_ashrrev_i32_e32 v113, 31, v112
	ds_write2_b32 v138, v108, v104 offset1:16
	ds_write2_b32 v138, v109, v105 offset0:68 offset1:84
	ds_write2_b32 v138, v110, v106 offset0:136 offset1:152
	ds_write2_b32 v138, v111, v107 offset0:204 offset1:220
	ds_write2_b32 v138, v100, v96 offset0:32 offset1:48
	ds_write2_b32 v138, v101, v97 offset0:100 offset1:116
	ds_write2_b32 v138, v102, v98 offset0:168 offset1:184
	ds_write2_b32 v138, v103, v99 offset0:236 offset1:252
	v_lshlrev_b64 v[88:89], 12, v[112:113]
	s_waitcnt lgkmcnt(0)
	v_lshl_add_u64 v[88:89], s[16:17], 0, v[88:89]
	ds_read_b128 v[60:63], v139
	ds_read_b128 v[102:105], v139 offset:16
	s_waitcnt lgkmcnt(14)
	ds_read_b128 v[80:83], v139 offset:32
	ds_read_b128 v[48:51], v139 offset:48
	v_lshl_add_u64 v[96:97], v[88:89], 0, v[132:133]
	global_load_dwordx4 v[98:101], v[96:97], off
	global_load_dwordx4 v[106:109], v[96:97], off offset:16
	s_waitcnt lgkmcnt(14)
	v_mul_f32_e32 v56, 0xbfb8aa3b, v56
	v_mul_f32_e32 v57, 0xbfb8aa3b, v57
	v_exp_f32_e32 v110, v56
	v_exp_f32_e32 v111, v57
	v_mul_f32_e32 v58, 0xbfb8aa3b, v58
	v_mul_f32_e32 v59, 0xbfb8aa3b, v59
	v_exp_f32_e32 v116, v58
	v_pk_add_f32 v[110:111], v[110:111], 1.0 op_sel_hi:[1,0]
	v_exp_f32_e32 v117, v59
	v_div_scale_f32 v120, s[0:1], v110, v110, 1.0
	v_rcp_f32_e32 v124, v120
	v_pk_add_f32 v[116:117], v[116:117], 1.0 op_sel_hi:[1,0]
	v_div_scale_f32 v122, s[0:1], v117, v117, 1.0
	v_fma_f32 v128, -v120, v124, 1.0
	v_div_scale_f32 v121, s[10:11], 1.0, v110, 1.0
	v_rcp_f32_e32 v125, v122
	v_fmac_f32_e32 v124, v128, v124
	v_mul_f32_e32 v128, v121, v124
	global_load_dwordx4 v[56:59], v[96:97], off offset:48
	global_load_dwordx4 v[88:91], v[96:97], off offset:32
	v_fma_f32 v131, -v120, v128, v121
	v_fmac_f32_e32 v128, v131, v124
	v_fma_f32 v129, -v122, v125, 1.0
	v_fma_f32 v119, -v120, v128, v121
	s_mov_b64 vcc, s[10:11]
	v_div_scale_f32 v126, s[12:13], 1.0, v117, 1.0
	v_fmac_f32_e32 v125, v129, v125
	v_rcp_f32_e32 v111, v111
	s_nop 4
	v_div_fmas_f32 v118, v119, v124, v128
	v_mul_f32_e32 v129, v126, v125
	v_div_fixup_f32 v110, v118, v110, 1.0
	v_fma_f32 v135, -v122, v129, v126
	v_fmac_f32_e32 v129, v135, v125
	s_mov_b64 vcc, s[12:13]
	v_mul_f32_e32 v92, 0xbfb8aa3b, v92
	v_mul_f32_e32 v93, 0xbfb8aa3b, v93
	v_exp_f32_e32 v92, v92
	v_exp_f32_e32 v93, v93
	v_mul_f32_e32 v94, 0xbfb8aa3b, v94
	v_mul_f32_e32 v95, 0xbfb8aa3b, v95
	v_exp_f32_e32 v94, v94
	v_pk_add_f32 v[92:93], v[92:93], 1.0 op_sel_hi:[1,0]
	v_exp_f32_e32 v95, v95
	s_waitcnt lgkmcnt(13)
	v_mul_f32_e32 v84, 0xbfb8aa3b, v84
	v_mul_f32_e32 v85, 0xbfb8aa3b, v85
	v_exp_f32_e32 v84, v84
	v_pk_add_f32 v[94:95], v[94:95], 1.0 op_sel_hi:[1,0]
	v_exp_f32_e32 v85, v85
	v_mul_f32_e32 v86, 0xbfb8aa3b, v86
	v_mul_f32_e32 v87, 0xbfb8aa3b, v87
	v_exp_f32_e32 v86, v86
	v_pk_add_f32 v[84:85], v[84:85], 1.0 op_sel_hi:[1,0]
	v_exp_f32_e32 v87, v87
	s_waitcnt lgkmcnt(12)
	v_mul_f32_e32 v52, 0xbfb8aa3b, v52
	v_mul_f32_e32 v53, 0xbfb8aa3b, v53
	v_exp_f32_e32 v52, v52
	v_pk_add_f32 v[86:87], v[86:87], 1.0 op_sel_hi:[1,0]
	v_exp_f32_e32 v53, v53
	v_mul_f32_e32 v54, 0xbfb8aa3b, v54
	v_mul_f32_e32 v55, 0xbfb8aa3b, v55
	s_waitcnt vmcnt(3) lgkmcnt(3)
	v_pk_fma_f32 v[60:61], v[110:111], v[60:61], v[98:99]
	v_fma_f32 v110, -v122, v129, v126
	v_div_fmas_f32 v110, v110, v125, v129
	v_div_fixup_f32 v111, v110, v117, 1.0
	v_rcp_f32_e32 v110, v116
	s_nop 0
	v_pk_fma_f32 v[62:63], v[110:111], v[62:63], v[100:101]
	v_pk_add_f32 v[52:53], v[52:53], 1.0 op_sel_hi:[1,0]
	v_rcp_f32_e32 v93, v93
	v_exp_f32_e32 v54, v54
	v_rcp_f32_e32 v92, v92
	s_waitcnt vmcnt(2) lgkmcnt(2)
	v_pk_fma_f32 v[92:93], v[92:93], v[102:103], v[106:107]
	v_exp_f32_e32 v55, v55
	v_rcp_f32_e32 v95, v95
	v_pk_add_f32 v[54:55], v[54:55], 1.0 op_sel_hi:[1,0]
	v_rcp_f32_e32 v94, v94
	s_nop 0
	v_pk_fma_f32 v[94:95], v[94:95], v[104:105], v[108:109]
	v_pk_mul_f32 v[98:99], v[60:61], v[60:61]
	v_rcp_f32_e32 v85, v85
	v_pk_mul_f32 v[100:101], v[62:63], v[62:63]
	v_rcp_f32_e32 v84, v84
	s_waitcnt vmcnt(0) lgkmcnt(1)
	v_pk_fma_f32 v[80:81], v[84:85], v[80:81], v[88:89]
	v_pk_mul_f32 v[102:103], v[92:93], v[92:93]
	v_rcp_f32_e32 v87, v87
	v_pk_mul_f32 v[104:105], v[94:95], v[94:95]
	v_rcp_f32_e32 v86, v86
	s_nop 0
	v_pk_fma_f32 v[82:83], v[86:87], v[82:83], v[90:91]
	v_pk_mul_f32 v[84:85], v[80:81], v[80:81]
	v_rcp_f32_e32 v53, v53
	v_pk_mul_f32 v[86:87], v[82:83], v[82:83]
	v_rcp_f32_e32 v52, v52
	s_waitcnt lgkmcnt(0)
	v_pk_fma_f32 v[52:53], v[52:53], v[48:49], v[56:57]
	v_div_scale_f32 v88, s[0:1], v54, v54, 1.0
	v_rcp_f32_e32 v89, v88
	v_rcp_f32_e32 v55, v55
	v_pk_mul_f32 v[48:49], v[52:53], v[52:53]
	v_fma_f32 v56, -v88, v89, 1.0
	v_fmac_f32_e32 v89, v56, v89
	v_div_scale_f32 v56, vcc, 1.0, v54, 1.0
	v_mul_f32_e32 v57, v56, v89
	v_fma_f32 v90, -v88, v57, v56
	v_fmac_f32_e32 v57, v90, v89
	v_fma_f32 v56, -v88, v57, v56
	v_div_fmas_f32 v56, v56, v89, v57
	v_div_fixup_f32 v54, v56, v54, 1.0
	v_add_f32_e32 v56, v98, v99
	v_add_f32_e32 v56, v100, v56
	v_add_f32_e32 v56, v101, v56
	v_add_f32_e32 v56, v102, v56
	v_add_f32_e32 v56, v103, v56
	v_add_f32_e32 v56, v104, v56
	v_add_f32_e32 v56, v105, v56
	v_add_f32_e32 v56, v84, v56
	v_add_f32_e32 v56, v85, v56
	v_add_f32_e32 v56, v86, v56
	v_add_f32_e32 v56, v87, v56
	v_pk_fma_f32 v[54:55], v[54:55], v[50:51], v[58:59]
	v_add_f32_e32 v48, v48, v56
	v_pk_mul_f32 v[50:51], v[54:55], v[54:55]
	v_add_f32_e32 v48, v49, v48
	v_add_f32_e32 v48, v50, v48
	v_add_f32_e32 v48, v51, v48
	ds_bpermute_b32 v49, v114, v48
	global_store_dwordx4 v[96:97], v[60:63], off
	global_store_dwordx4 v[96:97], v[92:95], off offset:16
	global_store_dwordx4 v[96:97], v[80:83], off offset:32
	global_store_dwordx4 v[96:97], v[52:55], off offset:48
	s_waitcnt lgkmcnt(0)
	v_add_f32_e32 v48, v48, v49
	ds_bpermute_b32 v49, v115, v48
	s_and_saveexec_b64 s[0:1], s[8:9]
	s_cbranch_execz .LBB0_1856
	s_waitcnt lgkmcnt(0)
	v_add_f32_e32 v50, v48, v49
	v_lshl_add_u64 v[48:49], v[112:113], 2, s[14:15]
	global_atomic_add_f32 v[48:49], v50, off
; DI float sigm(float x) { return 1.f / (1.f + __expf(-x)); }
; DI void phase_ple(const Params& p, int layer, const bft* hbin, bft* hbout, int ldo, float* ssq) {
;     ...
;       float v2[16]; epi_stage(tid, acc2[m], v2); float h[16]; float* hp = p.out + (size_t)row * 1024 + col; load16_f(hp, h); float ss = 0.f;
; #pragma unroll
;       for (int i = 0; i < 16; ++i) { h[i] += sigm(v[i]) * v2[i]; ss += h[i] * h[i]; }
;       store16_f(hp, h); if (hbout) store16_bf(hbout + (size_t)row * ldo + col, h);
;       ss += __shfl_xor(ss, 1); ss += __shfl_xor(ss, 2);
;       if ((lane & 3) == 0) atomicAdd(ssq + row, ss);
.LBB0_1856:
	s_or_b64 exec, exec, s[0:1]
	ds_write2_b32 v138, v28, v24 offset1:16
	ds_write2_b32 v138, v29, v25 offset0:68 offset1:84
	ds_write2_b32 v138, v30, v26 offset0:136 offset1:152
	ds_write2_b32 v138, v31, v27 offset0:204 offset1:220
	ds_write2_b32 v138, v20, v16 offset0:32 offset1:48
	ds_write2_b32 v138, v21, v17 offset0:100 offset1:116
	ds_write2_b32 v138, v22, v18 offset0:168 offset1:184
	ds_write2_b32 v138, v23, v19 offset0:236 offset1:252
	s_waitcnt lgkmcnt(0)
	v_or_b32_e32 v80, 32, v134
	ds_read_b128 v[24:27], v139
	ds_read_b128 v[60:63], v139 offset:16
	ds_read_b128 v[52:55], v139 offset:32
	ds_read_b128 v[20:23], v139 offset:48
	v_ashrrev_i32_e32 v81, 31, v80
	ds_write2_b32 v138, v76, v72 offset1:16
	ds_write2_b32 v138, v77, v73 offset0:68 offset1:84
	ds_write2_b32 v138, v78, v74 offset0:136 offset1:152
	ds_write2_b32 v138, v79, v75 offset0:204 offset1:220
	ds_write2_b32 v138, v68, v64 offset0:32 offset1:48
	ds_write2_b32 v138, v69, v65 offset0:100 offset1:116
	ds_write2_b32 v138, v70, v66 offset0:168 offset1:184
	ds_write2_b32 v138, v71, v67 offset0:236 offset1:252
	v_lshlrev_b64 v[56:57], 12, v[80:81]
	s_waitcnt lgkmcnt(0)
	v_lshl_add_u64 v[56:57], s[16:17], 0, v[56:57]
	ds_read_b128 v[28:31], v139
	ds_read_b128 v[70:73], v139 offset:16
	s_waitcnt lgkmcnt(14)
	ds_read_b128 v[48:51], v139 offset:32
	ds_read_b128 v[16:19], v139 offset:48
	v_lshl_add_u64 v[64:65], v[56:57], 0, v[132:133]
	global_load_dwordx4 v[66:69], v[64:65], off
	global_load_dwordx4 v[74:77], v[64:65], off offset:16
	s_waitcnt lgkmcnt(14)
	v_mul_f32_e32 v24, 0xbfb8aa3b, v24
	v_mul_f32_e32 v25, 0xbfb8aa3b, v25
	v_exp_f32_e32 v78, v24
	v_exp_f32_e32 v79, v25
	v_mul_f32_e32 v26, 0xbfb8aa3b, v26
	v_mul_f32_e32 v27, 0xbfb8aa3b, v27
	v_exp_f32_e32 v82, v26
	v_pk_add_f32 v[78:79], v[78:79], 1.0 op_sel_hi:[1,0]
	v_exp_f32_e32 v83, v27
	v_div_scale_f32 v86, s[0:1], v78, v78, 1.0
	v_rcp_f32_e32 v90, v86
	v_pk_add_f32 v[82:83], v[82:83], 1.0 op_sel_hi:[1,0]
	v_div_scale_f32 v88, s[0:1], v83, v83, 1.0
	v_fma_f32 v94, -v86, v90, 1.0
	v_div_scale_f32 v87, s[10:11], 1.0, v78, 1.0
	v_rcp_f32_e32 v91, v88
	v_fmac_f32_e32 v90, v94, v90
	v_mul_f32_e32 v94, v87, v90
	global_load_dwordx4 v[24:27], v[64:65], off offset:48
	global_load_dwordx4 v[56:59], v[64:65], off offset:32
	v_fma_f32 v97, -v86, v94, v87
	v_fmac_f32_e32 v94, v97, v90
	v_fma_f32 v95, -v88, v91, 1.0
	v_fma_f32 v85, -v86, v94, v87
	s_mov_b64 vcc, s[10:11]
	v_div_scale_f32 v92, s[12:13], 1.0, v83, 1.0
	v_fmac_f32_e32 v91, v95, v91
	v_rcp_f32_e32 v79, v79
	s_nop 4
	v_div_fmas_f32 v84, v85, v90, v94
	v_mul_f32_e32 v95, v92, v91
	v_div_fixup_f32 v78, v84, v78, 1.0
	v_fma_f32 v98, -v88, v95, v92
	v_fmac_f32_e32 v95, v98, v91
	s_mov_b64 vcc, s[12:13]
	v_mul_f32_e32 v60, 0xbfb8aa3b, v60
	v_mul_f32_e32 v61, 0xbfb8aa3b, v61
	v_exp_f32_e32 v60, v60
	v_exp_f32_e32 v61, v61
	v_mul_f32_e32 v62, 0xbfb8aa3b, v62
	v_mul_f32_e32 v63, 0xbfb8aa3b, v63
	v_exp_f32_e32 v62, v62
	v_pk_add_f32 v[60:61], v[60:61], 1.0 op_sel_hi:[1,0]
	v_exp_f32_e32 v63, v63
	s_waitcnt lgkmcnt(13)
	v_mul_f32_e32 v52, 0xbfb8aa3b, v52
	v_mul_f32_e32 v53, 0xbfb8aa3b, v53
	v_exp_f32_e32 v52, v52
	v_pk_add_f32 v[62:63], v[62:63], 1.0 op_sel_hi:[1,0]
	v_exp_f32_e32 v53, v53
	v_mul_f32_e32 v54, 0xbfb8aa3b, v54
	v_mul_f32_e32 v55, 0xbfb8aa3b, v55
	v_exp_f32_e32 v54, v54
	v_pk_add_f32 v[52:53], v[52:53], 1.0 op_sel_hi:[1,0]
	v_exp_f32_e32 v55, v55
	s_waitcnt lgkmcnt(12)
	v_mul_f32_e32 v20, 0xbfb8aa3b, v20
	v_mul_f32_e32 v21, 0xbfb8aa3b, v21
	v_exp_f32_e32 v20, v20
	v_pk_add_f32 v[54:55], v[54:55], 1.0 op_sel_hi:[1,0]
	v_exp_f32_e32 v21, v21
	v_mul_f32_e32 v22, 0xbfb8aa3b, v22
	v_mul_f32_e32 v23, 0xbfb8aa3b, v23
	s_waitcnt vmcnt(3) lgkmcnt(3)
	v_pk_fma_f32 v[28:29], v[78:79], v[28:29], v[66:67]
	v_fma_f32 v78, -v88, v95, v92
	v_div_fmas_f32 v78, v78, v91, v95
	v_div_fixup_f32 v79, v78, v83, 1.0
	v_rcp_f32_e32 v78, v82
	s_nop 0
	v_pk_fma_f32 v[30:31], v[78:79], v[30:31], v[68:69]
	v_pk_add_f32 v[20:21], v[20:21], 1.0 op_sel_hi:[1,0]
	v_rcp_f32_e32 v61, v61
	v_exp_f32_e32 v22, v22
	v_rcp_f32_e32 v60, v60
	s_waitcnt vmcnt(2) lgkmcnt(2)
	v_pk_fma_f32 v[60:61], v[60:61], v[70:71], v[74:75]
	v_exp_f32_e32 v23, v23
	v_rcp_f32_e32 v63, v63
	v_pk_add_f32 v[22:23], v[22:23], 1.0 op_sel_hi:[1,0]
	v_rcp_f32_e32 v62, v62
	s_nop 0
	v_pk_fma_f32 v[62:63], v[62:63], v[72:73], v[76:77]
	v_pk_mul_f32 v[66:67], v[28:29], v[28:29]
	v_rcp_f32_e32 v53, v53
	v_pk_mul_f32 v[68:69], v[30:31], v[30:31]
	v_rcp_f32_e32 v52, v52
	s_waitcnt vmcnt(0) lgkmcnt(1)
	v_pk_fma_f32 v[48:49], v[52:53], v[48:49], v[56:57]
	v_pk_mul_f32 v[70:71], v[60:61], v[60:61]
	v_rcp_f32_e32 v55, v55
	v_pk_mul_f32 v[72:73], v[62:63], v[62:63]
	v_rcp_f32_e32 v54, v54
	s_nop 0
	v_pk_fma_f32 v[50:51], v[54:55], v[50:51], v[58:59]
	v_pk_mul_f32 v[52:53], v[48:49], v[48:49]
	v_rcp_f32_e32 v21, v21
	v_pk_mul_f32 v[54:55], v[50:51], v[50:51]
	v_rcp_f32_e32 v20, v20
	s_waitcnt lgkmcnt(0)
	v_pk_fma_f32 v[20:21], v[20:21], v[16:17], v[24:25]
	v_div_scale_f32 v56, s[0:1], v22, v22, 1.0
	v_rcp_f32_e32 v57, v56
	v_rcp_f32_e32 v23, v23
	v_pk_mul_f32 v[16:17], v[20:21], v[20:21]
	v_fma_f32 v24, -v56, v57, 1.0
	v_fmac_f32_e32 v57, v24, v57
	v_div_scale_f32 v24, vcc, 1.0, v22, 1.0
	v_mul_f32_e32 v25, v24, v57
	v_fma_f32 v58, -v56, v25, v24
	v_fmac_f32_e32 v25, v58, v57
	v_fma_f32 v24, -v56, v25, v24
	v_div_fmas_f32 v24, v24, v57, v25
	v_div_fixup_f32 v22, v24, v22, 1.0
	v_add_f32_e32 v24, v66, v67
	v_add_f32_e32 v24, v68, v24
	v_add_f32_e32 v24, v69, v24
	v_add_f32_e32 v24, v70, v24
	v_add_f32_e32 v24, v71, v24
	v_add_f32_e32 v24, v72, v24
	v_add_f32_e32 v24, v73, v24
	v_add_f32_e32 v24, v52, v24
	v_add_f32_e32 v24, v53, v24
	v_add_f32_e32 v24, v54, v24
	v_add_f32_e32 v24, v55, v24
	v_pk_fma_f32 v[22:23], v[22:23], v[18:19], v[26:27]
	v_add_f32_e32 v16, v16, v24
	v_pk_mul_f32 v[18:19], v[22:23], v[22:23]
	v_add_f32_e32 v16, v17, v16
	v_add_f32_e32 v16, v18, v16
	v_add_f32_e32 v16, v19, v16
	ds_bpermute_b32 v17, v114, v16
	global_store_dwordx4 v[64:65], v[28:31], off
	global_store_dwordx4 v[64:65], v[60:63], off offset:16
	global_store_dwordx4 v[64:65], v[48:51], off offset:32
	global_store_dwordx4 v[64:65], v[20:23], off offset:48
	s_waitcnt lgkmcnt(0)
	v_add_f32_e32 v16, v16, v17
	ds_bpermute_b32 v17, v115, v16
	s_and_saveexec_b64 s[0:1], s[8:9]
	s_cbranch_execz .LBB0_1858
	s_waitcnt lgkmcnt(0)
	v_add_f32_e32 v18, v16, v17
	v_lshl_add_u64 v[16:17], v[80:81], 2, s[14:15]
	global_atomic_add_f32 v[16:17], v18, off
; DI float sigm(float x) { return 1.f / (1.f + __expf(-x)); }
; DI void phase_ple(const Params& p, int layer, const bft* hbin, bft* hbout, int ldo, float* ssq) {
;     ...
;       float v2[16]; epi_stage(tid, acc2[m], v2); float h[16]; float* hp = p.out + (size_t)row * 1024 + col; load16_f(hp, h); float ss = 0.f;
; #pragma unroll
;       for (int i = 0; i < 16; ++i) { h[i] += sigm(v[i]) * v2[i]; ss += h[i] * h[i]; }
;       store16_f(hp, h); if (hbout) store16_bf(hbout + (size_t)row * ldo + col, h);
;       ss += __shfl_xor(ss, 1); ss += __shfl_xor(ss, 2);
;       if ((lane & 3) == 0) atomicAdd(ssq + row, ss);
.LBB0_1858:
	s_or_b64 exec, exec, s[0:1]
	ds_write2_b32 v138, v8, v4 offset1:16
	ds_write2_b32 v138, v9, v5 offset0:68 offset1:84
	ds_write2_b32 v138, v10, v6 offset0:136 offset1:152
	ds_write2_b32 v138, v11, v7 offset0:204 offset1:220
	ds_write2_b32 v138, v0, v12 offset0:32 offset1:48
	ds_write2_b32 v138, v1, v13 offset0:100 offset1:116
	ds_write2_b32 v138, v2, v14 offset0:168 offset1:184
	ds_write2_b32 v138, v3, v15 offset0:236 offset1:252
	s_waitcnt lgkmcnt(0)
	v_or_b32_e32 v48, 48, v134
	ds_read_b128 v[8:11], v139
	ds_read_b128 v[28:31], v139 offset:16
	ds_read_b128 v[20:23], v139 offset:32
	ds_read_b128 v[4:7], v139 offset:48
	v_ashrrev_i32_e32 v49, 31, v48
	ds_write2_b32 v138, v40, v36 offset1:16
	ds_write2_b32 v138, v41, v37 offset0:68 offset1:84
	ds_write2_b32 v138, v42, v38 offset0:136 offset1:152
	ds_write2_b32 v138, v43, v39 offset0:204 offset1:220
	ds_write2_b32 v138, v32, v44 offset0:32 offset1:48
	ds_write2_b32 v138, v33, v45 offset0:100 offset1:116
	ds_write2_b32 v138, v34, v46 offset0:168 offset1:184
	ds_write2_b32 v138, v35, v47 offset0:236 offset1:252
	v_lshlrev_b64 v[24:25], 12, v[48:49]
	s_waitcnt lgkmcnt(0)
	v_lshl_add_u64 v[24:25], s[16:17], 0, v[24:25]
	ds_read_b128 v[12:15], v139
	ds_read_b128 v[38:41], v139 offset:16
	s_waitcnt lgkmcnt(14)
	ds_read_b128 v[16:19], v139 offset:32
	ds_read_b128 v[0:3], v139 offset:48
	v_lshl_add_u64 v[32:33], v[24:25], 0, v[132:133]
	global_load_dwordx4 v[34:37], v[32:33], off
	global_load_dwordx4 v[42:45], v[32:33], off offset:16
	s_waitcnt lgkmcnt(14)
	v_mul_f32_e32 v8, 0xbfb8aa3b, v8
	v_mul_f32_e32 v9, 0xbfb8aa3b, v9
	v_exp_f32_e32 v46, v8
	v_exp_f32_e32 v47, v9
	v_mul_f32_e32 v10, 0xbfb8aa3b, v10
	v_mul_f32_e32 v11, 0xbfb8aa3b, v11
	v_exp_f32_e32 v50, v10
	v_pk_add_f32 v[46:47], v[46:47], 1.0 op_sel_hi:[1,0]
	v_exp_f32_e32 v51, v11
	v_div_scale_f32 v54, s[0:1], v46, v46, 1.0
	v_rcp_f32_e32 v58, v54
	v_pk_add_f32 v[50:51], v[50:51], 1.0 op_sel_hi:[1,0]
	v_div_scale_f32 v56, s[0:1], v51, v51, 1.0
	v_fma_f32 v62, -v54, v58, 1.0
	v_div_scale_f32 v55, s[10:11], 1.0, v46, 1.0
	v_rcp_f32_e32 v59, v56
	v_fmac_f32_e32 v58, v62, v58
	v_mul_f32_e32 v62, v55, v58
	global_load_dwordx4 v[8:11], v[32:33], off offset:48
	global_load_dwordx4 v[24:27], v[32:33], off offset:32
	v_fma_f32 v65, -v54, v62, v55
	v_fmac_f32_e32 v62, v65, v58
	v_fma_f32 v63, -v56, v59, 1.0
	v_fma_f32 v53, -v54, v62, v55
	s_mov_b64 vcc, s[10:11]
	v_div_scale_f32 v60, s[12:13], 1.0, v51, 1.0
	v_fmac_f32_e32 v59, v63, v59
	v_rcp_f32_e32 v47, v47
	s_nop 4
	v_div_fmas_f32 v52, v53, v58, v62
	v_mul_f32_e32 v63, v60, v59
	v_div_fixup_f32 v46, v52, v46, 1.0
	v_fma_f32 v66, -v56, v63, v60
	v_fmac_f32_e32 v63, v66, v59
	s_mov_b64 vcc, s[12:13]
	v_mul_f32_e32 v28, 0xbfb8aa3b, v28
	v_mul_f32_e32 v29, 0xbfb8aa3b, v29
	v_exp_f32_e32 v28, v28
	v_exp_f32_e32 v29, v29
	v_mul_f32_e32 v30, 0xbfb8aa3b, v30
	v_mul_f32_e32 v31, 0xbfb8aa3b, v31
	v_exp_f32_e32 v30, v30
	v_pk_add_f32 v[28:29], v[28:29], 1.0 op_sel_hi:[1,0]
	v_exp_f32_e32 v31, v31
	s_waitcnt lgkmcnt(13)
	v_mul_f32_e32 v20, 0xbfb8aa3b, v20
	v_mul_f32_e32 v21, 0xbfb8aa3b, v21
	v_exp_f32_e32 v20, v20
	v_pk_add_f32 v[30:31], v[30:31], 1.0 op_sel_hi:[1,0]
	v_exp_f32_e32 v21, v21
	v_mul_f32_e32 v22, 0xbfb8aa3b, v22
	v_mul_f32_e32 v23, 0xbfb8aa3b, v23
	v_exp_f32_e32 v22, v22
	v_pk_add_f32 v[20:21], v[20:21], 1.0 op_sel_hi:[1,0]
	v_exp_f32_e32 v23, v23
	s_waitcnt lgkmcnt(12)
	v_mul_f32_e32 v4, 0xbfb8aa3b, v4
	v_mul_f32_e32 v5, 0xbfb8aa3b, v5
	v_exp_f32_e32 v4, v4
	v_pk_add_f32 v[22:23], v[22:23], 1.0 op_sel_hi:[1,0]
	v_exp_f32_e32 v5, v5
	v_mul_f32_e32 v6, 0xbfb8aa3b, v6
	v_mul_f32_e32 v7, 0xbfb8aa3b, v7
	s_waitcnt vmcnt(3) lgkmcnt(3)
	v_pk_fma_f32 v[12:13], v[46:47], v[12:13], v[34:35]
	v_fma_f32 v46, -v56, v63, v60
	v_div_fmas_f32 v46, v46, v59, v63
	v_div_fixup_f32 v47, v46, v51, 1.0
	v_rcp_f32_e32 v46, v50
	s_nop 0
	v_pk_fma_f32 v[14:15], v[46:47], v[14:15], v[36:37]
	v_pk_add_f32 v[4:5], v[4:5], 1.0 op_sel_hi:[1,0]
	v_rcp_f32_e32 v29, v29
	v_exp_f32_e32 v6, v6
	v_rcp_f32_e32 v28, v28
	s_waitcnt vmcnt(2) lgkmcnt(2)
	v_pk_fma_f32 v[28:29], v[28:29], v[38:39], v[42:43]
	v_exp_f32_e32 v7, v7
	v_rcp_f32_e32 v31, v31
	v_pk_add_f32 v[6:7], v[6:7], 1.0 op_sel_hi:[1,0]
	v_rcp_f32_e32 v30, v30
	s_nop 0
	v_pk_fma_f32 v[30:31], v[30:31], v[40:41], v[44:45]
	v_pk_mul_f32 v[34:35], v[12:13], v[12:13]
	v_rcp_f32_e32 v21, v21
	v_pk_mul_f32 v[36:37], v[14:15], v[14:15]
	v_rcp_f32_e32 v20, v20
	s_waitcnt vmcnt(0) lgkmcnt(1)
	v_pk_fma_f32 v[16:17], v[20:21], v[16:17], v[24:25]
	v_pk_mul_f32 v[38:39], v[28:29], v[28:29]
	v_rcp_f32_e32 v23, v23
	v_pk_mul_f32 v[40:41], v[30:31], v[30:31]
	v_rcp_f32_e32 v22, v22
	s_nop 0
	v_pk_fma_f32 v[18:19], v[22:23], v[18:19], v[26:27]
	v_pk_mul_f32 v[20:21], v[16:17], v[16:17]
	v_rcp_f32_e32 v5, v5
	v_pk_mul_f32 v[22:23], v[18:19], v[18:19]
	v_rcp_f32_e32 v4, v4
	s_waitcnt lgkmcnt(0)
	v_pk_fma_f32 v[4:5], v[4:5], v[0:1], v[8:9]
	v_div_scale_f32 v24, s[0:1], v6, v6, 1.0
	v_rcp_f32_e32 v25, v24
	v_rcp_f32_e32 v7, v7
	v_pk_mul_f32 v[0:1], v[4:5], v[4:5]
	v_fma_f32 v8, -v24, v25, 1.0
	v_fmac_f32_e32 v25, v8, v25
	v_div_scale_f32 v8, vcc, 1.0, v6, 1.0
	v_mul_f32_e32 v9, v8, v25
	v_fma_f32 v26, -v24, v9, v8
	v_fmac_f32_e32 v9, v26, v25
	v_fma_f32 v8, -v24, v9, v8
	v_div_fmas_f32 v8, v8, v25, v9
	v_div_fixup_f32 v6, v8, v6, 1.0
	v_add_f32_e32 v8, v34, v35
	v_add_f32_e32 v8, v36, v8
	v_add_f32_e32 v8, v37, v8
	v_add_f32_e32 v8, v38, v8
	v_add_f32_e32 v8, v39, v8
	v_add_f32_e32 v8, v40, v8
	v_add_f32_e32 v8, v41, v8
	v_add_f32_e32 v8, v20, v8
	v_add_f32_e32 v8, v21, v8
	v_add_f32_e32 v8, v22, v8
	v_add_f32_e32 v8, v23, v8
	v_pk_fma_f32 v[6:7], v[6:7], v[2:3], v[10:11]
	v_add_f32_e32 v0, v0, v8
	v_pk_mul_f32 v[2:3], v[6:7], v[6:7]
	v_add_f32_e32 v0, v1, v0
	v_add_f32_e32 v0, v2, v0
	v_add_f32_e32 v0, v3, v0
	ds_bpermute_b32 v1, v114, v0
	global_store_dwordx4 v[32:33], v[12:15], off
	global_store_dwordx4 v[32:33], v[28:31], off offset:16
	global_store_dwordx4 v[32:33], v[16:19], off offset:32
	global_store_dwordx4 v[32:33], v[4:7], off offset:48
	s_waitcnt lgkmcnt(0)
	v_add_f32_e32 v0, v0, v1
	ds_bpermute_b32 v1, v115, v0
	s_and_saveexec_b64 s[0:1], s[8:9]
	s_cbranch_execz .LBB0_1833
	s_waitcnt lgkmcnt(0)
	v_add_f32_e32 v2, v0, v1
	v_lshl_add_u64 v[0:1], v[48:49], 2, s[14:15]
	global_atomic_add_f32 v[0:1], v2, off
	s_branch .LBB0_1833
